# pass-1 S and P items of a chunk fused in one wave (shared operand stream, one item per wave, static); attention as 8-wave cooperative LDS-tile kernel before the scans
# speedup vs baseline: 1.0794x; 1.0196x over previous
; __device__ __forceinline__ void nat_phase(const Params& p, float* ldsf, int wave0, int nwaves) {
;     const int lane = threadIdx.x & 63, wid = __builtin_amdgcn_readfirstlane(threadIdx.x >> 6), l15 = lane & 15, lq = lane >> 4;
;     const u16* Qn = (const u16*)p.out; const u16* Kn = Qn + (size_t)NTOK * RW; const u16* VT = Kn + (size_t)NTOK * RW; const u16* Gn = VT + (size_t)NTOK * RW;
;     u16* MIX = (u16*)(p.ws + O_HN);
;     for (int item = wave0; item < 8192; item += nwaves) {
;         const int r = item & 255, h = (item >> 8) & 15, b = item >> 12;
;         const int rs = min(max(r - 4, 0), 248);
;         const u16* Qb = Qn + (size_t)(b * SEQ + r * 64) * RW + h * 64;
;         const u16* Kb = Kn + (size_t)(b * SEQ + rs * 64) * RW + h * 64;
;         const u16* Vb = VT + (size_t)((b * 16 + h) * 64) * SEQ + rs * 64;
;         float* tb = ldsf + wid * 256;
;         { const float* rpb = p.rpb + h * 465 + (rs - r + 7) * 31;
; #pragma unroll
;           for (int q = 0; q < 4; ++q) { const int e = lane + q * 64; if (e < 248) tb[e] = rpb[e]; } }
; #pragma unroll 1
;         for (int qt = 0; qt < 4; ++qt) {
;             const int c0 = qt * 16, cs0 = (qt == 0) ? 0 : (qt == 1 ? 8 : (qt == 2 ? 24 : 32));
;             const int c = c0 + l15, csq = min(max(c - 8, 0), 48);
;             const bf16x8 bq0 = *(const bf16x8*)(Qb + (size_t)c * RW + lq * 8), bq1 = *(const bf16x8*)(Qb + (size_t)c * RW + 32 + lq * 8);
.LBB0_413:
	s_cmp_lt_i32 s58, 5
	s_cselect_b64 s[0:1], -1, 0
	s_cmp_gt_i32 s59, 4
	s_cselect_b64 s[4:5], -1, 0
	s_and_b64 s[0:1], s[0:1], s[4:5]
	s_andn2_b64 vcc, exec, s[0:1]
	s_cbranch_vccnz .LBB0_628
	v_readfirstlane_b32 s0, v254
	v_and_b32_e32 v96, 63, v254
	s_cmp_lt_u32 s0, 0
	v_and_b32_e32 v65, 15, v254
	s_cbranch_scc1 .LBB0_555
	s_setprio 0
	s_lshr_b32 s1, s0, 6
	s_mov_b32 s64, s56
	s_and_b32 s65, s57, 0xffff
	s_brev_b32 s66, -2
	s_mov_b32 s67, 0x27000
	s_mov_b32 s68, s54
	s_and_b32 s69, s55, 0xffff
	s_mov_b32 s70, s66
	s_mov_b32 s71, s67
	s_mov_b32 s72, s50
	s_and_b32 s73, s51, 0xffff
	s_movk_i32 s74, 0x7440
	s_mov_b32 s75, s67
	v_and_b32_e32 v237, 15, v254
	v_bfe_u32 v238, v254, 4, 2
	v_and_b32_e32 v242, 63, v254
	v_lshlrev_b32_e32 v243, 4, v238
	v_lshl_add_u32 v224, v237, 11, v243
	v_lshl_add_u32 v226, v237, 15, v243
	v_lshrrev_b32_e32 v244, 2, v237
	v_and_b32_e32 v245, 3, v237
	v_lshl_add_u32 v244, v244, 3, v245
	v_lshl_add_u32 v225, v244, 11, v243
	v_lshlrev_b32_e32 v243, 3, v238
	v_lshl_add_u32 v227, v237, 11, v243
	v_lshl_add_u32 v228, v237, 12, v243
	v_xor_b32_e32 v248, 16, v242
	v_lshlrev_b32_e32 v248, 2, v248
	v_xor_b32_e32 v249, 32, v242
	v_lshlrev_b32_e32 v249, 2, v249
	s_cmp_lt_u32 s1, 4
	s_cselect_b64 vcc, -1, 0
	s_nop 3
	v_cndmask_b32_e32 v34, v226, v225, vcc
	s_and_b32 s4, s1, 3
	s_lshl_b32 s4, s4, 8
	s_add_u32 s4, s4, 0x1e800
	v_lshl_add_u32 v244, v242, 2, s4
	v_mov_b32_e32 v243, 0xf2c9f2ca
	ds_write_b32 v244, v243
	v_mov_b32_e32 v252, 0x3e38aa3b
	v_mov_b32_e32 v253, 0x3e38aa3b
	s_mov_b32 s88, s2
	s_mov_b32 s94, s96
	s_cmpk_lg_u32 s96, 0x100
	s_cbranch_scc1 .Lmy_nat_unit
	s_and_b32 s88, s2, 7
	s_lshl_b32 s88, s88, 5
	s_lshr_b32 s4, s2, 3
	s_add_u32 s88, s88, s4
	s_movk_i32 s94, 0x100
	s_bfe_u32 s4, s2, 0x20003
.Lmy_nat_stag:
	s_cmp_eq_u32 s4, 0
	s_cbranch_scc1 .Lmy_nat_nostag
	s_sleep 90
	s_sub_u32 s4, s4, 1
	s_branch .Lmy_nat_stag
.Lmy_nat_nostag:
.Lmy_nat_unit:
	s_cmpk_gt_i32 s88, 0x3ff
	s_cbranch_scc1 .Lmy_nat_end
	s_lshr_b32 s4, s88, 5
	s_and_b32 s5, s4, 15
	s_lshr_b32 s6, s4, 4
	s_and_b32 s4, s88, 31
	s_lshl_b32 s4, s4, 3
	s_add_i32 s7, s4, -4
	s_max_i32 s7, s7, 0
	s_min_i32 s7, s7, 0xf1
	s_add_u32 s92, s4, s1
	s_add_i32 s90, s92, -4
	s_max_i32 s90, s90, 0
	s_min_i32 s90, s90, 0xf8
	s_sub_u32 s89, s90, s7
	s_lshl_b32 s8, s6, 14
	s_lshl_b32 s9, s92, 6
	s_add_u32 s9, s9, s8
	s_lshl_b32 s84, s5, 7
	s_lshl_b32 s76, s9, 11
	s_add_u32 s76, s76, s84
	s_add_u32 s79, s76, 0xc000000
	s_lshl_b32 s80, s9, 12
	s_add_u32 s80, s80, s84
	s_add_u32 s80, s80, 0x3800800
	s_lshl_b32 s85, s7, 6
	s_add_u32 s85, s85, s8
	s_lshl_b32 s77, s85, 11
	s_add_u32 s77, s77, s84
	s_add_u32 s77, s77, 0x4000000
	s_lshl_b32 s85, s6, 4
	s_add_u32 s85, s85, s5
	s_lshl_b32 s78, s85, 21
	s_lshl_b32 s86, s7, 7
	s_add_u32 s78, s78, s86
	s_add_u32 s78, s78, 0x8000000
	s_sub_i32 s3, s90, s92
	s_add_i32 s3, s3, 7
	s_mul_i32 s3, s3, 124
	s_add_u32 s3, s3, 0x1e000
	s_lshl_b32 s85, s89, 12
	v_and_b32_e32 v242, 63, v254
	v_lshl_add_u32 v32, v242, 4, s85
	s_add_u32 s85, s85, 0xf000
	v_lshl_add_u32 v33, v242, 4, s85
	s_barrier
	s_mul_i32 s85, s5, 1860
	s_lshl_b32 s86, s1, 8
	s_add_u32 s85, s85, s86
	v_lshlrev_b32_e32 v244, 2, v242
	buffer_load_dword v243, v244, s[72:75], s85 offen
	s_add_u32 s86, s86, 0x1e000
	v_add_u32_e32 v244, s86, v244
	s_waitcnt vmcnt(0)
	v_mul_f32_e32 v243, 0x41000000, v243
	ds_write_b32 v244, v243
	s_waitcnt lgkmcnt(0)
	s_mov_b32 s16, 0
.Lmy_nat_cqt:
	s_lshl_b32 s82, s16, 4
	s_add_i32 s83, s82, -8
	s_max_i32 s83, s83, 0
	s_min_i32 s83, s83, 32
	s_lshl_b32 s84, s82, 11
	s_add_u32 s84, s84, s76
	buffer_load_dwordx4 v[192:195], v224, s[68:71], s84 offen
	buffer_load_dwordx4 v[196:199], v224, s[68:71], s84 offen offset:64
	s_cmp_lt_u32 s1, 4
	s_cbranch_scc0 .Lmy_nat_vkind
	s_lshl_b32 s91, s83, 11
	s_add_u32 s91, s91, s77
	s_lshr_b32 s85, s1, 1
	s_lshl_b32 s85, s85, 13
	s_add_u32 s91, s91, s85
	s_and_b32 s85, s1, 1
	s_lshl_b32 s85, s85, 6
	s_add_u32 s91, s91, s85
	s_mov_b32 s93, 0x20000
	s_lshl_b32 s86, s1, 10
	s_branch .Lmy_nat_kindset
.Lmy_nat_vkind:
	s_lshl_b32 s91, s83, 1
	s_add_u32 s91, s91, s78
	s_and_b32 s85, s1, 3
	s_lshl_b32 s85, s85, 19
	s_add_u32 s91, s91, s85
	s_movk_i32 s93, 0x80
	s_and_b32 s86, s1, 3
	s_lshl_b32 s86, s86, 10
	s_add_u32 s86, s86, 0xf000

; __device__ __forceinline__ void nat_phase(const Params& p, float* ldsf, int wave0, int nwaves) {
;     ...
;             for (int i = 0; i < 8; ++i)
; #pragma unroll
;                 for (int hf = 0; hf < 2; ++hf) { const u16* kp = Kb + (size_t)(i * 64 + cs0 + (l15 >> 2) * 8 + hf * 4 + (l15 & 3)) * RW + lq * 8;
;                     const bf16x8 a0 = *(const bf16x8*)kp, a1 = *(const bf16x8*)(kp + 32); f32x4 z = {0.f, 0.f, 0.f, 0.f};
;                     z = __builtin_amdgcn_mfma_f32_16x16x32_bf16(a0, bq0, z, 0, 0, 0); z = __builtin_amdgcn_mfma_f32_16x16x32_bf16(a1, bq1, z, 0, 0, 0); sc[i][hf] = z; }
;     ...
;                 for (int mt = 0; mt < 4; ++mt) { const u16* vp = Vb + (size_t)(mt * 16 + l15) * SEQ + i * 64 + cs0 + lq * 8;
.Lmy_nat_dma0:
	s_mov_b32 m0, s86
	s_nop 0
	buffer_load_dwordx4 v34, s[68:71], s91 offen lds
	s_add_u32 m0, m0, 0x1000
	s_add_u32 s91, s91, s93
	buffer_load_dwordx4 v34, s[68:71], s91 offen lds
	s_add_u32 m0, m0, 0x1000
	s_add_u32 s91, s91, s93
	buffer_load_dwordx4 v34, s[68:71], s91 offen lds
	s_add_u32 m0, m0, 0x1000
	s_add_u32 s91, s91, s93
	buffer_load_dwordx4 v34, s[68:71], s91 offen lds
	s_add_u32 m0, m0, 0x1000
	s_add_u32 s91, s91, s93
	buffer_load_dwordx4 v34, s[68:71], s91 offen lds
	s_add_u32 m0, m0, 0x1000
	s_add_u32 s91, s91, s93
	buffer_load_dwordx4 v34, s[68:71], s91 offen lds
	s_add_u32 m0, m0, 0x1000
	s_add_u32 s91, s91, s93
	buffer_load_dwordx4 v34, s[68:71], s91 offen lds
	s_add_u32 m0, m0, 0x1000
	s_add_u32 s91, s91, s93
	buffer_load_dwordx4 v34, s[68:71], s91 offen lds
	s_add_u32 m0, m0, 0x1000
	s_add_u32 s91, s91, s93
	buffer_load_dwordx4 v34, s[68:71], s91 offen lds
	s_add_u32 m0, m0, 0x1000
	s_add_u32 s91, s91, s93
	buffer_load_dwordx4 v34, s[68:71], s91 offen lds
	s_add_u32 m0, m0, 0x1000
	s_add_u32 s91, s91, s93
	buffer_load_dwordx4 v34, s[68:71], s91 offen lds
	s_add_u32 m0, m0, 0x1000
	s_add_u32 s91, s91, s93
	buffer_load_dwordx4 v34, s[68:71], s91 offen lds
	s_add_u32 m0, m0, 0x1000
	s_add_u32 s91, s91, s93
	buffer_load_dwordx4 v34, s[68:71], s91 offen lds
	s_add_u32 m0, m0, 0x1000
	s_add_u32 s91, s91, s93
	buffer_load_dwordx4 v34, s[68:71], s91 offen lds
	s_add_u32 m0, m0, 0x1000
	s_add_u32 s91, s91, s93
	buffer_load_dwordx4 v34, s[68:71], s91 offen lds
.Lmy_nat_dma1:
	s_cmp_lt_u32 s1, 4
	s_cbranch_scc0 .Lmy_nat_vw
	s_waitcnt vmcnt(0)
	s_branch .Lmy_nat_vj
.Lmy_nat_vw:
	s_waitcnt vmcnt(15)

; __device__ __forceinline__ void nat_phase(const Params& p, float* ldsf, int wave0, int nwaves) {
;     ...
;             for (int i = 0; i < 8; ++i)
; #pragma unroll
;                 for (int hf = 0; hf < 2; ++hf) { const u16* kp = Kb + (size_t)(i * 64 + cs0 + (l15 >> 2) * 8 + hf * 4 + (l15 & 3)) * RW + lq * 8;
;                     const bf16x8 a0 = *(const bf16x8*)kp, a1 = *(const bf16x8*)(kp + 32); f32x4 z = {0.f, 0.f, 0.f, 0.f};
;                     z = __builtin_amdgcn_mfma_f32_16x16x32_bf16(a0, bq0, z, 0, 0, 0); z = __builtin_amdgcn_mfma_f32_16x16x32_bf16(a1, bq1, z, 0, 0, 0); sc[i][hf] = z; }
;             float mx = -1e30f;
; #pragma unroll
;             for (int i = 0; i < 8; ++i)
; #pragma unroll
;                 for (int hf = 0; hf < 2; ++hf)
; #pragma unroll
;                     for (int j = 0; j < 4; ++j) { const int kc = cs0 + lq * 8 + hf * 4 + j; const bool valid = (kc >= csq) && (kc < csq + 16); const int bc = valid ? (kc - c + 15) : 0;
;                         const float s = valid ? sc[i][hf][j] * 0.125f + tb[i * 31 + bc] : -1e30f; sc[i][hf][j] = s; mx = fmaxf(mx, s); }
.Lmy_nat_cmp0:
	v_add_u32_e32 v241, s82, v237
	v_add_u32_e32 v242, -8, v241
	v_med3_i32 v242, v242, 0, 48
	v_lshl_add_u32 v251, v238, 3, s83
	v_sub_u32_e32 v243, v251, v242
	v_sub_u32_e32 v244, v251, v241
	v_lshl_add_u32 v244, v244, 2, s3
	v_mov_b32_e32 v245, 0x1e800
	v_add_u32_e32 v246, 0, v243
	v_cmp_gt_u32_e32 vcc, 16, v246
	v_add_u32_e32 v247, 60, v244
	s_nop 0
	v_cndmask_b32_e32 v229, v245, v247, vcc
	v_add_u32_e32 v246, 1, v243
	v_cmp_gt_u32_e32 vcc, 16, v246
	v_add_u32_e32 v247, 64, v244
	s_nop 0
	v_cndmask_b32_e32 v230, v245, v247, vcc
	v_add_u32_e32 v246, 2, v243
	v_cmp_gt_u32_e32 vcc, 16, v246
	v_add_u32_e32 v247, 68, v244
	s_nop 0
	v_cndmask_b32_e32 v231, v245, v247, vcc
	v_add_u32_e32 v246, 3, v243
	v_cmp_gt_u32_e32 vcc, 16, v246
	v_add_u32_e32 v247, 72, v244
	s_nop 0
	v_cndmask_b32_e32 v232, v245, v247, vcc
	v_add_u32_e32 v246, 4, v243
	v_cmp_gt_u32_e32 vcc, 16, v246
	v_add_u32_e32 v247, 76, v244
	s_nop 0
	v_cndmask_b32_e32 v233, v245, v247, vcc
	v_add_u32_e32 v246, 5, v243
	v_cmp_gt_u32_e32 vcc, 16, v246
	v_add_u32_e32 v247, 80, v244
	s_nop 0
	v_cndmask_b32_e32 v234, v245, v247, vcc
	v_add_u32_e32 v246, 6, v243
	v_cmp_gt_u32_e32 vcc, 16, v246
	v_add_u32_e32 v247, 84, v244
	s_nop 0
	v_cndmask_b32_e32 v235, v245, v247, vcc
	v_add_u32_e32 v246, 7, v243
	v_cmp_gt_u32_e32 vcc, 16, v246
	v_add_u32_e32 v247, 88, v244
	s_nop 0
	v_cndmask_b32_e32 v236, v245, v247, vcc
	ds_read_b32 v128, v229 offset:0
	ds_read_b32 v129, v230 offset:0
	ds_read_b32 v130, v231 offset:0
	ds_read_b32 v131, v232 offset:0
	ds_read_b32 v132, v233 offset:0
	ds_read_b32 v133, v234 offset:0
	ds_read_b32 v134, v235 offset:0
	ds_read_b32 v135, v236 offset:0
	ds_read_b32 v136, v229 offset:124
	ds_read_b32 v137, v230 offset:124
	ds_read_b32 v138, v231 offset:124
	ds_read_b32 v139, v232 offset:124
	ds_read_b32 v140, v233 offset:124
	ds_read_b32 v141, v234 offset:124
	ds_read_b32 v142, v235 offset:124
	ds_read_b32 v143, v236 offset:124
	ds_read_b32 v144, v229 offset:248
	ds_read_b32 v145, v230 offset:248
	ds_read_b32 v146, v231 offset:248
	ds_read_b32 v147, v232 offset:248
	ds_read_b32 v148, v233 offset:248
	ds_read_b32 v149, v234 offset:248
	ds_read_b32 v150, v235 offset:248
	ds_read_b32 v151, v236 offset:248
	ds_read_b32 v152, v229 offset:372
	ds_read_b32 v153, v230 offset:372
	ds_read_b32 v154, v231 offset:372
	ds_read_b32 v155, v232 offset:372
	ds_read_b32 v156, v233 offset:372
	ds_read_b32 v157, v234 offset:372
	ds_read_b32 v158, v235 offset:372
	ds_read_b32 v159, v236 offset:372
	ds_read_b32 v160, v229 offset:496
	ds_read_b32 v161, v230 offset:496
	ds_read_b32 v162, v231 offset:496
	ds_read_b32 v163, v232 offset:496
	ds_read_b32 v164, v233 offset:496
	ds_read_b32 v165, v234 offset:496
	ds_read_b32 v166, v235 offset:496
	ds_read_b32 v167, v236 offset:496
	ds_read_b32 v168, v229 offset:620
	ds_read_b32 v169, v230 offset:620
	ds_read_b32 v170, v231 offset:620
	ds_read_b32 v171, v232 offset:620
	ds_read_b32 v172, v233 offset:620
	ds_read_b32 v173, v234 offset:620
	ds_read_b32 v174, v235 offset:620
	ds_read_b32 v175, v236 offset:620
	ds_read_b32 v176, v229 offset:744
	ds_read_b32 v177, v230 offset:744
	ds_read_b32 v178, v231 offset:744
	ds_read_b32 v179, v232 offset:744
	ds_read_b32 v180, v233 offset:744
	ds_read_b32 v181, v234 offset:744
	ds_read_b32 v182, v235 offset:744
	ds_read_b32 v183, v236 offset:744
	ds_read_b32 v184, v229 offset:868
	ds_read_b32 v185, v230 offset:868
	ds_read_b32 v186, v231 offset:868
	ds_read_b32 v187, v232 offset:868
	ds_read_b32 v188, v233 offset:868
	ds_read_b32 v189, v234 offset:868
	ds_read_b32 v190, v235 offset:868
	ds_read_b32 v191, v236 offset:868
	s_waitcnt lgkmcnt(0)
	ds_read_b128 v[0:3], v32 offset:0
	ds_read_b128 v[4:7], v32 offset:1024
	ds_read_b128 v[8:11], v32 offset:2048
	ds_read_b128 v[12:15], v32 offset:3072
	ds_read_b128 v[16:19], v32 offset:4096
	ds_read_b128 v[20:23], v32 offset:5120
	ds_read_b128 v[24:27], v32 offset:6144
	ds_read_b128 v[28:31], v32 offset:7168
	s_waitcnt lgkmcnt(7)
	v_mfma_f32_16x16x32_bf16 v[128:131], v[0:3], v[192:195], v[128:131]
	ds_read_b128 v[0:3], v32 offset:8192
	s_waitcnt lgkmcnt(7)
	v_mfma_f32_16x16x32_bf16 v[128:131], v[4:7], v[196:199], v[128:131]
	ds_read_b128 v[4:7], v32 offset:9216
	s_waitcnt lgkmcnt(7)
	v_mfma_f32_16x16x32_bf16 v[132:135], v[8:11], v[192:195], v[132:135]
	ds_read_b128 v[8:11], v32 offset:10240
	s_waitcnt lgkmcnt(7)
	v_mfma_f32_16x16x32_bf16 v[132:135], v[12:15], v[196:199], v[132:135]
	ds_read_b128 v[12:15], v32 offset:11264
	s_waitcnt lgkmcnt(7)
	v_mfma_f32_16x16x32_bf16 v[136:139], v[16:19], v[192:195], v[136:139]
	ds_read_b128 v[16:19], v32 offset:12288
	s_waitcnt lgkmcnt(7)
	v_mfma_f32_16x16x32_bf16 v[136:139], v[20:23], v[196:199], v[136:139]
	ds_read_b128 v[20:23], v32 offset:13312
	s_waitcnt lgkmcnt(7)
	v_mfma_f32_16x16x32_bf16 v[140:143], v[24:27], v[192:195], v[140:143]
	ds_read_b128 v[24:27], v32 offset:14336
	s_waitcnt lgkmcnt(7)
	v_mfma_f32_16x16x32_bf16 v[140:143], v[28:31], v[196:199], v[140:143]
	ds_read_b128 v[28:31], v32 offset:15360
	s_waitcnt lgkmcnt(7)
	v_mfma_f32_16x16x32_bf16 v[144:147], v[0:3], v[192:195], v[144:147]
	ds_read_b128 v[0:3], v32 offset:16384
	s_waitcnt lgkmcnt(7)
	v_mfma_f32_16x16x32_bf16 v[144:147], v[4:7], v[196:199], v[144:147]
	ds_read_b128 v[4:7], v32 offset:17408
	s_waitcnt lgkmcnt(7)
	v_mfma_f32_16x16x32_bf16 v[148:151], v[8:11], v[192:195], v[148:151]
	ds_read_b128 v[8:11], v32 offset:18432
	s_waitcnt lgkmcnt(7)
	v_mfma_f32_16x16x32_bf16 v[148:151], v[12:15], v[196:199], v[148:151]
	ds_read_b128 v[12:15], v32 offset:19456
	s_waitcnt lgkmcnt(7)
	v_mfma_f32_16x16x32_bf16 v[152:155], v[16:19], v[192:195], v[152:155]
	ds_read_b128 v[16:19], v32 offset:20480
	s_waitcnt lgkmcnt(7)
; __device__ __forceinline__ void nat_phase(const Params& p, float* ldsf, int wave0, int nwaves) {
;     ...
;             float mx = -1e30f;
; #pragma unroll
;             for (int i = 0; i < 8; ++i)
; #pragma unroll
;                 for (int hf = 0; hf < 2; ++hf)
; #pragma unroll
;                     for (int j = 0; j < 4; ++j) { const int kc = cs0 + lq * 8 + hf * 4 + j; const bool valid = (kc >= csq) && (kc < csq + 16); const int bc = valid ? (kc - c + 15) : 0;
;                         const float s = valid ? sc[i][hf][j] * 0.125f + tb[i * 31 + bc] : -1e30f; sc[i][hf][j] = s; mx = fmaxf(mx, s); }
;             mx = fmaxf(mx, __shfl_xor(mx, 16)); mx = fmaxf(mx, __shfl_xor(mx, 32));
;     ...
;             for (int mt = 0; mt < 4; ++mt) { const int ch = h * 64 + mt * 16 + lq * 4; const u32x2 gw = *(const u32x2*)(Gn + tok * RW + ch);
	v_mfma_f32_16x16x32_bf16 v[152:155], v[20:23], v[196:199], v[152:155]
	ds_read_b128 v[20:23], v32 offset:21504
	s_waitcnt lgkmcnt(7)
	v_mfma_f32_16x16x32_bf16 v[156:159], v[24:27], v[192:195], v[156:159]
	ds_read_b128 v[24:27], v32 offset:22528
	s_waitcnt lgkmcnt(7)
	v_mfma_f32_16x16x32_bf16 v[156:159], v[28:31], v[196:199], v[156:159]
	ds_read_b128 v[28:31], v32 offset:23552
	s_waitcnt lgkmcnt(7)
	v_mfma_f32_16x16x32_bf16 v[160:163], v[0:3], v[192:195], v[160:163]
	ds_read_b128 v[0:3], v32 offset:24576
	s_waitcnt lgkmcnt(7)
	v_mfma_f32_16x16x32_bf16 v[160:163], v[4:7], v[196:199], v[160:163]
	ds_read_b128 v[4:7], v32 offset:25600
	s_waitcnt lgkmcnt(7)
	v_mfma_f32_16x16x32_bf16 v[164:167], v[8:11], v[192:195], v[164:167]
	ds_read_b128 v[8:11], v32 offset:26624
	s_waitcnt lgkmcnt(7)
	v_mfma_f32_16x16x32_bf16 v[164:167], v[12:15], v[196:199], v[164:167]
	ds_read_b128 v[12:15], v32 offset:27648
	s_waitcnt lgkmcnt(7)
	v_mfma_f32_16x16x32_bf16 v[168:171], v[16:19], v[192:195], v[168:171]
	ds_read_b128 v[16:19], v32 offset:28672
	s_waitcnt lgkmcnt(7)
	v_mfma_f32_16x16x32_bf16 v[168:171], v[20:23], v[196:199], v[168:171]
	ds_read_b128 v[20:23], v32 offset:29696
	s_waitcnt lgkmcnt(7)
	v_mfma_f32_16x16x32_bf16 v[172:175], v[24:27], v[192:195], v[172:175]
	ds_read_b128 v[24:27], v32 offset:30720
	s_waitcnt lgkmcnt(7)
	v_mfma_f32_16x16x32_bf16 v[172:175], v[28:31], v[196:199], v[172:175]
	ds_read_b128 v[28:31], v32 offset:31744
	s_waitcnt lgkmcnt(7)
	v_mfma_f32_16x16x32_bf16 v[176:179], v[0:3], v[192:195], v[176:179]
	s_waitcnt lgkmcnt(6)
	v_mfma_f32_16x16x32_bf16 v[176:179], v[4:7], v[196:199], v[176:179]
	s_waitcnt lgkmcnt(5)
	v_mfma_f32_16x16x32_bf16 v[180:183], v[8:11], v[192:195], v[180:183]
	s_waitcnt lgkmcnt(4)
	v_mfma_f32_16x16x32_bf16 v[180:183], v[12:15], v[196:199], v[180:183]
	s_waitcnt lgkmcnt(3)
	v_mfma_f32_16x16x32_bf16 v[184:187], v[16:19], v[192:195], v[184:187]
	s_waitcnt lgkmcnt(2)
	v_mfma_f32_16x16x32_bf16 v[184:187], v[20:23], v[196:199], v[184:187]
	s_waitcnt lgkmcnt(1)
	v_mfma_f32_16x16x32_bf16 v[188:191], v[24:27], v[192:195], v[188:191]
	s_waitcnt lgkmcnt(0)
	v_mfma_f32_16x16x32_bf16 v[188:191], v[28:31], v[196:199], v[188:191]
	s_lshl_b32 s84, s82, 11
	s_add_u32 s84, s84, s79
	buffer_load_dwordx2 v[216:217], v227, s[68:71], s84 offen offset:0
	buffer_load_dwordx2 v[218:219], v227, s[68:71], s84 offen offset:32
	buffer_load_dwordx2 v[220:221], v227, s[68:71], s84 offen offset:64
	buffer_load_dwordx2 v[222:223], v227, s[68:71], s84 offen offset:96
	v_max3_f32 v239, v128, v129, v130
	v_max3_f32 v239, v239, v131, v132
	v_max3_f32 v239, v239, v133, v134
	v_max3_f32 v239, v239, v135, v136
	v_max3_f32 v239, v239, v137, v138
	v_max3_f32 v239, v239, v139, v140
	v_max3_f32 v239, v239, v141, v142
	v_max3_f32 v239, v239, v143, v144
	v_max3_f32 v239, v239, v145, v146
	v_max3_f32 v239, v239, v147, v148
	v_max3_f32 v239, v239, v149, v150
	v_max3_f32 v239, v239, v151, v152
	v_max3_f32 v239, v239, v153, v154
	v_max3_f32 v239, v239, v155, v156
	v_max3_f32 v239, v239, v157, v158
	v_max3_f32 v239, v239, v159, v160
	v_max3_f32 v239, v239, v161, v162
	v_max3_f32 v239, v239, v163, v164
	v_max3_f32 v239, v239, v165, v166
	v_max3_f32 v239, v239, v167, v168
	v_max3_f32 v239, v239, v169, v170
	v_max3_f32 v239, v239, v171, v172
	v_max3_f32 v239, v239, v173, v174
	v_max3_f32 v239, v239, v175, v176
	v_max3_f32 v239, v239, v177, v178
	v_max3_f32 v239, v239, v179, v180
	v_max3_f32 v239, v239, v181, v182
	v_max3_f32 v239, v239, v183, v184
	v_max3_f32 v239, v239, v185, v186
	v_max3_f32 v239, v239, v187, v188
	v_max3_f32 v239, v239, v189, v190
	v_max_f32_e32 v239, v239, v191
	ds_bpermute_b32 v242, v248, v239
	s_waitcnt lgkmcnt(0)
	v_max_f32_e32 v239, v239, v242
	ds_bpermute_b32 v242, v249, v239
	s_waitcnt lgkmcnt(0)
	v_max_f32_e32 v239, v239, v242
	v_mul_f32_e64 v242, -v239, v252
	v_mov_b32_e32 v243, v242
	v_pk_fma_f32 v[128:129], v[128:129], v[252:253], v[242:243]
	v_pk_fma_f32 v[130:131], v[130:131], v[252:253], v[242:243]
	v_pk_fma_f32 v[132:133], v[132:133], v[252:253], v[242:243]
	v_pk_fma_f32 v[134:135], v[134:135], v[252:253], v[242:243]
	v_pk_fma_f32 v[136:137], v[136:137], v[252:253], v[242:243]
	v_pk_fma_f32 v[138:139], v[138:139], v[252:253], v[242:243]
	v_pk_fma_f32 v[140:141], v[140:141], v[252:253], v[242:243]
	v_pk_fma_f32 v[142:143], v[142:143], v[252:253], v[242:243]
	v_pk_fma_f32 v[144:145], v[144:145], v[252:253], v[242:243]
	v_pk_fma_f32 v[146:147], v[146:147], v[252:253], v[242:243]
	v_pk_fma_f32 v[148:149], v[148:149], v[252:253], v[242:243]
	v_pk_fma_f32 v[150:151], v[150:151], v[252:253], v[242:243]
	v_pk_fma_f32 v[152:153], v[152:153], v[252:253], v[242:243]
	v_pk_fma_f32 v[154:155], v[154:155], v[252:253], v[242:243]
	v_pk_fma_f32 v[156:157], v[156:157], v[252:253], v[242:243]
	v_pk_fma_f32 v[158:159], v[158:159], v[252:253], v[242:243]
	v_pk_fma_f32 v[160:161], v[160:161], v[252:253], v[242:243]
	v_pk_fma_f32 v[162:163], v[162:163], v[252:253], v[242:243]
	v_pk_fma_f32 v[164:165], v[164:165], v[252:253], v[242:243]
	v_pk_fma_f32 v[166:167], v[166:167], v[252:253], v[242:243]
	v_pk_fma_f32 v[168:169], v[168:169], v[252:253], v[242:243]
	v_pk_fma_f32 v[170:171], v[170:171], v[252:253], v[242:243]
	v_pk_fma_f32 v[172:173], v[172:173], v[252:253], v[242:243]
	v_pk_fma_f32 v[174:175], v[174:175], v[252:253], v[242:243]
	v_pk_fma_f32 v[176:177], v[176:177], v[252:253], v[242:243]
	v_pk_fma_f32 v[178:179], v[178:179], v[252:253], v[242:243]
	v_pk_fma_f32 v[180:181], v[180:181], v[252:253], v[242:243]
	v_pk_fma_f32 v[182:183], v[182:183], v[252:253], v[242:243]
	v_pk_fma_f32 v[184:185], v[184:185], v[252:253], v[242:243]
; __device__ __forceinline__ unsigned cvt_pk_bf16(float lo, float hi) { unsigned r; asm volatile("v_cvt_pk_bf16_f32 %0, %1, %2" : "=v"(r) : "v"(lo), "v"(hi)); return r; }
; __device__ __forceinline__ void nat_phase(const Params& p, float* ldsf, int wave0, int nwaves) {
;     ...
;             float sum = 0.f;
; #pragma unroll
;             for (int i = 0; i < 8; ++i)
; #pragma unroll
;                 for (int hf = 0; hf < 2; ++hf)
; #pragma unroll
;                     for (int j = 0; j < 4; ++j) { const float e = __expf(sc[i][hf][j] - mx); sc[i][hf][j] = e; sum += e; }
;             sum += __shfl_xor(sum, 16); sum += __shfl_xor(sum, 32);
;             const float inv = 1.0f / sum;
;             f32x4 o[4];
; #pragma unroll
;             for (int mt = 0; mt < 4; ++mt) o[mt] = (f32x4){0.f, 0.f, 0.f, 0.f};
; #pragma unroll
;             for (int i = 0; i < 8; ++i) {
;                 u32x4 pw; pw.x = cvt_pk_bf16(sc[i][0][0] * inv, sc[i][0][1] * inv); pw.y = cvt_pk_bf16(sc[i][0][2] * inv, sc[i][0][3] * inv);
;                 pw.z = cvt_pk_bf16(sc[i][1][0] * inv, sc[i][1][1] * inv); pw.w = cvt_pk_bf16(sc[i][1][2] * inv, sc[i][1][3] * inv);
;                 const bf16x8 bp = __builtin_bit_cast(bf16x8, pw);
	v_pk_fma_f32 v[186:187], v[186:187], v[252:253], v[242:243]
	v_pk_fma_f32 v[188:189], v[188:189], v[252:253], v[242:243]
	v_pk_fma_f32 v[190:191], v[190:191], v[252:253], v[242:243]
	v_exp_f32_e32 v128, v128
	v_exp_f32_e32 v129, v129
	v_exp_f32_e32 v130, v130
	v_exp_f32_e32 v131, v131
	v_exp_f32_e32 v132, v132
	v_exp_f32_e32 v133, v133
	v_exp_f32_e32 v134, v134
	v_exp_f32_e32 v135, v135
	v_exp_f32_e32 v136, v136
	v_exp_f32_e32 v137, v137
	v_exp_f32_e32 v138, v138
	v_exp_f32_e32 v139, v139
	v_exp_f32_e32 v140, v140
	v_exp_f32_e32 v141, v141
	v_exp_f32_e32 v142, v142
	v_exp_f32_e32 v143, v143
	v_exp_f32_e32 v144, v144
	v_exp_f32_e32 v145, v145
	v_exp_f32_e32 v146, v146
	v_exp_f32_e32 v147, v147
	v_exp_f32_e32 v148, v148
	v_exp_f32_e32 v149, v149
	v_exp_f32_e32 v150, v150
	v_exp_f32_e32 v151, v151
	v_exp_f32_e32 v152, v152
	v_exp_f32_e32 v153, v153
	v_exp_f32_e32 v154, v154
	v_exp_f32_e32 v155, v155
	v_exp_f32_e32 v156, v156
	v_exp_f32_e32 v157, v157
	v_exp_f32_e32 v158, v158
	v_exp_f32_e32 v159, v159
	v_exp_f32_e32 v160, v160
	v_exp_f32_e32 v161, v161
	v_exp_f32_e32 v162, v162
	v_exp_f32_e32 v163, v163
	v_exp_f32_e32 v164, v164
	v_exp_f32_e32 v165, v165
	v_exp_f32_e32 v166, v166
	v_exp_f32_e32 v167, v167
	v_exp_f32_e32 v168, v168
	v_exp_f32_e32 v169, v169
	v_exp_f32_e32 v170, v170
	v_exp_f32_e32 v171, v171
	v_exp_f32_e32 v172, v172
	v_exp_f32_e32 v173, v173
	v_exp_f32_e32 v174, v174
	v_exp_f32_e32 v175, v175
	v_exp_f32_e32 v176, v176
	v_exp_f32_e32 v177, v177
	v_exp_f32_e32 v178, v178
	v_exp_f32_e32 v179, v179
	v_exp_f32_e32 v180, v180
	v_exp_f32_e32 v181, v181
	v_exp_f32_e32 v182, v182
	v_exp_f32_e32 v183, v183
	v_exp_f32_e32 v184, v184
	v_exp_f32_e32 v185, v185
	v_exp_f32_e32 v186, v186
	v_exp_f32_e32 v187, v187
	v_exp_f32_e32 v188, v188
	v_exp_f32_e32 v189, v189
	v_exp_f32_e32 v190, v190
	v_exp_f32_e32 v191, v191
	s_nop 0
	v_pk_add_f32 v[244:245], v[128:129], v[130:131]
	v_pk_add_f32 v[246:247], v[132:133], v[134:135]
	v_pk_add_f32 v[244:245], v[244:245], v[136:137]
	v_pk_add_f32 v[246:247], v[246:247], v[138:139]
	v_pk_add_f32 v[244:245], v[244:245], v[140:141]
	v_pk_add_f32 v[246:247], v[246:247], v[142:143]
	v_pk_add_f32 v[244:245], v[244:245], v[144:145]
	v_pk_add_f32 v[246:247], v[246:247], v[146:147]
	v_pk_add_f32 v[244:245], v[244:245], v[148:149]
	v_pk_add_f32 v[246:247], v[246:247], v[150:151]
	v_pk_add_f32 v[244:245], v[244:245], v[152:153]
	v_pk_add_f32 v[246:247], v[246:247], v[154:155]
	v_pk_add_f32 v[244:245], v[244:245], v[156:157]
	v_pk_add_f32 v[246:247], v[246:247], v[158:159]
	v_pk_add_f32 v[244:245], v[244:245], v[160:161]
	v_pk_add_f32 v[246:247], v[246:247], v[162:163]
	v_pk_add_f32 v[244:245], v[244:245], v[164:165]
	v_pk_add_f32 v[246:247], v[246:247], v[166:167]
	v_pk_add_f32 v[244:245], v[244:245], v[168:169]
	v_pk_add_f32 v[246:247], v[246:247], v[170:171]
	v_pk_add_f32 v[244:245], v[244:245], v[172:173]
	v_pk_add_f32 v[246:247], v[246:247], v[174:175]
	v_pk_add_f32 v[244:245], v[244:245], v[176:177]
	v_pk_add_f32 v[246:247], v[246:247], v[178:179]
	v_pk_add_f32 v[244:245], v[244:245], v[180:181]
	v_pk_add_f32 v[246:247], v[246:247], v[182:183]
	v_pk_add_f32 v[244:245], v[244:245], v[184:185]
	v_pk_add_f32 v[246:247], v[246:247], v[186:187]
	v_pk_add_f32 v[244:245], v[244:245], v[188:189]
	v_pk_add_f32 v[246:247], v[246:247], v[190:191]
	v_pk_add_f32 v[244:245], v[244:245], v[246:247]
	v_add_f32_e32 v240, v244, v245
	ds_bpermute_b32 v242, v248, v240
	s_waitcnt lgkmcnt(0)
	v_add_f32_e32 v240, v240, v242
	ds_bpermute_b32 v242, v249, v240
	s_waitcnt lgkmcnt(0)
	v_add_f32_e32 v240, v240, v242
	v_rcp_f32_e32 v242, v240
	s_nop 0
	v_mov_b32_e32 v243, v242
	v_pk_mul_f32 v[128:129], v[128:129], v[242:243]
	v_pk_mul_f32 v[130:131], v[130:131], v[242:243]
	v_pk_mul_f32 v[132:133], v[132:133], v[242:243]
	v_pk_mul_f32 v[134:135], v[134:135], v[242:243]
	v_pk_mul_f32 v[136:137], v[136:137], v[242:243]
	v_pk_mul_f32 v[138:139], v[138:139], v[242:243]
	v_pk_mul_f32 v[140:141], v[140:141], v[242:243]
	v_pk_mul_f32 v[142:143], v[142:143], v[242:243]
	v_pk_mul_f32 v[144:145], v[144:145], v[242:243]
	v_pk_mul_f32 v[146:147], v[146:147], v[242:243]
	v_pk_mul_f32 v[148:149], v[148:149], v[242:243]
	v_pk_mul_f32 v[150:151], v[150:151], v[242:243]
	v_pk_mul_f32 v[152:153], v[152:153], v[242:243]
	v_pk_mul_f32 v[154:155], v[154:155], v[242:243]
	v_pk_mul_f32 v[156:157], v[156:157], v[242:243]
	v_pk_mul_f32 v[158:159], v[158:159], v[242:243]
	v_pk_mul_f32 v[160:161], v[160:161], v[242:243]
	v_pk_mul_f32 v[162:163], v[162:163], v[242:243]
	v_pk_mul_f32 v[164:165], v[164:165], v[242:243]
	v_pk_mul_f32 v[166:167], v[166:167], v[242:243]
	v_pk_mul_f32 v[168:169], v[168:169], v[242:243]
	v_pk_mul_f32 v[170:171], v[170:171], v[242:243]
	v_pk_mul_f32 v[172:173], v[172:173], v[242:243]
	v_pk_mul_f32 v[174:175], v[174:175], v[242:243]
	v_pk_mul_f32 v[176:177], v[176:177], v[242:243]
	v_pk_mul_f32 v[178:179], v[178:179], v[242:243]
	v_pk_mul_f32 v[180:181], v[180:181], v[242:243]
	v_pk_mul_f32 v[182:183], v[182:183], v[242:243]
	v_pk_mul_f32 v[184:185], v[184:185], v[242:243]
	v_pk_mul_f32 v[186:187], v[186:187], v[242:243]
	v_pk_mul_f32 v[188:189], v[188:189], v[242:243]
	v_pk_mul_f32 v[190:191], v[190:191], v[242:243]
	v_cvt_pk_bf16_f32 v128, v128, v129
	v_cvt_pk_bf16_f32 v129, v130, v131
	v_cvt_pk_bf16_f32 v130, v132, v133
	v_cvt_pk_bf16_f32 v131, v134, v135
	v_cvt_pk_bf16_f32 v136, v136, v137
	v_cvt_pk_bf16_f32 v137, v138, v139
	v_cvt_pk_bf16_f32 v138, v140, v141
	v_cvt_pk_bf16_f32 v139, v142, v143
	v_cvt_pk_bf16_f32 v144, v144, v145
	v_cvt_pk_bf16_f32 v145, v146, v147
	v_cvt_pk_bf16_f32 v146, v148, v149
	v_cvt_pk_bf16_f32 v147, v150, v151
	v_cvt_pk_bf16_f32 v152, v152, v153
	v_cvt_pk_bf16_f32 v153, v154, v155
	v_cvt_pk_bf16_f32 v154, v156, v157
	v_cvt_pk_bf16_f32 v155, v158, v159
	v_cvt_pk_bf16_f32 v160, v160, v161
	v_cvt_pk_bf16_f32 v161, v162, v163
	v_cvt_pk_bf16_f32 v162, v164, v165
	v_cvt_pk_bf16_f32 v163, v166, v167
	v_cvt_pk_bf16_f32 v168, v168, v169
	v_cvt_pk_bf16_f32 v169, v170, v171
	v_cvt_pk_bf16_f32 v170, v172, v173
	v_cvt_pk_bf16_f32 v171, v174, v175
	v_cvt_pk_bf16_f32 v176, v176, v177
	v_cvt_pk_bf16_f32 v177, v178, v179
	v_cvt_pk_bf16_f32 v178, v180, v181
	v_cvt_pk_bf16_f32 v179, v182, v183
	v_cvt_pk_bf16_f32 v184, v184, v185
	v_cvt_pk_bf16_f32 v185, v186, v187
	v_cvt_pk_bf16_f32 v186, v188, v189
	v_cvt_pk_bf16_f32 v187, v190, v191
	s_waitcnt vmcnt(4)
	s_barrier
; __device__ __forceinline__ float bflo(unsigned w) { return __uint_as_float(w << 16); }
; __device__ __forceinline__ float bfhi(unsigned w) { return __uint_as_float(w & 0xffff0000u); }
; __device__ __forceinline__ unsigned cvt_pk_bf16(float lo, float hi) { unsigned r; asm volatile("v_cvt_pk_bf16_f32 %0, %1, %2" : "=v"(r) : "v"(lo), "v"(hi)); return r; }
; __device__ __forceinline__ float sigmoidf_(float x) { return __builtin_amdgcn_rcpf(1.0f + __expf(-x)); }
; __device__ __forceinline__ void nat_phase(const Params& p, float* ldsf, int wave0, int nwaves) {
;     ...
; #pragma unroll
;             for (int mt = 0; mt < 4; ++mt) o[mt] = (f32x4){0.f, 0.f, 0.f, 0.f};
; #pragma unroll
;             for (int i = 0; i < 8; ++i) {
;                 u32x4 pw; pw.x = cvt_pk_bf16(sc[i][0][0] * inv, sc[i][0][1] * inv); pw.y = cvt_pk_bf16(sc[i][0][2] * inv, sc[i][0][3] * inv);
;                 pw.z = cvt_pk_bf16(sc[i][1][0] * inv, sc[i][1][1] * inv); pw.w = cvt_pk_bf16(sc[i][1][2] * inv, sc[i][1][3] * inv);
;                 const bf16x8 bp = __builtin_bit_cast(bf16x8, pw);
; #pragma unroll
;                 for (int mt = 0; mt < 4; ++mt) { const u16* vp = Vb + (size_t)(mt * 16 + l15) * SEQ + i * 64 + cs0 + lq * 8;
;                     o[mt] = __builtin_amdgcn_mfma_f32_16x16x32_bf16(*(const bf16x8*)vp, bp, o[mt], 0, 0, 0); }
;             }
;             const size_t tok = (size_t)(b * SEQ + r * 64 + c);
; #pragma unroll
;             for (int mt = 0; mt < 4; ++mt) { const int ch = h * 64 + mt * 16 + lq * 4; const u32x2 gw = *(const u32x2*)(Gn + tok * RW + ch);
;                 const float g0 = bflo(gw.x), g1 = bfhi(gw.x), g2 = bflo(gw.y), g3 = bfhi(gw.y);
;                 u32x2 w; w.x = cvt_pk_bf16(o[mt][0] * g0 * sigmoidf_(g0), o[mt][1] * g1 * sigmoidf_(g1)); w.y = cvt_pk_bf16(o[mt][2] * g2 * sigmoidf_(g2), o[mt][3] * g3 * sigmoidf_(g3));
;                 *(u32x2*)(MIX + tok * DM + 1024 + ch) = w; }
	ds_read_b128 v[0:3], v33 offset:0
	ds_read_b128 v[4:7], v33 offset:1024
	ds_read_b128 v[8:11], v33 offset:2048
	ds_read_b128 v[12:15], v33 offset:3072
	ds_read_b128 v[16:19], v33 offset:4096
	ds_read_b128 v[20:23], v33 offset:5120
	ds_read_b128 v[24:27], v33 offset:6144
	ds_read_b128 v[28:31], v33 offset:7168
	s_waitcnt lgkmcnt(7)
	v_mfma_f32_16x16x32_bf16 v[200:203], v[0:3], v[128:131], 0
	ds_read_b128 v[0:3], v33 offset:8192
	s_waitcnt lgkmcnt(7)
	v_mfma_f32_16x16x32_bf16 v[204:207], v[4:7], v[128:131], 0
	ds_read_b128 v[4:7], v33 offset:9216
	s_waitcnt lgkmcnt(7)
	v_mfma_f32_16x16x32_bf16 v[208:211], v[8:11], v[128:131], 0
	ds_read_b128 v[8:11], v33 offset:10240
	s_waitcnt lgkmcnt(7)
	v_mfma_f32_16x16x32_bf16 v[212:215], v[12:15], v[128:131], 0
	ds_read_b128 v[12:15], v33 offset:11264
	s_waitcnt lgkmcnt(7)
	v_mfma_f32_16x16x32_bf16 v[200:203], v[16:19], v[136:139], v[200:203]
	ds_read_b128 v[16:19], v33 offset:12288
	s_waitcnt lgkmcnt(7)
	v_mfma_f32_16x16x32_bf16 v[204:207], v[20:23], v[136:139], v[204:207]
	ds_read_b128 v[20:23], v33 offset:13312
	s_waitcnt lgkmcnt(7)
	v_mfma_f32_16x16x32_bf16 v[208:211], v[24:27], v[136:139], v[208:211]
	ds_read_b128 v[24:27], v33 offset:14336
	s_waitcnt lgkmcnt(7)
	v_mfma_f32_16x16x32_bf16 v[212:215], v[28:31], v[136:139], v[212:215]
	ds_read_b128 v[28:31], v33 offset:15360
	s_waitcnt lgkmcnt(7)
	v_mfma_f32_16x16x32_bf16 v[200:203], v[0:3], v[144:147], v[200:203]
	ds_read_b128 v[0:3], v33 offset:16384
	s_waitcnt lgkmcnt(7)
	v_mfma_f32_16x16x32_bf16 v[204:207], v[4:7], v[144:147], v[204:207]
	ds_read_b128 v[4:7], v33 offset:17408
	s_waitcnt lgkmcnt(7)
	v_mfma_f32_16x16x32_bf16 v[208:211], v[8:11], v[144:147], v[208:211]
	ds_read_b128 v[8:11], v33 offset:18432
	s_waitcnt lgkmcnt(7)
	v_mfma_f32_16x16x32_bf16 v[212:215], v[12:15], v[144:147], v[212:215]
	ds_read_b128 v[12:15], v33 offset:19456
	s_waitcnt lgkmcnt(7)
	v_mfma_f32_16x16x32_bf16 v[200:203], v[16:19], v[152:155], v[200:203]
	ds_read_b128 v[16:19], v33 offset:20480
	s_waitcnt lgkmcnt(7)
	v_mfma_f32_16x16x32_bf16 v[204:207], v[20:23], v[152:155], v[204:207]
	ds_read_b128 v[20:23], v33 offset:21504
	s_waitcnt lgkmcnt(7)
	v_mfma_f32_16x16x32_bf16 v[208:211], v[24:27], v[152:155], v[208:211]
	ds_read_b128 v[24:27], v33 offset:22528
	s_waitcnt lgkmcnt(7)
	v_mfma_f32_16x16x32_bf16 v[212:215], v[28:31], v[152:155], v[212:215]
	ds_read_b128 v[28:31], v33 offset:23552
	s_waitcnt lgkmcnt(7)
	v_mfma_f32_16x16x32_bf16 v[200:203], v[0:3], v[160:163], v[200:203]
	ds_read_b128 v[0:3], v33 offset:24576
	s_waitcnt lgkmcnt(7)
	v_mfma_f32_16x16x32_bf16 v[204:207], v[4:7], v[160:163], v[204:207]
	ds_read_b128 v[4:7], v33 offset:25600
	s_waitcnt lgkmcnt(7)
	v_mfma_f32_16x16x32_bf16 v[208:211], v[8:11], v[160:163], v[208:211]
	ds_read_b128 v[8:11], v33 offset:26624
	s_waitcnt lgkmcnt(7)
	v_mfma_f32_16x16x32_bf16 v[212:215], v[12:15], v[160:163], v[212:215]
	ds_read_b128 v[12:15], v33 offset:27648
	s_waitcnt lgkmcnt(7)
	v_mfma_f32_16x16x32_bf16 v[200:203], v[16:19], v[168:171], v[200:203]
	ds_read_b128 v[16:19], v33 offset:28672
	s_waitcnt lgkmcnt(7)
	v_mfma_f32_16x16x32_bf16 v[204:207], v[20:23], v[168:171], v[204:207]
	ds_read_b128 v[20:23], v33 offset:29696
	s_waitcnt lgkmcnt(7)
	v_mfma_f32_16x16x32_bf16 v[208:211], v[24:27], v[168:171], v[208:211]
	ds_read_b128 v[24:27], v33 offset:30720
	s_waitcnt lgkmcnt(7)
	v_mfma_f32_16x16x32_bf16 v[212:215], v[28:31], v[168:171], v[212:215]
	ds_read_b128 v[28:31], v33 offset:31744
	s_waitcnt lgkmcnt(7)
	v_mfma_f32_16x16x32_bf16 v[200:203], v[0:3], v[176:179], v[200:203]
	s_waitcnt lgkmcnt(6)
	v_mfma_f32_16x16x32_bf16 v[204:207], v[4:7], v[176:179], v[204:207]
	s_waitcnt lgkmcnt(5)
	v_mfma_f32_16x16x32_bf16 v[208:211], v[8:11], v[176:179], v[208:211]
	s_waitcnt lgkmcnt(4)
	v_mfma_f32_16x16x32_bf16 v[212:215], v[12:15], v[176:179], v[212:215]
	s_waitcnt lgkmcnt(3)
	v_mfma_f32_16x16x32_bf16 v[200:203], v[16:19], v[184:187], v[200:203]
	s_waitcnt lgkmcnt(2)
	v_mfma_f32_16x16x32_bf16 v[204:207], v[20:23], v[184:187], v[204:207]
	s_waitcnt lgkmcnt(1)
	v_mfma_f32_16x16x32_bf16 v[208:211], v[24:27], v[184:187], v[208:211]
	s_waitcnt lgkmcnt(0)
	v_mfma_f32_16x16x32_bf16 v[212:215], v[28:31], v[184:187], v[212:215]
	s_waitcnt vmcnt(0)
	s_lshl_b32 s84, s82, 12
	s_add_u32 s84, s84, s80
	v_lshlrev_b32_e32 v132, 16, v216
	v_and_b32_e32 v133, 0xffff0000, v216
	v_lshlrev_b32_e32 v134, 16, v217
	v_and_b32_e32 v135, 0xffff0000, v217
	v_lshlrev_b32_e32 v140, 16, v218
	v_and_b32_e32 v141, 0xffff0000, v218
	v_lshlrev_b32_e32 v142, 16, v219
	v_and_b32_e32 v143, 0xffff0000, v219
	v_lshlrev_b32_e32 v148, 16, v220
	v_and_b32_e32 v149, 0xffff0000, v220
	v_lshlrev_b32_e32 v150, 16, v221
	v_and_b32_e32 v151, 0xffff0000, v221
	v_lshlrev_b32_e32 v156, 16, v222
	v_and_b32_e32 v157, 0xffff0000, v222
	v_lshlrev_b32_e32 v158, 16, v223
	v_and_b32_e32 v159, 0xffff0000, v223
	v_mul_f32_e32 v164, 0xbfb8aa3b, v132
	v_mul_f32_e32 v165, 0xbfb8aa3b, v133
	v_mul_f32_e32 v166, 0xbfb8aa3b, v134
	v_mul_f32_e32 v167, 0xbfb8aa3b, v135
	v_mul_f32_e32 v172, 0xbfb8aa3b, v140
	v_mul_f32_e32 v173, 0xbfb8aa3b, v141
	v_mul_f32_e32 v174, 0xbfb8aa3b, v142
	v_mul_f32_e32 v175, 0xbfb8aa3b, v143
	v_mul_f32_e32 v180, 0xbfb8aa3b, v148
	v_mul_f32_e32 v181, 0xbfb8aa3b, v149
	v_mul_f32_e32 v182, 0xbfb8aa3b, v150
	v_mul_f32_e32 v183, 0xbfb8aa3b, v151
	v_mul_f32_e32 v188, 0xbfb8aa3b, v156
	v_mul_f32_e32 v189, 0xbfb8aa3b, v157
	v_mul_f32_e32 v190, 0xbfb8aa3b, v158
	v_mul_f32_e32 v191, 0xbfb8aa3b, v159
	v_exp_f32_e32 v164, v164
	v_exp_f32_e32 v165, v165
	v_exp_f32_e32 v166, v166
	v_exp_f32_e32 v167, v167
	v_exp_f32_e32 v172, v172
	v_exp_f32_e32 v173, v173
	v_exp_f32_e32 v174, v174
; __device__ __forceinline__ float bflo(unsigned w) { return __uint_as_float(w << 16); }
; __device__ __forceinline__ void nat_phase(const Params& p, float* ldsf, int wave0, int nwaves) {
;     ...
;             for (int mt = 0; mt < 4; ++mt) { const int ch = h * 64 + mt * 16 + lq * 4; const u32x2 gw = *(const u32x2*)(Gn + tok * RW + ch);
;                 const float g0 = bflo(gw.x), g1 = bfhi(gw.x), g2 = bflo(gw.y), g3 = bfhi(gw.y);
;                 u32x2 w; w.x = cvt_pk_bf16(o[mt][0] * g0 * sigmoidf_(g0), o[mt][1] * g1 * sigmoidf_(g1)); w.y = cvt_pk_bf16(o[mt][2] * g2 * sigmoidf_(g2), o[mt][3] * g3 * sigmoidf_(g3));
;                 *(u32x2*)(MIX + tok * DM + 1024 + ch) = w; }
; template <bool MIX> __device__ __forceinline__ void scan_pass1(const Params& p, int d, float* ldsf) {
;     const int lane = threadIdx.x & 63, wid = __builtin_amdgcn_readfirstlane(threadIdx.x >> 6); const unsigned lo16 = (lane & 15) * 16, lo2 = lane * 2;
;     const float* Wd = (const float*)(p.ws + O_KD); const float* Bd = (const float*)(p.ws + O_Y); const u16* KB = (const u16*)(p.ws + O_K); const float* A = (const float*)(p.ws + O_A);
;     const u16* V = (const u16*)(p.ws + O_V); float* PT = (float*)(p.ws + O_PT); float* SLT = (float*)(p.ws + O_SLT); const unsigned lo8 = (lane & 15) * 8;
;     constexpr int NS = 32 * (NC - 1);
;     unsigned* qctr = (unsigned*)(p.ws + O_BAR);
;     if (MIX && wid >= 4) nat_phase(p, ldsf, blockIdx.x * 4 + (wid - 4), gridDim.x * 4);
;     ...
;     for (int item = MIX ? NEXT_ITEM() : (int)(blockIdx.x * 8 + wid); item < 2 * NS; item = NEXT_ITEM()) {
;         const bool isP = item >= NS; const int idx = isP ? item - NS : item;
;         const int bh = idx / (NC - 1), c = idx - bh * (NC - 1), b = bh >> 4, h = bh & 15;
;         const int t0 = d ? (SEQ - 1 - c * LC) : c * LC;
;         const size_t off0 = ((size_t)(b * SEQ + t0)) * RW + h * 64; const long stp = d ? -(long)RW : (long)RW;
;         const unsigned ob4 = (unsigned)(off0 * 4), ob2 = (unsigned)(off0 * 2);
;         const f32x4 ka4 = *(const f32x4*)(p.k_a + h * 64 + (lane & 15) * 4), c04 = 1.0f - ka4;
;         float S[64]; int ln = lane; asm volatile("" : "+v"(ln));
;     ...
;         const __amdgpu_buffer_rsrc_t rW = MKR(Wd), rA = MKR(A), rB = MKR(Bd), rK = MKR(KB), rV = MKR(V);
;         if (!isP) {
; #pragma unroll
;             for (int i = 0; i < 64; ++i) S[i] = 0.f;
;     ...
;             In1 i0, i1; LD1(i0, 0);
	v_exp_f32_e32 v175, v175
	v_exp_f32_e32 v180, v180
	v_exp_f32_e32 v181, v181
	v_exp_f32_e32 v182, v182
	v_exp_f32_e32 v183, v183
	v_exp_f32_e32 v188, v188
	v_exp_f32_e32 v189, v189
	v_exp_f32_e32 v190, v190
	v_exp_f32_e32 v191, v191
	s_nop 0
	v_add_f32_e32 v164, 1.0, v164
	v_add_f32_e32 v165, 1.0, v165
	v_add_f32_e32 v166, 1.0, v166
	v_add_f32_e32 v167, 1.0, v167
	v_add_f32_e32 v172, 1.0, v172
	v_add_f32_e32 v173, 1.0, v173
	v_add_f32_e32 v174, 1.0, v174
	v_add_f32_e32 v175, 1.0, v175
	v_add_f32_e32 v180, 1.0, v180
	v_add_f32_e32 v181, 1.0, v181
	v_add_f32_e32 v182, 1.0, v182
	v_add_f32_e32 v183, 1.0, v183
	v_add_f32_e32 v188, 1.0, v188
	v_add_f32_e32 v189, 1.0, v189
	v_add_f32_e32 v190, 1.0, v190
	v_add_f32_e32 v191, 1.0, v191
	v_rcp_f32_e32 v164, v164
	v_rcp_f32_e32 v165, v165
	v_rcp_f32_e32 v166, v166
	v_rcp_f32_e32 v167, v167
	v_rcp_f32_e32 v172, v172
	v_rcp_f32_e32 v173, v173
	v_rcp_f32_e32 v174, v174
	v_rcp_f32_e32 v175, v175
	v_rcp_f32_e32 v180, v180
	v_rcp_f32_e32 v181, v181
	v_rcp_f32_e32 v182, v182
	v_rcp_f32_e32 v183, v183
	v_rcp_f32_e32 v188, v188
	v_rcp_f32_e32 v189, v189
	v_rcp_f32_e32 v190, v190
	v_rcp_f32_e32 v191, v191
	s_nop 0
	v_mul_f32_e32 v200, v200, v132
	v_mul_f32_e32 v201, v201, v133
	v_mul_f32_e32 v202, v202, v134
	v_mul_f32_e32 v203, v203, v135
	v_mul_f32_e32 v204, v204, v140
	v_mul_f32_e32 v205, v205, v141
	v_mul_f32_e32 v206, v206, v142
	v_mul_f32_e32 v207, v207, v143
	v_mul_f32_e32 v208, v208, v148
	v_mul_f32_e32 v209, v209, v149
	v_mul_f32_e32 v210, v210, v150
	v_mul_f32_e32 v211, v211, v151
	v_mul_f32_e32 v212, v212, v156
	v_mul_f32_e32 v213, v213, v157
	v_mul_f32_e32 v214, v214, v158
	v_mul_f32_e32 v215, v215, v159
	v_mul_f32_e32 v200, v200, v164
	v_mul_f32_e32 v201, v201, v165
	v_mul_f32_e32 v202, v202, v166
	v_mul_f32_e32 v203, v203, v167
	v_mul_f32_e32 v204, v204, v172
	v_mul_f32_e32 v205, v205, v173
	v_mul_f32_e32 v206, v206, v174
	v_mul_f32_e32 v207, v207, v175
	v_mul_f32_e32 v208, v208, v180
	v_mul_f32_e32 v209, v209, v181
	v_mul_f32_e32 v210, v210, v182
	v_mul_f32_e32 v211, v211, v183
	v_mul_f32_e32 v212, v212, v188
	v_mul_f32_e32 v213, v213, v189
	v_mul_f32_e32 v214, v214, v190
	v_mul_f32_e32 v215, v215, v191
	v_cvt_pk_bf16_f32 v200, v200, v201
	v_cvt_pk_bf16_f32 v201, v202, v203
	v_cvt_pk_bf16_f32 v204, v204, v205
	v_cvt_pk_bf16_f32 v205, v206, v207
	v_cvt_pk_bf16_f32 v208, v208, v209
	v_cvt_pk_bf16_f32 v209, v210, v211
	v_cvt_pk_bf16_f32 v212, v212, v213
	v_cvt_pk_bf16_f32 v213, v214, v215
	buffer_store_dwordx2 v[200:201], v228, s[64:67], s84 offen offset:0
	buffer_store_dwordx2 v[204:205], v228, s[64:67], s84 offen offset:32
	buffer_store_dwordx2 v[208:209], v228, s[64:67], s84 offen offset:64
	buffer_store_dwordx2 v[212:213], v228, s[64:67], s84 offen offset:96
.Lmy_nat_cmp1:
	s_add_u32 s16, s16, 1
	s_cmp_lt_u32 s16, 4
	s_cbranch_scc1 .Lmy_nat_cqt
	s_add_u32 s88, s88, s94
	s_branch .Lmy_nat_unit
.Lmy_nat_end:
	s_waitcnt vmcnt(0) lgkmcnt(0)
	s_barrier
.LBB0_555:
	s_mov_b64 exec, -1
	v_readfirstlane_b32 s0, v254
	s_nop 3
	s_lshr_b32 s1, s0, 6
	s_lshl_b32 s0, s2, 3
	s_add_i32 s0, s1, s0
	s_mov_b32 s64, s56
	s_and_b32 s65, s57, 0xffff
	s_brev_b32 s66, -2
	s_mov_b32 s67, 0x27000
	v_and_b32_e32 v128, 63, v254
	v_and_b32_e32 v129, 15, v254
	s_lshl_b32 s3, s1, 10
	s_add_u32 s3, s3, 0x10000
	v_lshl_add_u32 v248, v129, 2, s3
	v_and_b32_e32 v249, 3, v254
	v_lshl_add_u32 v249, v249, 6, s3
	v_lshlrev_b32_e32 v130, 4, v129
	v_add_u32_e32 v235, 0xb800000, v130
	v_add_u32_e32 v250, 0x24800000, v130
	v_add_u32_e32 v251, 0x35a00000, v130
	v_lshlrev_b32_e32 v130, 3, v129
	v_add_u32_e32 v252, 0x30800000, v130
	v_lshlrev_b32_e32 v130, 1, v128
	v_add_u32_e32 v253, 0x2c800000, v130
.Lmy_p1d0_item:
	s_cmpk_gt_i32 s0, 0x7df
	s_cbranch_scc1 .Lmy_p1d0_end
	s_mul_i32 s86, s0, 2081
	s_lshr_b32 s86, s86, 17
	s_mul_i32 s7, s86, 63
	s_sub_u32 s85, s0, s7
	s_and_b32 s87, s86, 15
	s_lshr_b32 s6, s86, 4
	s_lshl_b32 s6, s6, 14
	s_lshl_b32 s7, s85, 8
	s_add_u32 s6, s6, s7
	s_lshl_b32 s6, s6, 10
	s_lshl_b32 s7, s87, 6
	s_add_u32 s84, s6, s7
	s_lshl_b32 s72, s84, 2
	s_lshl_b32 s76, s84, 1
	s_lshl_b32 s6, s86, 6
	s_add_u32 s6, s6, s85
	s_lshl_b32 s6, s6, 14
	s_add_u32 s7, s6, 0x15800000
	s_add_u32 s90, s56, s7
	s_addc_u32 s91, s57, 0
	s_add_u32 s7, s6, 0x13800000
	s_add_u32 s92, s56, s7
	s_addc_u32 s93, s57, 0
	s_lshl_b32 s8, s87, 8
	s_add_u32 s4, s42, s8
	s_addc_u32 s5, s43, 0
	v_and_b32_e32 v129, 15, v254
	v_lshlrev_b32_e32 v130, 4, v129
	global_load_dwordx4 v[216:219], v130, s[4:5]
	buffer_load_dwordx4 v[160:163], v235, s[64:67], s72 offen
	buffer_load_dwordx4 v[164:167], v250, s[64:67], s72 offen
	buffer_load_dwordx4 v[168:171], v251, s[64:67], s72 offen
	buffer_load_dwordx2 v[172:173], v252, s[64:67], s76 offen
	buffer_load_ushort v174, v253, s[64:67], s76 offen
	s_add_u32 s72, s72, 0x1000
	s_add_u32 s76, s76, 0x800
	buffer_load_dwordx4 v[176:179], v235, s[64:67], s72 offen
	buffer_load_dwordx4 v[180:183], v250, s[64:67], s72 offen
	buffer_load_dwordx4 v[184:187], v251, s[64:67], s72 offen
	buffer_load_dwordx2 v[188:189], v252, s[64:67], s76 offen
	buffer_load_ushort v190, v253, s[64:67], s76 offen
	s_add_u32 s72, s72, 0x1000
	s_add_u32 s76, s76, 0x800
	v_and_b32_e32 v128, 63, v254
	v_mov_b32_e32 v129, 1.0
	v_mov_b32_e32 v0, 0
	v_mov_b32_e32 v1, 0
	v_mov_b32_e32 v2, 0
	v_mov_b32_e32 v3, 0
	v_mov_b32_e32 v4, 0
	v_mov_b32_e32 v5, 0
	v_mov_b32_e32 v6, 0
	v_mov_b32_e32 v7, 0
	v_mov_b32_e32 v8, 0
	v_mov_b32_e32 v9, 0
	v_mov_b32_e32 v10, 0
	v_mov_b32_e32 v11, 0
	v_mov_b32_e32 v12, 0
	v_mov_b32_e32 v13, 0
	v_mov_b32_e32 v14, 0
	v_mov_b32_e32 v15, 0
	v_mov_b32_e32 v16, 0
	v_mov_b32_e32 v17, 0
	v_mov_b32_e32 v18, 0
	v_mov_b32_e32 v19, 0
; #define SB __builtin_amdgcn_sched_barrier(0)
; #define MKR(ptr) __builtin_amdgcn_make_buffer_rsrc((void*)(ptr), 0, 0x7fffffff, 0x00027000)
; #define LD1(set, s) { const int e_ = min((int)(s), LC - 1) * (int)stp; const unsigned s4_ = ob4 + (unsigned)(e_ * 4), s2_ = ob2 + (unsigned)(e_ * 2); set.w = LDX(rW, s4_); set.a = LDX(rA, s4_); set.b = LDX(rB, s4_); \
;             set.kw = __builtin_amdgcn_raw_buffer_load_b64(rK, lo8, s2_, 0); set.v = __builtin_amdgcn_raw_buffer_load_b16(rV, lo2, s2_, 0); }
; #define TOUCH1(set) asm volatile("" :: "v"(set.w), "v"(set.a), "v"(set.b), "v"(set.kw), "v"(set.v))
; #define ST1(set) { DERIVE_BK(set); float sd[4]; ScanK<0>::dot(S, set.a, sd); ScanK<0>::updS(S, set, -((sd[0] + sd[1]) + (sd[2] + sd[3])), __uint_as_float(set.v << 16)); }
; #define LD1(set, s) { const int e_ = min((int)(s), LC - 1) * (int)stp; const unsigned s4_ = ob4 + (unsigned)(e_ * 4); set.w = LDX(rW, s4_); set.a = LDX(rA, s4_); set.b = LDX(rB, s4_); }
; #define TOUCH1(set) asm volatile("" :: "v"(set.w), "v"(set.a), "v"(set.b))
; #define ST1(set) { DERIVE_B(set); float sd[4]; ScanK<0>::dot(S, set.a, sd); ScanK<0>::updP(S, set, -((sd[0] + sd[1]) + (sd[2] + sd[3]))); }
; template <bool MIX> __device__ __forceinline__ void scan_pass1(const Params& p, int d, float* ldsf) {
;     ...
;         const f32x4 ka4 = *(const f32x4*)(p.k_a + h * 64 + (lane & 15) * 4), c04 = 1.0f - ka4;
;         float S[64]; int ln = lane; asm volatile("" : "+v"(ln));
;     ...
;         const __amdgpu_buffer_rsrc_t rW = MKR(Wd), rA = MKR(A), rB = MKR(Bd), rK = MKR(KB), rV = MKR(V);
;         if (!isP) {
; #pragma unroll
;             for (int i = 0; i < 64; ++i) S[i] = 0.f;
;     ...
;             In1 i0, i1; LD1(i0, 0);
; #pragma unroll 1
;             for (int s = 0; s < LC; s += 2) { TOUCH1(i0); SB; LD1(i1, s + 1); SB; ST1(i0); TOUCH1(i1); SB; LD1(i0, s + 2); SB; ST1(i1); }
;     ...
;         } else {
; #pragma unroll
;             for (int i = 0; i < 64; ++i) S[i] = (ln == i) ? 1.f : 0.f;
;     ...
;             In1 i0, i1; LD1(i0, 0);
	v_mov_b32_e32 v20, 0
	v_mov_b32_e32 v21, 0
	v_mov_b32_e32 v22, 0
	v_mov_b32_e32 v23, 0
	v_mov_b32_e32 v24, 0
	v_mov_b32_e32 v25, 0
	v_mov_b32_e32 v26, 0
	v_mov_b32_e32 v27, 0
	v_mov_b32_e32 v28, 0
	v_mov_b32_e32 v29, 0
	v_mov_b32_e32 v30, 0
	v_mov_b32_e32 v31, 0
	v_mov_b32_e32 v32, 0
	v_mov_b32_e32 v33, 0
	v_mov_b32_e32 v34, 0
	v_mov_b32_e32 v35, 0
	v_mov_b32_e32 v36, 0
	v_mov_b32_e32 v37, 0
	v_mov_b32_e32 v38, 0
	v_mov_b32_e32 v39, 0
	v_mov_b32_e32 v40, 0
	v_mov_b32_e32 v41, 0
	v_mov_b32_e32 v42, 0
	v_mov_b32_e32 v43, 0
	v_mov_b32_e32 v44, 0
	v_mov_b32_e32 v45, 0
	v_mov_b32_e32 v46, 0
	v_mov_b32_e32 v47, 0
	v_mov_b32_e32 v48, 0
	v_mov_b32_e32 v49, 0
	v_mov_b32_e32 v50, 0
	v_mov_b32_e32 v51, 0
	v_mov_b32_e32 v52, 0
	v_mov_b32_e32 v53, 0
	v_mov_b32_e32 v54, 0
	v_mov_b32_e32 v55, 0
	v_mov_b32_e32 v56, 0
	v_mov_b32_e32 v57, 0
	v_mov_b32_e32 v58, 0
	v_mov_b32_e32 v59, 0
	v_mov_b32_e32 v60, 0
	v_mov_b32_e32 v61, 0
	v_mov_b32_e32 v62, 0
	v_mov_b32_e32 v63, 0
	v_cmp_eq_u32_e32 vcc, 0, v128
	s_nop 1
	v_cndmask_b32_e32 v64, 0, v129, vcc
	v_cmp_eq_u32_e32 vcc, 1, v128
	s_nop 1
	v_cndmask_b32_e32 v65, 0, v129, vcc
	v_cmp_eq_u32_e32 vcc, 2, v128
	s_nop 1
	v_cndmask_b32_e32 v66, 0, v129, vcc
	v_cmp_eq_u32_e32 vcc, 3, v128
	s_nop 1
	v_cndmask_b32_e32 v67, 0, v129, vcc
	v_cmp_eq_u32_e32 vcc, 4, v128
	s_nop 1
	v_cndmask_b32_e32 v68, 0, v129, vcc
	v_cmp_eq_u32_e32 vcc, 5, v128
	s_nop 1
	v_cndmask_b32_e32 v69, 0, v129, vcc
	v_cmp_eq_u32_e32 vcc, 6, v128
	s_nop 1
	v_cndmask_b32_e32 v70, 0, v129, vcc
	v_cmp_eq_u32_e32 vcc, 7, v128
	s_nop 1
	v_cndmask_b32_e32 v71, 0, v129, vcc
	v_cmp_eq_u32_e32 vcc, 8, v128
	s_nop 1
	v_cndmask_b32_e32 v72, 0, v129, vcc
	v_cmp_eq_u32_e32 vcc, 9, v128
	s_nop 1
	v_cndmask_b32_e32 v73, 0, v129, vcc
	v_cmp_eq_u32_e32 vcc, 10, v128
	s_nop 1
	v_cndmask_b32_e32 v74, 0, v129, vcc
	v_cmp_eq_u32_e32 vcc, 11, v128
	s_nop 1
	v_cndmask_b32_e32 v75, 0, v129, vcc
	v_cmp_eq_u32_e32 vcc, 12, v128
	s_nop 1
	v_cndmask_b32_e32 v76, 0, v129, vcc
	v_cmp_eq_u32_e32 vcc, 13, v128
	s_nop 1
	v_cndmask_b32_e32 v77, 0, v129, vcc
	v_cmp_eq_u32_e32 vcc, 14, v128
	s_nop 1
	v_cndmask_b32_e32 v78, 0, v129, vcc
	v_cmp_eq_u32_e32 vcc, 15, v128
	s_nop 1
	v_cndmask_b32_e32 v79, 0, v129, vcc
	v_cmp_eq_u32_e32 vcc, 16, v128
	s_nop 1
	v_cndmask_b32_e32 v80, 0, v129, vcc
	v_cmp_eq_u32_e32 vcc, 17, v128
	s_nop 1
	v_cndmask_b32_e32 v81, 0, v129, vcc
	v_cmp_eq_u32_e32 vcc, 18, v128
	s_nop 1
	v_cndmask_b32_e32 v82, 0, v129, vcc
	v_cmp_eq_u32_e32 vcc, 19, v128
	s_nop 1
	v_cndmask_b32_e32 v83, 0, v129, vcc
	v_cmp_eq_u32_e32 vcc, 20, v128
	s_nop 1
	v_cndmask_b32_e32 v84, 0, v129, vcc
	v_cmp_eq_u32_e32 vcc, 21, v128
	s_nop 1
	v_cndmask_b32_e32 v85, 0, v129, vcc
	v_cmp_eq_u32_e32 vcc, 22, v128
	s_nop 1
	v_cndmask_b32_e32 v86, 0, v129, vcc
	v_cmp_eq_u32_e32 vcc, 23, v128
	s_nop 1
	v_cndmask_b32_e32 v87, 0, v129, vcc
	v_cmp_eq_u32_e32 vcc, 24, v128
	s_nop 1
	v_cndmask_b32_e32 v88, 0, v129, vcc
	v_cmp_eq_u32_e32 vcc, 25, v128
	s_nop 1
	v_cndmask_b32_e32 v89, 0, v129, vcc
	v_cmp_eq_u32_e32 vcc, 26, v128
	s_nop 1
	v_cndmask_b32_e32 v90, 0, v129, vcc
	v_cmp_eq_u32_e32 vcc, 27, v128
	s_nop 1
	v_cndmask_b32_e32 v91, 0, v129, vcc
	v_cmp_eq_u32_e32 vcc, 28, v128
	s_nop 1
	v_cndmask_b32_e32 v92, 0, v129, vcc
	v_cmp_eq_u32_e32 vcc, 29, v128
	s_nop 1
	v_cndmask_b32_e32 v93, 0, v129, vcc
	v_cmp_eq_u32_e32 vcc, 30, v128
	s_nop 1
	v_cndmask_b32_e32 v94, 0, v129, vcc
	v_cmp_eq_u32_e32 vcc, 31, v128
	s_nop 1
	v_cndmask_b32_e32 v95, 0, v129, vcc
	v_cmp_eq_u32_e32 vcc, 32, v128
	s_nop 1
	v_cndmask_b32_e32 v96, 0, v129, vcc
	v_cmp_eq_u32_e32 vcc, 33, v128
	s_nop 1
	v_cndmask_b32_e32 v97, 0, v129, vcc
	v_cmp_eq_u32_e32 vcc, 34, v128
	s_nop 1
	v_cndmask_b32_e32 v98, 0, v129, vcc
	v_cmp_eq_u32_e32 vcc, 35, v128
	s_nop 1
	v_cndmask_b32_e32 v99, 0, v129, vcc
	v_cmp_eq_u32_e32 vcc, 36, v128
	s_nop 1
	v_cndmask_b32_e32 v100, 0, v129, vcc
	v_cmp_eq_u32_e32 vcc, 37, v128
	s_nop 1
	v_cndmask_b32_e32 v101, 0, v129, vcc
	v_cmp_eq_u32_e32 vcc, 38, v128
	s_nop 1
	v_cndmask_b32_e32 v102, 0, v129, vcc
	v_cmp_eq_u32_e32 vcc, 39, v128
	s_nop 1
	v_cndmask_b32_e32 v103, 0, v129, vcc
	v_cmp_eq_u32_e32 vcc, 40, v128
	s_nop 1
	v_cndmask_b32_e32 v104, 0, v129, vcc
	v_cmp_eq_u32_e32 vcc, 41, v128
	s_nop 1
	v_cndmask_b32_e32 v105, 0, v129, vcc
	v_cmp_eq_u32_e32 vcc, 42, v128
	s_nop 1
	v_cndmask_b32_e32 v106, 0, v129, vcc
	v_cmp_eq_u32_e32 vcc, 43, v128
	s_nop 1
	v_cndmask_b32_e32 v107, 0, v129, vcc
	v_cmp_eq_u32_e32 vcc, 44, v128
	s_nop 1
	v_cndmask_b32_e32 v108, 0, v129, vcc
	v_cmp_eq_u32_e32 vcc, 45, v128
	s_nop 1
	v_cndmask_b32_e32 v109, 0, v129, vcc
	v_cmp_eq_u32_e32 vcc, 46, v128
	s_nop 1
	v_cndmask_b32_e32 v110, 0, v129, vcc
	v_cmp_eq_u32_e32 vcc, 47, v128
	s_nop 1
	v_cndmask_b32_e32 v111, 0, v129, vcc
	v_cmp_eq_u32_e32 vcc, 48, v128
	s_nop 1
	v_cndmask_b32_e32 v112, 0, v129, vcc
	v_cmp_eq_u32_e32 vcc, 49, v128
	s_nop 1
	v_cndmask_b32_e32 v113, 0, v129, vcc
	v_cmp_eq_u32_e32 vcc, 50, v128
	s_nop 1
	v_cndmask_b32_e32 v114, 0, v129, vcc
	v_cmp_eq_u32_e32 vcc, 51, v128
	s_nop 1
	v_cndmask_b32_e32 v115, 0, v129, vcc
	v_cmp_eq_u32_e32 vcc, 52, v128
	s_nop 1
	v_cndmask_b32_e32 v116, 0, v129, vcc
	v_cmp_eq_u32_e32 vcc, 53, v128
	s_nop 1
	v_cndmask_b32_e32 v117, 0, v129, vcc
	v_cmp_eq_u32_e32 vcc, 54, v128
	s_nop 1
	v_cndmask_b32_e32 v118, 0, v129, vcc
	v_cmp_eq_u32_e32 vcc, 55, v128
	s_nop 1
	v_cndmask_b32_e32 v119, 0, v129, vcc
	v_cmp_eq_u32_e32 vcc, 56, v128
	s_nop 1
	v_cndmask_b32_e32 v120, 0, v129, vcc
	v_cmp_eq_u32_e32 vcc, 57, v128
	s_nop 1
	v_cndmask_b32_e32 v121, 0, v129, vcc
	v_cmp_eq_u32_e32 vcc, 58, v128
	s_nop 1
	v_cndmask_b32_e32 v122, 0, v129, vcc
	v_cmp_eq_u32_e32 vcc, 59, v128
	s_nop 1
	v_cndmask_b32_e32 v123, 0, v129, vcc
	v_cmp_eq_u32_e32 vcc, 60, v128
	s_nop 1
	v_cndmask_b32_e32 v124, 0, v129, vcc
	v_cmp_eq_u32_e32 vcc, 61, v128
	s_nop 1
	v_cndmask_b32_e32 v125, 0, v129, vcc
	v_cmp_eq_u32_e32 vcc, 62, v128
	s_nop 1
	v_cndmask_b32_e32 v126, 0, v129, vcc
	v_cmp_eq_u32_e32 vcc, 63, v128
	s_nop 1
	v_cndmask_b32_e32 v127, 0, v129, vcc
	s_waitcnt vmcnt(0)
	v_sub_f32_e32 v220, 1.0, v216
	v_sub_f32_e32 v221, 1.0, v217
	v_sub_f32_e32 v222, 1.0, v218
	v_sub_f32_e32 v223, 1.0, v219
	v_mov_b32_e32 v236, 1.0
	v_mov_b32_e32 v237, 1.0
	v_mov_b32_e32 v238, 1.0
	v_mov_b32_e32 v239, 1.0
	s_movk_i32 s83, 85
	s_movk_i32 s9, 11
	s_branch .Lmy_p1d0_loop
; #define SB __builtin_amdgcn_sched_barrier(0)
; #define LD1(set, s) { const int e_ = min((int)(s), LC - 1) * (int)stp; const unsigned s4_ = ob4 + (unsigned)(e_ * 4), s2_ = ob2 + (unsigned)(e_ * 2); set.w = LDX(rW, s4_); set.a = LDX(rA, s4_); set.b = LDX(rB, s4_); \
;             set.kw = __builtin_amdgcn_raw_buffer_load_b64(rK, lo8, s2_, 0); set.v = __builtin_amdgcn_raw_buffer_load_b16(rV, lo2, s2_, 0); }
; #define TOUCH1(set) asm volatile("" :: "v"(set.w), "v"(set.a), "v"(set.b), "v"(set.kw), "v"(set.v))
; #define ST1(set) { DERIVE_BK(set); float sd[4]; ScanK<0>::dot(S, set.a, sd); ScanK<0>::updS(S, set, -((sd[0] + sd[1]) + (sd[2] + sd[3])), __uint_as_float(set.v << 16)); }
; #define LD1(set, s) { const int e_ = min((int)(s), LC - 1) * (int)stp; const unsigned s4_ = ob4 + (unsigned)(e_ * 4); set.w = LDX(rW, s4_); set.a = LDX(rA, s4_); set.b = LDX(rB, s4_); }
; #define TOUCH1(set) asm volatile("" :: "v"(set.w), "v"(set.a), "v"(set.b))
; #define ST1(set) { DERIVE_B(set); float sd[4]; ScanK<0>::dot(S, set.a, sd); ScanK<0>::updP(S, set, -((sd[0] + sd[1]) + (sd[2] + sd[3]))); }
; template <bool MIX> __device__ __forceinline__ void scan_pass1(const Params& p, int d, float* ldsf) {
;     ...
;             In1 i0, i1; LD1(i0, 0);
; #pragma unroll 1
;             for (int s = 0; s < LC; s += 2) { TOUCH1(i0); SB; LD1(i1, s + 1); SB; ST1(i0); TOUCH1(i1); SB; LD1(i0, s + 2); SB; ST1(i1); }
;     ...
;         } else {
; #pragma unroll
;             for (int i = 0; i < 64; ++i) S[i] = (ln == i) ? 1.f : 0.f;
;     ...
;             In1 i0, i1; LD1(i0, 0);
; #pragma unroll 1
;             for (int s = 0; s < LC; s += 2) { TOUCH1(i0); SB; LD1(i1, s + 1); SB; ST1(i0); TOUCH1(i1); SB; LD1(i0, s + 2); SB; ST1(i1); }
.Lmy_p1d0_renorm:
	v_mul_f32_dpp v0, v236, v0 row_newbcast:0 row_mask:0xf bank_mask:0xf
	v_mul_f32_dpp v1, v237, v1 row_newbcast:0 row_mask:0xf bank_mask:0xf
	v_mul_f32_dpp v2, v238, v2 row_newbcast:0 row_mask:0xf bank_mask:0xf
	v_mul_f32_dpp v3, v239, v3 row_newbcast:0 row_mask:0xf bank_mask:0xf
	v_mul_f32_dpp v4, v236, v4 row_newbcast:1 row_mask:0xf bank_mask:0xf
	v_mul_f32_dpp v5, v237, v5 row_newbcast:1 row_mask:0xf bank_mask:0xf
	v_mul_f32_dpp v6, v238, v6 row_newbcast:1 row_mask:0xf bank_mask:0xf
	v_mul_f32_dpp v7, v239, v7 row_newbcast:1 row_mask:0xf bank_mask:0xf
	v_mul_f32_dpp v8, v236, v8 row_newbcast:2 row_mask:0xf bank_mask:0xf
	v_mul_f32_dpp v9, v237, v9 row_newbcast:2 row_mask:0xf bank_mask:0xf
	v_mul_f32_dpp v10, v238, v10 row_newbcast:2 row_mask:0xf bank_mask:0xf
	v_mul_f32_dpp v11, v239, v11 row_newbcast:2 row_mask:0xf bank_mask:0xf
	v_mul_f32_dpp v12, v236, v12 row_newbcast:3 row_mask:0xf bank_mask:0xf
	v_mul_f32_dpp v13, v237, v13 row_newbcast:3 row_mask:0xf bank_mask:0xf
	v_mul_f32_dpp v14, v238, v14 row_newbcast:3 row_mask:0xf bank_mask:0xf
	v_mul_f32_dpp v15, v239, v15 row_newbcast:3 row_mask:0xf bank_mask:0xf
	v_mul_f32_dpp v16, v236, v16 row_newbcast:4 row_mask:0xf bank_mask:0xf
	v_mul_f32_dpp v17, v237, v17 row_newbcast:4 row_mask:0xf bank_mask:0xf
	v_mul_f32_dpp v18, v238, v18 row_newbcast:4 row_mask:0xf bank_mask:0xf
	v_mul_f32_dpp v19, v239, v19 row_newbcast:4 row_mask:0xf bank_mask:0xf
	v_mul_f32_dpp v20, v236, v20 row_newbcast:5 row_mask:0xf bank_mask:0xf
	v_mul_f32_dpp v21, v237, v21 row_newbcast:5 row_mask:0xf bank_mask:0xf
	v_mul_f32_dpp v22, v238, v22 row_newbcast:5 row_mask:0xf bank_mask:0xf
	v_mul_f32_dpp v23, v239, v23 row_newbcast:5 row_mask:0xf bank_mask:0xf
	v_mul_f32_dpp v24, v236, v24 row_newbcast:6 row_mask:0xf bank_mask:0xf
	v_mul_f32_dpp v25, v237, v25 row_newbcast:6 row_mask:0xf bank_mask:0xf
	v_mul_f32_dpp v26, v238, v26 row_newbcast:6 row_mask:0xf bank_mask:0xf
	v_mul_f32_dpp v27, v239, v27 row_newbcast:6 row_mask:0xf bank_mask:0xf
	v_mul_f32_dpp v28, v236, v28 row_newbcast:7 row_mask:0xf bank_mask:0xf
	v_mul_f32_dpp v29, v237, v29 row_newbcast:7 row_mask:0xf bank_mask:0xf
	v_mul_f32_dpp v30, v238, v30 row_newbcast:7 row_mask:0xf bank_mask:0xf
	v_mul_f32_dpp v31, v239, v31 row_newbcast:7 row_mask:0xf bank_mask:0xf
	v_mul_f32_dpp v32, v236, v32 row_newbcast:8 row_mask:0xf bank_mask:0xf
	v_mul_f32_dpp v33, v237, v33 row_newbcast:8 row_mask:0xf bank_mask:0xf
	v_mul_f32_dpp v34, v238, v34 row_newbcast:8 row_mask:0xf bank_mask:0xf
	v_mul_f32_dpp v35, v239, v35 row_newbcast:8 row_mask:0xf bank_mask:0xf
	v_mul_f32_dpp v36, v236, v36 row_newbcast:9 row_mask:0xf bank_mask:0xf
	v_mul_f32_dpp v37, v237, v37 row_newbcast:9 row_mask:0xf bank_mask:0xf
	v_mul_f32_dpp v38, v238, v38 row_newbcast:9 row_mask:0xf bank_mask:0xf
	v_mul_f32_dpp v39, v239, v39 row_newbcast:9 row_mask:0xf bank_mask:0xf
	v_mul_f32_dpp v40, v236, v40 row_newbcast:10 row_mask:0xf bank_mask:0xf
	v_mul_f32_dpp v41, v237, v41 row_newbcast:10 row_mask:0xf bank_mask:0xf
	v_mul_f32_dpp v42, v238, v42 row_newbcast:10 row_mask:0xf bank_mask:0xf
	v_mul_f32_dpp v43, v239, v43 row_newbcast:10 row_mask:0xf bank_mask:0xf
	v_mul_f32_dpp v44, v236, v44 row_newbcast:11 row_mask:0xf bank_mask:0xf
	v_mul_f32_dpp v45, v237, v45 row_newbcast:11 row_mask:0xf bank_mask:0xf
	v_mul_f32_dpp v46, v238, v46 row_newbcast:11 row_mask:0xf bank_mask:0xf
	v_mul_f32_dpp v47, v239, v47 row_newbcast:11 row_mask:0xf bank_mask:0xf
	v_mul_f32_dpp v48, v236, v48 row_newbcast:12 row_mask:0xf bank_mask:0xf
	v_mul_f32_dpp v49, v237, v49 row_newbcast:12 row_mask:0xf bank_mask:0xf
	v_mul_f32_dpp v50, v238, v50 row_newbcast:12 row_mask:0xf bank_mask:0xf
	v_mul_f32_dpp v51, v239, v51 row_newbcast:12 row_mask:0xf bank_mask:0xf
	v_mul_f32_dpp v52, v236, v52 row_newbcast:13 row_mask:0xf bank_mask:0xf
	v_mul_f32_dpp v53, v237, v53 row_newbcast:13 row_mask:0xf bank_mask:0xf
	v_mul_f32_dpp v54, v238, v54 row_newbcast:13 row_mask:0xf bank_mask:0xf
	v_mul_f32_dpp v55, v239, v55 row_newbcast:13 row_mask:0xf bank_mask:0xf
	v_mul_f32_dpp v56, v236, v56 row_newbcast:14 row_mask:0xf bank_mask:0xf
	v_mul_f32_dpp v57, v237, v57 row_newbcast:14 row_mask:0xf bank_mask:0xf
	v_mul_f32_dpp v58, v238, v58 row_newbcast:14 row_mask:0xf bank_mask:0xf
	v_mul_f32_dpp v59, v239, v59 row_newbcast:14 row_mask:0xf bank_mask:0xf
	v_mul_f32_dpp v60, v236, v60 row_newbcast:15 row_mask:0xf bank_mask:0xf
	v_mul_f32_dpp v61, v237, v61 row_newbcast:15 row_mask:0xf bank_mask:0xf
	v_mul_f32_dpp v62, v238, v62 row_newbcast:15 row_mask:0xf bank_mask:0xf
	v_mul_f32_dpp v63, v239, v63 row_newbcast:15 row_mask:0xf bank_mask:0xf
	v_mul_f32_dpp v64, v236, v64 row_newbcast:0 row_mask:0xf bank_mask:0xf
	v_mul_f32_dpp v65, v237, v65 row_newbcast:0 row_mask:0xf bank_mask:0xf
	v_mul_f32_dpp v66, v238, v66 row_newbcast:0 row_mask:0xf bank_mask:0xf
	v_mul_f32_dpp v67, v239, v67 row_newbcast:0 row_mask:0xf bank_mask:0xf
	v_mul_f32_dpp v68, v236, v68 row_newbcast:1 row_mask:0xf bank_mask:0xf
	v_mul_f32_dpp v69, v237, v69 row_newbcast:1 row_mask:0xf bank_mask:0xf
	v_mul_f32_dpp v70, v238, v70 row_newbcast:1 row_mask:0xf bank_mask:0xf
	v_mul_f32_dpp v71, v239, v71 row_newbcast:1 row_mask:0xf bank_mask:0xf
	v_mul_f32_dpp v72, v236, v72 row_newbcast:2 row_mask:0xf bank_mask:0xf
	v_mul_f32_dpp v73, v237, v73 row_newbcast:2 row_mask:0xf bank_mask:0xf
	v_mul_f32_dpp v74, v238, v74 row_newbcast:2 row_mask:0xf bank_mask:0xf
	v_mul_f32_dpp v75, v239, v75 row_newbcast:2 row_mask:0xf bank_mask:0xf
	v_mul_f32_dpp v76, v236, v76 row_newbcast:3 row_mask:0xf bank_mask:0xf
	v_mul_f32_dpp v77, v237, v77 row_newbcast:3 row_mask:0xf bank_mask:0xf
; #define SB __builtin_amdgcn_sched_barrier(0)
; #define LD1(set, s) { const int e_ = min((int)(s), LC - 1) * (int)stp; const unsigned s4_ = ob4 + (unsigned)(e_ * 4), s2_ = ob2 + (unsigned)(e_ * 2); set.w = LDX(rW, s4_); set.a = LDX(rA, s4_); set.b = LDX(rB, s4_); \
;             set.kw = __builtin_amdgcn_raw_buffer_load_b64(rK, lo8, s2_, 0); set.v = __builtin_amdgcn_raw_buffer_load_b16(rV, lo2, s2_, 0); }
; #define TOUCH1(set) asm volatile("" :: "v"(set.w), "v"(set.a), "v"(set.b), "v"(set.kw), "v"(set.v))
; #define ST1(set) { DERIVE_BK(set); float sd[4]; ScanK<0>::dot(S, set.a, sd); ScanK<0>::updS(S, set, -((sd[0] + sd[1]) + (sd[2] + sd[3])), __uint_as_float(set.v << 16)); }
; #define LD1(set, s) { const int e_ = min((int)(s), LC - 1) * (int)stp; const unsigned s4_ = ob4 + (unsigned)(e_ * 4); set.w = LDX(rW, s4_); set.a = LDX(rA, s4_); set.b = LDX(rB, s4_); }
; #define TOUCH1(set) asm volatile("" :: "v"(set.w), "v"(set.a), "v"(set.b))
; #define ST1(set) { DERIVE_B(set); float sd[4]; ScanK<0>::dot(S, set.a, sd); ScanK<0>::updP(S, set, -((sd[0] + sd[1]) + (sd[2] + sd[3]))); }
; template <bool MIX> __device__ __forceinline__ void scan_pass1(const Params& p, int d, float* ldsf) {
;     ...
;             In1 i0, i1; LD1(i0, 0);
; #pragma unroll 1
;             for (int s = 0; s < LC; s += 2) { TOUCH1(i0); SB; LD1(i1, s + 1); SB; ST1(i0); TOUCH1(i1); SB; LD1(i0, s + 2); SB; ST1(i1); }
	v_mul_f32_dpp v78, v238, v78 row_newbcast:3 row_mask:0xf bank_mask:0xf
	v_mul_f32_dpp v79, v239, v79 row_newbcast:3 row_mask:0xf bank_mask:0xf
	v_mul_f32_dpp v80, v236, v80 row_newbcast:4 row_mask:0xf bank_mask:0xf
	v_mul_f32_dpp v81, v237, v81 row_newbcast:4 row_mask:0xf bank_mask:0xf
	v_mul_f32_dpp v82, v238, v82 row_newbcast:4 row_mask:0xf bank_mask:0xf
	v_mul_f32_dpp v83, v239, v83 row_newbcast:4 row_mask:0xf bank_mask:0xf
	v_mul_f32_dpp v84, v236, v84 row_newbcast:5 row_mask:0xf bank_mask:0xf
	v_mul_f32_dpp v85, v237, v85 row_newbcast:5 row_mask:0xf bank_mask:0xf
	v_mul_f32_dpp v86, v238, v86 row_newbcast:5 row_mask:0xf bank_mask:0xf
	v_mul_f32_dpp v87, v239, v87 row_newbcast:5 row_mask:0xf bank_mask:0xf
	v_mul_f32_dpp v88, v236, v88 row_newbcast:6 row_mask:0xf bank_mask:0xf
	v_mul_f32_dpp v89, v237, v89 row_newbcast:6 row_mask:0xf bank_mask:0xf
	v_mul_f32_dpp v90, v238, v90 row_newbcast:6 row_mask:0xf bank_mask:0xf
	v_mul_f32_dpp v91, v239, v91 row_newbcast:6 row_mask:0xf bank_mask:0xf
	v_mul_f32_dpp v92, v236, v92 row_newbcast:7 row_mask:0xf bank_mask:0xf
	v_mul_f32_dpp v93, v237, v93 row_newbcast:7 row_mask:0xf bank_mask:0xf
	v_mul_f32_dpp v94, v238, v94 row_newbcast:7 row_mask:0xf bank_mask:0xf
	v_mul_f32_dpp v95, v239, v95 row_newbcast:7 row_mask:0xf bank_mask:0xf
	v_mul_f32_dpp v96, v236, v96 row_newbcast:8 row_mask:0xf bank_mask:0xf
	v_mul_f32_dpp v97, v237, v97 row_newbcast:8 row_mask:0xf bank_mask:0xf
	v_mul_f32_dpp v98, v238, v98 row_newbcast:8 row_mask:0xf bank_mask:0xf
	v_mul_f32_dpp v99, v239, v99 row_newbcast:8 row_mask:0xf bank_mask:0xf
	v_mul_f32_dpp v100, v236, v100 row_newbcast:9 row_mask:0xf bank_mask:0xf
	v_mul_f32_dpp v101, v237, v101 row_newbcast:9 row_mask:0xf bank_mask:0xf
	v_mul_f32_dpp v102, v238, v102 row_newbcast:9 row_mask:0xf bank_mask:0xf
	v_mul_f32_dpp v103, v239, v103 row_newbcast:9 row_mask:0xf bank_mask:0xf
	v_mul_f32_dpp v104, v236, v104 row_newbcast:10 row_mask:0xf bank_mask:0xf
	v_mul_f32_dpp v105, v237, v105 row_newbcast:10 row_mask:0xf bank_mask:0xf
	v_mul_f32_dpp v106, v238, v106 row_newbcast:10 row_mask:0xf bank_mask:0xf
	v_mul_f32_dpp v107, v239, v107 row_newbcast:10 row_mask:0xf bank_mask:0xf
	v_mul_f32_dpp v108, v236, v108 row_newbcast:11 row_mask:0xf bank_mask:0xf
	v_mul_f32_dpp v109, v237, v109 row_newbcast:11 row_mask:0xf bank_mask:0xf
	v_mul_f32_dpp v110, v238, v110 row_newbcast:11 row_mask:0xf bank_mask:0xf
	v_mul_f32_dpp v111, v239, v111 row_newbcast:11 row_mask:0xf bank_mask:0xf
	v_mul_f32_dpp v112, v236, v112 row_newbcast:12 row_mask:0xf bank_mask:0xf
	v_mul_f32_dpp v113, v237, v113 row_newbcast:12 row_mask:0xf bank_mask:0xf
	v_mul_f32_dpp v114, v238, v114 row_newbcast:12 row_mask:0xf bank_mask:0xf
	v_mul_f32_dpp v115, v239, v115 row_newbcast:12 row_mask:0xf bank_mask:0xf
	v_mul_f32_dpp v116, v236, v116 row_newbcast:13 row_mask:0xf bank_mask:0xf
	v_mul_f32_dpp v117, v237, v117 row_newbcast:13 row_mask:0xf bank_mask:0xf
	v_mul_f32_dpp v118, v238, v118 row_newbcast:13 row_mask:0xf bank_mask:0xf
	v_mul_f32_dpp v119, v239, v119 row_newbcast:13 row_mask:0xf bank_mask:0xf
	v_mul_f32_dpp v120, v236, v120 row_newbcast:14 row_mask:0xf bank_mask:0xf
	v_mul_f32_dpp v121, v237, v121 row_newbcast:14 row_mask:0xf bank_mask:0xf
	v_mul_f32_dpp v122, v238, v122 row_newbcast:14 row_mask:0xf bank_mask:0xf
	v_mul_f32_dpp v123, v239, v123 row_newbcast:14 row_mask:0xf bank_mask:0xf
	v_mul_f32_dpp v124, v236, v124 row_newbcast:15 row_mask:0xf bank_mask:0xf
	v_mul_f32_dpp v125, v237, v125 row_newbcast:15 row_mask:0xf bank_mask:0xf
	v_mul_f32_dpp v126, v238, v126 row_newbcast:15 row_mask:0xf bank_mask:0xf
	v_mul_f32_dpp v127, v239, v127 row_newbcast:15 row_mask:0xf bank_mask:0xf
	v_mov_b32_e32 v236, 1.0
	v_mov_b32_e32 v237, 1.0
	v_mov_b32_e32 v238, 1.0
	v_mov_b32_e32 v239, 1.0
	s_movk_i32 s9, 11
.Lmy_p1d0_loop:
	s_waitcnt vmcnt(5)
	buffer_load_dwordx4 v[192:195], v235, s[64:67], s72 offen
	buffer_load_dwordx4 v[196:199], v250, s[64:67], s72 offen
	buffer_load_dwordx4 v[200:203], v251, s[64:67], s72 offen
	buffer_load_dwordx2 v[204:205], v252, s[64:67], s76 offen
	buffer_load_ushort v206, v253, s[64:67], s76 offen
	s_add_u32 s72, s72, 0x1000
	s_add_u32 s76, s76, 0x800
	v_pk_mul_f32 v[244:245], v[164:165], v[236:237]
	v_pk_mul_f32 v[246:247], v[166:167], v[238:239]
	v_pk_mul_f32 v[236:237], v[236:237], v[160:161]
	v_pk_mul_f32 v[238:239], v[238:239], v[162:163]
	v_pk_fma_f32 v[228:229], v[168:169], v[216:217], v[220:221]
	v_pk_fma_f32 v[230:231], v[170:171], v[218:219], v[222:223]
	v_pk_mul_f32 v[208:209], v[164:165], v[168:169]
	v_pk_mul_f32 v[210:211], v[166:167], v[170:171]
	v_rcp_f32_e32 v240, v236
	v_rcp_f32_e32 v241, v237
	v_rcp_f32_e32 v242, v238
	v_rcp_f32_e32 v243, v239
	v_lshlrev_b32_e32 v212, 16, v172
	v_and_b32_e32 v213, 0xffff0000, v172
	v_lshlrev_b32_e32 v214, 16, v173
	v_and_b32_e32 v215, 0xffff0000, v173
	v_pk_mul_f32 v[212:213], v[212:213], v[228:229]
	v_pk_mul_f32 v[214:215], v[214:215], v[230:231]
	v_lshlrev_b32_e32 v234, 16, v174
	v_pk_mul_f32 v[208:209], v[208:209], v[240:241]
	v_pk_mul_f32 v[210:211], v[210:211], v[242:243]
	v_pk_mul_f32 v[212:213], v[212:213], v[240:241]
	v_pk_mul_f32 v[214:215], v[214:215], v[242:243]
	ds_write2_b32 v248, v208, v209 offset0:0 offset1:16
	ds_write2_b32 v248, v210, v211 offset0:32 offset1:48
	ds_write2_b32 v248, v212, v213 offset0:64 offset1:80
	ds_write2_b32 v248, v214, v215 offset0:96 offset1:112
	ds_read_b128 v[128:131], v249 offset:0
	ds_read_b128 v[132:135], v249 offset:16
	ds_read_b128 v[136:139], v249 offset:32
	ds_read_b128 v[140:143], v249 offset:48
	ds_read_b128 v[144:147], v249 offset:256
	ds_read_b128 v[148:151], v249 offset:272
;     static __device__ __forceinline__ void dot(const float (&S)[64], const f32x4& a, float (&s)[4]) {
;         if constexpr (K == 0) {
;             asm volatile("v_mul_f32_dpp %0, %4, %8 row_newbcast:%16" DPPM "v_mul_f32_dpp %1, %5, %9 row_newbcast:%16" DPPM "v_mul_f32_dpp %2, %6, %10 row_newbcast:%16" DPPM "v_mul_f32_dpp %3, %7, %11 row_newbcast:%16" DPPM
;                          "v_fmac_f32_dpp %0, %4, %12 row_newbcast:%17" DPPM "v_fmac_f32_dpp %1, %5, %13 row_newbcast:%17" DPPM "v_fmac_f32_dpp %2, %6, %14 row_newbcast:%17" DPPM "v_fmac_f32_dpp %3, %7, %15 row_newbcast:%17" DPPM
;                          : "=&v"(s[0]), "=&v"(s[1]), "=&v"(s[2]), "=&v"(s[3])
;                          : "v"(a[0]), "v"(a[1]), "v"(a[2]), "v"(a[3]), "v"(S[K]), "v"(S[K + 1]), "v"(S[K + 2]), "v"(S[K + 3]), "v"(S[K + 4]), "v"(S[K + 5]), "v"(S[K + 6]), "v"(S[K + 7]), "n"(N0), "n"(N1));
;         } else
;         asm volatile("v_fmac_f32_dpp %0, %4, %8 row_newbcast:%16" DPPM "v_fmac_f32_dpp %1, %5, %9 row_newbcast:%16" DPPM "v_fmac_f32_dpp %2, %6, %10 row_newbcast:%16" DPPM "v_fmac_f32_dpp %3, %7, %11 row_newbcast:%16" DPPM
;                      "v_fmac_f32_dpp %0, %4, %12 row_newbcast:%17" DPPM "v_fmac_f32_dpp %1, %5, %13 row_newbcast:%17" DPPM "v_fmac_f32_dpp %2, %6, %14 row_newbcast:%17" DPPM "v_fmac_f32_dpp %3, %7, %15 row_newbcast:%17" DPPM
;                      : "+v"(s[0]), "+v"(s[1]), "+v"(s[2]), "+v"(s[3])
;                      : "v"(a[0]), "v"(a[1]), "v"(a[2]), "v"(a[3]), "v"(S[K]), "v"(S[K + 1]), "v"(S[K + 2]), "v"(S[K + 3]), "v"(S[K + 4]), "v"(S[K + 5]), "v"(S[K + 6]), "v"(S[K + 7]), "n"(N0), "n"(N1));
;         if constexpr (K + 8 < 64) ScanK<K + 8>::dot(S, a, s);
;     }
	ds_read_b128 v[152:155], v249 offset:288
	ds_read_b128 v[156:159], v249 offset:304
	v_mul_f32_dpp v224, v244, v0 row_newbcast:0 row_mask:0xf bank_mask:0xf
	v_mul_f32_dpp v225, v245, v1 row_newbcast:0 row_mask:0xf bank_mask:0xf
	v_mul_f32_dpp v226, v246, v2 row_newbcast:0 row_mask:0xf bank_mask:0xf
	v_mul_f32_dpp v227, v247, v3 row_newbcast:0 row_mask:0xf bank_mask:0xf
	v_fmac_f32_dpp v224, v244, v4 row_newbcast:1 row_mask:0xf bank_mask:0xf
	v_fmac_f32_dpp v225, v245, v5 row_newbcast:1 row_mask:0xf bank_mask:0xf
	v_fmac_f32_dpp v226, v246, v6 row_newbcast:1 row_mask:0xf bank_mask:0xf
	v_fmac_f32_dpp v227, v247, v7 row_newbcast:1 row_mask:0xf bank_mask:0xf
	v_fmac_f32_dpp v224, v244, v8 row_newbcast:2 row_mask:0xf bank_mask:0xf
	v_fmac_f32_dpp v225, v245, v9 row_newbcast:2 row_mask:0xf bank_mask:0xf
	v_fmac_f32_dpp v226, v246, v10 row_newbcast:2 row_mask:0xf bank_mask:0xf
	v_fmac_f32_dpp v227, v247, v11 row_newbcast:2 row_mask:0xf bank_mask:0xf
	v_fmac_f32_dpp v224, v244, v12 row_newbcast:3 row_mask:0xf bank_mask:0xf
	v_fmac_f32_dpp v225, v245, v13 row_newbcast:3 row_mask:0xf bank_mask:0xf
	v_fmac_f32_dpp v226, v246, v14 row_newbcast:3 row_mask:0xf bank_mask:0xf
	v_fmac_f32_dpp v227, v247, v15 row_newbcast:3 row_mask:0xf bank_mask:0xf
	v_fmac_f32_dpp v224, v244, v16 row_newbcast:4 row_mask:0xf bank_mask:0xf
	v_fmac_f32_dpp v225, v245, v17 row_newbcast:4 row_mask:0xf bank_mask:0xf
	v_fmac_f32_dpp v226, v246, v18 row_newbcast:4 row_mask:0xf bank_mask:0xf
	v_fmac_f32_dpp v227, v247, v19 row_newbcast:4 row_mask:0xf bank_mask:0xf
	v_fmac_f32_dpp v224, v244, v20 row_newbcast:5 row_mask:0xf bank_mask:0xf
	v_fmac_f32_dpp v225, v245, v21 row_newbcast:5 row_mask:0xf bank_mask:0xf
	v_fmac_f32_dpp v226, v246, v22 row_newbcast:5 row_mask:0xf bank_mask:0xf
	v_fmac_f32_dpp v227, v247, v23 row_newbcast:5 row_mask:0xf bank_mask:0xf
	v_fmac_f32_dpp v224, v244, v24 row_newbcast:6 row_mask:0xf bank_mask:0xf
	v_fmac_f32_dpp v225, v245, v25 row_newbcast:6 row_mask:0xf bank_mask:0xf
	v_fmac_f32_dpp v226, v246, v26 row_newbcast:6 row_mask:0xf bank_mask:0xf
	v_fmac_f32_dpp v227, v247, v27 row_newbcast:6 row_mask:0xf bank_mask:0xf
	v_fmac_f32_dpp v224, v244, v28 row_newbcast:7 row_mask:0xf bank_mask:0xf
	v_fmac_f32_dpp v225, v245, v29 row_newbcast:7 row_mask:0xf bank_mask:0xf
	v_fmac_f32_dpp v226, v246, v30 row_newbcast:7 row_mask:0xf bank_mask:0xf
	v_fmac_f32_dpp v227, v247, v31 row_newbcast:7 row_mask:0xf bank_mask:0xf
	v_fmac_f32_dpp v224, v244, v32 row_newbcast:8 row_mask:0xf bank_mask:0xf
	v_fmac_f32_dpp v225, v245, v33 row_newbcast:8 row_mask:0xf bank_mask:0xf
	v_fmac_f32_dpp v226, v246, v34 row_newbcast:8 row_mask:0xf bank_mask:0xf
	v_fmac_f32_dpp v227, v247, v35 row_newbcast:8 row_mask:0xf bank_mask:0xf
	v_fmac_f32_dpp v224, v244, v36 row_newbcast:9 row_mask:0xf bank_mask:0xf
	v_fmac_f32_dpp v225, v245, v37 row_newbcast:9 row_mask:0xf bank_mask:0xf
	v_fmac_f32_dpp v226, v246, v38 row_newbcast:9 row_mask:0xf bank_mask:0xf
	v_fmac_f32_dpp v227, v247, v39 row_newbcast:9 row_mask:0xf bank_mask:0xf
	v_fmac_f32_dpp v224, v244, v40 row_newbcast:10 row_mask:0xf bank_mask:0xf
	v_fmac_f32_dpp v225, v245, v41 row_newbcast:10 row_mask:0xf bank_mask:0xf
	v_fmac_f32_dpp v226, v246, v42 row_newbcast:10 row_mask:0xf bank_mask:0xf
	v_fmac_f32_dpp v227, v247, v43 row_newbcast:10 row_mask:0xf bank_mask:0xf
	v_fmac_f32_dpp v224, v244, v44 row_newbcast:11 row_mask:0xf bank_mask:0xf
	v_fmac_f32_dpp v225, v245, v45 row_newbcast:11 row_mask:0xf bank_mask:0xf
	v_fmac_f32_dpp v226, v246, v46 row_newbcast:11 row_mask:0xf bank_mask:0xf
	v_fmac_f32_dpp v227, v247, v47 row_newbcast:11 row_mask:0xf bank_mask:0xf
	v_fmac_f32_dpp v224, v244, v48 row_newbcast:12 row_mask:0xf bank_mask:0xf
	v_fmac_f32_dpp v225, v245, v49 row_newbcast:12 row_mask:0xf bank_mask:0xf
	v_fmac_f32_dpp v226, v246, v50 row_newbcast:12 row_mask:0xf bank_mask:0xf
	v_fmac_f32_dpp v227, v247, v51 row_newbcast:12 row_mask:0xf bank_mask:0xf
	v_fmac_f32_dpp v224, v244, v52 row_newbcast:13 row_mask:0xf bank_mask:0xf
	v_fmac_f32_dpp v225, v245, v53 row_newbcast:13 row_mask:0xf bank_mask:0xf
	v_fmac_f32_dpp v226, v246, v54 row_newbcast:13 row_mask:0xf bank_mask:0xf
	v_fmac_f32_dpp v227, v247, v55 row_newbcast:13 row_mask:0xf bank_mask:0xf
	v_fmac_f32_dpp v224, v244, v56 row_newbcast:14 row_mask:0xf bank_mask:0xf
	v_fmac_f32_dpp v225, v245, v57 row_newbcast:14 row_mask:0xf bank_mask:0xf
	v_fmac_f32_dpp v226, v246, v58 row_newbcast:14 row_mask:0xf bank_mask:0xf
	v_fmac_f32_dpp v227, v247, v59 row_newbcast:14 row_mask:0xf bank_mask:0xf
	v_fmac_f32_dpp v224, v244, v60 row_newbcast:15 row_mask:0xf bank_mask:0xf
	v_fmac_f32_dpp v225, v245, v61 row_newbcast:15 row_mask:0xf bank_mask:0xf
	v_fmac_f32_dpp v226, v246, v62 row_newbcast:15 row_mask:0xf bank_mask:0xf
	v_fmac_f32_dpp v227, v247, v63 row_newbcast:15 row_mask:0xf bank_mask:0xf
	v_mul_f32_dpp v228, v244, v64 row_newbcast:0 row_mask:0xf bank_mask:0xf
	v_mul_f32_dpp v229, v245, v65 row_newbcast:0 row_mask:0xf bank_mask:0xf
	v_mul_f32_dpp v230, v246, v66 row_newbcast:0 row_mask:0xf bank_mask:0xf
	v_mul_f32_dpp v231, v247, v67 row_newbcast:0 row_mask:0xf bank_mask:0xf
	v_fmac_f32_dpp v228, v244, v68 row_newbcast:1 row_mask:0xf bank_mask:0xf
	v_fmac_f32_dpp v229, v245, v69 row_newbcast:1 row_mask:0xf bank_mask:0xf
	v_fmac_f32_dpp v230, v246, v70 row_newbcast:1 row_mask:0xf bank_mask:0xf
	v_fmac_f32_dpp v231, v247, v71 row_newbcast:1 row_mask:0xf bank_mask:0xf
	v_fmac_f32_dpp v228, v244, v72 row_newbcast:2 row_mask:0xf bank_mask:0xf
	v_fmac_f32_dpp v229, v245, v73 row_newbcast:2 row_mask:0xf bank_mask:0xf
	v_fmac_f32_dpp v230, v246, v74 row_newbcast:2 row_mask:0xf bank_mask:0xf
;     static __device__ __forceinline__ void updS(float (&S)[64], const In1& in, float sa, float vv) {
;         float t0, t1, t2, t3;
;         asm volatile("v_mul_f32_dpp %0, %8, %21 row_newbcast:%22" DPPM "v_mul_f32_dpp %1, %9, %21 row_newbcast:%22" DPPM "v_mul_f32_dpp %2, %10, %21 row_newbcast:%22" DPPM "v_mul_f32_dpp %3, %11, %21 row_newbcast:%22" DPPM
;                      "v_fmac_f32_dpp %0, %12, %4 row_newbcast:%22" DPPM "v_fmac_f32_dpp %1, %13, %5 row_newbcast:%22" DPPM "v_fmac_f32_dpp %2, %14, %6 row_newbcast:%22" DPPM "v_fmac_f32_dpp %3, %15, %7 row_newbcast:%22" DPPM
;                      "v_fmac_f32_dpp %0, %16, %20 row_newbcast:%22" DPPM "v_fmac_f32_dpp %1, %17, %20 row_newbcast:%22" DPPM "v_fmac_f32_dpp %2, %18, %20 row_newbcast:%22" DPPM "v_fmac_f32_dpp %3, %19, %20 row_newbcast:%22" DPPM
;                      : "=&v"(t0), "=&v"(t1), "=&v"(t2), "=&v"(t3)
;                      : "v"(S[K]), "v"(S[K + 1]), "v"(S[K + 2]), "v"(S[K + 3]), "v"(in.kd[0]), "v"(in.kd[1]), "v"(in.kd[2]), "v"(in.kd[3]), "v"(in.w[0]), "v"(in.w[1]), "v"(in.w[2]), "v"(in.w[3]),
;                        "v"(in.b[0]), "v"(in.b[1]), "v"(in.b[2]), "v"(in.b[3]), "v"(sa), "v"(vv), "n"(N0));
;         S[K] = t0; S[K + 1] = t1; S[K + 2] = t2; S[K + 3] = t3;
;         if constexpr (K + 4 < 64) ScanK<K + 4>::updS(S, in, sa, vv);
;     }
;     static __device__ __forceinline__ void updP(float (&P)[64], const In1& in, float sa) {
;         float u0, u1, u2, u3;
;         asm volatile("v_mul_f32_dpp %0, %8, %4 row_newbcast:%17" DPPM "v_mul_f32_dpp %1, %9, %5 row_newbcast:%17" DPPM "v_mul_f32_dpp %2, %10, %6 row_newbcast:%17" DPPM "v_mul_f32_dpp %3, %11, %7 row_newbcast:%17" DPPM
;                      "v_fmac_f32_dpp %0, %12, %16 row_newbcast:%17" DPPM "v_fmac_f32_dpp %1, %13, %16 row_newbcast:%17" DPPM "v_fmac_f32_dpp %2, %14, %16 row_newbcast:%17" DPPM "v_fmac_f32_dpp %3, %15, %16 row_newbcast:%17" DPPM
;                      : "=&v"(u0), "=&v"(u1), "=&v"(u2), "=&v"(u3)
;                      : "v"(P[K]), "v"(P[K + 1]), "v"(P[K + 2]), "v"(P[K + 3]), "v"(in.w[0]), "v"(in.w[1]), "v"(in.w[2]), "v"(in.w[3]), "v"(in.b[0]), "v"(in.b[1]), "v"(in.b[2]), "v"(in.b[3]), "v"(sa), "n"(N0));
;         P[K] = u0; P[K + 1] = u1; P[K + 2] = u2; P[K + 3] = u3;
;         if constexpr (K + 4 < 64) ScanK<K + 4>::updP(P, in, sa);
	v_fmac_f32_dpp v231, v247, v75 row_newbcast:2 row_mask:0xf bank_mask:0xf
	v_fmac_f32_dpp v228, v244, v76 row_newbcast:3 row_mask:0xf bank_mask:0xf
	v_fmac_f32_dpp v229, v245, v77 row_newbcast:3 row_mask:0xf bank_mask:0xf
	v_fmac_f32_dpp v230, v246, v78 row_newbcast:3 row_mask:0xf bank_mask:0xf
	v_fmac_f32_dpp v231, v247, v79 row_newbcast:3 row_mask:0xf bank_mask:0xf
	v_fmac_f32_dpp v228, v244, v80 row_newbcast:4 row_mask:0xf bank_mask:0xf
	v_fmac_f32_dpp v229, v245, v81 row_newbcast:4 row_mask:0xf bank_mask:0xf
	v_fmac_f32_dpp v230, v246, v82 row_newbcast:4 row_mask:0xf bank_mask:0xf
	v_fmac_f32_dpp v231, v247, v83 row_newbcast:4 row_mask:0xf bank_mask:0xf
	v_fmac_f32_dpp v228, v244, v84 row_newbcast:5 row_mask:0xf bank_mask:0xf
	v_fmac_f32_dpp v229, v245, v85 row_newbcast:5 row_mask:0xf bank_mask:0xf
	v_fmac_f32_dpp v230, v246, v86 row_newbcast:5 row_mask:0xf bank_mask:0xf
	v_fmac_f32_dpp v231, v247, v87 row_newbcast:5 row_mask:0xf bank_mask:0xf
	v_fmac_f32_dpp v228, v244, v88 row_newbcast:6 row_mask:0xf bank_mask:0xf
	v_fmac_f32_dpp v229, v245, v89 row_newbcast:6 row_mask:0xf bank_mask:0xf
	v_fmac_f32_dpp v230, v246, v90 row_newbcast:6 row_mask:0xf bank_mask:0xf
	v_fmac_f32_dpp v231, v247, v91 row_newbcast:6 row_mask:0xf bank_mask:0xf
	v_fmac_f32_dpp v228, v244, v92 row_newbcast:7 row_mask:0xf bank_mask:0xf
	v_fmac_f32_dpp v229, v245, v93 row_newbcast:7 row_mask:0xf bank_mask:0xf
	v_fmac_f32_dpp v230, v246, v94 row_newbcast:7 row_mask:0xf bank_mask:0xf
	v_fmac_f32_dpp v231, v247, v95 row_newbcast:7 row_mask:0xf bank_mask:0xf
	v_fmac_f32_dpp v228, v244, v96 row_newbcast:8 row_mask:0xf bank_mask:0xf
	v_fmac_f32_dpp v229, v245, v97 row_newbcast:8 row_mask:0xf bank_mask:0xf
	v_fmac_f32_dpp v230, v246, v98 row_newbcast:8 row_mask:0xf bank_mask:0xf
	v_fmac_f32_dpp v231, v247, v99 row_newbcast:8 row_mask:0xf bank_mask:0xf
	v_fmac_f32_dpp v228, v244, v100 row_newbcast:9 row_mask:0xf bank_mask:0xf
	v_fmac_f32_dpp v229, v245, v101 row_newbcast:9 row_mask:0xf bank_mask:0xf
	v_fmac_f32_dpp v230, v246, v102 row_newbcast:9 row_mask:0xf bank_mask:0xf
	v_fmac_f32_dpp v231, v247, v103 row_newbcast:9 row_mask:0xf bank_mask:0xf
	v_fmac_f32_dpp v228, v244, v104 row_newbcast:10 row_mask:0xf bank_mask:0xf
	v_fmac_f32_dpp v229, v245, v105 row_newbcast:10 row_mask:0xf bank_mask:0xf
	v_fmac_f32_dpp v230, v246, v106 row_newbcast:10 row_mask:0xf bank_mask:0xf
	v_fmac_f32_dpp v231, v247, v107 row_newbcast:10 row_mask:0xf bank_mask:0xf
	v_fmac_f32_dpp v228, v244, v108 row_newbcast:11 row_mask:0xf bank_mask:0xf
	v_fmac_f32_dpp v229, v245, v109 row_newbcast:11 row_mask:0xf bank_mask:0xf
	v_fmac_f32_dpp v230, v246, v110 row_newbcast:11 row_mask:0xf bank_mask:0xf
	v_fmac_f32_dpp v231, v247, v111 row_newbcast:11 row_mask:0xf bank_mask:0xf
	v_fmac_f32_dpp v228, v244, v112 row_newbcast:12 row_mask:0xf bank_mask:0xf
	v_fmac_f32_dpp v229, v245, v113 row_newbcast:12 row_mask:0xf bank_mask:0xf
	v_fmac_f32_dpp v230, v246, v114 row_newbcast:12 row_mask:0xf bank_mask:0xf
	v_fmac_f32_dpp v231, v247, v115 row_newbcast:12 row_mask:0xf bank_mask:0xf
	v_fmac_f32_dpp v228, v244, v116 row_newbcast:13 row_mask:0xf bank_mask:0xf
	v_fmac_f32_dpp v229, v245, v117 row_newbcast:13 row_mask:0xf bank_mask:0xf
	v_fmac_f32_dpp v230, v246, v118 row_newbcast:13 row_mask:0xf bank_mask:0xf
	v_fmac_f32_dpp v231, v247, v119 row_newbcast:13 row_mask:0xf bank_mask:0xf
	v_fmac_f32_dpp v228, v244, v120 row_newbcast:14 row_mask:0xf bank_mask:0xf
	v_fmac_f32_dpp v229, v245, v121 row_newbcast:14 row_mask:0xf bank_mask:0xf
	v_fmac_f32_dpp v230, v246, v122 row_newbcast:14 row_mask:0xf bank_mask:0xf
	v_fmac_f32_dpp v231, v247, v123 row_newbcast:14 row_mask:0xf bank_mask:0xf
	v_fmac_f32_dpp v228, v244, v124 row_newbcast:15 row_mask:0xf bank_mask:0xf
	v_fmac_f32_dpp v229, v245, v125 row_newbcast:15 row_mask:0xf bank_mask:0xf
	v_fmac_f32_dpp v230, v246, v126 row_newbcast:15 row_mask:0xf bank_mask:0xf
	v_fmac_f32_dpp v231, v247, v127 row_newbcast:15 row_mask:0xf bank_mask:0xf
	v_add_f32_e32 v224, v224, v225
	v_add_f32_e32 v226, v226, v227
	v_sub_f32_e64 v232, -v224, v226
	v_add_f32_e32 v228, v228, v229
	v_add_f32_e32 v230, v230, v231
	v_sub_f32_e64 v233, -v228, v230
	s_waitcnt lgkmcnt(0)
	s_nop 1
	v_mfma_f32_4x4x1_16b_f32 v[0:3], v128, v232, v[0:3]
	v_mfma_f32_4x4x1_16b_f32 v[4:7], v129, v232, v[4:7]
	v_mfma_f32_4x4x1_16b_f32 v[8:11], v130, v232, v[8:11]
	v_mfma_f32_4x4x1_16b_f32 v[12:15], v131, v232, v[12:15]
	v_mfma_f32_4x4x1_16b_f32 v[16:19], v132, v232, v[16:19]
	v_mfma_f32_4x4x1_16b_f32 v[20:23], v133, v232, v[20:23]
	v_mfma_f32_4x4x1_16b_f32 v[24:27], v134, v232, v[24:27]
	v_mfma_f32_4x4x1_16b_f32 v[28:31], v135, v232, v[28:31]
	v_mfma_f32_4x4x1_16b_f32 v[32:35], v136, v232, v[32:35]
	v_mfma_f32_4x4x1_16b_f32 v[36:39], v137, v232, v[36:39]
	v_mfma_f32_4x4x1_16b_f32 v[40:43], v138, v232, v[40:43]
	v_mfma_f32_4x4x1_16b_f32 v[44:47], v139, v232, v[44:47]
	v_mfma_f32_4x4x1_16b_f32 v[48:51], v140, v232, v[48:51]
	v_mfma_f32_4x4x1_16b_f32 v[52:55], v141, v232, v[52:55]
	v_mfma_f32_4x4x1_16b_f32 v[56:59], v142, v232, v[56:59]
	v_mfma_f32_4x4x1_16b_f32 v[60:63], v143, v232, v[60:63]
	v_mfma_f32_4x4x1_16b_f32 v[0:3], v144, v234, v[0:3]
	v_mfma_f32_4x4x1_16b_f32 v[4:7], v145, v234, v[4:7]
	v_mfma_f32_4x4x1_16b_f32 v[8:11], v146, v234, v[8:11]
	v_mfma_f32_4x4x1_16b_f32 v[12:15], v147, v234, v[12:15]
	v_mfma_f32_4x4x1_16b_f32 v[16:19], v148, v234, v[16:19]
	v_mfma_f32_4x4x1_16b_f32 v[20:23], v149, v234, v[20:23]
	v_mfma_f32_4x4x1_16b_f32 v[24:27], v150, v234, v[24:27]
	v_mfma_f32_4x4x1_16b_f32 v[28:31], v151, v234, v[28:31]
	v_mfma_f32_4x4x1_16b_f32 v[32:35], v152, v234, v[32:35]
	v_mfma_f32_4x4x1_16b_f32 v[36:39], v153, v234, v[36:39]
	v_mfma_f32_4x4x1_16b_f32 v[40:43], v154, v234, v[40:43]
	v_mfma_f32_4x4x1_16b_f32 v[44:47], v155, v234, v[44:47]
	v_mfma_f32_4x4x1_16b_f32 v[48:51], v156, v234, v[48:51]
	v_mfma_f32_4x4x1_16b_f32 v[52:55], v157, v234, v[52:55]
	v_mfma_f32_4x4x1_16b_f32 v[56:59], v158, v234, v[56:59]
	v_mfma_f32_4x4x1_16b_f32 v[60:63], v159, v234, v[60:63]
	v_mfma_f32_4x4x1_16b_f32 v[64:67], v128, v233, v[64:67]
	v_mfma_f32_4x4x1_16b_f32 v[68:71], v129, v233, v[68:71]
	v_mfma_f32_4x4x1_16b_f32 v[72:75], v130, v233, v[72:75]
	v_mfma_f32_4x4x1_16b_f32 v[76:79], v131, v233, v[76:79]
	v_mfma_f32_4x4x1_16b_f32 v[80:83], v132, v233, v[80:83]
	v_mfma_f32_4x4x1_16b_f32 v[84:87], v133, v233, v[84:87]
	v_mfma_f32_4x4x1_16b_f32 v[88:91], v134, v233, v[88:91]
	v_mfma_f32_4x4x1_16b_f32 v[92:95], v135, v233, v[92:95]
	v_mfma_f32_4x4x1_16b_f32 v[96:99], v136, v233, v[96:99]
	v_mfma_f32_4x4x1_16b_f32 v[100:103], v137, v233, v[100:103]
	v_mfma_f32_4x4x1_16b_f32 v[104:107], v138, v233, v[104:107]
	v_mfma_f32_4x4x1_16b_f32 v[108:111], v139, v233, v[108:111]
	v_mfma_f32_4x4x1_16b_f32 v[112:115], v140, v233, v[112:115]
	v_mfma_f32_4x4x1_16b_f32 v[116:119], v141, v233, v[116:119]
	v_mfma_f32_4x4x1_16b_f32 v[120:123], v142, v233, v[120:123]
	v_mfma_f32_4x4x1_16b_f32 v[124:127], v143, v233, v[124:127]
	s_waitcnt vmcnt(5)
; #define SB __builtin_amdgcn_sched_barrier(0)
; #define LD1(set, s) { const int e_ = min((int)(s), LC - 1) * (int)stp; const unsigned s4_ = ob4 + (unsigned)(e_ * 4), s2_ = ob2 + (unsigned)(e_ * 2); set.w = LDX(rW, s4_); set.a = LDX(rA, s4_); set.b = LDX(rB, s4_); \
;             set.kw = __builtin_amdgcn_raw_buffer_load_b64(rK, lo8, s2_, 0); set.v = __builtin_amdgcn_raw_buffer_load_b16(rV, lo2, s2_, 0); }
; #define TOUCH1(set) asm volatile("" :: "v"(set.w), "v"(set.a), "v"(set.b), "v"(set.kw), "v"(set.v))
; #define ST1(set) { DERIVE_BK(set); float sd[4]; ScanK<0>::dot(S, set.a, sd); ScanK<0>::updS(S, set, -((sd[0] + sd[1]) + (sd[2] + sd[3])), __uint_as_float(set.v << 16)); }
; #define LD1(set, s) { const int e_ = min((int)(s), LC - 1) * (int)stp; const unsigned s4_ = ob4 + (unsigned)(e_ * 4); set.w = LDX(rW, s4_); set.a = LDX(rA, s4_); set.b = LDX(rB, s4_); }
; #define TOUCH1(set) asm volatile("" :: "v"(set.w), "v"(set.a), "v"(set.b))
; #define ST1(set) { DERIVE_B(set); float sd[4]; ScanK<0>::dot(S, set.a, sd); ScanK<0>::updP(S, set, -((sd[0] + sd[1]) + (sd[2] + sd[3]))); }
; template <bool MIX> __device__ __forceinline__ void scan_pass1(const Params& p, int d, float* ldsf) {
;     ...
;             In1 i0, i1; LD1(i0, 0);
; #pragma unroll 1
;             for (int s = 0; s < LC; s += 2) { TOUCH1(i0); SB; LD1(i1, s + 1); SB; ST1(i0); TOUCH1(i1); SB; LD1(i0, s + 2); SB; ST1(i1); }
	buffer_load_dwordx4 v[160:163], v235, s[64:67], s72 offen
	buffer_load_dwordx4 v[164:167], v250, s[64:67], s72 offen
	buffer_load_dwordx4 v[168:171], v251, s[64:67], s72 offen
	buffer_load_dwordx2 v[172:173], v252, s[64:67], s76 offen
	buffer_load_ushort v174, v253, s[64:67], s76 offen
	s_add_u32 s72, s72, 0x1000
	s_add_u32 s76, s76, 0x800
	v_pk_mul_f32 v[244:245], v[180:181], v[236:237]
	v_pk_mul_f32 v[246:247], v[182:183], v[238:239]
	v_pk_mul_f32 v[236:237], v[236:237], v[176:177]
	v_pk_mul_f32 v[238:239], v[238:239], v[178:179]
	v_pk_fma_f32 v[228:229], v[184:185], v[216:217], v[220:221]
	v_pk_fma_f32 v[230:231], v[186:187], v[218:219], v[222:223]
	v_pk_mul_f32 v[208:209], v[180:181], v[184:185]
	v_pk_mul_f32 v[210:211], v[182:183], v[186:187]
	v_rcp_f32_e32 v240, v236
	v_rcp_f32_e32 v241, v237
	v_rcp_f32_e32 v242, v238
	v_rcp_f32_e32 v243, v239
	v_lshlrev_b32_e32 v212, 16, v188
	v_and_b32_e32 v213, 0xffff0000, v188
	v_lshlrev_b32_e32 v214, 16, v189
	v_and_b32_e32 v215, 0xffff0000, v189
	v_pk_mul_f32 v[212:213], v[212:213], v[228:229]
	v_pk_mul_f32 v[214:215], v[214:215], v[230:231]
	v_lshlrev_b32_e32 v234, 16, v190
	v_pk_mul_f32 v[208:209], v[208:209], v[240:241]
	v_pk_mul_f32 v[210:211], v[210:211], v[242:243]
	v_pk_mul_f32 v[212:213], v[212:213], v[240:241]
	v_pk_mul_f32 v[214:215], v[214:215], v[242:243]
	ds_write2_b32 v248, v208, v209 offset0:0 offset1:16
	ds_write2_b32 v248, v210, v211 offset0:32 offset1:48
	ds_write2_b32 v248, v212, v213 offset0:64 offset1:80
	ds_write2_b32 v248, v214, v215 offset0:96 offset1:112
	ds_read_b128 v[128:131], v249 offset:0
	ds_read_b128 v[132:135], v249 offset:16
	ds_read_b128 v[136:139], v249 offset:32
	ds_read_b128 v[140:143], v249 offset:48
	ds_read_b128 v[144:147], v249 offset:256
	ds_read_b128 v[148:151], v249 offset:272
	ds_read_b128 v[152:155], v249 offset:288
	ds_read_b128 v[156:159], v249 offset:304
	v_mul_f32_dpp v224, v244, v0 row_newbcast:0 row_mask:0xf bank_mask:0xf
	v_mul_f32_dpp v225, v245, v1 row_newbcast:0 row_mask:0xf bank_mask:0xf
	v_mul_f32_dpp v226, v246, v2 row_newbcast:0 row_mask:0xf bank_mask:0xf
	v_mul_f32_dpp v227, v247, v3 row_newbcast:0 row_mask:0xf bank_mask:0xf
	v_fmac_f32_dpp v224, v244, v4 row_newbcast:1 row_mask:0xf bank_mask:0xf
	v_fmac_f32_dpp v225, v245, v5 row_newbcast:1 row_mask:0xf bank_mask:0xf
	v_fmac_f32_dpp v226, v246, v6 row_newbcast:1 row_mask:0xf bank_mask:0xf
	v_fmac_f32_dpp v227, v247, v7 row_newbcast:1 row_mask:0xf bank_mask:0xf
	v_fmac_f32_dpp v224, v244, v8 row_newbcast:2 row_mask:0xf bank_mask:0xf
	v_fmac_f32_dpp v225, v245, v9 row_newbcast:2 row_mask:0xf bank_mask:0xf
	v_fmac_f32_dpp v226, v246, v10 row_newbcast:2 row_mask:0xf bank_mask:0xf
	v_fmac_f32_dpp v227, v247, v11 row_newbcast:2 row_mask:0xf bank_mask:0xf
	v_fmac_f32_dpp v224, v244, v12 row_newbcast:3 row_mask:0xf bank_mask:0xf
	v_fmac_f32_dpp v225, v245, v13 row_newbcast:3 row_mask:0xf bank_mask:0xf
	v_fmac_f32_dpp v226, v246, v14 row_newbcast:3 row_mask:0xf bank_mask:0xf
	v_fmac_f32_dpp v227, v247, v15 row_newbcast:3 row_mask:0xf bank_mask:0xf
	v_fmac_f32_dpp v224, v244, v16 row_newbcast:4 row_mask:0xf bank_mask:0xf
	v_fmac_f32_dpp v225, v245, v17 row_newbcast:4 row_mask:0xf bank_mask:0xf
	v_fmac_f32_dpp v226, v246, v18 row_newbcast:4 row_mask:0xf bank_mask:0xf
	v_fmac_f32_dpp v227, v247, v19 row_newbcast:4 row_mask:0xf bank_mask:0xf
	v_fmac_f32_dpp v224, v244, v20 row_newbcast:5 row_mask:0xf bank_mask:0xf
	v_fmac_f32_dpp v225, v245, v21 row_newbcast:5 row_mask:0xf bank_mask:0xf
	v_fmac_f32_dpp v226, v246, v22 row_newbcast:5 row_mask:0xf bank_mask:0xf
	v_fmac_f32_dpp v227, v247, v23 row_newbcast:5 row_mask:0xf bank_mask:0xf
	v_fmac_f32_dpp v224, v244, v24 row_newbcast:6 row_mask:0xf bank_mask:0xf
	v_fmac_f32_dpp v225, v245, v25 row_newbcast:6 row_mask:0xf bank_mask:0xf
	v_fmac_f32_dpp v226, v246, v26 row_newbcast:6 row_mask:0xf bank_mask:0xf
	v_fmac_f32_dpp v227, v247, v27 row_newbcast:6 row_mask:0xf bank_mask:0xf
	v_fmac_f32_dpp v224, v244, v28 row_newbcast:7 row_mask:0xf bank_mask:0xf
	v_fmac_f32_dpp v225, v245, v29 row_newbcast:7 row_mask:0xf bank_mask:0xf
	v_fmac_f32_dpp v226, v246, v30 row_newbcast:7 row_mask:0xf bank_mask:0xf
	v_fmac_f32_dpp v227, v247, v31 row_newbcast:7 row_mask:0xf bank_mask:0xf
	v_fmac_f32_dpp v224, v244, v32 row_newbcast:8 row_mask:0xf bank_mask:0xf
	v_fmac_f32_dpp v225, v245, v33 row_newbcast:8 row_mask:0xf bank_mask:0xf
	v_fmac_f32_dpp v226, v246, v34 row_newbcast:8 row_mask:0xf bank_mask:0xf
	v_fmac_f32_dpp v227, v247, v35 row_newbcast:8 row_mask:0xf bank_mask:0xf
	v_fmac_f32_dpp v224, v244, v36 row_newbcast:9 row_mask:0xf bank_mask:0xf
	v_fmac_f32_dpp v225, v245, v37 row_newbcast:9 row_mask:0xf bank_mask:0xf
	v_fmac_f32_dpp v226, v246, v38 row_newbcast:9 row_mask:0xf bank_mask:0xf
	v_fmac_f32_dpp v227, v247, v39 row_newbcast:9 row_mask:0xf bank_mask:0xf
	v_fmac_f32_dpp v224, v244, v40 row_newbcast:10 row_mask:0xf bank_mask:0xf
	v_fmac_f32_dpp v225, v245, v41 row_newbcast:10 row_mask:0xf bank_mask:0xf
	v_fmac_f32_dpp v226, v246, v42 row_newbcast:10 row_mask:0xf bank_mask:0xf
	v_fmac_f32_dpp v227, v247, v43 row_newbcast:10 row_mask:0xf bank_mask:0xf
	v_fmac_f32_dpp v224, v244, v44 row_newbcast:11 row_mask:0xf bank_mask:0xf
	v_fmac_f32_dpp v225, v245, v45 row_newbcast:11 row_mask:0xf bank_mask:0xf
	v_fmac_f32_dpp v226, v246, v46 row_newbcast:11 row_mask:0xf bank_mask:0xf
	v_fmac_f32_dpp v227, v247, v47 row_newbcast:11 row_mask:0xf bank_mask:0xf
	v_fmac_f32_dpp v224, v244, v48 row_newbcast:12 row_mask:0xf bank_mask:0xf
	v_fmac_f32_dpp v225, v245, v49 row_newbcast:12 row_mask:0xf bank_mask:0xf
	v_fmac_f32_dpp v226, v246, v50 row_newbcast:12 row_mask:0xf bank_mask:0xf
;     static __device__ __forceinline__ void dot(const float (&S)[64], const f32x4& a, float (&s)[4]) {
;         if constexpr (K == 0) {
;             asm volatile("v_mul_f32_dpp %0, %4, %8 row_newbcast:%16" DPPM "v_mul_f32_dpp %1, %5, %9 row_newbcast:%16" DPPM "v_mul_f32_dpp %2, %6, %10 row_newbcast:%16" DPPM "v_mul_f32_dpp %3, %7, %11 row_newbcast:%16" DPPM
;                          "v_fmac_f32_dpp %0, %4, %12 row_newbcast:%17" DPPM "v_fmac_f32_dpp %1, %5, %13 row_newbcast:%17" DPPM "v_fmac_f32_dpp %2, %6, %14 row_newbcast:%17" DPPM "v_fmac_f32_dpp %3, %7, %15 row_newbcast:%17" DPPM
;                          : "=&v"(s[0]), "=&v"(s[1]), "=&v"(s[2]), "=&v"(s[3])
;                          : "v"(a[0]), "v"(a[1]), "v"(a[2]), "v"(a[3]), "v"(S[K]), "v"(S[K + 1]), "v"(S[K + 2]), "v"(S[K + 3]), "v"(S[K + 4]), "v"(S[K + 5]), "v"(S[K + 6]), "v"(S[K + 7]), "n"(N0), "n"(N1));
;         } else
;         asm volatile("v_fmac_f32_dpp %0, %4, %8 row_newbcast:%16" DPPM "v_fmac_f32_dpp %1, %5, %9 row_newbcast:%16" DPPM "v_fmac_f32_dpp %2, %6, %10 row_newbcast:%16" DPPM "v_fmac_f32_dpp %3, %7, %11 row_newbcast:%16" DPPM
;                      "v_fmac_f32_dpp %0, %4, %12 row_newbcast:%17" DPPM "v_fmac_f32_dpp %1, %5, %13 row_newbcast:%17" DPPM "v_fmac_f32_dpp %2, %6, %14 row_newbcast:%17" DPPM "v_fmac_f32_dpp %3, %7, %15 row_newbcast:%17" DPPM
;                      : "+v"(s[0]), "+v"(s[1]), "+v"(s[2]), "+v"(s[3])
;                      : "v"(a[0]), "v"(a[1]), "v"(a[2]), "v"(a[3]), "v"(S[K]), "v"(S[K + 1]), "v"(S[K + 2]), "v"(S[K + 3]), "v"(S[K + 4]), "v"(S[K + 5]), "v"(S[K + 6]), "v"(S[K + 7]), "n"(N0), "n"(N1));
;         if constexpr (K + 8 < 64) ScanK<K + 8>::dot(S, a, s);
;     }
	v_fmac_f32_dpp v227, v247, v51 row_newbcast:12 row_mask:0xf bank_mask:0xf
	v_fmac_f32_dpp v224, v244, v52 row_newbcast:13 row_mask:0xf bank_mask:0xf
	v_fmac_f32_dpp v225, v245, v53 row_newbcast:13 row_mask:0xf bank_mask:0xf
	v_fmac_f32_dpp v226, v246, v54 row_newbcast:13 row_mask:0xf bank_mask:0xf
	v_fmac_f32_dpp v227, v247, v55 row_newbcast:13 row_mask:0xf bank_mask:0xf
	v_fmac_f32_dpp v224, v244, v56 row_newbcast:14 row_mask:0xf bank_mask:0xf
	v_fmac_f32_dpp v225, v245, v57 row_newbcast:14 row_mask:0xf bank_mask:0xf
	v_fmac_f32_dpp v226, v246, v58 row_newbcast:14 row_mask:0xf bank_mask:0xf
	v_fmac_f32_dpp v227, v247, v59 row_newbcast:14 row_mask:0xf bank_mask:0xf
	v_fmac_f32_dpp v224, v244, v60 row_newbcast:15 row_mask:0xf bank_mask:0xf
	v_fmac_f32_dpp v225, v245, v61 row_newbcast:15 row_mask:0xf bank_mask:0xf
	v_fmac_f32_dpp v226, v246, v62 row_newbcast:15 row_mask:0xf bank_mask:0xf
	v_fmac_f32_dpp v227, v247, v63 row_newbcast:15 row_mask:0xf bank_mask:0xf
	v_mul_f32_dpp v228, v244, v64 row_newbcast:0 row_mask:0xf bank_mask:0xf
	v_mul_f32_dpp v229, v245, v65 row_newbcast:0 row_mask:0xf bank_mask:0xf
	v_mul_f32_dpp v230, v246, v66 row_newbcast:0 row_mask:0xf bank_mask:0xf
	v_mul_f32_dpp v231, v247, v67 row_newbcast:0 row_mask:0xf bank_mask:0xf
	v_fmac_f32_dpp v228, v244, v68 row_newbcast:1 row_mask:0xf bank_mask:0xf
	v_fmac_f32_dpp v229, v245, v69 row_newbcast:1 row_mask:0xf bank_mask:0xf
	v_fmac_f32_dpp v230, v246, v70 row_newbcast:1 row_mask:0xf bank_mask:0xf
	v_fmac_f32_dpp v231, v247, v71 row_newbcast:1 row_mask:0xf bank_mask:0xf
	v_fmac_f32_dpp v228, v244, v72 row_newbcast:2 row_mask:0xf bank_mask:0xf
	v_fmac_f32_dpp v229, v245, v73 row_newbcast:2 row_mask:0xf bank_mask:0xf
	v_fmac_f32_dpp v230, v246, v74 row_newbcast:2 row_mask:0xf bank_mask:0xf
	v_fmac_f32_dpp v231, v247, v75 row_newbcast:2 row_mask:0xf bank_mask:0xf
	v_fmac_f32_dpp v228, v244, v76 row_newbcast:3 row_mask:0xf bank_mask:0xf
	v_fmac_f32_dpp v229, v245, v77 row_newbcast:3 row_mask:0xf bank_mask:0xf
	v_fmac_f32_dpp v230, v246, v78 row_newbcast:3 row_mask:0xf bank_mask:0xf
	v_fmac_f32_dpp v231, v247, v79 row_newbcast:3 row_mask:0xf bank_mask:0xf
	v_fmac_f32_dpp v228, v244, v80 row_newbcast:4 row_mask:0xf bank_mask:0xf
	v_fmac_f32_dpp v229, v245, v81 row_newbcast:4 row_mask:0xf bank_mask:0xf
	v_fmac_f32_dpp v230, v246, v82 row_newbcast:4 row_mask:0xf bank_mask:0xf
	v_fmac_f32_dpp v231, v247, v83 row_newbcast:4 row_mask:0xf bank_mask:0xf
	v_fmac_f32_dpp v228, v244, v84 row_newbcast:5 row_mask:0xf bank_mask:0xf
	v_fmac_f32_dpp v229, v245, v85 row_newbcast:5 row_mask:0xf bank_mask:0xf
	v_fmac_f32_dpp v230, v246, v86 row_newbcast:5 row_mask:0xf bank_mask:0xf
	v_fmac_f32_dpp v231, v247, v87 row_newbcast:5 row_mask:0xf bank_mask:0xf
	v_fmac_f32_dpp v228, v244, v88 row_newbcast:6 row_mask:0xf bank_mask:0xf
	v_fmac_f32_dpp v229, v245, v89 row_newbcast:6 row_mask:0xf bank_mask:0xf
	v_fmac_f32_dpp v230, v246, v90 row_newbcast:6 row_mask:0xf bank_mask:0xf
	v_fmac_f32_dpp v231, v247, v91 row_newbcast:6 row_mask:0xf bank_mask:0xf
	v_fmac_f32_dpp v228, v244, v92 row_newbcast:7 row_mask:0xf bank_mask:0xf
	v_fmac_f32_dpp v229, v245, v93 row_newbcast:7 row_mask:0xf bank_mask:0xf
	v_fmac_f32_dpp v230, v246, v94 row_newbcast:7 row_mask:0xf bank_mask:0xf
	v_fmac_f32_dpp v231, v247, v95 row_newbcast:7 row_mask:0xf bank_mask:0xf
	v_fmac_f32_dpp v228, v244, v96 row_newbcast:8 row_mask:0xf bank_mask:0xf
	v_fmac_f32_dpp v229, v245, v97 row_newbcast:8 row_mask:0xf bank_mask:0xf
	v_fmac_f32_dpp v230, v246, v98 row_newbcast:8 row_mask:0xf bank_mask:0xf
	v_fmac_f32_dpp v231, v247, v99 row_newbcast:8 row_mask:0xf bank_mask:0xf
	v_fmac_f32_dpp v228, v244, v100 row_newbcast:9 row_mask:0xf bank_mask:0xf
	v_fmac_f32_dpp v229, v245, v101 row_newbcast:9 row_mask:0xf bank_mask:0xf
	v_fmac_f32_dpp v230, v246, v102 row_newbcast:9 row_mask:0xf bank_mask:0xf
	v_fmac_f32_dpp v231, v247, v103 row_newbcast:9 row_mask:0xf bank_mask:0xf
	v_fmac_f32_dpp v228, v244, v104 row_newbcast:10 row_mask:0xf bank_mask:0xf
	v_fmac_f32_dpp v229, v245, v105 row_newbcast:10 row_mask:0xf bank_mask:0xf
	v_fmac_f32_dpp v230, v246, v106 row_newbcast:10 row_mask:0xf bank_mask:0xf
	v_fmac_f32_dpp v231, v247, v107 row_newbcast:10 row_mask:0xf bank_mask:0xf
	v_fmac_f32_dpp v228, v244, v108 row_newbcast:11 row_mask:0xf bank_mask:0xf
	v_fmac_f32_dpp v229, v245, v109 row_newbcast:11 row_mask:0xf bank_mask:0xf
	v_fmac_f32_dpp v230, v246, v110 row_newbcast:11 row_mask:0xf bank_mask:0xf
	v_fmac_f32_dpp v231, v247, v111 row_newbcast:11 row_mask:0xf bank_mask:0xf
	v_fmac_f32_dpp v228, v244, v112 row_newbcast:12 row_mask:0xf bank_mask:0xf
	v_fmac_f32_dpp v229, v245, v113 row_newbcast:12 row_mask:0xf bank_mask:0xf
	v_fmac_f32_dpp v230, v246, v114 row_newbcast:12 row_mask:0xf bank_mask:0xf
	v_fmac_f32_dpp v231, v247, v115 row_newbcast:12 row_mask:0xf bank_mask:0xf
	v_fmac_f32_dpp v228, v244, v116 row_newbcast:13 row_mask:0xf bank_mask:0xf
	v_fmac_f32_dpp v229, v245, v117 row_newbcast:13 row_mask:0xf bank_mask:0xf
	v_fmac_f32_dpp v230, v246, v118 row_newbcast:13 row_mask:0xf bank_mask:0xf
	v_fmac_f32_dpp v231, v247, v119 row_newbcast:13 row_mask:0xf bank_mask:0xf
	v_fmac_f32_dpp v228, v244, v120 row_newbcast:14 row_mask:0xf bank_mask:0xf
	v_fmac_f32_dpp v229, v245, v121 row_newbcast:14 row_mask:0xf bank_mask:0xf
	v_fmac_f32_dpp v230, v246, v122 row_newbcast:14 row_mask:0xf bank_mask:0xf
	v_fmac_f32_dpp v231, v247, v123 row_newbcast:14 row_mask:0xf bank_mask:0xf
	v_fmac_f32_dpp v228, v244, v124 row_newbcast:15 row_mask:0xf bank_mask:0xf
	v_fmac_f32_dpp v229, v245, v125 row_newbcast:15 row_mask:0xf bank_mask:0xf
	v_fmac_f32_dpp v230, v246, v126 row_newbcast:15 row_mask:0xf bank_mask:0xf
	v_fmac_f32_dpp v231, v247, v127 row_newbcast:15 row_mask:0xf bank_mask:0xf
	v_add_f32_e32 v224, v224, v225
	v_add_f32_e32 v226, v226, v227
	v_sub_f32_e64 v232, -v224, v226
	v_add_f32_e32 v228, v228, v229
	v_add_f32_e32 v230, v230, v231
	v_sub_f32_e64 v233, -v228, v230
	s_waitcnt lgkmcnt(0)
;     static __device__ __forceinline__ void updS(float (&S)[64], const In1& in, float sa, float vv) {
;         float t0, t1, t2, t3;
;         asm volatile("v_mul_f32_dpp %0, %8, %21 row_newbcast:%22" DPPM "v_mul_f32_dpp %1, %9, %21 row_newbcast:%22" DPPM "v_mul_f32_dpp %2, %10, %21 row_newbcast:%22" DPPM "v_mul_f32_dpp %3, %11, %21 row_newbcast:%22" DPPM
;                      "v_fmac_f32_dpp %0, %12, %4 row_newbcast:%22" DPPM "v_fmac_f32_dpp %1, %13, %5 row_newbcast:%22" DPPM "v_fmac_f32_dpp %2, %14, %6 row_newbcast:%22" DPPM "v_fmac_f32_dpp %3, %15, %7 row_newbcast:%22" DPPM
;                      "v_fmac_f32_dpp %0, %16, %20 row_newbcast:%22" DPPM "v_fmac_f32_dpp %1, %17, %20 row_newbcast:%22" DPPM "v_fmac_f32_dpp %2, %18, %20 row_newbcast:%22" DPPM "v_fmac_f32_dpp %3, %19, %20 row_newbcast:%22" DPPM
;                      : "=&v"(t0), "=&v"(t1), "=&v"(t2), "=&v"(t3)
;                      : "v"(S[K]), "v"(S[K + 1]), "v"(S[K + 2]), "v"(S[K + 3]), "v"(in.kd[0]), "v"(in.kd[1]), "v"(in.kd[2]), "v"(in.kd[3]), "v"(in.w[0]), "v"(in.w[1]), "v"(in.w[2]), "v"(in.w[3]),
;                        "v"(in.b[0]), "v"(in.b[1]), "v"(in.b[2]), "v"(in.b[3]), "v"(sa), "v"(vv), "n"(N0));
;         S[K] = t0; S[K + 1] = t1; S[K + 2] = t2; S[K + 3] = t3;
;         if constexpr (K + 4 < 64) ScanK<K + 4>::updS(S, in, sa, vv);
;     }
;     static __device__ __forceinline__ void updP(float (&P)[64], const In1& in, float sa) {
;         float u0, u1, u2, u3;
;         asm volatile("v_mul_f32_dpp %0, %8, %4 row_newbcast:%17" DPPM "v_mul_f32_dpp %1, %9, %5 row_newbcast:%17" DPPM "v_mul_f32_dpp %2, %10, %6 row_newbcast:%17" DPPM "v_mul_f32_dpp %3, %11, %7 row_newbcast:%17" DPPM
;                      "v_fmac_f32_dpp %0, %12, %16 row_newbcast:%17" DPPM "v_fmac_f32_dpp %1, %13, %16 row_newbcast:%17" DPPM "v_fmac_f32_dpp %2, %14, %16 row_newbcast:%17" DPPM "v_fmac_f32_dpp %3, %15, %16 row_newbcast:%17" DPPM
;                      : "=&v"(u0), "=&v"(u1), "=&v"(u2), "=&v"(u3)
;                      : "v"(P[K]), "v"(P[K + 1]), "v"(P[K + 2]), "v"(P[K + 3]), "v"(in.w[0]), "v"(in.w[1]), "v"(in.w[2]), "v"(in.w[3]), "v"(in.b[0]), "v"(in.b[1]), "v"(in.b[2]), "v"(in.b[3]), "v"(sa), "n"(N0));
;         P[K] = u0; P[K + 1] = u1; P[K + 2] = u2; P[K + 3] = u3;
;         if constexpr (K + 4 < 64) ScanK<K + 4>::updP(P, in, sa);
	s_nop 1
	v_mfma_f32_4x4x1_16b_f32 v[0:3], v128, v232, v[0:3]
	v_mfma_f32_4x4x1_16b_f32 v[4:7], v129, v232, v[4:7]
	v_mfma_f32_4x4x1_16b_f32 v[8:11], v130, v232, v[8:11]
	v_mfma_f32_4x4x1_16b_f32 v[12:15], v131, v232, v[12:15]
	v_mfma_f32_4x4x1_16b_f32 v[16:19], v132, v232, v[16:19]
	v_mfma_f32_4x4x1_16b_f32 v[20:23], v133, v232, v[20:23]
	v_mfma_f32_4x4x1_16b_f32 v[24:27], v134, v232, v[24:27]
	v_mfma_f32_4x4x1_16b_f32 v[28:31], v135, v232, v[28:31]
	v_mfma_f32_4x4x1_16b_f32 v[32:35], v136, v232, v[32:35]
	v_mfma_f32_4x4x1_16b_f32 v[36:39], v137, v232, v[36:39]
	v_mfma_f32_4x4x1_16b_f32 v[40:43], v138, v232, v[40:43]
	v_mfma_f32_4x4x1_16b_f32 v[44:47], v139, v232, v[44:47]
	v_mfma_f32_4x4x1_16b_f32 v[48:51], v140, v232, v[48:51]
	v_mfma_f32_4x4x1_16b_f32 v[52:55], v141, v232, v[52:55]
	v_mfma_f32_4x4x1_16b_f32 v[56:59], v142, v232, v[56:59]
	v_mfma_f32_4x4x1_16b_f32 v[60:63], v143, v232, v[60:63]
	v_mfma_f32_4x4x1_16b_f32 v[0:3], v144, v234, v[0:3]
	v_mfma_f32_4x4x1_16b_f32 v[4:7], v145, v234, v[4:7]
	v_mfma_f32_4x4x1_16b_f32 v[8:11], v146, v234, v[8:11]
	v_mfma_f32_4x4x1_16b_f32 v[12:15], v147, v234, v[12:15]
	v_mfma_f32_4x4x1_16b_f32 v[16:19], v148, v234, v[16:19]
	v_mfma_f32_4x4x1_16b_f32 v[20:23], v149, v234, v[20:23]
	v_mfma_f32_4x4x1_16b_f32 v[24:27], v150, v234, v[24:27]
	v_mfma_f32_4x4x1_16b_f32 v[28:31], v151, v234, v[28:31]
	v_mfma_f32_4x4x1_16b_f32 v[32:35], v152, v234, v[32:35]
	v_mfma_f32_4x4x1_16b_f32 v[36:39], v153, v234, v[36:39]
	v_mfma_f32_4x4x1_16b_f32 v[40:43], v154, v234, v[40:43]
	v_mfma_f32_4x4x1_16b_f32 v[44:47], v155, v234, v[44:47]
	v_mfma_f32_4x4x1_16b_f32 v[48:51], v156, v234, v[48:51]
	v_mfma_f32_4x4x1_16b_f32 v[52:55], v157, v234, v[52:55]
	v_mfma_f32_4x4x1_16b_f32 v[56:59], v158, v234, v[56:59]
	v_mfma_f32_4x4x1_16b_f32 v[60:63], v159, v234, v[60:63]
	v_mfma_f32_4x4x1_16b_f32 v[64:67], v128, v233, v[64:67]
	v_mfma_f32_4x4x1_16b_f32 v[68:71], v129, v233, v[68:71]
	v_mfma_f32_4x4x1_16b_f32 v[72:75], v130, v233, v[72:75]
	v_mfma_f32_4x4x1_16b_f32 v[76:79], v131, v233, v[76:79]
	v_mfma_f32_4x4x1_16b_f32 v[80:83], v132, v233, v[80:83]
	v_mfma_f32_4x4x1_16b_f32 v[84:87], v133, v233, v[84:87]
	v_mfma_f32_4x4x1_16b_f32 v[88:91], v134, v233, v[88:91]
	v_mfma_f32_4x4x1_16b_f32 v[92:95], v135, v233, v[92:95]
	v_mfma_f32_4x4x1_16b_f32 v[96:99], v136, v233, v[96:99]
	v_mfma_f32_4x4x1_16b_f32 v[100:103], v137, v233, v[100:103]
	v_mfma_f32_4x4x1_16b_f32 v[104:107], v138, v233, v[104:107]
	v_mfma_f32_4x4x1_16b_f32 v[108:111], v139, v233, v[108:111]
	v_mfma_f32_4x4x1_16b_f32 v[112:115], v140, v233, v[112:115]
	v_mfma_f32_4x4x1_16b_f32 v[116:119], v141, v233, v[116:119]
	v_mfma_f32_4x4x1_16b_f32 v[120:123], v142, v233, v[120:123]
	v_mfma_f32_4x4x1_16b_f32 v[124:127], v143, v233, v[124:127]
	s_waitcnt vmcnt(5)
	buffer_load_dwordx4 v[176:179], v235, s[64:67], s72 offen
	buffer_load_dwordx4 v[180:183], v250, s[64:67], s72 offen
	buffer_load_dwordx4 v[184:187], v251, s[64:67], s72 offen
	buffer_load_dwordx2 v[188:189], v252, s[64:67], s76 offen
	buffer_load_ushort v190, v253, s[64:67], s76 offen
	s_add_u32 s72, s72, 0x1000
	s_add_u32 s76, s76, 0x800
	v_pk_mul_f32 v[244:245], v[196:197], v[236:237]
	v_pk_mul_f32 v[246:247], v[198:199], v[238:239]
	v_pk_mul_f32 v[236:237], v[236:237], v[192:193]
	v_pk_mul_f32 v[238:239], v[238:239], v[194:195]
	v_pk_fma_f32 v[228:229], v[200:201], v[216:217], v[220:221]
	v_pk_fma_f32 v[230:231], v[202:203], v[218:219], v[222:223]
	v_pk_mul_f32 v[208:209], v[196:197], v[200:201]
	v_pk_mul_f32 v[210:211], v[198:199], v[202:203]
	v_rcp_f32_e32 v240, v236
	v_rcp_f32_e32 v241, v237
	v_rcp_f32_e32 v242, v238
	v_rcp_f32_e32 v243, v239
	v_lshlrev_b32_e32 v212, 16, v204
	v_and_b32_e32 v213, 0xffff0000, v204
	v_lshlrev_b32_e32 v214, 16, v205
	v_and_b32_e32 v215, 0xffff0000, v205
	v_pk_mul_f32 v[212:213], v[212:213], v[228:229]
	v_pk_mul_f32 v[214:215], v[214:215], v[230:231]
	v_lshlrev_b32_e32 v234, 16, v206
	v_pk_mul_f32 v[208:209], v[208:209], v[240:241]
	v_pk_mul_f32 v[210:211], v[210:211], v[242:243]
	v_pk_mul_f32 v[212:213], v[212:213], v[240:241]
	v_pk_mul_f32 v[214:215], v[214:215], v[242:243]
	ds_write2_b32 v248, v208, v209 offset0:0 offset1:16
	ds_write2_b32 v248, v210, v211 offset0:32 offset1:48
	ds_write2_b32 v248, v212, v213 offset0:64 offset1:80
	ds_write2_b32 v248, v214, v215 offset0:96 offset1:112
	ds_read_b128 v[128:131], v249 offset:0
	ds_read_b128 v[132:135], v249 offset:16
	ds_read_b128 v[136:139], v249 offset:32
	ds_read_b128 v[140:143], v249 offset:48
	ds_read_b128 v[144:147], v249 offset:256
	ds_read_b128 v[148:151], v249 offset:272
	ds_read_b128 v[152:155], v249 offset:288
	ds_read_b128 v[156:159], v249 offset:304
	v_mul_f32_dpp v224, v244, v0 row_newbcast:0 row_mask:0xf bank_mask:0xf
	v_mul_f32_dpp v225, v245, v1 row_newbcast:0 row_mask:0xf bank_mask:0xf
	v_mul_f32_dpp v226, v246, v2 row_newbcast:0 row_mask:0xf bank_mask:0xf
	v_mul_f32_dpp v227, v247, v3 row_newbcast:0 row_mask:0xf bank_mask:0xf
	v_fmac_f32_dpp v224, v244, v4 row_newbcast:1 row_mask:0xf bank_mask:0xf
	v_fmac_f32_dpp v225, v245, v5 row_newbcast:1 row_mask:0xf bank_mask:0xf
	v_fmac_f32_dpp v226, v246, v6 row_newbcast:1 row_mask:0xf bank_mask:0xf
	v_fmac_f32_dpp v227, v247, v7 row_newbcast:1 row_mask:0xf bank_mask:0xf
	v_fmac_f32_dpp v224, v244, v8 row_newbcast:2 row_mask:0xf bank_mask:0xf
	v_fmac_f32_dpp v225, v245, v9 row_newbcast:2 row_mask:0xf bank_mask:0xf
	v_fmac_f32_dpp v226, v246, v10 row_newbcast:2 row_mask:0xf bank_mask:0xf
	v_fmac_f32_dpp v227, v247, v11 row_newbcast:2 row_mask:0xf bank_mask:0xf
	v_fmac_f32_dpp v224, v244, v12 row_newbcast:3 row_mask:0xf bank_mask:0xf
;     static __device__ __forceinline__ void dot(const float (&S)[64], const f32x4& a, float (&s)[4]) {
;         if constexpr (K == 0) {
;             asm volatile("v_mul_f32_dpp %0, %4, %8 row_newbcast:%16" DPPM "v_mul_f32_dpp %1, %5, %9 row_newbcast:%16" DPPM "v_mul_f32_dpp %2, %6, %10 row_newbcast:%16" DPPM "v_mul_f32_dpp %3, %7, %11 row_newbcast:%16" DPPM
;                          "v_fmac_f32_dpp %0, %4, %12 row_newbcast:%17" DPPM "v_fmac_f32_dpp %1, %5, %13 row_newbcast:%17" DPPM "v_fmac_f32_dpp %2, %6, %14 row_newbcast:%17" DPPM "v_fmac_f32_dpp %3, %7, %15 row_newbcast:%17" DPPM
;                          : "=&v"(s[0]), "=&v"(s[1]), "=&v"(s[2]), "=&v"(s[3])
;                          : "v"(a[0]), "v"(a[1]), "v"(a[2]), "v"(a[3]), "v"(S[K]), "v"(S[K + 1]), "v"(S[K + 2]), "v"(S[K + 3]), "v"(S[K + 4]), "v"(S[K + 5]), "v"(S[K + 6]), "v"(S[K + 7]), "n"(N0), "n"(N1));
;         } else
;         asm volatile("v_fmac_f32_dpp %0, %4, %8 row_newbcast:%16" DPPM "v_fmac_f32_dpp %1, %5, %9 row_newbcast:%16" DPPM "v_fmac_f32_dpp %2, %6, %10 row_newbcast:%16" DPPM "v_fmac_f32_dpp %3, %7, %11 row_newbcast:%16" DPPM
;                      "v_fmac_f32_dpp %0, %4, %12 row_newbcast:%17" DPPM "v_fmac_f32_dpp %1, %5, %13 row_newbcast:%17" DPPM "v_fmac_f32_dpp %2, %6, %14 row_newbcast:%17" DPPM "v_fmac_f32_dpp %3, %7, %15 row_newbcast:%17" DPPM
;                      : "+v"(s[0]), "+v"(s[1]), "+v"(s[2]), "+v"(s[3])
;                      : "v"(a[0]), "v"(a[1]), "v"(a[2]), "v"(a[3]), "v"(S[K]), "v"(S[K + 1]), "v"(S[K + 2]), "v"(S[K + 3]), "v"(S[K + 4]), "v"(S[K + 5]), "v"(S[K + 6]), "v"(S[K + 7]), "n"(N0), "n"(N1));
;         if constexpr (K + 8 < 64) ScanK<K + 8>::dot(S, a, s);
;     }
	v_fmac_f32_dpp v225, v245, v13 row_newbcast:3 row_mask:0xf bank_mask:0xf
	v_fmac_f32_dpp v226, v246, v14 row_newbcast:3 row_mask:0xf bank_mask:0xf
	v_fmac_f32_dpp v227, v247, v15 row_newbcast:3 row_mask:0xf bank_mask:0xf
	v_fmac_f32_dpp v224, v244, v16 row_newbcast:4 row_mask:0xf bank_mask:0xf
	v_fmac_f32_dpp v225, v245, v17 row_newbcast:4 row_mask:0xf bank_mask:0xf
	v_fmac_f32_dpp v226, v246, v18 row_newbcast:4 row_mask:0xf bank_mask:0xf
	v_fmac_f32_dpp v227, v247, v19 row_newbcast:4 row_mask:0xf bank_mask:0xf
	v_fmac_f32_dpp v224, v244, v20 row_newbcast:5 row_mask:0xf bank_mask:0xf
	v_fmac_f32_dpp v225, v245, v21 row_newbcast:5 row_mask:0xf bank_mask:0xf
	v_fmac_f32_dpp v226, v246, v22 row_newbcast:5 row_mask:0xf bank_mask:0xf
	v_fmac_f32_dpp v227, v247, v23 row_newbcast:5 row_mask:0xf bank_mask:0xf
	v_fmac_f32_dpp v224, v244, v24 row_newbcast:6 row_mask:0xf bank_mask:0xf
	v_fmac_f32_dpp v225, v245, v25 row_newbcast:6 row_mask:0xf bank_mask:0xf
	v_fmac_f32_dpp v226, v246, v26 row_newbcast:6 row_mask:0xf bank_mask:0xf
	v_fmac_f32_dpp v227, v247, v27 row_newbcast:6 row_mask:0xf bank_mask:0xf
	v_fmac_f32_dpp v224, v244, v28 row_newbcast:7 row_mask:0xf bank_mask:0xf
	v_fmac_f32_dpp v225, v245, v29 row_newbcast:7 row_mask:0xf bank_mask:0xf
	v_fmac_f32_dpp v226, v246, v30 row_newbcast:7 row_mask:0xf bank_mask:0xf
	v_fmac_f32_dpp v227, v247, v31 row_newbcast:7 row_mask:0xf bank_mask:0xf
	v_fmac_f32_dpp v224, v244, v32 row_newbcast:8 row_mask:0xf bank_mask:0xf
	v_fmac_f32_dpp v225, v245, v33 row_newbcast:8 row_mask:0xf bank_mask:0xf
	v_fmac_f32_dpp v226, v246, v34 row_newbcast:8 row_mask:0xf bank_mask:0xf
	v_fmac_f32_dpp v227, v247, v35 row_newbcast:8 row_mask:0xf bank_mask:0xf
	v_fmac_f32_dpp v224, v244, v36 row_newbcast:9 row_mask:0xf bank_mask:0xf
	v_fmac_f32_dpp v225, v245, v37 row_newbcast:9 row_mask:0xf bank_mask:0xf
	v_fmac_f32_dpp v226, v246, v38 row_newbcast:9 row_mask:0xf bank_mask:0xf
	v_fmac_f32_dpp v227, v247, v39 row_newbcast:9 row_mask:0xf bank_mask:0xf
	v_fmac_f32_dpp v224, v244, v40 row_newbcast:10 row_mask:0xf bank_mask:0xf
	v_fmac_f32_dpp v225, v245, v41 row_newbcast:10 row_mask:0xf bank_mask:0xf
	v_fmac_f32_dpp v226, v246, v42 row_newbcast:10 row_mask:0xf bank_mask:0xf
	v_fmac_f32_dpp v227, v247, v43 row_newbcast:10 row_mask:0xf bank_mask:0xf
	v_fmac_f32_dpp v224, v244, v44 row_newbcast:11 row_mask:0xf bank_mask:0xf
	v_fmac_f32_dpp v225, v245, v45 row_newbcast:11 row_mask:0xf bank_mask:0xf
	v_fmac_f32_dpp v226, v246, v46 row_newbcast:11 row_mask:0xf bank_mask:0xf
	v_fmac_f32_dpp v227, v247, v47 row_newbcast:11 row_mask:0xf bank_mask:0xf
	v_fmac_f32_dpp v224, v244, v48 row_newbcast:12 row_mask:0xf bank_mask:0xf
	v_fmac_f32_dpp v225, v245, v49 row_newbcast:12 row_mask:0xf bank_mask:0xf
	v_fmac_f32_dpp v226, v246, v50 row_newbcast:12 row_mask:0xf bank_mask:0xf
	v_fmac_f32_dpp v227, v247, v51 row_newbcast:12 row_mask:0xf bank_mask:0xf
	v_fmac_f32_dpp v224, v244, v52 row_newbcast:13 row_mask:0xf bank_mask:0xf
	v_fmac_f32_dpp v225, v245, v53 row_newbcast:13 row_mask:0xf bank_mask:0xf
	v_fmac_f32_dpp v226, v246, v54 row_newbcast:13 row_mask:0xf bank_mask:0xf
	v_fmac_f32_dpp v227, v247, v55 row_newbcast:13 row_mask:0xf bank_mask:0xf
	v_fmac_f32_dpp v224, v244, v56 row_newbcast:14 row_mask:0xf bank_mask:0xf
	v_fmac_f32_dpp v225, v245, v57 row_newbcast:14 row_mask:0xf bank_mask:0xf
	v_fmac_f32_dpp v226, v246, v58 row_newbcast:14 row_mask:0xf bank_mask:0xf
	v_fmac_f32_dpp v227, v247, v59 row_newbcast:14 row_mask:0xf bank_mask:0xf
	v_fmac_f32_dpp v224, v244, v60 row_newbcast:15 row_mask:0xf bank_mask:0xf
	v_fmac_f32_dpp v225, v245, v61 row_newbcast:15 row_mask:0xf bank_mask:0xf
	v_fmac_f32_dpp v226, v246, v62 row_newbcast:15 row_mask:0xf bank_mask:0xf
	v_fmac_f32_dpp v227, v247, v63 row_newbcast:15 row_mask:0xf bank_mask:0xf
	v_mul_f32_dpp v228, v244, v64 row_newbcast:0 row_mask:0xf bank_mask:0xf
	v_mul_f32_dpp v229, v245, v65 row_newbcast:0 row_mask:0xf bank_mask:0xf
	v_mul_f32_dpp v230, v246, v66 row_newbcast:0 row_mask:0xf bank_mask:0xf
	v_mul_f32_dpp v231, v247, v67 row_newbcast:0 row_mask:0xf bank_mask:0xf
	v_fmac_f32_dpp v228, v244, v68 row_newbcast:1 row_mask:0xf bank_mask:0xf
	v_fmac_f32_dpp v229, v245, v69 row_newbcast:1 row_mask:0xf bank_mask:0xf
	v_fmac_f32_dpp v230, v246, v70 row_newbcast:1 row_mask:0xf bank_mask:0xf
	v_fmac_f32_dpp v231, v247, v71 row_newbcast:1 row_mask:0xf bank_mask:0xf
	v_fmac_f32_dpp v228, v244, v72 row_newbcast:2 row_mask:0xf bank_mask:0xf
	v_fmac_f32_dpp v229, v245, v73 row_newbcast:2 row_mask:0xf bank_mask:0xf
	v_fmac_f32_dpp v230, v246, v74 row_newbcast:2 row_mask:0xf bank_mask:0xf
	v_fmac_f32_dpp v231, v247, v75 row_newbcast:2 row_mask:0xf bank_mask:0xf
	v_fmac_f32_dpp v228, v244, v76 row_newbcast:3 row_mask:0xf bank_mask:0xf
	v_fmac_f32_dpp v229, v245, v77 row_newbcast:3 row_mask:0xf bank_mask:0xf
	v_fmac_f32_dpp v230, v246, v78 row_newbcast:3 row_mask:0xf bank_mask:0xf
	v_fmac_f32_dpp v231, v247, v79 row_newbcast:3 row_mask:0xf bank_mask:0xf
	v_fmac_f32_dpp v228, v244, v80 row_newbcast:4 row_mask:0xf bank_mask:0xf
	v_fmac_f32_dpp v229, v245, v81 row_newbcast:4 row_mask:0xf bank_mask:0xf
	v_fmac_f32_dpp v230, v246, v82 row_newbcast:4 row_mask:0xf bank_mask:0xf
	v_fmac_f32_dpp v231, v247, v83 row_newbcast:4 row_mask:0xf bank_mask:0xf
	v_fmac_f32_dpp v228, v244, v84 row_newbcast:5 row_mask:0xf bank_mask:0xf
	v_fmac_f32_dpp v229, v245, v85 row_newbcast:5 row_mask:0xf bank_mask:0xf
	v_fmac_f32_dpp v230, v246, v86 row_newbcast:5 row_mask:0xf bank_mask:0xf
	v_fmac_f32_dpp v231, v247, v87 row_newbcast:5 row_mask:0xf bank_mask:0xf
	v_fmac_f32_dpp v228, v244, v88 row_newbcast:6 row_mask:0xf bank_mask:0xf
;     static __device__ __forceinline__ void updS(float (&S)[64], const In1& in, float sa, float vv) {
;         float t0, t1, t2, t3;
;         asm volatile("v_mul_f32_dpp %0, %8, %21 row_newbcast:%22" DPPM "v_mul_f32_dpp %1, %9, %21 row_newbcast:%22" DPPM "v_mul_f32_dpp %2, %10, %21 row_newbcast:%22" DPPM "v_mul_f32_dpp %3, %11, %21 row_newbcast:%22" DPPM
;                      "v_fmac_f32_dpp %0, %12, %4 row_newbcast:%22" DPPM "v_fmac_f32_dpp %1, %13, %5 row_newbcast:%22" DPPM "v_fmac_f32_dpp %2, %14, %6 row_newbcast:%22" DPPM "v_fmac_f32_dpp %3, %15, %7 row_newbcast:%22" DPPM
;                      "v_fmac_f32_dpp %0, %16, %20 row_newbcast:%22" DPPM "v_fmac_f32_dpp %1, %17, %20 row_newbcast:%22" DPPM "v_fmac_f32_dpp %2, %18, %20 row_newbcast:%22" DPPM "v_fmac_f32_dpp %3, %19, %20 row_newbcast:%22" DPPM
;                      : "=&v"(t0), "=&v"(t1), "=&v"(t2), "=&v"(t3)
;                      : "v"(S[K]), "v"(S[K + 1]), "v"(S[K + 2]), "v"(S[K + 3]), "v"(in.kd[0]), "v"(in.kd[1]), "v"(in.kd[2]), "v"(in.kd[3]), "v"(in.w[0]), "v"(in.w[1]), "v"(in.w[2]), "v"(in.w[3]),
;                        "v"(in.b[0]), "v"(in.b[1]), "v"(in.b[2]), "v"(in.b[3]), "v"(sa), "v"(vv), "n"(N0));
;         S[K] = t0; S[K + 1] = t1; S[K + 2] = t2; S[K + 3] = t3;
;         if constexpr (K + 4 < 64) ScanK<K + 4>::updS(S, in, sa, vv);
;     }
;     static __device__ __forceinline__ void updP(float (&P)[64], const In1& in, float sa) {
;         float u0, u1, u2, u3;
;         asm volatile("v_mul_f32_dpp %0, %8, %4 row_newbcast:%17" DPPM "v_mul_f32_dpp %1, %9, %5 row_newbcast:%17" DPPM "v_mul_f32_dpp %2, %10, %6 row_newbcast:%17" DPPM "v_mul_f32_dpp %3, %11, %7 row_newbcast:%17" DPPM
;                      "v_fmac_f32_dpp %0, %12, %16 row_newbcast:%17" DPPM "v_fmac_f32_dpp %1, %13, %16 row_newbcast:%17" DPPM "v_fmac_f32_dpp %2, %14, %16 row_newbcast:%17" DPPM "v_fmac_f32_dpp %3, %15, %16 row_newbcast:%17" DPPM
;                      : "=&v"(u0), "=&v"(u1), "=&v"(u2), "=&v"(u3)
;                      : "v"(P[K]), "v"(P[K + 1]), "v"(P[K + 2]), "v"(P[K + 3]), "v"(in.w[0]), "v"(in.w[1]), "v"(in.w[2]), "v"(in.w[3]), "v"(in.b[0]), "v"(in.b[1]), "v"(in.b[2]), "v"(in.b[3]), "v"(sa), "n"(N0));
;         P[K] = u0; P[K + 1] = u1; P[K + 2] = u2; P[K + 3] = u3;
;         if constexpr (K + 4 < 64) ScanK<K + 4>::updP(P, in, sa);
	v_fmac_f32_dpp v229, v245, v89 row_newbcast:6 row_mask:0xf bank_mask:0xf
	v_fmac_f32_dpp v230, v246, v90 row_newbcast:6 row_mask:0xf bank_mask:0xf
	v_fmac_f32_dpp v231, v247, v91 row_newbcast:6 row_mask:0xf bank_mask:0xf
	v_fmac_f32_dpp v228, v244, v92 row_newbcast:7 row_mask:0xf bank_mask:0xf
	v_fmac_f32_dpp v229, v245, v93 row_newbcast:7 row_mask:0xf bank_mask:0xf
	v_fmac_f32_dpp v230, v246, v94 row_newbcast:7 row_mask:0xf bank_mask:0xf
	v_fmac_f32_dpp v231, v247, v95 row_newbcast:7 row_mask:0xf bank_mask:0xf
	v_fmac_f32_dpp v228, v244, v96 row_newbcast:8 row_mask:0xf bank_mask:0xf
	v_fmac_f32_dpp v229, v245, v97 row_newbcast:8 row_mask:0xf bank_mask:0xf
	v_fmac_f32_dpp v230, v246, v98 row_newbcast:8 row_mask:0xf bank_mask:0xf
	v_fmac_f32_dpp v231, v247, v99 row_newbcast:8 row_mask:0xf bank_mask:0xf
	v_fmac_f32_dpp v228, v244, v100 row_newbcast:9 row_mask:0xf bank_mask:0xf
	v_fmac_f32_dpp v229, v245, v101 row_newbcast:9 row_mask:0xf bank_mask:0xf
	v_fmac_f32_dpp v230, v246, v102 row_newbcast:9 row_mask:0xf bank_mask:0xf
	v_fmac_f32_dpp v231, v247, v103 row_newbcast:9 row_mask:0xf bank_mask:0xf
	v_fmac_f32_dpp v228, v244, v104 row_newbcast:10 row_mask:0xf bank_mask:0xf
	v_fmac_f32_dpp v229, v245, v105 row_newbcast:10 row_mask:0xf bank_mask:0xf
	v_fmac_f32_dpp v230, v246, v106 row_newbcast:10 row_mask:0xf bank_mask:0xf
	v_fmac_f32_dpp v231, v247, v107 row_newbcast:10 row_mask:0xf bank_mask:0xf
	v_fmac_f32_dpp v228, v244, v108 row_newbcast:11 row_mask:0xf bank_mask:0xf
	v_fmac_f32_dpp v229, v245, v109 row_newbcast:11 row_mask:0xf bank_mask:0xf
	v_fmac_f32_dpp v230, v246, v110 row_newbcast:11 row_mask:0xf bank_mask:0xf
	v_fmac_f32_dpp v231, v247, v111 row_newbcast:11 row_mask:0xf bank_mask:0xf
	v_fmac_f32_dpp v228, v244, v112 row_newbcast:12 row_mask:0xf bank_mask:0xf
	v_fmac_f32_dpp v229, v245, v113 row_newbcast:12 row_mask:0xf bank_mask:0xf
	v_fmac_f32_dpp v230, v246, v114 row_newbcast:12 row_mask:0xf bank_mask:0xf
	v_fmac_f32_dpp v231, v247, v115 row_newbcast:12 row_mask:0xf bank_mask:0xf
	v_fmac_f32_dpp v228, v244, v116 row_newbcast:13 row_mask:0xf bank_mask:0xf
	v_fmac_f32_dpp v229, v245, v117 row_newbcast:13 row_mask:0xf bank_mask:0xf
	v_fmac_f32_dpp v230, v246, v118 row_newbcast:13 row_mask:0xf bank_mask:0xf
	v_fmac_f32_dpp v231, v247, v119 row_newbcast:13 row_mask:0xf bank_mask:0xf
	v_fmac_f32_dpp v228, v244, v120 row_newbcast:14 row_mask:0xf bank_mask:0xf
	v_fmac_f32_dpp v229, v245, v121 row_newbcast:14 row_mask:0xf bank_mask:0xf
	v_fmac_f32_dpp v230, v246, v122 row_newbcast:14 row_mask:0xf bank_mask:0xf
	v_fmac_f32_dpp v231, v247, v123 row_newbcast:14 row_mask:0xf bank_mask:0xf
	v_fmac_f32_dpp v228, v244, v124 row_newbcast:15 row_mask:0xf bank_mask:0xf
	v_fmac_f32_dpp v229, v245, v125 row_newbcast:15 row_mask:0xf bank_mask:0xf
	v_fmac_f32_dpp v230, v246, v126 row_newbcast:15 row_mask:0xf bank_mask:0xf
	v_fmac_f32_dpp v231, v247, v127 row_newbcast:15 row_mask:0xf bank_mask:0xf
	v_add_f32_e32 v224, v224, v225
	v_add_f32_e32 v226, v226, v227
	v_sub_f32_e64 v232, -v224, v226
	v_add_f32_e32 v228, v228, v229
	v_add_f32_e32 v230, v230, v231
	v_sub_f32_e64 v233, -v228, v230
	s_waitcnt lgkmcnt(0)
	s_nop 1
	v_mfma_f32_4x4x1_16b_f32 v[0:3], v128, v232, v[0:3]
	v_mfma_f32_4x4x1_16b_f32 v[4:7], v129, v232, v[4:7]
	v_mfma_f32_4x4x1_16b_f32 v[8:11], v130, v232, v[8:11]
	v_mfma_f32_4x4x1_16b_f32 v[12:15], v131, v232, v[12:15]
	v_mfma_f32_4x4x1_16b_f32 v[16:19], v132, v232, v[16:19]
	v_mfma_f32_4x4x1_16b_f32 v[20:23], v133, v232, v[20:23]
	v_mfma_f32_4x4x1_16b_f32 v[24:27], v134, v232, v[24:27]
	v_mfma_f32_4x4x1_16b_f32 v[28:31], v135, v232, v[28:31]
	v_mfma_f32_4x4x1_16b_f32 v[32:35], v136, v232, v[32:35]
	v_mfma_f32_4x4x1_16b_f32 v[36:39], v137, v232, v[36:39]
	v_mfma_f32_4x4x1_16b_f32 v[40:43], v138, v232, v[40:43]
	v_mfma_f32_4x4x1_16b_f32 v[44:47], v139, v232, v[44:47]
	v_mfma_f32_4x4x1_16b_f32 v[48:51], v140, v232, v[48:51]
	v_mfma_f32_4x4x1_16b_f32 v[52:55], v141, v232, v[52:55]
	v_mfma_f32_4x4x1_16b_f32 v[56:59], v142, v232, v[56:59]
	v_mfma_f32_4x4x1_16b_f32 v[60:63], v143, v232, v[60:63]
	v_mfma_f32_4x4x1_16b_f32 v[0:3], v144, v234, v[0:3]
	v_mfma_f32_4x4x1_16b_f32 v[4:7], v145, v234, v[4:7]
	v_mfma_f32_4x4x1_16b_f32 v[8:11], v146, v234, v[8:11]
	v_mfma_f32_4x4x1_16b_f32 v[12:15], v147, v234, v[12:15]
	v_mfma_f32_4x4x1_16b_f32 v[16:19], v148, v234, v[16:19]
	v_mfma_f32_4x4x1_16b_f32 v[20:23], v149, v234, v[20:23]
	v_mfma_f32_4x4x1_16b_f32 v[24:27], v150, v234, v[24:27]
	v_mfma_f32_4x4x1_16b_f32 v[28:31], v151, v234, v[28:31]
	v_mfma_f32_4x4x1_16b_f32 v[32:35], v152, v234, v[32:35]
	v_mfma_f32_4x4x1_16b_f32 v[36:39], v153, v234, v[36:39]
	v_mfma_f32_4x4x1_16b_f32 v[40:43], v154, v234, v[40:43]
	v_mfma_f32_4x4x1_16b_f32 v[44:47], v155, v234, v[44:47]
	v_mfma_f32_4x4x1_16b_f32 v[48:51], v156, v234, v[48:51]
	v_mfma_f32_4x4x1_16b_f32 v[52:55], v157, v234, v[52:55]
	v_mfma_f32_4x4x1_16b_f32 v[56:59], v158, v234, v[56:59]
	v_mfma_f32_4x4x1_16b_f32 v[60:63], v159, v234, v[60:63]
	v_mfma_f32_4x4x1_16b_f32 v[64:67], v128, v233, v[64:67]
	v_mfma_f32_4x4x1_16b_f32 v[68:71], v129, v233, v[68:71]
	v_mfma_f32_4x4x1_16b_f32 v[72:75], v130, v233, v[72:75]
	v_mfma_f32_4x4x1_16b_f32 v[76:79], v131, v233, v[76:79]
	v_mfma_f32_4x4x1_16b_f32 v[80:83], v132, v233, v[80:83]
	v_mfma_f32_4x4x1_16b_f32 v[84:87], v133, v233, v[84:87]
	v_mfma_f32_4x4x1_16b_f32 v[88:91], v134, v233, v[88:91]
	v_mfma_f32_4x4x1_16b_f32 v[92:95], v135, v233, v[92:95]
	v_mfma_f32_4x4x1_16b_f32 v[96:99], v136, v233, v[96:99]
	v_mfma_f32_4x4x1_16b_f32 v[100:103], v137, v233, v[100:103]
	v_mfma_f32_4x4x1_16b_f32 v[104:107], v138, v233, v[104:107]
	v_mfma_f32_4x4x1_16b_f32 v[108:111], v139, v233, v[108:111]
	v_mfma_f32_4x4x1_16b_f32 v[112:115], v140, v233, v[112:115]
	v_mfma_f32_4x4x1_16b_f32 v[116:119], v141, v233, v[116:119]
	v_mfma_f32_4x4x1_16b_f32 v[120:123], v142, v233, v[120:123]
	v_mfma_f32_4x4x1_16b_f32 v[124:127], v143, v233, v[124:127]
	s_sub_u32 s83, s83, 1
	s_cmp_eq_u32 s83, 0
	s_cbranch_scc1 .Lmy_p1d0_ldone
	s_sub_u32 s9, s9, 1
	s_cmp_eq_u32 s9, 0
	s_cbranch_scc1 .Lmy_p1d0_renorm
	s_branch .Lmy_p1d0_loop
; #define SB __builtin_amdgcn_sched_barrier(0)
; #define LD1(set, s) { const int e_ = min((int)(s), LC - 1) * (int)stp; const unsigned s4_ = ob4 + (unsigned)(e_ * 4), s2_ = ob2 + (unsigned)(e_ * 2); set.w = LDX(rW, s4_); set.a = LDX(rA, s4_); set.b = LDX(rB, s4_); \
;             set.kw = __builtin_amdgcn_raw_buffer_load_b64(rK, lo8, s2_, 0); set.v = __builtin_amdgcn_raw_buffer_load_b16(rV, lo2, s2_, 0); }
; #define TOUCH1(set) asm volatile("" :: "v"(set.w), "v"(set.a), "v"(set.b), "v"(set.kw), "v"(set.v))
; #define ST1(set) { DERIVE_BK(set); float sd[4]; ScanK<0>::dot(S, set.a, sd); ScanK<0>::updS(S, set, -((sd[0] + sd[1]) + (sd[2] + sd[3])), __uint_as_float(set.v << 16)); }
; #define LD1(set, s) { const int e_ = min((int)(s), LC - 1) * (int)stp; const unsigned s4_ = ob4 + (unsigned)(e_ * 4); set.w = LDX(rW, s4_); set.a = LDX(rA, s4_); set.b = LDX(rB, s4_); }
; #define TOUCH1(set) asm volatile("" :: "v"(set.w), "v"(set.a), "v"(set.b))
; #define ST1(set) { DERIVE_B(set); float sd[4]; ScanK<0>::dot(S, set.a, sd); ScanK<0>::updP(S, set, -((sd[0] + sd[1]) + (sd[2] + sd[3]))); }
; template <bool MIX> __device__ __forceinline__ void scan_pass1(const Params& p, int d, float* ldsf) {
;     ...
;             In1 i0, i1; LD1(i0, 0);
; #pragma unroll 1
;             for (int s = 0; s < LC; s += 2) { TOUCH1(i0); SB; LD1(i1, s + 1); SB; ST1(i0); TOUCH1(i1); SB; LD1(i0, s + 2); SB; ST1(i1); }
.Lmy_p1d0_ldone:
	s_waitcnt vmcnt(5)
	buffer_load_dwordx4 v[192:195], v235, s[64:67], s72 offen
	buffer_load_dwordx4 v[196:199], v250, s[64:67], s72 offen
	buffer_load_dwordx4 v[200:203], v251, s[64:67], s72 offen
	buffer_load_dwordx2 v[204:205], v252, s[64:67], s76 offen
	buffer_load_ushort v206, v253, s[64:67], s76 offen
	s_add_u32 s72, s72, 0x1000
	s_add_u32 s76, s76, 0x800
	v_pk_mul_f32 v[244:245], v[164:165], v[236:237]
	v_pk_mul_f32 v[246:247], v[166:167], v[238:239]
	v_pk_mul_f32 v[236:237], v[236:237], v[160:161]
	v_pk_mul_f32 v[238:239], v[238:239], v[162:163]
	v_pk_fma_f32 v[228:229], v[168:169], v[216:217], v[220:221]
	v_pk_fma_f32 v[230:231], v[170:171], v[218:219], v[222:223]
	v_pk_mul_f32 v[208:209], v[164:165], v[168:169]
	v_pk_mul_f32 v[210:211], v[166:167], v[170:171]
	v_rcp_f32_e32 v240, v236
	v_rcp_f32_e32 v241, v237
	v_rcp_f32_e32 v242, v238
	v_rcp_f32_e32 v243, v239
	v_lshlrev_b32_e32 v212, 16, v172
	v_and_b32_e32 v213, 0xffff0000, v172
	v_lshlrev_b32_e32 v214, 16, v173
	v_and_b32_e32 v215, 0xffff0000, v173
	v_pk_mul_f32 v[212:213], v[212:213], v[228:229]
	v_pk_mul_f32 v[214:215], v[214:215], v[230:231]
	v_lshlrev_b32_e32 v234, 16, v174
	v_pk_mul_f32 v[208:209], v[208:209], v[240:241]
	v_pk_mul_f32 v[210:211], v[210:211], v[242:243]
	v_pk_mul_f32 v[212:213], v[212:213], v[240:241]
	v_pk_mul_f32 v[214:215], v[214:215], v[242:243]
	ds_write2_b32 v248, v208, v209 offset0:0 offset1:16
	ds_write2_b32 v248, v210, v211 offset0:32 offset1:48
	ds_write2_b32 v248, v212, v213 offset0:64 offset1:80
	ds_write2_b32 v248, v214, v215 offset0:96 offset1:112
	ds_read_b128 v[128:131], v249 offset:0
	ds_read_b128 v[132:135], v249 offset:16
	ds_read_b128 v[136:139], v249 offset:32
	ds_read_b128 v[140:143], v249 offset:48
	ds_read_b128 v[144:147], v249 offset:256
	ds_read_b128 v[148:151], v249 offset:272
	ds_read_b128 v[152:155], v249 offset:288
	ds_read_b128 v[156:159], v249 offset:304
	v_mul_f32_dpp v224, v244, v0 row_newbcast:0 row_mask:0xf bank_mask:0xf
	v_mul_f32_dpp v225, v245, v1 row_newbcast:0 row_mask:0xf bank_mask:0xf
	v_mul_f32_dpp v226, v246, v2 row_newbcast:0 row_mask:0xf bank_mask:0xf
	v_mul_f32_dpp v227, v247, v3 row_newbcast:0 row_mask:0xf bank_mask:0xf
	v_fmac_f32_dpp v224, v244, v4 row_newbcast:1 row_mask:0xf bank_mask:0xf
	v_fmac_f32_dpp v225, v245, v5 row_newbcast:1 row_mask:0xf bank_mask:0xf
	v_fmac_f32_dpp v226, v246, v6 row_newbcast:1 row_mask:0xf bank_mask:0xf
	v_fmac_f32_dpp v227, v247, v7 row_newbcast:1 row_mask:0xf bank_mask:0xf
	v_fmac_f32_dpp v224, v244, v8 row_newbcast:2 row_mask:0xf bank_mask:0xf
	v_fmac_f32_dpp v225, v245, v9 row_newbcast:2 row_mask:0xf bank_mask:0xf
	v_fmac_f32_dpp v226, v246, v10 row_newbcast:2 row_mask:0xf bank_mask:0xf
	v_fmac_f32_dpp v227, v247, v11 row_newbcast:2 row_mask:0xf bank_mask:0xf
	v_fmac_f32_dpp v224, v244, v12 row_newbcast:3 row_mask:0xf bank_mask:0xf
	v_fmac_f32_dpp v225, v245, v13 row_newbcast:3 row_mask:0xf bank_mask:0xf
	v_fmac_f32_dpp v226, v246, v14 row_newbcast:3 row_mask:0xf bank_mask:0xf
	v_fmac_f32_dpp v227, v247, v15 row_newbcast:3 row_mask:0xf bank_mask:0xf
	v_fmac_f32_dpp v224, v244, v16 row_newbcast:4 row_mask:0xf bank_mask:0xf
	v_fmac_f32_dpp v225, v245, v17 row_newbcast:4 row_mask:0xf bank_mask:0xf
	v_fmac_f32_dpp v226, v246, v18 row_newbcast:4 row_mask:0xf bank_mask:0xf
	v_fmac_f32_dpp v227, v247, v19 row_newbcast:4 row_mask:0xf bank_mask:0xf
	v_fmac_f32_dpp v224, v244, v20 row_newbcast:5 row_mask:0xf bank_mask:0xf
	v_fmac_f32_dpp v225, v245, v21 row_newbcast:5 row_mask:0xf bank_mask:0xf
	v_fmac_f32_dpp v226, v246, v22 row_newbcast:5 row_mask:0xf bank_mask:0xf
	v_fmac_f32_dpp v227, v247, v23 row_newbcast:5 row_mask:0xf bank_mask:0xf
	v_fmac_f32_dpp v224, v244, v24 row_newbcast:6 row_mask:0xf bank_mask:0xf
	v_fmac_f32_dpp v225, v245, v25 row_newbcast:6 row_mask:0xf bank_mask:0xf
	v_fmac_f32_dpp v226, v246, v26 row_newbcast:6 row_mask:0xf bank_mask:0xf
	v_fmac_f32_dpp v227, v247, v27 row_newbcast:6 row_mask:0xf bank_mask:0xf
	v_fmac_f32_dpp v224, v244, v28 row_newbcast:7 row_mask:0xf bank_mask:0xf
	v_fmac_f32_dpp v225, v245, v29 row_newbcast:7 row_mask:0xf bank_mask:0xf
	v_fmac_f32_dpp v226, v246, v30 row_newbcast:7 row_mask:0xf bank_mask:0xf
	v_fmac_f32_dpp v227, v247, v31 row_newbcast:7 row_mask:0xf bank_mask:0xf
	v_fmac_f32_dpp v224, v244, v32 row_newbcast:8 row_mask:0xf bank_mask:0xf
	v_fmac_f32_dpp v225, v245, v33 row_newbcast:8 row_mask:0xf bank_mask:0xf
	v_fmac_f32_dpp v226, v246, v34 row_newbcast:8 row_mask:0xf bank_mask:0xf
	v_fmac_f32_dpp v227, v247, v35 row_newbcast:8 row_mask:0xf bank_mask:0xf
	v_fmac_f32_dpp v224, v244, v36 row_newbcast:9 row_mask:0xf bank_mask:0xf
	v_fmac_f32_dpp v225, v245, v37 row_newbcast:9 row_mask:0xf bank_mask:0xf
	v_fmac_f32_dpp v226, v246, v38 row_newbcast:9 row_mask:0xf bank_mask:0xf
	v_fmac_f32_dpp v227, v247, v39 row_newbcast:9 row_mask:0xf bank_mask:0xf
	v_fmac_f32_dpp v224, v244, v40 row_newbcast:10 row_mask:0xf bank_mask:0xf
	v_fmac_f32_dpp v225, v245, v41 row_newbcast:10 row_mask:0xf bank_mask:0xf
	v_fmac_f32_dpp v226, v246, v42 row_newbcast:10 row_mask:0xf bank_mask:0xf
	v_fmac_f32_dpp v227, v247, v43 row_newbcast:10 row_mask:0xf bank_mask:0xf
	v_fmac_f32_dpp v224, v244, v44 row_newbcast:11 row_mask:0xf bank_mask:0xf
	v_fmac_f32_dpp v225, v245, v45 row_newbcast:11 row_mask:0xf bank_mask:0xf
	v_fmac_f32_dpp v226, v246, v46 row_newbcast:11 row_mask:0xf bank_mask:0xf
	v_fmac_f32_dpp v227, v247, v47 row_newbcast:11 row_mask:0xf bank_mask:0xf
	v_fmac_f32_dpp v224, v244, v48 row_newbcast:12 row_mask:0xf bank_mask:0xf
	v_fmac_f32_dpp v225, v245, v49 row_newbcast:12 row_mask:0xf bank_mask:0xf
;     static __device__ __forceinline__ void dot(const float (&S)[64], const f32x4& a, float (&s)[4]) {
;         if constexpr (K == 0) {
;             asm volatile("v_mul_f32_dpp %0, %4, %8 row_newbcast:%16" DPPM "v_mul_f32_dpp %1, %5, %9 row_newbcast:%16" DPPM "v_mul_f32_dpp %2, %6, %10 row_newbcast:%16" DPPM "v_mul_f32_dpp %3, %7, %11 row_newbcast:%16" DPPM
;                          "v_fmac_f32_dpp %0, %4, %12 row_newbcast:%17" DPPM "v_fmac_f32_dpp %1, %5, %13 row_newbcast:%17" DPPM "v_fmac_f32_dpp %2, %6, %14 row_newbcast:%17" DPPM "v_fmac_f32_dpp %3, %7, %15 row_newbcast:%17" DPPM
;                          : "=&v"(s[0]), "=&v"(s[1]), "=&v"(s[2]), "=&v"(s[3])
;                          : "v"(a[0]), "v"(a[1]), "v"(a[2]), "v"(a[3]), "v"(S[K]), "v"(S[K + 1]), "v"(S[K + 2]), "v"(S[K + 3]), "v"(S[K + 4]), "v"(S[K + 5]), "v"(S[K + 6]), "v"(S[K + 7]), "n"(N0), "n"(N1));
;         } else
;         asm volatile("v_fmac_f32_dpp %0, %4, %8 row_newbcast:%16" DPPM "v_fmac_f32_dpp %1, %5, %9 row_newbcast:%16" DPPM "v_fmac_f32_dpp %2, %6, %10 row_newbcast:%16" DPPM "v_fmac_f32_dpp %3, %7, %11 row_newbcast:%16" DPPM
;                      "v_fmac_f32_dpp %0, %4, %12 row_newbcast:%17" DPPM "v_fmac_f32_dpp %1, %5, %13 row_newbcast:%17" DPPM "v_fmac_f32_dpp %2, %6, %14 row_newbcast:%17" DPPM "v_fmac_f32_dpp %3, %7, %15 row_newbcast:%17" DPPM
;                      : "+v"(s[0]), "+v"(s[1]), "+v"(s[2]), "+v"(s[3])
;                      : "v"(a[0]), "v"(a[1]), "v"(a[2]), "v"(a[3]), "v"(S[K]), "v"(S[K + 1]), "v"(S[K + 2]), "v"(S[K + 3]), "v"(S[K + 4]), "v"(S[K + 5]), "v"(S[K + 6]), "v"(S[K + 7]), "n"(N0), "n"(N1));
;         if constexpr (K + 8 < 64) ScanK<K + 8>::dot(S, a, s);
;     }
	v_fmac_f32_dpp v226, v246, v50 row_newbcast:12 row_mask:0xf bank_mask:0xf
	v_fmac_f32_dpp v227, v247, v51 row_newbcast:12 row_mask:0xf bank_mask:0xf
	v_fmac_f32_dpp v224, v244, v52 row_newbcast:13 row_mask:0xf bank_mask:0xf
	v_fmac_f32_dpp v225, v245, v53 row_newbcast:13 row_mask:0xf bank_mask:0xf
	v_fmac_f32_dpp v226, v246, v54 row_newbcast:13 row_mask:0xf bank_mask:0xf
	v_fmac_f32_dpp v227, v247, v55 row_newbcast:13 row_mask:0xf bank_mask:0xf
	v_fmac_f32_dpp v224, v244, v56 row_newbcast:14 row_mask:0xf bank_mask:0xf
	v_fmac_f32_dpp v225, v245, v57 row_newbcast:14 row_mask:0xf bank_mask:0xf
	v_fmac_f32_dpp v226, v246, v58 row_newbcast:14 row_mask:0xf bank_mask:0xf
	v_fmac_f32_dpp v227, v247, v59 row_newbcast:14 row_mask:0xf bank_mask:0xf
	v_fmac_f32_dpp v224, v244, v60 row_newbcast:15 row_mask:0xf bank_mask:0xf
	v_fmac_f32_dpp v225, v245, v61 row_newbcast:15 row_mask:0xf bank_mask:0xf
	v_fmac_f32_dpp v226, v246, v62 row_newbcast:15 row_mask:0xf bank_mask:0xf
	v_fmac_f32_dpp v227, v247, v63 row_newbcast:15 row_mask:0xf bank_mask:0xf
	v_mul_f32_dpp v228, v244, v64 row_newbcast:0 row_mask:0xf bank_mask:0xf
	v_mul_f32_dpp v229, v245, v65 row_newbcast:0 row_mask:0xf bank_mask:0xf
	v_mul_f32_dpp v230, v246, v66 row_newbcast:0 row_mask:0xf bank_mask:0xf
	v_mul_f32_dpp v231, v247, v67 row_newbcast:0 row_mask:0xf bank_mask:0xf
	v_fmac_f32_dpp v228, v244, v68 row_newbcast:1 row_mask:0xf bank_mask:0xf
	v_fmac_f32_dpp v229, v245, v69 row_newbcast:1 row_mask:0xf bank_mask:0xf
	v_fmac_f32_dpp v230, v246, v70 row_newbcast:1 row_mask:0xf bank_mask:0xf
	v_fmac_f32_dpp v231, v247, v71 row_newbcast:1 row_mask:0xf bank_mask:0xf
	v_fmac_f32_dpp v228, v244, v72 row_newbcast:2 row_mask:0xf bank_mask:0xf
	v_fmac_f32_dpp v229, v245, v73 row_newbcast:2 row_mask:0xf bank_mask:0xf
	v_fmac_f32_dpp v230, v246, v74 row_newbcast:2 row_mask:0xf bank_mask:0xf
	v_fmac_f32_dpp v231, v247, v75 row_newbcast:2 row_mask:0xf bank_mask:0xf
	v_fmac_f32_dpp v228, v244, v76 row_newbcast:3 row_mask:0xf bank_mask:0xf
	v_fmac_f32_dpp v229, v245, v77 row_newbcast:3 row_mask:0xf bank_mask:0xf
	v_fmac_f32_dpp v230, v246, v78 row_newbcast:3 row_mask:0xf bank_mask:0xf
	v_fmac_f32_dpp v231, v247, v79 row_newbcast:3 row_mask:0xf bank_mask:0xf
	v_fmac_f32_dpp v228, v244, v80 row_newbcast:4 row_mask:0xf bank_mask:0xf
	v_fmac_f32_dpp v229, v245, v81 row_newbcast:4 row_mask:0xf bank_mask:0xf
	v_fmac_f32_dpp v230, v246, v82 row_newbcast:4 row_mask:0xf bank_mask:0xf
	v_fmac_f32_dpp v231, v247, v83 row_newbcast:4 row_mask:0xf bank_mask:0xf
	v_fmac_f32_dpp v228, v244, v84 row_newbcast:5 row_mask:0xf bank_mask:0xf
	v_fmac_f32_dpp v229, v245, v85 row_newbcast:5 row_mask:0xf bank_mask:0xf
	v_fmac_f32_dpp v230, v246, v86 row_newbcast:5 row_mask:0xf bank_mask:0xf
	v_fmac_f32_dpp v231, v247, v87 row_newbcast:5 row_mask:0xf bank_mask:0xf
	v_fmac_f32_dpp v228, v244, v88 row_newbcast:6 row_mask:0xf bank_mask:0xf
	v_fmac_f32_dpp v229, v245, v89 row_newbcast:6 row_mask:0xf bank_mask:0xf
	v_fmac_f32_dpp v230, v246, v90 row_newbcast:6 row_mask:0xf bank_mask:0xf
	v_fmac_f32_dpp v231, v247, v91 row_newbcast:6 row_mask:0xf bank_mask:0xf
	v_fmac_f32_dpp v228, v244, v92 row_newbcast:7 row_mask:0xf bank_mask:0xf
	v_fmac_f32_dpp v229, v245, v93 row_newbcast:7 row_mask:0xf bank_mask:0xf
	v_fmac_f32_dpp v230, v246, v94 row_newbcast:7 row_mask:0xf bank_mask:0xf
	v_fmac_f32_dpp v231, v247, v95 row_newbcast:7 row_mask:0xf bank_mask:0xf
	v_fmac_f32_dpp v228, v244, v96 row_newbcast:8 row_mask:0xf bank_mask:0xf
	v_fmac_f32_dpp v229, v245, v97 row_newbcast:8 row_mask:0xf bank_mask:0xf
	v_fmac_f32_dpp v230, v246, v98 row_newbcast:8 row_mask:0xf bank_mask:0xf
	v_fmac_f32_dpp v231, v247, v99 row_newbcast:8 row_mask:0xf bank_mask:0xf
	v_fmac_f32_dpp v228, v244, v100 row_newbcast:9 row_mask:0xf bank_mask:0xf
	v_fmac_f32_dpp v229, v245, v101 row_newbcast:9 row_mask:0xf bank_mask:0xf
	v_fmac_f32_dpp v230, v246, v102 row_newbcast:9 row_mask:0xf bank_mask:0xf
	v_fmac_f32_dpp v231, v247, v103 row_newbcast:9 row_mask:0xf bank_mask:0xf
	v_fmac_f32_dpp v228, v244, v104 row_newbcast:10 row_mask:0xf bank_mask:0xf
	v_fmac_f32_dpp v229, v245, v105 row_newbcast:10 row_mask:0xf bank_mask:0xf
	v_fmac_f32_dpp v230, v246, v106 row_newbcast:10 row_mask:0xf bank_mask:0xf
	v_fmac_f32_dpp v231, v247, v107 row_newbcast:10 row_mask:0xf bank_mask:0xf
	v_fmac_f32_dpp v228, v244, v108 row_newbcast:11 row_mask:0xf bank_mask:0xf
	v_fmac_f32_dpp v229, v245, v109 row_newbcast:11 row_mask:0xf bank_mask:0xf
	v_fmac_f32_dpp v230, v246, v110 row_newbcast:11 row_mask:0xf bank_mask:0xf
	v_fmac_f32_dpp v231, v247, v111 row_newbcast:11 row_mask:0xf bank_mask:0xf
	v_fmac_f32_dpp v228, v244, v112 row_newbcast:12 row_mask:0xf bank_mask:0xf
	v_fmac_f32_dpp v229, v245, v113 row_newbcast:12 row_mask:0xf bank_mask:0xf
	v_fmac_f32_dpp v230, v246, v114 row_newbcast:12 row_mask:0xf bank_mask:0xf
	v_fmac_f32_dpp v231, v247, v115 row_newbcast:12 row_mask:0xf bank_mask:0xf
	v_fmac_f32_dpp v228, v244, v116 row_newbcast:13 row_mask:0xf bank_mask:0xf
	v_fmac_f32_dpp v229, v245, v117 row_newbcast:13 row_mask:0xf bank_mask:0xf
	v_fmac_f32_dpp v230, v246, v118 row_newbcast:13 row_mask:0xf bank_mask:0xf
	v_fmac_f32_dpp v231, v247, v119 row_newbcast:13 row_mask:0xf bank_mask:0xf
	v_fmac_f32_dpp v228, v244, v120 row_newbcast:14 row_mask:0xf bank_mask:0xf
	v_fmac_f32_dpp v229, v245, v121 row_newbcast:14 row_mask:0xf bank_mask:0xf
	v_fmac_f32_dpp v230, v246, v122 row_newbcast:14 row_mask:0xf bank_mask:0xf
	v_fmac_f32_dpp v231, v247, v123 row_newbcast:14 row_mask:0xf bank_mask:0xf
	v_fmac_f32_dpp v228, v244, v124 row_newbcast:15 row_mask:0xf bank_mask:0xf
	v_fmac_f32_dpp v229, v245, v125 row_newbcast:15 row_mask:0xf bank_mask:0xf
	v_fmac_f32_dpp v230, v246, v126 row_newbcast:15 row_mask:0xf bank_mask:0xf
	v_fmac_f32_dpp v231, v247, v127 row_newbcast:15 row_mask:0xf bank_mask:0xf
	v_add_f32_e32 v224, v224, v225
	v_add_f32_e32 v226, v226, v227
	v_sub_f32_e64 v232, -v224, v226
	v_add_f32_e32 v228, v228, v229
	v_add_f32_e32 v230, v230, v231
	v_sub_f32_e64 v233, -v228, v230
	s_waitcnt lgkmcnt(0)
;     static __device__ __forceinline__ void updS(float (&S)[64], const In1& in, float sa, float vv) {
;         float t0, t1, t2, t3;
;         asm volatile("v_mul_f32_dpp %0, %8, %21 row_newbcast:%22" DPPM "v_mul_f32_dpp %1, %9, %21 row_newbcast:%22" DPPM "v_mul_f32_dpp %2, %10, %21 row_newbcast:%22" DPPM "v_mul_f32_dpp %3, %11, %21 row_newbcast:%22" DPPM
;                      "v_fmac_f32_dpp %0, %12, %4 row_newbcast:%22" DPPM "v_fmac_f32_dpp %1, %13, %5 row_newbcast:%22" DPPM "v_fmac_f32_dpp %2, %14, %6 row_newbcast:%22" DPPM "v_fmac_f32_dpp %3, %15, %7 row_newbcast:%22" DPPM
;                      "v_fmac_f32_dpp %0, %16, %20 row_newbcast:%22" DPPM "v_fmac_f32_dpp %1, %17, %20 row_newbcast:%22" DPPM "v_fmac_f32_dpp %2, %18, %20 row_newbcast:%22" DPPM "v_fmac_f32_dpp %3, %19, %20 row_newbcast:%22" DPPM
;                      : "=&v"(t0), "=&v"(t1), "=&v"(t2), "=&v"(t3)
;                      : "v"(S[K]), "v"(S[K + 1]), "v"(S[K + 2]), "v"(S[K + 3]), "v"(in.kd[0]), "v"(in.kd[1]), "v"(in.kd[2]), "v"(in.kd[3]), "v"(in.w[0]), "v"(in.w[1]), "v"(in.w[2]), "v"(in.w[3]),
;                        "v"(in.b[0]), "v"(in.b[1]), "v"(in.b[2]), "v"(in.b[3]), "v"(sa), "v"(vv), "n"(N0));
;         S[K] = t0; S[K + 1] = t1; S[K + 2] = t2; S[K + 3] = t3;
;         if constexpr (K + 4 < 64) ScanK<K + 4>::updS(S, in, sa, vv);
;     }
;     static __device__ __forceinline__ void updP(float (&P)[64], const In1& in, float sa) {
;         float u0, u1, u2, u3;
;         asm volatile("v_mul_f32_dpp %0, %8, %4 row_newbcast:%17" DPPM "v_mul_f32_dpp %1, %9, %5 row_newbcast:%17" DPPM "v_mul_f32_dpp %2, %10, %6 row_newbcast:%17" DPPM "v_mul_f32_dpp %3, %11, %7 row_newbcast:%17" DPPM
;                      "v_fmac_f32_dpp %0, %12, %16 row_newbcast:%17" DPPM "v_fmac_f32_dpp %1, %13, %16 row_newbcast:%17" DPPM "v_fmac_f32_dpp %2, %14, %16 row_newbcast:%17" DPPM "v_fmac_f32_dpp %3, %15, %16 row_newbcast:%17" DPPM
;                      : "=&v"(u0), "=&v"(u1), "=&v"(u2), "=&v"(u3)
;                      : "v"(P[K]), "v"(P[K + 1]), "v"(P[K + 2]), "v"(P[K + 3]), "v"(in.w[0]), "v"(in.w[1]), "v"(in.w[2]), "v"(in.w[3]), "v"(in.b[0]), "v"(in.b[1]), "v"(in.b[2]), "v"(in.b[3]), "v"(sa), "n"(N0));
;         P[K] = u0; P[K + 1] = u1; P[K + 2] = u2; P[K + 3] = u3;
;         if constexpr (K + 4 < 64) ScanK<K + 4>::updP(P, in, sa);
	s_nop 1
	v_mfma_f32_4x4x1_16b_f32 v[0:3], v128, v232, v[0:3]
	v_mfma_f32_4x4x1_16b_f32 v[4:7], v129, v232, v[4:7]
	v_mfma_f32_4x4x1_16b_f32 v[8:11], v130, v232, v[8:11]
	v_mfma_f32_4x4x1_16b_f32 v[12:15], v131, v232, v[12:15]
	v_mfma_f32_4x4x1_16b_f32 v[16:19], v132, v232, v[16:19]
	v_mfma_f32_4x4x1_16b_f32 v[20:23], v133, v232, v[20:23]
	v_mfma_f32_4x4x1_16b_f32 v[24:27], v134, v232, v[24:27]
	v_mfma_f32_4x4x1_16b_f32 v[28:31], v135, v232, v[28:31]
	v_mfma_f32_4x4x1_16b_f32 v[32:35], v136, v232, v[32:35]
	v_mfma_f32_4x4x1_16b_f32 v[36:39], v137, v232, v[36:39]
	v_mfma_f32_4x4x1_16b_f32 v[40:43], v138, v232, v[40:43]
	v_mfma_f32_4x4x1_16b_f32 v[44:47], v139, v232, v[44:47]
	v_mfma_f32_4x4x1_16b_f32 v[48:51], v140, v232, v[48:51]
	v_mfma_f32_4x4x1_16b_f32 v[52:55], v141, v232, v[52:55]
	v_mfma_f32_4x4x1_16b_f32 v[56:59], v142, v232, v[56:59]
	v_mfma_f32_4x4x1_16b_f32 v[60:63], v143, v232, v[60:63]
	v_mfma_f32_4x4x1_16b_f32 v[0:3], v144, v234, v[0:3]
	v_mfma_f32_4x4x1_16b_f32 v[4:7], v145, v234, v[4:7]
	v_mfma_f32_4x4x1_16b_f32 v[8:11], v146, v234, v[8:11]
	v_mfma_f32_4x4x1_16b_f32 v[12:15], v147, v234, v[12:15]
	v_mfma_f32_4x4x1_16b_f32 v[16:19], v148, v234, v[16:19]
	v_mfma_f32_4x4x1_16b_f32 v[20:23], v149, v234, v[20:23]
	v_mfma_f32_4x4x1_16b_f32 v[24:27], v150, v234, v[24:27]
	v_mfma_f32_4x4x1_16b_f32 v[28:31], v151, v234, v[28:31]
	v_mfma_f32_4x4x1_16b_f32 v[32:35], v152, v234, v[32:35]
	v_mfma_f32_4x4x1_16b_f32 v[36:39], v153, v234, v[36:39]
	v_mfma_f32_4x4x1_16b_f32 v[40:43], v154, v234, v[40:43]
	v_mfma_f32_4x4x1_16b_f32 v[44:47], v155, v234, v[44:47]
	v_mfma_f32_4x4x1_16b_f32 v[48:51], v156, v234, v[48:51]
	v_mfma_f32_4x4x1_16b_f32 v[52:55], v157, v234, v[52:55]
	v_mfma_f32_4x4x1_16b_f32 v[56:59], v158, v234, v[56:59]
	v_mfma_f32_4x4x1_16b_f32 v[60:63], v159, v234, v[60:63]
	v_mfma_f32_4x4x1_16b_f32 v[64:67], v128, v233, v[64:67]
	v_mfma_f32_4x4x1_16b_f32 v[68:71], v129, v233, v[68:71]
	v_mfma_f32_4x4x1_16b_f32 v[72:75], v130, v233, v[72:75]
	v_mfma_f32_4x4x1_16b_f32 v[76:79], v131, v233, v[76:79]
	v_mfma_f32_4x4x1_16b_f32 v[80:83], v132, v233, v[80:83]
	v_mfma_f32_4x4x1_16b_f32 v[84:87], v133, v233, v[84:87]
	v_mfma_f32_4x4x1_16b_f32 v[88:91], v134, v233, v[88:91]
	v_mfma_f32_4x4x1_16b_f32 v[92:95], v135, v233, v[92:95]
	v_mfma_f32_4x4x1_16b_f32 v[96:99], v136, v233, v[96:99]
	v_mfma_f32_4x4x1_16b_f32 v[100:103], v137, v233, v[100:103]
	v_mfma_f32_4x4x1_16b_f32 v[104:107], v138, v233, v[104:107]
	v_mfma_f32_4x4x1_16b_f32 v[108:111], v139, v233, v[108:111]
	v_mfma_f32_4x4x1_16b_f32 v[112:115], v140, v233, v[112:115]
	v_mfma_f32_4x4x1_16b_f32 v[116:119], v141, v233, v[116:119]
	v_mfma_f32_4x4x1_16b_f32 v[120:123], v142, v233, v[120:123]
	v_mfma_f32_4x4x1_16b_f32 v[124:127], v143, v233, v[124:127]
	v_mul_f32_dpp v0, v236, v0 row_newbcast:0 row_mask:0xf bank_mask:0xf
	v_mul_f32_dpp v1, v237, v1 row_newbcast:0 row_mask:0xf bank_mask:0xf
	v_mul_f32_dpp v2, v238, v2 row_newbcast:0 row_mask:0xf bank_mask:0xf
	v_mul_f32_dpp v3, v239, v3 row_newbcast:0 row_mask:0xf bank_mask:0xf
	v_mul_f32_dpp v4, v236, v4 row_newbcast:1 row_mask:0xf bank_mask:0xf
	v_mul_f32_dpp v5, v237, v5 row_newbcast:1 row_mask:0xf bank_mask:0xf
	v_mul_f32_dpp v6, v238, v6 row_newbcast:1 row_mask:0xf bank_mask:0xf
	v_mul_f32_dpp v7, v239, v7 row_newbcast:1 row_mask:0xf bank_mask:0xf
	v_mul_f32_dpp v8, v236, v8 row_newbcast:2 row_mask:0xf bank_mask:0xf
	v_mul_f32_dpp v9, v237, v9 row_newbcast:2 row_mask:0xf bank_mask:0xf
	v_mul_f32_dpp v10, v238, v10 row_newbcast:2 row_mask:0xf bank_mask:0xf
	v_mul_f32_dpp v11, v239, v11 row_newbcast:2 row_mask:0xf bank_mask:0xf
	v_mul_f32_dpp v12, v236, v12 row_newbcast:3 row_mask:0xf bank_mask:0xf
	v_mul_f32_dpp v13, v237, v13 row_newbcast:3 row_mask:0xf bank_mask:0xf
	v_mul_f32_dpp v14, v238, v14 row_newbcast:3 row_mask:0xf bank_mask:0xf
	v_mul_f32_dpp v15, v239, v15 row_newbcast:3 row_mask:0xf bank_mask:0xf
	v_mul_f32_dpp v16, v236, v16 row_newbcast:4 row_mask:0xf bank_mask:0xf
	v_mul_f32_dpp v17, v237, v17 row_newbcast:4 row_mask:0xf bank_mask:0xf
	v_mul_f32_dpp v18, v238, v18 row_newbcast:4 row_mask:0xf bank_mask:0xf
	v_mul_f32_dpp v19, v239, v19 row_newbcast:4 row_mask:0xf bank_mask:0xf
	v_mul_f32_dpp v20, v236, v20 row_newbcast:5 row_mask:0xf bank_mask:0xf
	v_mul_f32_dpp v21, v237, v21 row_newbcast:5 row_mask:0xf bank_mask:0xf
	v_mul_f32_dpp v22, v238, v22 row_newbcast:5 row_mask:0xf bank_mask:0xf
	v_mul_f32_dpp v23, v239, v23 row_newbcast:5 row_mask:0xf bank_mask:0xf
	v_mul_f32_dpp v24, v236, v24 row_newbcast:6 row_mask:0xf bank_mask:0xf
	v_mul_f32_dpp v25, v237, v25 row_newbcast:6 row_mask:0xf bank_mask:0xf
	v_mul_f32_dpp v26, v238, v26 row_newbcast:6 row_mask:0xf bank_mask:0xf
	v_mul_f32_dpp v27, v239, v27 row_newbcast:6 row_mask:0xf bank_mask:0xf
	v_mul_f32_dpp v28, v236, v28 row_newbcast:7 row_mask:0xf bank_mask:0xf
	v_mul_f32_dpp v29, v237, v29 row_newbcast:7 row_mask:0xf bank_mask:0xf
	v_mul_f32_dpp v30, v238, v30 row_newbcast:7 row_mask:0xf bank_mask:0xf
	v_mul_f32_dpp v31, v239, v31 row_newbcast:7 row_mask:0xf bank_mask:0xf
	v_mul_f32_dpp v32, v236, v32 row_newbcast:8 row_mask:0xf bank_mask:0xf
	v_mul_f32_dpp v33, v237, v33 row_newbcast:8 row_mask:0xf bank_mask:0xf
	v_mul_f32_dpp v34, v238, v34 row_newbcast:8 row_mask:0xf bank_mask:0xf
	v_mul_f32_dpp v35, v239, v35 row_newbcast:8 row_mask:0xf bank_mask:0xf
	v_mul_f32_dpp v36, v236, v36 row_newbcast:9 row_mask:0xf bank_mask:0xf
	v_mul_f32_dpp v37, v237, v37 row_newbcast:9 row_mask:0xf bank_mask:0xf
	v_mul_f32_dpp v38, v238, v38 row_newbcast:9 row_mask:0xf bank_mask:0xf
	v_mul_f32_dpp v39, v239, v39 row_newbcast:9 row_mask:0xf bank_mask:0xf
;     static __device__ __forceinline__ void updP(float (&P)[64], const In1& in, float sa) {
;         float u0, u1, u2, u3;
;         asm volatile("v_mul_f32_dpp %0, %8, %4 row_newbcast:%17" DPPM "v_mul_f32_dpp %1, %9, %5 row_newbcast:%17" DPPM "v_mul_f32_dpp %2, %10, %6 row_newbcast:%17" DPPM "v_mul_f32_dpp %3, %11, %7 row_newbcast:%17" DPPM
;                      "v_fmac_f32_dpp %0, %12, %16 row_newbcast:%17" DPPM "v_fmac_f32_dpp %1, %13, %16 row_newbcast:%17" DPPM "v_fmac_f32_dpp %2, %14, %16 row_newbcast:%17" DPPM "v_fmac_f32_dpp %3, %15, %16 row_newbcast:%17" DPPM
;                      : "=&v"(u0), "=&v"(u1), "=&v"(u2), "=&v"(u3)
;                      : "v"(P[K]), "v"(P[K + 1]), "v"(P[K + 2]), "v"(P[K + 3]), "v"(in.w[0]), "v"(in.w[1]), "v"(in.w[2]), "v"(in.w[3]), "v"(in.b[0]), "v"(in.b[1]), "v"(in.b[2]), "v"(in.b[3]), "v"(sa), "n"(N0));
;         P[K] = u0; P[K + 1] = u1; P[K + 2] = u2; P[K + 3] = u3;
;         if constexpr (K + 4 < 64) ScanK<K + 4>::updP(P, in, sa);
	v_mul_f32_dpp v40, v236, v40 row_newbcast:10 row_mask:0xf bank_mask:0xf
	v_mul_f32_dpp v41, v237, v41 row_newbcast:10 row_mask:0xf bank_mask:0xf
	v_mul_f32_dpp v42, v238, v42 row_newbcast:10 row_mask:0xf bank_mask:0xf
	v_mul_f32_dpp v43, v239, v43 row_newbcast:10 row_mask:0xf bank_mask:0xf
	v_mul_f32_dpp v44, v236, v44 row_newbcast:11 row_mask:0xf bank_mask:0xf
	v_mul_f32_dpp v45, v237, v45 row_newbcast:11 row_mask:0xf bank_mask:0xf
	v_mul_f32_dpp v46, v238, v46 row_newbcast:11 row_mask:0xf bank_mask:0xf
	v_mul_f32_dpp v47, v239, v47 row_newbcast:11 row_mask:0xf bank_mask:0xf
	v_mul_f32_dpp v48, v236, v48 row_newbcast:12 row_mask:0xf bank_mask:0xf
	v_mul_f32_dpp v49, v237, v49 row_newbcast:12 row_mask:0xf bank_mask:0xf
	v_mul_f32_dpp v50, v238, v50 row_newbcast:12 row_mask:0xf bank_mask:0xf
	v_mul_f32_dpp v51, v239, v51 row_newbcast:12 row_mask:0xf bank_mask:0xf
	v_mul_f32_dpp v52, v236, v52 row_newbcast:13 row_mask:0xf bank_mask:0xf
	v_mul_f32_dpp v53, v237, v53 row_newbcast:13 row_mask:0xf bank_mask:0xf
	v_mul_f32_dpp v54, v238, v54 row_newbcast:13 row_mask:0xf bank_mask:0xf
	v_mul_f32_dpp v55, v239, v55 row_newbcast:13 row_mask:0xf bank_mask:0xf
	v_mul_f32_dpp v56, v236, v56 row_newbcast:14 row_mask:0xf bank_mask:0xf
	v_mul_f32_dpp v57, v237, v57 row_newbcast:14 row_mask:0xf bank_mask:0xf
	v_mul_f32_dpp v58, v238, v58 row_newbcast:14 row_mask:0xf bank_mask:0xf
	v_mul_f32_dpp v59, v239, v59 row_newbcast:14 row_mask:0xf bank_mask:0xf
	v_mul_f32_dpp v60, v236, v60 row_newbcast:15 row_mask:0xf bank_mask:0xf
	v_mul_f32_dpp v61, v237, v61 row_newbcast:15 row_mask:0xf bank_mask:0xf
	v_mul_f32_dpp v62, v238, v62 row_newbcast:15 row_mask:0xf bank_mask:0xf
	v_mul_f32_dpp v63, v239, v63 row_newbcast:15 row_mask:0xf bank_mask:0xf
	v_mul_f32_dpp v64, v236, v64 row_newbcast:0 row_mask:0xf bank_mask:0xf
	v_mul_f32_dpp v65, v237, v65 row_newbcast:0 row_mask:0xf bank_mask:0xf
	v_mul_f32_dpp v66, v238, v66 row_newbcast:0 row_mask:0xf bank_mask:0xf
	v_mul_f32_dpp v67, v239, v67 row_newbcast:0 row_mask:0xf bank_mask:0xf
	v_mul_f32_dpp v68, v236, v68 row_newbcast:1 row_mask:0xf bank_mask:0xf
	v_mul_f32_dpp v69, v237, v69 row_newbcast:1 row_mask:0xf bank_mask:0xf
	v_mul_f32_dpp v70, v238, v70 row_newbcast:1 row_mask:0xf bank_mask:0xf
	v_mul_f32_dpp v71, v239, v71 row_newbcast:1 row_mask:0xf bank_mask:0xf
	v_mul_f32_dpp v72, v236, v72 row_newbcast:2 row_mask:0xf bank_mask:0xf
	v_mul_f32_dpp v73, v237, v73 row_newbcast:2 row_mask:0xf bank_mask:0xf
	v_mul_f32_dpp v74, v238, v74 row_newbcast:2 row_mask:0xf bank_mask:0xf
	v_mul_f32_dpp v75, v239, v75 row_newbcast:2 row_mask:0xf bank_mask:0xf
	v_mul_f32_dpp v76, v236, v76 row_newbcast:3 row_mask:0xf bank_mask:0xf
	v_mul_f32_dpp v77, v237, v77 row_newbcast:3 row_mask:0xf bank_mask:0xf
	v_mul_f32_dpp v78, v238, v78 row_newbcast:3 row_mask:0xf bank_mask:0xf
	v_mul_f32_dpp v79, v239, v79 row_newbcast:3 row_mask:0xf bank_mask:0xf
	v_mul_f32_dpp v80, v236, v80 row_newbcast:4 row_mask:0xf bank_mask:0xf
	v_mul_f32_dpp v81, v237, v81 row_newbcast:4 row_mask:0xf bank_mask:0xf
	v_mul_f32_dpp v82, v238, v82 row_newbcast:4 row_mask:0xf bank_mask:0xf
	v_mul_f32_dpp v83, v239, v83 row_newbcast:4 row_mask:0xf bank_mask:0xf
	v_mul_f32_dpp v84, v236, v84 row_newbcast:5 row_mask:0xf bank_mask:0xf
	v_mul_f32_dpp v85, v237, v85 row_newbcast:5 row_mask:0xf bank_mask:0xf
	v_mul_f32_dpp v86, v238, v86 row_newbcast:5 row_mask:0xf bank_mask:0xf
	v_mul_f32_dpp v87, v239, v87 row_newbcast:5 row_mask:0xf bank_mask:0xf
	v_mul_f32_dpp v88, v236, v88 row_newbcast:6 row_mask:0xf bank_mask:0xf
	v_mul_f32_dpp v89, v237, v89 row_newbcast:6 row_mask:0xf bank_mask:0xf
	v_mul_f32_dpp v90, v238, v90 row_newbcast:6 row_mask:0xf bank_mask:0xf
	v_mul_f32_dpp v91, v239, v91 row_newbcast:6 row_mask:0xf bank_mask:0xf
	v_mul_f32_dpp v92, v236, v92 row_newbcast:7 row_mask:0xf bank_mask:0xf
	v_mul_f32_dpp v93, v237, v93 row_newbcast:7 row_mask:0xf bank_mask:0xf
	v_mul_f32_dpp v94, v238, v94 row_newbcast:7 row_mask:0xf bank_mask:0xf
	v_mul_f32_dpp v95, v239, v95 row_newbcast:7 row_mask:0xf bank_mask:0xf
	v_mul_f32_dpp v96, v236, v96 row_newbcast:8 row_mask:0xf bank_mask:0xf
	v_mul_f32_dpp v97, v237, v97 row_newbcast:8 row_mask:0xf bank_mask:0xf
	v_mul_f32_dpp v98, v238, v98 row_newbcast:8 row_mask:0xf bank_mask:0xf
	v_mul_f32_dpp v99, v239, v99 row_newbcast:8 row_mask:0xf bank_mask:0xf
	v_mul_f32_dpp v100, v236, v100 row_newbcast:9 row_mask:0xf bank_mask:0xf
	v_mul_f32_dpp v101, v237, v101 row_newbcast:9 row_mask:0xf bank_mask:0xf
	v_mul_f32_dpp v102, v238, v102 row_newbcast:9 row_mask:0xf bank_mask:0xf
	v_mul_f32_dpp v103, v239, v103 row_newbcast:9 row_mask:0xf bank_mask:0xf
	v_mul_f32_dpp v104, v236, v104 row_newbcast:10 row_mask:0xf bank_mask:0xf
	v_mul_f32_dpp v105, v237, v105 row_newbcast:10 row_mask:0xf bank_mask:0xf
	v_mul_f32_dpp v106, v238, v106 row_newbcast:10 row_mask:0xf bank_mask:0xf
	v_mul_f32_dpp v107, v239, v107 row_newbcast:10 row_mask:0xf bank_mask:0xf
	v_mul_f32_dpp v108, v236, v108 row_newbcast:11 row_mask:0xf bank_mask:0xf
	v_mul_f32_dpp v109, v237, v109 row_newbcast:11 row_mask:0xf bank_mask:0xf
	v_mul_f32_dpp v110, v238, v110 row_newbcast:11 row_mask:0xf bank_mask:0xf
	v_mul_f32_dpp v111, v239, v111 row_newbcast:11 row_mask:0xf bank_mask:0xf
	v_mul_f32_dpp v112, v236, v112 row_newbcast:12 row_mask:0xf bank_mask:0xf
	v_mul_f32_dpp v113, v237, v113 row_newbcast:12 row_mask:0xf bank_mask:0xf
	v_mul_f32_dpp v114, v238, v114 row_newbcast:12 row_mask:0xf bank_mask:0xf
	v_mul_f32_dpp v115, v239, v115 row_newbcast:12 row_mask:0xf bank_mask:0xf
	v_mul_f32_dpp v116, v236, v116 row_newbcast:13 row_mask:0xf bank_mask:0xf
	v_mul_f32_dpp v117, v237, v117 row_newbcast:13 row_mask:0xf bank_mask:0xf
	v_mul_f32_dpp v118, v238, v118 row_newbcast:13 row_mask:0xf bank_mask:0xf
	v_mul_f32_dpp v119, v239, v119 row_newbcast:13 row_mask:0xf bank_mask:0xf
	v_mul_f32_dpp v120, v236, v120 row_newbcast:14 row_mask:0xf bank_mask:0xf
	v_mul_f32_dpp v121, v237, v121 row_newbcast:14 row_mask:0xf bank_mask:0xf
	v_mul_f32_dpp v122, v238, v122 row_newbcast:14 row_mask:0xf bank_mask:0xf
	v_mul_f32_dpp v123, v239, v123 row_newbcast:14 row_mask:0xf bank_mask:0xf
	v_mul_f32_dpp v124, v236, v124 row_newbcast:15 row_mask:0xf bank_mask:0xf
	v_mul_f32_dpp v125, v237, v125 row_newbcast:15 row_mask:0xf bank_mask:0xf
	v_mul_f32_dpp v126, v238, v126 row_newbcast:15 row_mask:0xf bank_mask:0xf
	v_mul_f32_dpp v127, v239, v127 row_newbcast:15 row_mask:0xf bank_mask:0xf
	v_mov_b32_e32 v236, 1.0
	v_mov_b32_e32 v237, 1.0
	v_mov_b32_e32 v238, 1.0
	v_mov_b32_e32 v239, 1.0
	s_waitcnt vmcnt(0)
; #define NEXT_ITEM() (MIX ? (int)__builtin_amdgcn_readfirstlane(lane == 0 ? __hip_atomic_fetch_add(qctr, 1u, __ATOMIC_RELAXED, __HIP_MEMORY_SCOPE_AGENT) : 0u) : item + (int)gridDim.x * 8)
; template <bool MIX> __device__ __forceinline__ void scan_pass1(const Params& p, int d, float* ldsf) {
;     ...
;     for (int item = MIX ? NEXT_ITEM() : (int)(blockIdx.x * 8 + wid); item < 2 * NS; item = NEXT_ITEM()) {
;     ...
;         float* po = (isP ? PT : SLT) + ((size_t)(bh * NC + c)) * 4096 + lane * 64;
; #pragma unroll
;         for (int i = 0; i < 16; ++i) *(f32x4*)(po + 4 * i) = (f32x4){S[4 * i], S[4 * i + 1], S[4 * i + 2], S[4 * i + 3]};
	s_nop 1
	v_and_b32_e32 v128, 63, v254
	v_lshlrev_b32_e32 v129, 8, v128
	v_lshlrev_b32_e32 v130, 2, v128
	global_store_dwordx4 v129, v[0:3], s[90:91] offset:0
	global_store_dwordx4 v129, v[4:7], s[90:91] offset:16
	global_store_dwordx4 v129, v[8:11], s[90:91] offset:32
	global_store_dwordx4 v129, v[12:15], s[90:91] offset:48
	global_store_dwordx4 v129, v[16:19], s[90:91] offset:64
	global_store_dwordx4 v129, v[20:23], s[90:91] offset:80
	global_store_dwordx4 v129, v[24:27], s[90:91] offset:96
	global_store_dwordx4 v129, v[28:31], s[90:91] offset:112
	global_store_dwordx4 v129, v[32:35], s[90:91] offset:128
	global_store_dwordx4 v129, v[36:39], s[90:91] offset:144
	global_store_dwordx4 v129, v[40:43], s[90:91] offset:160
	global_store_dwordx4 v129, v[44:47], s[90:91] offset:176
	global_store_dwordx4 v129, v[48:51], s[90:91] offset:192
	global_store_dwordx4 v129, v[52:55], s[90:91] offset:208
	global_store_dwordx4 v129, v[56:59], s[90:91] offset:224
	global_store_dwordx4 v129, v[60:63], s[90:91] offset:240
	global_store_dword v130, v64, s[92:93] offset:0
	global_store_dword v130, v65, s[92:93] offset:256
	global_store_dword v130, v66, s[92:93] offset:512
	global_store_dword v130, v67, s[92:93] offset:768
	global_store_dword v130, v68, s[92:93] offset:1024
	global_store_dword v130, v69, s[92:93] offset:1280
	global_store_dword v130, v70, s[92:93] offset:1536
	global_store_dword v130, v71, s[92:93] offset:1792
	global_store_dword v130, v72, s[92:93] offset:2048
	global_store_dword v130, v73, s[92:93] offset:2304
	global_store_dword v130, v74, s[92:93] offset:2560
	global_store_dword v130, v75, s[92:93] offset:2816
	global_store_dword v130, v76, s[92:93] offset:3072
	global_store_dword v130, v77, s[92:93] offset:3328
	global_store_dword v130, v78, s[92:93] offset:3584
	global_store_dword v130, v79, s[92:93] offset:3840
	s_add_u32 s92, s92, 0x1000
	s_addc_u32 s93, s93, 0
	global_store_dword v130, v80, s[92:93] offset:0
	global_store_dword v130, v81, s[92:93] offset:256
	global_store_dword v130, v82, s[92:93] offset:512
	global_store_dword v130, v83, s[92:93] offset:768
	global_store_dword v130, v84, s[92:93] offset:1024
	global_store_dword v130, v85, s[92:93] offset:1280
	global_store_dword v130, v86, s[92:93] offset:1536
	global_store_dword v130, v87, s[92:93] offset:1792
	global_store_dword v130, v88, s[92:93] offset:2048
	global_store_dword v130, v89, s[92:93] offset:2304
	global_store_dword v130, v90, s[92:93] offset:2560
	global_store_dword v130, v91, s[92:93] offset:2816
	global_store_dword v130, v92, s[92:93] offset:3072
	global_store_dword v130, v93, s[92:93] offset:3328
	global_store_dword v130, v94, s[92:93] offset:3584
	global_store_dword v130, v95, s[92:93] offset:3840
	s_add_u32 s92, s92, 0x1000
	s_addc_u32 s93, s93, 0
	global_store_dword v130, v96, s[92:93] offset:0
	global_store_dword v130, v97, s[92:93] offset:256
	global_store_dword v130, v98, s[92:93] offset:512
	global_store_dword v130, v99, s[92:93] offset:768
	global_store_dword v130, v100, s[92:93] offset:1024
	global_store_dword v130, v101, s[92:93] offset:1280
	global_store_dword v130, v102, s[92:93] offset:1536
	global_store_dword v130, v103, s[92:93] offset:1792
	global_store_dword v130, v104, s[92:93] offset:2048
	global_store_dword v130, v105, s[92:93] offset:2304
	global_store_dword v130, v106, s[92:93] offset:2560
	global_store_dword v130, v107, s[92:93] offset:2816
	global_store_dword v130, v108, s[92:93] offset:3072
	global_store_dword v130, v109, s[92:93] offset:3328
	global_store_dword v130, v110, s[92:93] offset:3584
	global_store_dword v130, v111, s[92:93] offset:3840
	s_add_u32 s92, s92, 0x1000
	s_addc_u32 s93, s93, 0
	global_store_dword v130, v112, s[92:93] offset:0
	global_store_dword v130, v113, s[92:93] offset:256
	global_store_dword v130, v114, s[92:93] offset:512
	global_store_dword v130, v115, s[92:93] offset:768
	global_store_dword v130, v116, s[92:93] offset:1024
	global_store_dword v130, v117, s[92:93] offset:1280
	global_store_dword v130, v118, s[92:93] offset:1536
	global_store_dword v130, v119, s[92:93] offset:1792
	global_store_dword v130, v120, s[92:93] offset:2048
	global_store_dword v130, v121, s[92:93] offset:2304
	global_store_dword v130, v122, s[92:93] offset:2560
	global_store_dword v130, v123, s[92:93] offset:2816
	global_store_dword v130, v124, s[92:93] offset:3072
	global_store_dword v130, v125, s[92:93] offset:3328
	global_store_dword v130, v126, s[92:93] offset:3584
	global_store_dword v130, v127, s[92:93] offset:3840
	s_nop 1
	s_lshl_b32 s6, s96, 3
	s_add_i32 s0, s0, s6
	s_branch .Lmy_p1d0_item

; #define NEXT_ITEM() (MIX ? (int)__builtin_amdgcn_readfirstlane(lane == 0 ? __hip_atomic_fetch_add(qctr, 1u, __ATOMIC_RELAXED, __HIP_MEMORY_SCOPE_AGENT) : 0u) : item + (int)gridDim.x * 8)
; #define MKR(ptr) __builtin_amdgcn_make_buffer_rsrc((void*)(ptr), 0, 0x7fffffff, 0x00027000)
; #define LD1(set, s) { const int e_ = min((int)(s), LC - 1) * (int)stp; const unsigned s4_ = ob4 + (unsigned)(e_ * 4); set.w = LDX(rW, s4_); set.a = LDX(rA, s4_); set.b = LDX(rB, s4_); }
; template <bool MIX> __device__ __forceinline__ void scan_pass1(const Params& p, int d, float* ldsf) {
;     const int lane = threadIdx.x & 63, wid = __builtin_amdgcn_readfirstlane(threadIdx.x >> 6); const unsigned lo16 = (lane & 15) * 16, lo2 = lane * 2;
;     const float* Wd = (const float*)(p.ws + O_KD); const float* Bd = (const float*)(p.ws + O_Y); const u16* KB = (const u16*)(p.ws + O_K); const float* A = (const float*)(p.ws + O_A);
;     const u16* V = (const u16*)(p.ws + O_V); float* PT = (float*)(p.ws + O_PT); float* SLT = (float*)(p.ws + O_SLT); const unsigned lo8 = (lane & 15) * 8;
;     constexpr int NS = 32 * (NC - 1);
;     unsigned* qctr = (unsigned*)(p.ws + O_BAR);
;     if (MIX && wid >= 4) nat_phase(p, ldsf, blockIdx.x * 4 + (wid - 4), gridDim.x * 4);
;     ...
;     for (int item = MIX ? NEXT_ITEM() : (int)(blockIdx.x * 8 + wid); item < 2 * NS; item = NEXT_ITEM()) {
;         const bool isP = item >= NS; const int idx = isP ? item - NS : item;
;         const int bh = idx / (NC - 1), c = idx - bh * (NC - 1), b = bh >> 4, h = bh & 15;
;         const int t0 = d ? (SEQ - 1 - c * LC) : c * LC;
;         const size_t off0 = ((size_t)(b * SEQ + t0)) * RW + h * 64; const long stp = d ? -(long)RW : (long)RW;
;         const unsigned ob4 = (unsigned)(off0 * 4), ob2 = (unsigned)(off0 * 2);
;         const f32x4 ka4 = *(const f32x4*)(p.k_a + h * 64 + (lane & 15) * 4), c04 = 1.0f - ka4;
;         float S[64]; int ln = lane; asm volatile("" : "+v"(ln));
;     ...
;         const __amdgpu_buffer_rsrc_t rW = MKR(Wd), rA = MKR(A), rB = MKR(Bd), rK = MKR(KB), rV = MKR(V);
;         if (!isP) {
; #pragma unroll
;             for (int i = 0; i < 64; ++i) S[i] = 0.f;
;     ...
;             In1 i0, i1; LD1(i0, 0);
;     ...
;             for (int i = 0; i < 64; ++i) S[i] = (ln == i) ? 1.f : 0.f;
.LBB0_827:
	s_cmp_lt_i32 s58, 9
	s_cselect_b64 s[0:1], -1, 0
	s_cmp_gt_i32 s59, 8
	s_cselect_b64 s[4:5], -1, 0
	s_and_b64 s[0:1], s[0:1], s[4:5]
	s_andn2_b64 vcc, exec, s[0:1]
	s_cbranch_vccnz .LBB0_893
	s_mov_b64 exec, -1
	v_readfirstlane_b32 s0, v254
	s_nop 3
	s_lshr_b32 s1, s0, 6
	s_lshl_b32 s0, s2, 3
	s_add_i32 s0, s1, s0
	s_mov_b32 s64, s56
	s_and_b32 s65, s57, 0xffff
	s_brev_b32 s66, -2
	s_mov_b32 s67, 0x27000
	v_and_b32_e32 v128, 63, v254
	v_and_b32_e32 v129, 15, v254
	s_lshl_b32 s3, s1, 10
	s_add_u32 s3, s3, 0x10000
	v_lshl_add_u32 v248, v129, 2, s3
	v_and_b32_e32 v249, 3, v254
	v_lshl_add_u32 v249, v249, 6, s3
	v_lshlrev_b32_e32 v130, 4, v129
	v_add_u32_e32 v235, 0xb800000, v130
	v_add_u32_e32 v250, 0x24800000, v130
	v_add_u32_e32 v251, 0x35a00000, v130
	v_lshlrev_b32_e32 v130, 3, v129
	v_add_u32_e32 v252, 0x30800000, v130
	v_lshlrev_b32_e32 v130, 1, v128
	v_add_u32_e32 v253, 0x2c800000, v130
.Lmy_p1d1_item:
	s_cmpk_gt_i32 s0, 0x7df
	s_cbranch_scc1 .Lmy_p1d1_end
	s_mul_i32 s86, s0, 2081
	s_lshr_b32 s86, s86, 17
	s_mul_i32 s7, s86, 63
	s_sub_u32 s85, s0, s7
	s_and_b32 s87, s86, 15
	s_lshr_b32 s6, s86, 4
	s_lshl_b32 s6, s6, 14
	s_lshl_b32 s7, s85, 8
	s_sub_u32 s7, 0x3fff, s7
	s_add_u32 s6, s6, s7
	s_lshl_b32 s6, s6, 10
	s_lshl_b32 s7, s87, 6
	s_add_u32 s84, s6, s7
	s_lshl_b32 s72, s84, 2
	s_lshl_b32 s76, s84, 1
	s_lshl_b32 s6, s86, 6
	s_add_u32 s6, s6, s85
	s_lshl_b32 s6, s6, 14
	s_add_u32 s7, s6, 0x15800000
	s_add_u32 s90, s56, s7
	s_addc_u32 s91, s57, 0
	s_add_u32 s7, s6, 0x13800000
	s_add_u32 s92, s56, s7
	s_addc_u32 s93, s57, 0
	s_lshl_b32 s8, s87, 8
	s_add_u32 s4, s42, s8
	s_addc_u32 s5, s43, 0
	v_and_b32_e32 v129, 15, v254
	v_lshlrev_b32_e32 v130, 4, v129
	global_load_dwordx4 v[216:219], v130, s[4:5]
	buffer_load_dwordx4 v[160:163], v235, s[64:67], s72 offen
	buffer_load_dwordx4 v[164:167], v250, s[64:67], s72 offen
	buffer_load_dwordx4 v[168:171], v251, s[64:67], s72 offen
	buffer_load_dwordx2 v[172:173], v252, s[64:67], s76 offen
	buffer_load_ushort v174, v253, s[64:67], s76 offen
	s_add_i32 s72, s72, 0xfffff000
	s_max_i32 s72, s72, 0
	s_add_i32 s76, s76, 0xfffff800
	s_max_i32 s76, s76, 0
	buffer_load_dwordx4 v[176:179], v235, s[64:67], s72 offen
	buffer_load_dwordx4 v[180:183], v250, s[64:67], s72 offen
	buffer_load_dwordx4 v[184:187], v251, s[64:67], s72 offen
	buffer_load_dwordx2 v[188:189], v252, s[64:67], s76 offen
	buffer_load_ushort v190, v253, s[64:67], s76 offen
	s_add_i32 s72, s72, 0xfffff000
	s_max_i32 s72, s72, 0
	s_add_i32 s76, s76, 0xfffff800
	s_max_i32 s76, s76, 0
	v_and_b32_e32 v128, 63, v254
	v_mov_b32_e32 v129, 1.0
	v_mov_b32_e32 v0, 0
	v_mov_b32_e32 v1, 0
	v_mov_b32_e32 v2, 0
	v_mov_b32_e32 v3, 0
	v_mov_b32_e32 v4, 0
	v_mov_b32_e32 v5, 0
	v_mov_b32_e32 v6, 0
	v_mov_b32_e32 v7, 0
	v_mov_b32_e32 v8, 0
	v_mov_b32_e32 v9, 0
	v_mov_b32_e32 v10, 0
	v_mov_b32_e32 v11, 0
	v_mov_b32_e32 v12, 0
	v_mov_b32_e32 v13, 0
	v_mov_b32_e32 v14, 0
	v_mov_b32_e32 v15, 0
	v_mov_b32_e32 v16, 0
	v_mov_b32_e32 v17, 0
	v_mov_b32_e32 v18, 0
	v_mov_b32_e32 v19, 0
	v_mov_b32_e32 v20, 0
	v_mov_b32_e32 v21, 0
	v_mov_b32_e32 v22, 0
	v_mov_b32_e32 v23, 0
	v_mov_b32_e32 v24, 0
	v_mov_b32_e32 v25, 0
	v_mov_b32_e32 v26, 0
	v_mov_b32_e32 v27, 0
	v_mov_b32_e32 v28, 0
	v_mov_b32_e32 v29, 0
	v_mov_b32_e32 v30, 0
	v_mov_b32_e32 v31, 0
	v_mov_b32_e32 v32, 0
	v_mov_b32_e32 v33, 0
	v_mov_b32_e32 v34, 0
	v_mov_b32_e32 v35, 0
	v_mov_b32_e32 v36, 0
	v_mov_b32_e32 v37, 0
	v_mov_b32_e32 v38, 0
	v_mov_b32_e32 v39, 0
	v_mov_b32_e32 v40, 0
	v_mov_b32_e32 v41, 0
	v_mov_b32_e32 v42, 0
	v_mov_b32_e32 v43, 0
	v_mov_b32_e32 v44, 0
	v_mov_b32_e32 v45, 0
	v_mov_b32_e32 v46, 0
	v_mov_b32_e32 v47, 0
	v_mov_b32_e32 v48, 0
	v_mov_b32_e32 v49, 0
	v_mov_b32_e32 v50, 0
	v_mov_b32_e32 v51, 0
	v_mov_b32_e32 v52, 0
	v_mov_b32_e32 v53, 0
	v_mov_b32_e32 v54, 0
	v_mov_b32_e32 v55, 0
	v_mov_b32_e32 v56, 0
	v_mov_b32_e32 v57, 0
	v_mov_b32_e32 v58, 0
	v_mov_b32_e32 v59, 0
	v_mov_b32_e32 v60, 0
	v_mov_b32_e32 v61, 0
	v_mov_b32_e32 v62, 0
	v_mov_b32_e32 v63, 0
	v_cmp_eq_u32_e32 vcc, 0, v128
	s_nop 1
	v_cndmask_b32_e32 v64, 0, v129, vcc
	v_cmp_eq_u32_e32 vcc, 1, v128
	s_nop 1
	v_cndmask_b32_e32 v65, 0, v129, vcc
	v_cmp_eq_u32_e32 vcc, 2, v128
	s_nop 1
	v_cndmask_b32_e32 v66, 0, v129, vcc
	v_cmp_eq_u32_e32 vcc, 3, v128
	s_nop 1
	v_cndmask_b32_e32 v67, 0, v129, vcc
	v_cmp_eq_u32_e32 vcc, 4, v128
	s_nop 1
	v_cndmask_b32_e32 v68, 0, v129, vcc
	v_cmp_eq_u32_e32 vcc, 5, v128
	s_nop 1
	v_cndmask_b32_e32 v69, 0, v129, vcc
	v_cmp_eq_u32_e32 vcc, 6, v128
	s_nop 1
	v_cndmask_b32_e32 v70, 0, v129, vcc
	v_cmp_eq_u32_e32 vcc, 7, v128
	s_nop 1
	v_cndmask_b32_e32 v71, 0, v129, vcc
	v_cmp_eq_u32_e32 vcc, 8, v128
	s_nop 1
; #define SB __builtin_amdgcn_sched_barrier(0)
; #define MKR(ptr) __builtin_amdgcn_make_buffer_rsrc((void*)(ptr), 0, 0x7fffffff, 0x00027000)
; #define LD1(set, s) { const int e_ = min((int)(s), LC - 1) * (int)stp; const unsigned s4_ = ob4 + (unsigned)(e_ * 4), s2_ = ob2 + (unsigned)(e_ * 2); set.w = LDX(rW, s4_); set.a = LDX(rA, s4_); set.b = LDX(rB, s4_); \
;             set.kw = __builtin_amdgcn_raw_buffer_load_b64(rK, lo8, s2_, 0); set.v = __builtin_amdgcn_raw_buffer_load_b16(rV, lo2, s2_, 0); }
; #define TOUCH1(set) asm volatile("" :: "v"(set.w), "v"(set.a), "v"(set.b), "v"(set.kw), "v"(set.v))
; #define ST1(set) { DERIVE_BK(set); float sd[4]; ScanK<0>::dot(S, set.a, sd); ScanK<0>::updS(S, set, -((sd[0] + sd[1]) + (sd[2] + sd[3])), __uint_as_float(set.v << 16)); }
; #define LD1(set, s) { const int e_ = min((int)(s), LC - 1) * (int)stp; const unsigned s4_ = ob4 + (unsigned)(e_ * 4); set.w = LDX(rW, s4_); set.a = LDX(rA, s4_); set.b = LDX(rB, s4_); }
; #define TOUCH1(set) asm volatile("" :: "v"(set.w), "v"(set.a), "v"(set.b))
; #define ST1(set) { DERIVE_B(set); float sd[4]; ScanK<0>::dot(S, set.a, sd); ScanK<0>::updP(S, set, -((sd[0] + sd[1]) + (sd[2] + sd[3]))); }
; template <bool MIX> __device__ __forceinline__ void scan_pass1(const Params& p, int d, float* ldsf) {
;     ...
;         const f32x4 ka4 = *(const f32x4*)(p.k_a + h * 64 + (lane & 15) * 4), c04 = 1.0f - ka4;
;         float S[64]; int ln = lane; asm volatile("" : "+v"(ln));
;     ...
;         const __amdgpu_buffer_rsrc_t rW = MKR(Wd), rA = MKR(A), rB = MKR(Bd), rK = MKR(KB), rV = MKR(V);
;         if (!isP) {
; #pragma unroll
;             for (int i = 0; i < 64; ++i) S[i] = 0.f;
;     ...
;             In1 i0, i1; LD1(i0, 0);
; #pragma unroll 1
;             for (int s = 0; s < LC; s += 2) { TOUCH1(i0); SB; LD1(i1, s + 1); SB; ST1(i0); TOUCH1(i1); SB; LD1(i0, s + 2); SB; ST1(i1); }
;     ...
;         } else {
; #pragma unroll
;             for (int i = 0; i < 64; ++i) S[i] = (ln == i) ? 1.f : 0.f;
	v_cndmask_b32_e32 v72, 0, v129, vcc
	v_cmp_eq_u32_e32 vcc, 9, v128
	s_nop 1
	v_cndmask_b32_e32 v73, 0, v129, vcc
	v_cmp_eq_u32_e32 vcc, 10, v128
	s_nop 1
	v_cndmask_b32_e32 v74, 0, v129, vcc
	v_cmp_eq_u32_e32 vcc, 11, v128
	s_nop 1
	v_cndmask_b32_e32 v75, 0, v129, vcc
	v_cmp_eq_u32_e32 vcc, 12, v128
	s_nop 1
	v_cndmask_b32_e32 v76, 0, v129, vcc
	v_cmp_eq_u32_e32 vcc, 13, v128
	s_nop 1
	v_cndmask_b32_e32 v77, 0, v129, vcc
	v_cmp_eq_u32_e32 vcc, 14, v128
	s_nop 1
	v_cndmask_b32_e32 v78, 0, v129, vcc
	v_cmp_eq_u32_e32 vcc, 15, v128
	s_nop 1
	v_cndmask_b32_e32 v79, 0, v129, vcc
	v_cmp_eq_u32_e32 vcc, 16, v128
	s_nop 1
	v_cndmask_b32_e32 v80, 0, v129, vcc
	v_cmp_eq_u32_e32 vcc, 17, v128
	s_nop 1
	v_cndmask_b32_e32 v81, 0, v129, vcc
	v_cmp_eq_u32_e32 vcc, 18, v128
	s_nop 1
	v_cndmask_b32_e32 v82, 0, v129, vcc
	v_cmp_eq_u32_e32 vcc, 19, v128
	s_nop 1
	v_cndmask_b32_e32 v83, 0, v129, vcc
	v_cmp_eq_u32_e32 vcc, 20, v128
	s_nop 1
	v_cndmask_b32_e32 v84, 0, v129, vcc
	v_cmp_eq_u32_e32 vcc, 21, v128
	s_nop 1
	v_cndmask_b32_e32 v85, 0, v129, vcc
	v_cmp_eq_u32_e32 vcc, 22, v128
	s_nop 1
	v_cndmask_b32_e32 v86, 0, v129, vcc
	v_cmp_eq_u32_e32 vcc, 23, v128
	s_nop 1
	v_cndmask_b32_e32 v87, 0, v129, vcc
	v_cmp_eq_u32_e32 vcc, 24, v128
	s_nop 1
	v_cndmask_b32_e32 v88, 0, v129, vcc
	v_cmp_eq_u32_e32 vcc, 25, v128
	s_nop 1
	v_cndmask_b32_e32 v89, 0, v129, vcc
	v_cmp_eq_u32_e32 vcc, 26, v128
	s_nop 1
	v_cndmask_b32_e32 v90, 0, v129, vcc
	v_cmp_eq_u32_e32 vcc, 27, v128
	s_nop 1
	v_cndmask_b32_e32 v91, 0, v129, vcc
	v_cmp_eq_u32_e32 vcc, 28, v128
	s_nop 1
	v_cndmask_b32_e32 v92, 0, v129, vcc
	v_cmp_eq_u32_e32 vcc, 29, v128
	s_nop 1
	v_cndmask_b32_e32 v93, 0, v129, vcc
	v_cmp_eq_u32_e32 vcc, 30, v128
	s_nop 1
	v_cndmask_b32_e32 v94, 0, v129, vcc
	v_cmp_eq_u32_e32 vcc, 31, v128
	s_nop 1
	v_cndmask_b32_e32 v95, 0, v129, vcc
	v_cmp_eq_u32_e32 vcc, 32, v128
	s_nop 1
	v_cndmask_b32_e32 v96, 0, v129, vcc
	v_cmp_eq_u32_e32 vcc, 33, v128
	s_nop 1
	v_cndmask_b32_e32 v97, 0, v129, vcc
	v_cmp_eq_u32_e32 vcc, 34, v128
	s_nop 1
	v_cndmask_b32_e32 v98, 0, v129, vcc
	v_cmp_eq_u32_e32 vcc, 35, v128
	s_nop 1
	v_cndmask_b32_e32 v99, 0, v129, vcc
	v_cmp_eq_u32_e32 vcc, 36, v128
	s_nop 1
	v_cndmask_b32_e32 v100, 0, v129, vcc
	v_cmp_eq_u32_e32 vcc, 37, v128
	s_nop 1
	v_cndmask_b32_e32 v101, 0, v129, vcc
	v_cmp_eq_u32_e32 vcc, 38, v128
	s_nop 1
	v_cndmask_b32_e32 v102, 0, v129, vcc
	v_cmp_eq_u32_e32 vcc, 39, v128
	s_nop 1
	v_cndmask_b32_e32 v103, 0, v129, vcc
	v_cmp_eq_u32_e32 vcc, 40, v128
	s_nop 1
	v_cndmask_b32_e32 v104, 0, v129, vcc
	v_cmp_eq_u32_e32 vcc, 41, v128
	s_nop 1
	v_cndmask_b32_e32 v105, 0, v129, vcc
	v_cmp_eq_u32_e32 vcc, 42, v128
	s_nop 1
	v_cndmask_b32_e32 v106, 0, v129, vcc
	v_cmp_eq_u32_e32 vcc, 43, v128
	s_nop 1
	v_cndmask_b32_e32 v107, 0, v129, vcc
	v_cmp_eq_u32_e32 vcc, 44, v128
	s_nop 1
	v_cndmask_b32_e32 v108, 0, v129, vcc
	v_cmp_eq_u32_e32 vcc, 45, v128
	s_nop 1
	v_cndmask_b32_e32 v109, 0, v129, vcc
	v_cmp_eq_u32_e32 vcc, 46, v128
	s_nop 1
	v_cndmask_b32_e32 v110, 0, v129, vcc
	v_cmp_eq_u32_e32 vcc, 47, v128
	s_nop 1
	v_cndmask_b32_e32 v111, 0, v129, vcc
	v_cmp_eq_u32_e32 vcc, 48, v128
	s_nop 1
	v_cndmask_b32_e32 v112, 0, v129, vcc
	v_cmp_eq_u32_e32 vcc, 49, v128
	s_nop 1
	v_cndmask_b32_e32 v113, 0, v129, vcc
	v_cmp_eq_u32_e32 vcc, 50, v128
	s_nop 1
	v_cndmask_b32_e32 v114, 0, v129, vcc
	v_cmp_eq_u32_e32 vcc, 51, v128
	s_nop 1
	v_cndmask_b32_e32 v115, 0, v129, vcc
	v_cmp_eq_u32_e32 vcc, 52, v128
	s_nop 1
	v_cndmask_b32_e32 v116, 0, v129, vcc
	v_cmp_eq_u32_e32 vcc, 53, v128
	s_nop 1
	v_cndmask_b32_e32 v117, 0, v129, vcc
	v_cmp_eq_u32_e32 vcc, 54, v128
	s_nop 1
	v_cndmask_b32_e32 v118, 0, v129, vcc
	v_cmp_eq_u32_e32 vcc, 55, v128
	s_nop 1
	v_cndmask_b32_e32 v119, 0, v129, vcc
	v_cmp_eq_u32_e32 vcc, 56, v128
	s_nop 1
	v_cndmask_b32_e32 v120, 0, v129, vcc
	v_cmp_eq_u32_e32 vcc, 57, v128
	s_nop 1
	v_cndmask_b32_e32 v121, 0, v129, vcc
	v_cmp_eq_u32_e32 vcc, 58, v128
	s_nop 1
	v_cndmask_b32_e32 v122, 0, v129, vcc
	v_cmp_eq_u32_e32 vcc, 59, v128
	s_nop 1
	v_cndmask_b32_e32 v123, 0, v129, vcc
	v_cmp_eq_u32_e32 vcc, 60, v128
	s_nop 1
	v_cndmask_b32_e32 v124, 0, v129, vcc
	v_cmp_eq_u32_e32 vcc, 61, v128
	s_nop 1
	v_cndmask_b32_e32 v125, 0, v129, vcc
	v_cmp_eq_u32_e32 vcc, 62, v128
	s_nop 1
	v_cndmask_b32_e32 v126, 0, v129, vcc
	v_cmp_eq_u32_e32 vcc, 63, v128
	s_nop 1
	v_cndmask_b32_e32 v127, 0, v129, vcc
	s_waitcnt vmcnt(0)
	v_sub_f32_e32 v220, 1.0, v216
	v_sub_f32_e32 v221, 1.0, v217
	v_sub_f32_e32 v222, 1.0, v218
	v_sub_f32_e32 v223, 1.0, v219
	v_mov_b32_e32 v236, 1.0
	v_mov_b32_e32 v237, 1.0
	v_mov_b32_e32 v238, 1.0
	v_mov_b32_e32 v239, 1.0
	s_movk_i32 s83, 85
	s_movk_i32 s9, 11
	s_branch .Lmy_p1d1_loop

; #define SB __builtin_amdgcn_sched_barrier(0)
; #define TOUCH1(set) asm volatile("" :: "v"(set.w), "v"(set.a), "v"(set.b), "v"(set.kw), "v"(set.v))
; #define ST1(set) { DERIVE_BK(set); float sd[4]; ScanK<0>::dot(S, set.a, sd); ScanK<0>::updS(S, set, -((sd[0] + sd[1]) + (sd[2] + sd[3])), __uint_as_float(set.v << 16)); }
; #define TOUCH1(set) asm volatile("" :: "v"(set.w), "v"(set.a), "v"(set.b))
;     static __device__ __forceinline__ void dot(const float (&S)[64], const f32x4& a, float (&s)[4]) {
;         if constexpr (K == 0) {
;             asm volatile("v_mul_f32_dpp %0, %4, %8 row_newbcast:%16" DPPM "v_mul_f32_dpp %1, %5, %9 row_newbcast:%16" DPPM "v_mul_f32_dpp %2, %6, %10 row_newbcast:%16" DPPM "v_mul_f32_dpp %3, %7, %11 row_newbcast:%16" DPPM
;                          "v_fmac_f32_dpp %0, %4, %12 row_newbcast:%17" DPPM "v_fmac_f32_dpp %1, %5, %13 row_newbcast:%17" DPPM "v_fmac_f32_dpp %2, %6, %14 row_newbcast:%17" DPPM "v_fmac_f32_dpp %3, %7, %15 row_newbcast:%17" DPPM
;                          : "=&v"(s[0]), "=&v"(s[1]), "=&v"(s[2]), "=&v"(s[3])
;                          : "v"(a[0]), "v"(a[1]), "v"(a[2]), "v"(a[3]), "v"(S[K]), "v"(S[K + 1]), "v"(S[K + 2]), "v"(S[K + 3]), "v"(S[K + 4]), "v"(S[K + 5]), "v"(S[K + 6]), "v"(S[K + 7]), "n"(N0), "n"(N1));
;         } else
;         asm volatile("v_fmac_f32_dpp %0, %4, %8 row_newbcast:%16" DPPM "v_fmac_f32_dpp %1, %5, %9 row_newbcast:%16" DPPM "v_fmac_f32_dpp %2, %6, %10 row_newbcast:%16" DPPM "v_fmac_f32_dpp %3, %7, %11 row_newbcast:%16" DPPM
;                      "v_fmac_f32_dpp %0, %4, %12 row_newbcast:%17" DPPM "v_fmac_f32_dpp %1, %5, %13 row_newbcast:%17" DPPM "v_fmac_f32_dpp %2, %6, %14 row_newbcast:%17" DPPM "v_fmac_f32_dpp %3, %7, %15 row_newbcast:%17" DPPM
;                      : "+v"(s[0]), "+v"(s[1]), "+v"(s[2]), "+v"(s[3])
;                      : "v"(a[0]), "v"(a[1]), "v"(a[2]), "v"(a[3]), "v"(S[K]), "v"(S[K + 1]), "v"(S[K + 2]), "v"(S[K + 3]), "v"(S[K + 4]), "v"(S[K + 5]), "v"(S[K + 6]), "v"(S[K + 7]), "n"(N0), "n"(N1));
;         if constexpr (K + 8 < 64) ScanK<K + 8>::dot(S, a, s);
; template <bool MIX> __device__ __forceinline__ void scan_pass1(const Params& p, int d, float* ldsf) {
;     ...
;             In1 i0, i1; LD1(i0, 0);
; #pragma unroll 1
;             for (int s = 0; s < LC; s += 2) { TOUCH1(i0); SB; LD1(i1, s + 1); SB; ST1(i0); TOUCH1(i1); SB; LD1(i0, s + 2); SB; ST1(i1); }
.Lmy_p1d1_loop:
	s_waitcnt vmcnt(5)
	buffer_load_dwordx4 v[192:195], v235, s[64:67], s72 offen
	buffer_load_dwordx4 v[196:199], v250, s[64:67], s72 offen
	buffer_load_dwordx4 v[200:203], v251, s[64:67], s72 offen
	buffer_load_dwordx2 v[204:205], v252, s[64:67], s76 offen
	buffer_load_ushort v206, v253, s[64:67], s76 offen
	s_add_i32 s72, s72, 0xfffff000
	s_max_i32 s72, s72, 0
	s_add_i32 s76, s76, 0xfffff800
	s_max_i32 s76, s76, 0
	v_pk_mul_f32 v[244:245], v[164:165], v[236:237]
	v_pk_mul_f32 v[246:247], v[166:167], v[238:239]
	v_pk_mul_f32 v[236:237], v[236:237], v[160:161]
	v_pk_mul_f32 v[238:239], v[238:239], v[162:163]
	v_pk_fma_f32 v[228:229], v[168:169], v[216:217], v[220:221]
	v_pk_fma_f32 v[230:231], v[170:171], v[218:219], v[222:223]
	v_pk_mul_f32 v[208:209], v[164:165], v[168:169]
	v_pk_mul_f32 v[210:211], v[166:167], v[170:171]
	v_rcp_f32_e32 v240, v236
	v_rcp_f32_e32 v241, v237
	v_rcp_f32_e32 v242, v238
	v_rcp_f32_e32 v243, v239
	v_lshlrev_b32_e32 v212, 16, v172
	v_and_b32_e32 v213, 0xffff0000, v172
	v_lshlrev_b32_e32 v214, 16, v173
	v_and_b32_e32 v215, 0xffff0000, v173
	v_pk_mul_f32 v[212:213], v[212:213], v[228:229]
	v_pk_mul_f32 v[214:215], v[214:215], v[230:231]
	v_lshlrev_b32_e32 v234, 16, v174
	v_pk_mul_f32 v[208:209], v[208:209], v[240:241]
	v_pk_mul_f32 v[210:211], v[210:211], v[242:243]
	v_pk_mul_f32 v[212:213], v[212:213], v[240:241]
	v_pk_mul_f32 v[214:215], v[214:215], v[242:243]
	ds_write2_b32 v248, v208, v209 offset0:0 offset1:16
	ds_write2_b32 v248, v210, v211 offset0:32 offset1:48
	ds_write2_b32 v248, v212, v213 offset0:64 offset1:80
	ds_write2_b32 v248, v214, v215 offset0:96 offset1:112
	ds_read_b128 v[128:131], v249 offset:0
	ds_read_b128 v[132:135], v249 offset:16
	ds_read_b128 v[136:139], v249 offset:32
	ds_read_b128 v[140:143], v249 offset:48
	ds_read_b128 v[144:147], v249 offset:256
	ds_read_b128 v[148:151], v249 offset:272
	ds_read_b128 v[152:155], v249 offset:288
	ds_read_b128 v[156:159], v249 offset:304
	v_mul_f32_dpp v224, v244, v0 row_newbcast:0 row_mask:0xf bank_mask:0xf
	v_mul_f32_dpp v225, v245, v1 row_newbcast:0 row_mask:0xf bank_mask:0xf
	v_mul_f32_dpp v226, v246, v2 row_newbcast:0 row_mask:0xf bank_mask:0xf
	v_mul_f32_dpp v227, v247, v3 row_newbcast:0 row_mask:0xf bank_mask:0xf
	v_fmac_f32_dpp v224, v244, v4 row_newbcast:1 row_mask:0xf bank_mask:0xf
	v_fmac_f32_dpp v225, v245, v5 row_newbcast:1 row_mask:0xf bank_mask:0xf
	v_fmac_f32_dpp v226, v246, v6 row_newbcast:1 row_mask:0xf bank_mask:0xf
	v_fmac_f32_dpp v227, v247, v7 row_newbcast:1 row_mask:0xf bank_mask:0xf
	v_fmac_f32_dpp v224, v244, v8 row_newbcast:2 row_mask:0xf bank_mask:0xf
	v_fmac_f32_dpp v225, v245, v9 row_newbcast:2 row_mask:0xf bank_mask:0xf
	v_fmac_f32_dpp v226, v246, v10 row_newbcast:2 row_mask:0xf bank_mask:0xf
	v_fmac_f32_dpp v227, v247, v11 row_newbcast:2 row_mask:0xf bank_mask:0xf
	v_fmac_f32_dpp v224, v244, v12 row_newbcast:3 row_mask:0xf bank_mask:0xf
	v_fmac_f32_dpp v225, v245, v13 row_newbcast:3 row_mask:0xf bank_mask:0xf
	v_fmac_f32_dpp v226, v246, v14 row_newbcast:3 row_mask:0xf bank_mask:0xf
	v_fmac_f32_dpp v227, v247, v15 row_newbcast:3 row_mask:0xf bank_mask:0xf
	v_fmac_f32_dpp v224, v244, v16 row_newbcast:4 row_mask:0xf bank_mask:0xf
	v_fmac_f32_dpp v225, v245, v17 row_newbcast:4 row_mask:0xf bank_mask:0xf
	v_fmac_f32_dpp v226, v246, v18 row_newbcast:4 row_mask:0xf bank_mask:0xf
	v_fmac_f32_dpp v227, v247, v19 row_newbcast:4 row_mask:0xf bank_mask:0xf
	v_fmac_f32_dpp v224, v244, v20 row_newbcast:5 row_mask:0xf bank_mask:0xf
	v_fmac_f32_dpp v225, v245, v21 row_newbcast:5 row_mask:0xf bank_mask:0xf
	v_fmac_f32_dpp v226, v246, v22 row_newbcast:5 row_mask:0xf bank_mask:0xf
	v_fmac_f32_dpp v227, v247, v23 row_newbcast:5 row_mask:0xf bank_mask:0xf
	v_fmac_f32_dpp v224, v244, v24 row_newbcast:6 row_mask:0xf bank_mask:0xf
	v_fmac_f32_dpp v225, v245, v25 row_newbcast:6 row_mask:0xf bank_mask:0xf
	v_fmac_f32_dpp v226, v246, v26 row_newbcast:6 row_mask:0xf bank_mask:0xf
	v_fmac_f32_dpp v227, v247, v27 row_newbcast:6 row_mask:0xf bank_mask:0xf
	v_fmac_f32_dpp v224, v244, v28 row_newbcast:7 row_mask:0xf bank_mask:0xf
	v_fmac_f32_dpp v225, v245, v29 row_newbcast:7 row_mask:0xf bank_mask:0xf
	v_fmac_f32_dpp v226, v246, v30 row_newbcast:7 row_mask:0xf bank_mask:0xf
	v_fmac_f32_dpp v227, v247, v31 row_newbcast:7 row_mask:0xf bank_mask:0xf
	v_fmac_f32_dpp v224, v244, v32 row_newbcast:8 row_mask:0xf bank_mask:0xf
	v_fmac_f32_dpp v225, v245, v33 row_newbcast:8 row_mask:0xf bank_mask:0xf
	v_fmac_f32_dpp v226, v246, v34 row_newbcast:8 row_mask:0xf bank_mask:0xf
	v_fmac_f32_dpp v227, v247, v35 row_newbcast:8 row_mask:0xf bank_mask:0xf
	v_fmac_f32_dpp v224, v244, v36 row_newbcast:9 row_mask:0xf bank_mask:0xf
	v_fmac_f32_dpp v225, v245, v37 row_newbcast:9 row_mask:0xf bank_mask:0xf
	v_fmac_f32_dpp v226, v246, v38 row_newbcast:9 row_mask:0xf bank_mask:0xf
	v_fmac_f32_dpp v227, v247, v39 row_newbcast:9 row_mask:0xf bank_mask:0xf
	v_fmac_f32_dpp v224, v244, v40 row_newbcast:10 row_mask:0xf bank_mask:0xf
	v_fmac_f32_dpp v225, v245, v41 row_newbcast:10 row_mask:0xf bank_mask:0xf
	v_fmac_f32_dpp v226, v246, v42 row_newbcast:10 row_mask:0xf bank_mask:0xf
	v_fmac_f32_dpp v227, v247, v43 row_newbcast:10 row_mask:0xf bank_mask:0xf
	v_fmac_f32_dpp v224, v244, v44 row_newbcast:11 row_mask:0xf bank_mask:0xf
	v_fmac_f32_dpp v225, v245, v45 row_newbcast:11 row_mask:0xf bank_mask:0xf
	v_fmac_f32_dpp v226, v246, v46 row_newbcast:11 row_mask:0xf bank_mask:0xf
	v_fmac_f32_dpp v227, v247, v47 row_newbcast:11 row_mask:0xf bank_mask:0xf
	v_fmac_f32_dpp v224, v244, v48 row_newbcast:12 row_mask:0xf bank_mask:0xf
	v_fmac_f32_dpp v225, v245, v49 row_newbcast:12 row_mask:0xf bank_mask:0xf
; #define SB __builtin_amdgcn_sched_barrier(0)
; #define TOUCH1(set) asm volatile("" :: "v"(set.w), "v"(set.a), "v"(set.b), "v"(set.kw), "v"(set.v))
; #define TOUCH1(set) asm volatile("" :: "v"(set.w), "v"(set.a), "v"(set.b))
;     static __device__ __forceinline__ void dot(const float (&S)[64], const f32x4& a, float (&s)[4]) {
;         if constexpr (K == 0) {
;             asm volatile("v_mul_f32_dpp %0, %4, %8 row_newbcast:%16" DPPM "v_mul_f32_dpp %1, %5, %9 row_newbcast:%16" DPPM "v_mul_f32_dpp %2, %6, %10 row_newbcast:%16" DPPM "v_mul_f32_dpp %3, %7, %11 row_newbcast:%16" DPPM
;                          "v_fmac_f32_dpp %0, %4, %12 row_newbcast:%17" DPPM "v_fmac_f32_dpp %1, %5, %13 row_newbcast:%17" DPPM "v_fmac_f32_dpp %2, %6, %14 row_newbcast:%17" DPPM "v_fmac_f32_dpp %3, %7, %15 row_newbcast:%17" DPPM
;                          : "=&v"(s[0]), "=&v"(s[1]), "=&v"(s[2]), "=&v"(s[3])
;                          : "v"(a[0]), "v"(a[1]), "v"(a[2]), "v"(a[3]), "v"(S[K]), "v"(S[K + 1]), "v"(S[K + 2]), "v"(S[K + 3]), "v"(S[K + 4]), "v"(S[K + 5]), "v"(S[K + 6]), "v"(S[K + 7]), "n"(N0), "n"(N1));
;         } else
;         asm volatile("v_fmac_f32_dpp %0, %4, %8 row_newbcast:%16" DPPM "v_fmac_f32_dpp %1, %5, %9 row_newbcast:%16" DPPM "v_fmac_f32_dpp %2, %6, %10 row_newbcast:%16" DPPM "v_fmac_f32_dpp %3, %7, %11 row_newbcast:%16" DPPM
;                      "v_fmac_f32_dpp %0, %4, %12 row_newbcast:%17" DPPM "v_fmac_f32_dpp %1, %5, %13 row_newbcast:%17" DPPM "v_fmac_f32_dpp %2, %6, %14 row_newbcast:%17" DPPM "v_fmac_f32_dpp %3, %7, %15 row_newbcast:%17" DPPM
;                      : "+v"(s[0]), "+v"(s[1]), "+v"(s[2]), "+v"(s[3])
;                      : "v"(a[0]), "v"(a[1]), "v"(a[2]), "v"(a[3]), "v"(S[K]), "v"(S[K + 1]), "v"(S[K + 2]), "v"(S[K + 3]), "v"(S[K + 4]), "v"(S[K + 5]), "v"(S[K + 6]), "v"(S[K + 7]), "n"(N0), "n"(N1));
;         if constexpr (K + 8 < 64) ScanK<K + 8>::dot(S, a, s);
; template <bool MIX> __device__ __forceinline__ void scan_pass1(const Params& p, int d, float* ldsf) {
;     ...
;             In1 i0, i1; LD1(i0, 0);
; #pragma unroll 1
;             for (int s = 0; s < LC; s += 2) { TOUCH1(i0); SB; LD1(i1, s + 1); SB; ST1(i0); TOUCH1(i1); SB; LD1(i0, s + 2); SB; ST1(i1); }
;     ...
;         } else {
; #pragma unroll
;             for (int i = 0; i < 64; ++i) S[i] = (ln == i) ? 1.f : 0.f;
	v_fmac_f32_dpp v226, v246, v50 row_newbcast:12 row_mask:0xf bank_mask:0xf
	v_fmac_f32_dpp v227, v247, v51 row_newbcast:12 row_mask:0xf bank_mask:0xf
	v_fmac_f32_dpp v224, v244, v52 row_newbcast:13 row_mask:0xf bank_mask:0xf
	v_fmac_f32_dpp v225, v245, v53 row_newbcast:13 row_mask:0xf bank_mask:0xf
	v_fmac_f32_dpp v226, v246, v54 row_newbcast:13 row_mask:0xf bank_mask:0xf
	v_fmac_f32_dpp v227, v247, v55 row_newbcast:13 row_mask:0xf bank_mask:0xf
	v_fmac_f32_dpp v224, v244, v56 row_newbcast:14 row_mask:0xf bank_mask:0xf
	v_fmac_f32_dpp v225, v245, v57 row_newbcast:14 row_mask:0xf bank_mask:0xf
	v_fmac_f32_dpp v226, v246, v58 row_newbcast:14 row_mask:0xf bank_mask:0xf
	v_fmac_f32_dpp v227, v247, v59 row_newbcast:14 row_mask:0xf bank_mask:0xf
	v_fmac_f32_dpp v224, v244, v60 row_newbcast:15 row_mask:0xf bank_mask:0xf
	v_fmac_f32_dpp v225, v245, v61 row_newbcast:15 row_mask:0xf bank_mask:0xf
	v_fmac_f32_dpp v226, v246, v62 row_newbcast:15 row_mask:0xf bank_mask:0xf
	v_fmac_f32_dpp v227, v247, v63 row_newbcast:15 row_mask:0xf bank_mask:0xf
	v_mul_f32_dpp v228, v244, v64 row_newbcast:0 row_mask:0xf bank_mask:0xf
	v_mul_f32_dpp v229, v245, v65 row_newbcast:0 row_mask:0xf bank_mask:0xf
	v_mul_f32_dpp v230, v246, v66 row_newbcast:0 row_mask:0xf bank_mask:0xf
	v_mul_f32_dpp v231, v247, v67 row_newbcast:0 row_mask:0xf bank_mask:0xf
	v_fmac_f32_dpp v228, v244, v68 row_newbcast:1 row_mask:0xf bank_mask:0xf
	v_fmac_f32_dpp v229, v245, v69 row_newbcast:1 row_mask:0xf bank_mask:0xf
	v_fmac_f32_dpp v230, v246, v70 row_newbcast:1 row_mask:0xf bank_mask:0xf
	v_fmac_f32_dpp v231, v247, v71 row_newbcast:1 row_mask:0xf bank_mask:0xf
	v_fmac_f32_dpp v228, v244, v72 row_newbcast:2 row_mask:0xf bank_mask:0xf
	v_fmac_f32_dpp v229, v245, v73 row_newbcast:2 row_mask:0xf bank_mask:0xf
	v_fmac_f32_dpp v230, v246, v74 row_newbcast:2 row_mask:0xf bank_mask:0xf
	v_fmac_f32_dpp v231, v247, v75 row_newbcast:2 row_mask:0xf bank_mask:0xf
	v_fmac_f32_dpp v228, v244, v76 row_newbcast:3 row_mask:0xf bank_mask:0xf
	v_fmac_f32_dpp v229, v245, v77 row_newbcast:3 row_mask:0xf bank_mask:0xf
	v_fmac_f32_dpp v230, v246, v78 row_newbcast:3 row_mask:0xf bank_mask:0xf
	v_fmac_f32_dpp v231, v247, v79 row_newbcast:3 row_mask:0xf bank_mask:0xf
	v_fmac_f32_dpp v228, v244, v80 row_newbcast:4 row_mask:0xf bank_mask:0xf
	v_fmac_f32_dpp v229, v245, v81 row_newbcast:4 row_mask:0xf bank_mask:0xf
	v_fmac_f32_dpp v230, v246, v82 row_newbcast:4 row_mask:0xf bank_mask:0xf
	v_fmac_f32_dpp v231, v247, v83 row_newbcast:4 row_mask:0xf bank_mask:0xf
	v_fmac_f32_dpp v228, v244, v84 row_newbcast:5 row_mask:0xf bank_mask:0xf
	v_fmac_f32_dpp v229, v245, v85 row_newbcast:5 row_mask:0xf bank_mask:0xf
	v_fmac_f32_dpp v230, v246, v86 row_newbcast:5 row_mask:0xf bank_mask:0xf
	v_fmac_f32_dpp v231, v247, v87 row_newbcast:5 row_mask:0xf bank_mask:0xf
	v_fmac_f32_dpp v228, v244, v88 row_newbcast:6 row_mask:0xf bank_mask:0xf
	v_fmac_f32_dpp v229, v245, v89 row_newbcast:6 row_mask:0xf bank_mask:0xf
	v_fmac_f32_dpp v230, v246, v90 row_newbcast:6 row_mask:0xf bank_mask:0xf
	v_fmac_f32_dpp v231, v247, v91 row_newbcast:6 row_mask:0xf bank_mask:0xf
	v_fmac_f32_dpp v228, v244, v92 row_newbcast:7 row_mask:0xf bank_mask:0xf
	v_fmac_f32_dpp v229, v245, v93 row_newbcast:7 row_mask:0xf bank_mask:0xf
	v_fmac_f32_dpp v230, v246, v94 row_newbcast:7 row_mask:0xf bank_mask:0xf
	v_fmac_f32_dpp v231, v247, v95 row_newbcast:7 row_mask:0xf bank_mask:0xf
	v_fmac_f32_dpp v228, v244, v96 row_newbcast:8 row_mask:0xf bank_mask:0xf
	v_fmac_f32_dpp v229, v245, v97 row_newbcast:8 row_mask:0xf bank_mask:0xf
	v_fmac_f32_dpp v230, v246, v98 row_newbcast:8 row_mask:0xf bank_mask:0xf
	v_fmac_f32_dpp v231, v247, v99 row_newbcast:8 row_mask:0xf bank_mask:0xf
	v_fmac_f32_dpp v228, v244, v100 row_newbcast:9 row_mask:0xf bank_mask:0xf
	v_fmac_f32_dpp v229, v245, v101 row_newbcast:9 row_mask:0xf bank_mask:0xf
	v_fmac_f32_dpp v230, v246, v102 row_newbcast:9 row_mask:0xf bank_mask:0xf
	v_fmac_f32_dpp v231, v247, v103 row_newbcast:9 row_mask:0xf bank_mask:0xf
	v_fmac_f32_dpp v228, v244, v104 row_newbcast:10 row_mask:0xf bank_mask:0xf
	v_fmac_f32_dpp v229, v245, v105 row_newbcast:10 row_mask:0xf bank_mask:0xf
	v_fmac_f32_dpp v230, v246, v106 row_newbcast:10 row_mask:0xf bank_mask:0xf
	v_fmac_f32_dpp v231, v247, v107 row_newbcast:10 row_mask:0xf bank_mask:0xf
	v_fmac_f32_dpp v228, v244, v108 row_newbcast:11 row_mask:0xf bank_mask:0xf
	v_fmac_f32_dpp v229, v245, v109 row_newbcast:11 row_mask:0xf bank_mask:0xf
	v_fmac_f32_dpp v230, v246, v110 row_newbcast:11 row_mask:0xf bank_mask:0xf
	v_fmac_f32_dpp v231, v247, v111 row_newbcast:11 row_mask:0xf bank_mask:0xf
	v_fmac_f32_dpp v228, v244, v112 row_newbcast:12 row_mask:0xf bank_mask:0xf
	v_fmac_f32_dpp v229, v245, v113 row_newbcast:12 row_mask:0xf bank_mask:0xf
	v_fmac_f32_dpp v230, v246, v114 row_newbcast:12 row_mask:0xf bank_mask:0xf
	v_fmac_f32_dpp v231, v247, v115 row_newbcast:12 row_mask:0xf bank_mask:0xf
	v_fmac_f32_dpp v228, v244, v116 row_newbcast:13 row_mask:0xf bank_mask:0xf
	v_fmac_f32_dpp v229, v245, v117 row_newbcast:13 row_mask:0xf bank_mask:0xf
	v_fmac_f32_dpp v230, v246, v118 row_newbcast:13 row_mask:0xf bank_mask:0xf
	v_fmac_f32_dpp v231, v247, v119 row_newbcast:13 row_mask:0xf bank_mask:0xf
	v_fmac_f32_dpp v228, v244, v120 row_newbcast:14 row_mask:0xf bank_mask:0xf
	v_fmac_f32_dpp v229, v245, v121 row_newbcast:14 row_mask:0xf bank_mask:0xf
	v_fmac_f32_dpp v230, v246, v122 row_newbcast:14 row_mask:0xf bank_mask:0xf
	v_fmac_f32_dpp v231, v247, v123 row_newbcast:14 row_mask:0xf bank_mask:0xf
	v_fmac_f32_dpp v228, v244, v124 row_newbcast:15 row_mask:0xf bank_mask:0xf
	v_fmac_f32_dpp v229, v245, v125 row_newbcast:15 row_mask:0xf bank_mask:0xf
	v_fmac_f32_dpp v230, v246, v126 row_newbcast:15 row_mask:0xf bank_mask:0xf
	v_fmac_f32_dpp v231, v247, v127 row_newbcast:15 row_mask:0xf bank_mask:0xf
	v_add_f32_e32 v224, v224, v225
	v_add_f32_e32 v226, v226, v227
	v_sub_f32_e64 v232, -v224, v226
	v_add_f32_e32 v228, v228, v229
	v_add_f32_e32 v230, v230, v231
	v_sub_f32_e64 v233, -v228, v230
	s_waitcnt lgkmcnt(0)
;     static __device__ __forceinline__ void updS(float (&S)[64], const In1& in, float sa, float vv) {
;         float t0, t1, t2, t3;
;         asm volatile("v_mul_f32_dpp %0, %8, %21 row_newbcast:%22" DPPM "v_mul_f32_dpp %1, %9, %21 row_newbcast:%22" DPPM "v_mul_f32_dpp %2, %10, %21 row_newbcast:%22" DPPM "v_mul_f32_dpp %3, %11, %21 row_newbcast:%22" DPPM
;                      "v_fmac_f32_dpp %0, %12, %4 row_newbcast:%22" DPPM "v_fmac_f32_dpp %1, %13, %5 row_newbcast:%22" DPPM "v_fmac_f32_dpp %2, %14, %6 row_newbcast:%22" DPPM "v_fmac_f32_dpp %3, %15, %7 row_newbcast:%22" DPPM
;                      "v_fmac_f32_dpp %0, %16, %20 row_newbcast:%22" DPPM "v_fmac_f32_dpp %1, %17, %20 row_newbcast:%22" DPPM "v_fmac_f32_dpp %2, %18, %20 row_newbcast:%22" DPPM "v_fmac_f32_dpp %3, %19, %20 row_newbcast:%22" DPPM
;                      : "=&v"(t0), "=&v"(t1), "=&v"(t2), "=&v"(t3)
;                      : "v"(S[K]), "v"(S[K + 1]), "v"(S[K + 2]), "v"(S[K + 3]), "v"(in.kd[0]), "v"(in.kd[1]), "v"(in.kd[2]), "v"(in.kd[3]), "v"(in.w[0]), "v"(in.w[1]), "v"(in.w[2]), "v"(in.w[3]),
;                        "v"(in.b[0]), "v"(in.b[1]), "v"(in.b[2]), "v"(in.b[3]), "v"(sa), "v"(vv), "n"(N0));
;         S[K] = t0; S[K + 1] = t1; S[K + 2] = t2; S[K + 3] = t3;
;         if constexpr (K + 4 < 64) ScanK<K + 4>::updS(S, in, sa, vv);
;     }
;     static __device__ __forceinline__ void updP(float (&P)[64], const In1& in, float sa) {
;         float u0, u1, u2, u3;
;         asm volatile("v_mul_f32_dpp %0, %8, %4 row_newbcast:%17" DPPM "v_mul_f32_dpp %1, %9, %5 row_newbcast:%17" DPPM "v_mul_f32_dpp %2, %10, %6 row_newbcast:%17" DPPM "v_mul_f32_dpp %3, %11, %7 row_newbcast:%17" DPPM
;                      "v_fmac_f32_dpp %0, %12, %16 row_newbcast:%17" DPPM "v_fmac_f32_dpp %1, %13, %16 row_newbcast:%17" DPPM "v_fmac_f32_dpp %2, %14, %16 row_newbcast:%17" DPPM "v_fmac_f32_dpp %3, %15, %16 row_newbcast:%17" DPPM
;                      : "=&v"(u0), "=&v"(u1), "=&v"(u2), "=&v"(u3)
;                      : "v"(P[K]), "v"(P[K + 1]), "v"(P[K + 2]), "v"(P[K + 3]), "v"(in.w[0]), "v"(in.w[1]), "v"(in.w[2]), "v"(in.w[3]), "v"(in.b[0]), "v"(in.b[1]), "v"(in.b[2]), "v"(in.b[3]), "v"(sa), "n"(N0));
;         P[K] = u0; P[K + 1] = u1; P[K + 2] = u2; P[K + 3] = u3;
;         if constexpr (K + 4 < 64) ScanK<K + 4>::updP(P, in, sa);
;     }
	s_nop 1
	v_mfma_f32_4x4x1_16b_f32 v[0:3], v128, v232, v[0:3]
	v_mfma_f32_4x4x1_16b_f32 v[4:7], v129, v232, v[4:7]
	v_mfma_f32_4x4x1_16b_f32 v[8:11], v130, v232, v[8:11]
	v_mfma_f32_4x4x1_16b_f32 v[12:15], v131, v232, v[12:15]
	v_mfma_f32_4x4x1_16b_f32 v[16:19], v132, v232, v[16:19]
	v_mfma_f32_4x4x1_16b_f32 v[20:23], v133, v232, v[20:23]
	v_mfma_f32_4x4x1_16b_f32 v[24:27], v134, v232, v[24:27]
	v_mfma_f32_4x4x1_16b_f32 v[28:31], v135, v232, v[28:31]
	v_mfma_f32_4x4x1_16b_f32 v[32:35], v136, v232, v[32:35]
	v_mfma_f32_4x4x1_16b_f32 v[36:39], v137, v232, v[36:39]
	v_mfma_f32_4x4x1_16b_f32 v[40:43], v138, v232, v[40:43]
	v_mfma_f32_4x4x1_16b_f32 v[44:47], v139, v232, v[44:47]
	v_mfma_f32_4x4x1_16b_f32 v[48:51], v140, v232, v[48:51]
	v_mfma_f32_4x4x1_16b_f32 v[52:55], v141, v232, v[52:55]
	v_mfma_f32_4x4x1_16b_f32 v[56:59], v142, v232, v[56:59]
	v_mfma_f32_4x4x1_16b_f32 v[60:63], v143, v232, v[60:63]
	v_mfma_f32_4x4x1_16b_f32 v[0:3], v144, v234, v[0:3]
	v_mfma_f32_4x4x1_16b_f32 v[4:7], v145, v234, v[4:7]
	v_mfma_f32_4x4x1_16b_f32 v[8:11], v146, v234, v[8:11]
	v_mfma_f32_4x4x1_16b_f32 v[12:15], v147, v234, v[12:15]
	v_mfma_f32_4x4x1_16b_f32 v[16:19], v148, v234, v[16:19]
	v_mfma_f32_4x4x1_16b_f32 v[20:23], v149, v234, v[20:23]
	v_mfma_f32_4x4x1_16b_f32 v[24:27], v150, v234, v[24:27]
	v_mfma_f32_4x4x1_16b_f32 v[28:31], v151, v234, v[28:31]
	v_mfma_f32_4x4x1_16b_f32 v[32:35], v152, v234, v[32:35]
	v_mfma_f32_4x4x1_16b_f32 v[36:39], v153, v234, v[36:39]
	v_mfma_f32_4x4x1_16b_f32 v[40:43], v154, v234, v[40:43]
	v_mfma_f32_4x4x1_16b_f32 v[44:47], v155, v234, v[44:47]
	v_mfma_f32_4x4x1_16b_f32 v[48:51], v156, v234, v[48:51]
	v_mfma_f32_4x4x1_16b_f32 v[52:55], v157, v234, v[52:55]
	v_mfma_f32_4x4x1_16b_f32 v[56:59], v158, v234, v[56:59]
	v_mfma_f32_4x4x1_16b_f32 v[60:63], v159, v234, v[60:63]
	v_mfma_f32_4x4x1_16b_f32 v[64:67], v128, v233, v[64:67]
	v_mfma_f32_4x4x1_16b_f32 v[68:71], v129, v233, v[68:71]
	v_mfma_f32_4x4x1_16b_f32 v[72:75], v130, v233, v[72:75]
	v_mfma_f32_4x4x1_16b_f32 v[76:79], v131, v233, v[76:79]
	v_mfma_f32_4x4x1_16b_f32 v[80:83], v132, v233, v[80:83]
	v_mfma_f32_4x4x1_16b_f32 v[84:87], v133, v233, v[84:87]
	v_mfma_f32_4x4x1_16b_f32 v[88:91], v134, v233, v[88:91]
	v_mfma_f32_4x4x1_16b_f32 v[92:95], v135, v233, v[92:95]
	v_mfma_f32_4x4x1_16b_f32 v[96:99], v136, v233, v[96:99]
	v_mfma_f32_4x4x1_16b_f32 v[100:103], v137, v233, v[100:103]
	v_mfma_f32_4x4x1_16b_f32 v[104:107], v138, v233, v[104:107]
	v_mfma_f32_4x4x1_16b_f32 v[108:111], v139, v233, v[108:111]
	v_mfma_f32_4x4x1_16b_f32 v[112:115], v140, v233, v[112:115]
	v_mfma_f32_4x4x1_16b_f32 v[116:119], v141, v233, v[116:119]
	v_mfma_f32_4x4x1_16b_f32 v[120:123], v142, v233, v[120:123]
	v_mfma_f32_4x4x1_16b_f32 v[124:127], v143, v233, v[124:127]
	s_waitcnt vmcnt(5)
	buffer_load_dwordx4 v[160:163], v235, s[64:67], s72 offen
	buffer_load_dwordx4 v[164:167], v250, s[64:67], s72 offen
	buffer_load_dwordx4 v[168:171], v251, s[64:67], s72 offen
	buffer_load_dwordx2 v[172:173], v252, s[64:67], s76 offen
	buffer_load_ushort v174, v253, s[64:67], s76 offen
	s_add_i32 s72, s72, 0xfffff000
	s_max_i32 s72, s72, 0
	s_add_i32 s76, s76, 0xfffff800
	s_max_i32 s76, s76, 0
	v_pk_mul_f32 v[244:245], v[180:181], v[236:237]
	v_pk_mul_f32 v[246:247], v[182:183], v[238:239]
	v_pk_mul_f32 v[236:237], v[236:237], v[176:177]
	v_pk_mul_f32 v[238:239], v[238:239], v[178:179]
	v_pk_fma_f32 v[228:229], v[184:185], v[216:217], v[220:221]
	v_pk_fma_f32 v[230:231], v[186:187], v[218:219], v[222:223]
	v_pk_mul_f32 v[208:209], v[180:181], v[184:185]
	v_pk_mul_f32 v[210:211], v[182:183], v[186:187]
	v_rcp_f32_e32 v240, v236
	v_rcp_f32_e32 v241, v237
	v_rcp_f32_e32 v242, v238
	v_rcp_f32_e32 v243, v239
	v_lshlrev_b32_e32 v212, 16, v188
	v_and_b32_e32 v213, 0xffff0000, v188
	v_lshlrev_b32_e32 v214, 16, v189
	v_and_b32_e32 v215, 0xffff0000, v189
	v_pk_mul_f32 v[212:213], v[212:213], v[228:229]
	v_pk_mul_f32 v[214:215], v[214:215], v[230:231]
	v_lshlrev_b32_e32 v234, 16, v190
	v_pk_mul_f32 v[208:209], v[208:209], v[240:241]
	v_pk_mul_f32 v[210:211], v[210:211], v[242:243]
	v_pk_mul_f32 v[212:213], v[212:213], v[240:241]
	v_pk_mul_f32 v[214:215], v[214:215], v[242:243]
	ds_write2_b32 v248, v208, v209 offset0:0 offset1:16
	ds_write2_b32 v248, v210, v211 offset0:32 offset1:48
	ds_write2_b32 v248, v212, v213 offset0:64 offset1:80
	ds_write2_b32 v248, v214, v215 offset0:96 offset1:112
	ds_read_b128 v[128:131], v249 offset:0
	ds_read_b128 v[132:135], v249 offset:16
	ds_read_b128 v[136:139], v249 offset:32
	ds_read_b128 v[140:143], v249 offset:48
	ds_read_b128 v[144:147], v249 offset:256
	ds_read_b128 v[148:151], v249 offset:272
	ds_read_b128 v[152:155], v249 offset:288
	ds_read_b128 v[156:159], v249 offset:304
	v_mul_f32_dpp v224, v244, v0 row_newbcast:0 row_mask:0xf bank_mask:0xf
	v_mul_f32_dpp v225, v245, v1 row_newbcast:0 row_mask:0xf bank_mask:0xf
	v_mul_f32_dpp v226, v246, v2 row_newbcast:0 row_mask:0xf bank_mask:0xf
	v_mul_f32_dpp v227, v247, v3 row_newbcast:0 row_mask:0xf bank_mask:0xf
	v_fmac_f32_dpp v224, v244, v4 row_newbcast:1 row_mask:0xf bank_mask:0xf
	v_fmac_f32_dpp v225, v245, v5 row_newbcast:1 row_mask:0xf bank_mask:0xf
	v_fmac_f32_dpp v226, v246, v6 row_newbcast:1 row_mask:0xf bank_mask:0xf
	v_fmac_f32_dpp v227, v247, v7 row_newbcast:1 row_mask:0xf bank_mask:0xf
	v_fmac_f32_dpp v224, v244, v8 row_newbcast:2 row_mask:0xf bank_mask:0xf
	v_fmac_f32_dpp v225, v245, v9 row_newbcast:2 row_mask:0xf bank_mask:0xf
	v_fmac_f32_dpp v226, v246, v10 row_newbcast:2 row_mask:0xf bank_mask:0xf
	v_fmac_f32_dpp v227, v247, v11 row_newbcast:2 row_mask:0xf bank_mask:0xf
	v_fmac_f32_dpp v224, v244, v12 row_newbcast:3 row_mask:0xf bank_mask:0xf
;     static __device__ __forceinline__ void dot(const float (&S)[64], const f32x4& a, float (&s)[4]) {
;         if constexpr (K == 0) {
;             asm volatile("v_mul_f32_dpp %0, %4, %8 row_newbcast:%16" DPPM "v_mul_f32_dpp %1, %5, %9 row_newbcast:%16" DPPM "v_mul_f32_dpp %2, %6, %10 row_newbcast:%16" DPPM "v_mul_f32_dpp %3, %7, %11 row_newbcast:%16" DPPM
;                          "v_fmac_f32_dpp %0, %4, %12 row_newbcast:%17" DPPM "v_fmac_f32_dpp %1, %5, %13 row_newbcast:%17" DPPM "v_fmac_f32_dpp %2, %6, %14 row_newbcast:%17" DPPM "v_fmac_f32_dpp %3, %7, %15 row_newbcast:%17" DPPM
;                          : "=&v"(s[0]), "=&v"(s[1]), "=&v"(s[2]), "=&v"(s[3])
;                          : "v"(a[0]), "v"(a[1]), "v"(a[2]), "v"(a[3]), "v"(S[K]), "v"(S[K + 1]), "v"(S[K + 2]), "v"(S[K + 3]), "v"(S[K + 4]), "v"(S[K + 5]), "v"(S[K + 6]), "v"(S[K + 7]), "n"(N0), "n"(N1));
;         } else
;         asm volatile("v_fmac_f32_dpp %0, %4, %8 row_newbcast:%16" DPPM "v_fmac_f32_dpp %1, %5, %9 row_newbcast:%16" DPPM "v_fmac_f32_dpp %2, %6, %10 row_newbcast:%16" DPPM "v_fmac_f32_dpp %3, %7, %11 row_newbcast:%16" DPPM
;                      "v_fmac_f32_dpp %0, %4, %12 row_newbcast:%17" DPPM "v_fmac_f32_dpp %1, %5, %13 row_newbcast:%17" DPPM "v_fmac_f32_dpp %2, %6, %14 row_newbcast:%17" DPPM "v_fmac_f32_dpp %3, %7, %15 row_newbcast:%17" DPPM
;                      : "+v"(s[0]), "+v"(s[1]), "+v"(s[2]), "+v"(s[3])
;                      : "v"(a[0]), "v"(a[1]), "v"(a[2]), "v"(a[3]), "v"(S[K]), "v"(S[K + 1]), "v"(S[K + 2]), "v"(S[K + 3]), "v"(S[K + 4]), "v"(S[K + 5]), "v"(S[K + 6]), "v"(S[K + 7]), "n"(N0), "n"(N1));
;         if constexpr (K + 8 < 64) ScanK<K + 8>::dot(S, a, s);
	v_fmac_f32_dpp v225, v245, v13 row_newbcast:3 row_mask:0xf bank_mask:0xf
	v_fmac_f32_dpp v226, v246, v14 row_newbcast:3 row_mask:0xf bank_mask:0xf
	v_fmac_f32_dpp v227, v247, v15 row_newbcast:3 row_mask:0xf bank_mask:0xf
	v_fmac_f32_dpp v224, v244, v16 row_newbcast:4 row_mask:0xf bank_mask:0xf
	v_fmac_f32_dpp v225, v245, v17 row_newbcast:4 row_mask:0xf bank_mask:0xf
	v_fmac_f32_dpp v226, v246, v18 row_newbcast:4 row_mask:0xf bank_mask:0xf
	v_fmac_f32_dpp v227, v247, v19 row_newbcast:4 row_mask:0xf bank_mask:0xf
	v_fmac_f32_dpp v224, v244, v20 row_newbcast:5 row_mask:0xf bank_mask:0xf
	v_fmac_f32_dpp v225, v245, v21 row_newbcast:5 row_mask:0xf bank_mask:0xf
	v_fmac_f32_dpp v226, v246, v22 row_newbcast:5 row_mask:0xf bank_mask:0xf
	v_fmac_f32_dpp v227, v247, v23 row_newbcast:5 row_mask:0xf bank_mask:0xf
	v_fmac_f32_dpp v224, v244, v24 row_newbcast:6 row_mask:0xf bank_mask:0xf
	v_fmac_f32_dpp v225, v245, v25 row_newbcast:6 row_mask:0xf bank_mask:0xf
	v_fmac_f32_dpp v226, v246, v26 row_newbcast:6 row_mask:0xf bank_mask:0xf
	v_fmac_f32_dpp v227, v247, v27 row_newbcast:6 row_mask:0xf bank_mask:0xf
	v_fmac_f32_dpp v224, v244, v28 row_newbcast:7 row_mask:0xf bank_mask:0xf
	v_fmac_f32_dpp v225, v245, v29 row_newbcast:7 row_mask:0xf bank_mask:0xf
	v_fmac_f32_dpp v226, v246, v30 row_newbcast:7 row_mask:0xf bank_mask:0xf
	v_fmac_f32_dpp v227, v247, v31 row_newbcast:7 row_mask:0xf bank_mask:0xf
	v_fmac_f32_dpp v224, v244, v32 row_newbcast:8 row_mask:0xf bank_mask:0xf
	v_fmac_f32_dpp v225, v245, v33 row_newbcast:8 row_mask:0xf bank_mask:0xf
	v_fmac_f32_dpp v226, v246, v34 row_newbcast:8 row_mask:0xf bank_mask:0xf
	v_fmac_f32_dpp v227, v247, v35 row_newbcast:8 row_mask:0xf bank_mask:0xf
	v_fmac_f32_dpp v224, v244, v36 row_newbcast:9 row_mask:0xf bank_mask:0xf
	v_fmac_f32_dpp v225, v245, v37 row_newbcast:9 row_mask:0xf bank_mask:0xf
	v_fmac_f32_dpp v226, v246, v38 row_newbcast:9 row_mask:0xf bank_mask:0xf
	v_fmac_f32_dpp v227, v247, v39 row_newbcast:9 row_mask:0xf bank_mask:0xf
	v_fmac_f32_dpp v224, v244, v40 row_newbcast:10 row_mask:0xf bank_mask:0xf
	v_fmac_f32_dpp v225, v245, v41 row_newbcast:10 row_mask:0xf bank_mask:0xf
	v_fmac_f32_dpp v226, v246, v42 row_newbcast:10 row_mask:0xf bank_mask:0xf
	v_fmac_f32_dpp v227, v247, v43 row_newbcast:10 row_mask:0xf bank_mask:0xf
	v_fmac_f32_dpp v224, v244, v44 row_newbcast:11 row_mask:0xf bank_mask:0xf
	v_fmac_f32_dpp v225, v245, v45 row_newbcast:11 row_mask:0xf bank_mask:0xf
	v_fmac_f32_dpp v226, v246, v46 row_newbcast:11 row_mask:0xf bank_mask:0xf
	v_fmac_f32_dpp v227, v247, v47 row_newbcast:11 row_mask:0xf bank_mask:0xf
	v_fmac_f32_dpp v224, v244, v48 row_newbcast:12 row_mask:0xf bank_mask:0xf
	v_fmac_f32_dpp v225, v245, v49 row_newbcast:12 row_mask:0xf bank_mask:0xf
	v_fmac_f32_dpp v226, v246, v50 row_newbcast:12 row_mask:0xf bank_mask:0xf
	v_fmac_f32_dpp v227, v247, v51 row_newbcast:12 row_mask:0xf bank_mask:0xf
	v_fmac_f32_dpp v224, v244, v52 row_newbcast:13 row_mask:0xf bank_mask:0xf
	v_fmac_f32_dpp v225, v245, v53 row_newbcast:13 row_mask:0xf bank_mask:0xf
	v_fmac_f32_dpp v226, v246, v54 row_newbcast:13 row_mask:0xf bank_mask:0xf
	v_fmac_f32_dpp v227, v247, v55 row_newbcast:13 row_mask:0xf bank_mask:0xf
	v_fmac_f32_dpp v224, v244, v56 row_newbcast:14 row_mask:0xf bank_mask:0xf
	v_fmac_f32_dpp v225, v245, v57 row_newbcast:14 row_mask:0xf bank_mask:0xf
	v_fmac_f32_dpp v226, v246, v58 row_newbcast:14 row_mask:0xf bank_mask:0xf
	v_fmac_f32_dpp v227, v247, v59 row_newbcast:14 row_mask:0xf bank_mask:0xf
	v_fmac_f32_dpp v224, v244, v60 row_newbcast:15 row_mask:0xf bank_mask:0xf
	v_fmac_f32_dpp v225, v245, v61 row_newbcast:15 row_mask:0xf bank_mask:0xf
	v_fmac_f32_dpp v226, v246, v62 row_newbcast:15 row_mask:0xf bank_mask:0xf
	v_fmac_f32_dpp v227, v247, v63 row_newbcast:15 row_mask:0xf bank_mask:0xf
	v_mul_f32_dpp v228, v244, v64 row_newbcast:0 row_mask:0xf bank_mask:0xf
	v_mul_f32_dpp v229, v245, v65 row_newbcast:0 row_mask:0xf bank_mask:0xf
	v_mul_f32_dpp v230, v246, v66 row_newbcast:0 row_mask:0xf bank_mask:0xf
	v_mul_f32_dpp v231, v247, v67 row_newbcast:0 row_mask:0xf bank_mask:0xf
	v_fmac_f32_dpp v228, v244, v68 row_newbcast:1 row_mask:0xf bank_mask:0xf
	v_fmac_f32_dpp v229, v245, v69 row_newbcast:1 row_mask:0xf bank_mask:0xf
	v_fmac_f32_dpp v230, v246, v70 row_newbcast:1 row_mask:0xf bank_mask:0xf
	v_fmac_f32_dpp v231, v247, v71 row_newbcast:1 row_mask:0xf bank_mask:0xf
	v_fmac_f32_dpp v228, v244, v72 row_newbcast:2 row_mask:0xf bank_mask:0xf
	v_fmac_f32_dpp v229, v245, v73 row_newbcast:2 row_mask:0xf bank_mask:0xf
	v_fmac_f32_dpp v230, v246, v74 row_newbcast:2 row_mask:0xf bank_mask:0xf
	v_fmac_f32_dpp v231, v247, v75 row_newbcast:2 row_mask:0xf bank_mask:0xf
	v_fmac_f32_dpp v228, v244, v76 row_newbcast:3 row_mask:0xf bank_mask:0xf
	v_fmac_f32_dpp v229, v245, v77 row_newbcast:3 row_mask:0xf bank_mask:0xf
	v_fmac_f32_dpp v230, v246, v78 row_newbcast:3 row_mask:0xf bank_mask:0xf
	v_fmac_f32_dpp v231, v247, v79 row_newbcast:3 row_mask:0xf bank_mask:0xf
	v_fmac_f32_dpp v228, v244, v80 row_newbcast:4 row_mask:0xf bank_mask:0xf
	v_fmac_f32_dpp v229, v245, v81 row_newbcast:4 row_mask:0xf bank_mask:0xf
	v_fmac_f32_dpp v230, v246, v82 row_newbcast:4 row_mask:0xf bank_mask:0xf
	v_fmac_f32_dpp v231, v247, v83 row_newbcast:4 row_mask:0xf bank_mask:0xf
	v_fmac_f32_dpp v228, v244, v84 row_newbcast:5 row_mask:0xf bank_mask:0xf
	v_fmac_f32_dpp v229, v245, v85 row_newbcast:5 row_mask:0xf bank_mask:0xf
	v_fmac_f32_dpp v230, v246, v86 row_newbcast:5 row_mask:0xf bank_mask:0xf
	v_fmac_f32_dpp v231, v247, v87 row_newbcast:5 row_mask:0xf bank_mask:0xf
	v_fmac_f32_dpp v228, v244, v88 row_newbcast:6 row_mask:0xf bank_mask:0xf
;     static __device__ __forceinline__ void dot(const float (&S)[64], const f32x4& a, float (&s)[4]) {
;         if constexpr (K == 0) {
;             asm volatile("v_mul_f32_dpp %0, %4, %8 row_newbcast:%16" DPPM "v_mul_f32_dpp %1, %5, %9 row_newbcast:%16" DPPM "v_mul_f32_dpp %2, %6, %10 row_newbcast:%16" DPPM "v_mul_f32_dpp %3, %7, %11 row_newbcast:%16" DPPM
;                          "v_fmac_f32_dpp %0, %4, %12 row_newbcast:%17" DPPM "v_fmac_f32_dpp %1, %5, %13 row_newbcast:%17" DPPM "v_fmac_f32_dpp %2, %6, %14 row_newbcast:%17" DPPM "v_fmac_f32_dpp %3, %7, %15 row_newbcast:%17" DPPM
;                          : "=&v"(s[0]), "=&v"(s[1]), "=&v"(s[2]), "=&v"(s[3])
;                          : "v"(a[0]), "v"(a[1]), "v"(a[2]), "v"(a[3]), "v"(S[K]), "v"(S[K + 1]), "v"(S[K + 2]), "v"(S[K + 3]), "v"(S[K + 4]), "v"(S[K + 5]), "v"(S[K + 6]), "v"(S[K + 7]), "n"(N0), "n"(N1));
;         } else
;         asm volatile("v_fmac_f32_dpp %0, %4, %8 row_newbcast:%16" DPPM "v_fmac_f32_dpp %1, %5, %9 row_newbcast:%16" DPPM "v_fmac_f32_dpp %2, %6, %10 row_newbcast:%16" DPPM "v_fmac_f32_dpp %3, %7, %11 row_newbcast:%16" DPPM
;                      "v_fmac_f32_dpp %0, %4, %12 row_newbcast:%17" DPPM "v_fmac_f32_dpp %1, %5, %13 row_newbcast:%17" DPPM "v_fmac_f32_dpp %2, %6, %14 row_newbcast:%17" DPPM "v_fmac_f32_dpp %3, %7, %15 row_newbcast:%17" DPPM
;                      : "+v"(s[0]), "+v"(s[1]), "+v"(s[2]), "+v"(s[3])
;                      : "v"(a[0]), "v"(a[1]), "v"(a[2]), "v"(a[3]), "v"(S[K]), "v"(S[K + 1]), "v"(S[K + 2]), "v"(S[K + 3]), "v"(S[K + 4]), "v"(S[K + 5]), "v"(S[K + 6]), "v"(S[K + 7]), "n"(N0), "n"(N1));
;         if constexpr (K + 8 < 64) ScanK<K + 8>::dot(S, a, s);
;     }
;     static __device__ __forceinline__ void upd(float (&S)[64], const In2& in, float sa, float vv, float& y0, float& y1) {
;         float t0, t1, t2, t3;
;         asm volatile("v_mul_f32_dpp %0, %10, %27 row_newbcast:%28" DPPM "v_mul_f32_dpp %1, %11, %27 row_newbcast:%28" DPPM "v_mul_f32_dpp %2, %12, %27 row_newbcast:%28" DPPM "v_mul_f32_dpp %3, %13, %27 row_newbcast:%28" DPPM
;                      "v_fmac_f32_dpp %0, %14, %6 row_newbcast:%28" DPPM "v_fmac_f32_dpp %1, %15, %7 row_newbcast:%28" DPPM "v_fmac_f32_dpp %2, %16, %8 row_newbcast:%28" DPPM "v_fmac_f32_dpp %3, %17, %9 row_newbcast:%28" DPPM
	v_fmac_f32_dpp v229, v245, v89 row_newbcast:6 row_mask:0xf bank_mask:0xf
	v_fmac_f32_dpp v230, v246, v90 row_newbcast:6 row_mask:0xf bank_mask:0xf
	v_fmac_f32_dpp v231, v247, v91 row_newbcast:6 row_mask:0xf bank_mask:0xf
	v_fmac_f32_dpp v228, v244, v92 row_newbcast:7 row_mask:0xf bank_mask:0xf
	v_fmac_f32_dpp v229, v245, v93 row_newbcast:7 row_mask:0xf bank_mask:0xf
	v_fmac_f32_dpp v230, v246, v94 row_newbcast:7 row_mask:0xf bank_mask:0xf
	v_fmac_f32_dpp v231, v247, v95 row_newbcast:7 row_mask:0xf bank_mask:0xf
	v_fmac_f32_dpp v228, v244, v96 row_newbcast:8 row_mask:0xf bank_mask:0xf
	v_fmac_f32_dpp v229, v245, v97 row_newbcast:8 row_mask:0xf bank_mask:0xf
	v_fmac_f32_dpp v230, v246, v98 row_newbcast:8 row_mask:0xf bank_mask:0xf
	v_fmac_f32_dpp v231, v247, v99 row_newbcast:8 row_mask:0xf bank_mask:0xf
	v_fmac_f32_dpp v228, v244, v100 row_newbcast:9 row_mask:0xf bank_mask:0xf
	v_fmac_f32_dpp v229, v245, v101 row_newbcast:9 row_mask:0xf bank_mask:0xf
	v_fmac_f32_dpp v230, v246, v102 row_newbcast:9 row_mask:0xf bank_mask:0xf
	v_fmac_f32_dpp v231, v247, v103 row_newbcast:9 row_mask:0xf bank_mask:0xf
	v_fmac_f32_dpp v228, v244, v104 row_newbcast:10 row_mask:0xf bank_mask:0xf
	v_fmac_f32_dpp v229, v245, v105 row_newbcast:10 row_mask:0xf bank_mask:0xf
	v_fmac_f32_dpp v230, v246, v106 row_newbcast:10 row_mask:0xf bank_mask:0xf
	v_fmac_f32_dpp v231, v247, v107 row_newbcast:10 row_mask:0xf bank_mask:0xf
	v_fmac_f32_dpp v228, v244, v108 row_newbcast:11 row_mask:0xf bank_mask:0xf
	v_fmac_f32_dpp v229, v245, v109 row_newbcast:11 row_mask:0xf bank_mask:0xf
	v_fmac_f32_dpp v230, v246, v110 row_newbcast:11 row_mask:0xf bank_mask:0xf
	v_fmac_f32_dpp v231, v247, v111 row_newbcast:11 row_mask:0xf bank_mask:0xf
	v_fmac_f32_dpp v228, v244, v112 row_newbcast:12 row_mask:0xf bank_mask:0xf
	v_fmac_f32_dpp v229, v245, v113 row_newbcast:12 row_mask:0xf bank_mask:0xf
	v_fmac_f32_dpp v230, v246, v114 row_newbcast:12 row_mask:0xf bank_mask:0xf
	v_fmac_f32_dpp v231, v247, v115 row_newbcast:12 row_mask:0xf bank_mask:0xf
	v_fmac_f32_dpp v228, v244, v116 row_newbcast:13 row_mask:0xf bank_mask:0xf
	v_fmac_f32_dpp v229, v245, v117 row_newbcast:13 row_mask:0xf bank_mask:0xf
	v_fmac_f32_dpp v230, v246, v118 row_newbcast:13 row_mask:0xf bank_mask:0xf
	v_fmac_f32_dpp v231, v247, v119 row_newbcast:13 row_mask:0xf bank_mask:0xf
	v_fmac_f32_dpp v228, v244, v120 row_newbcast:14 row_mask:0xf bank_mask:0xf
	v_fmac_f32_dpp v229, v245, v121 row_newbcast:14 row_mask:0xf bank_mask:0xf
	v_fmac_f32_dpp v230, v246, v122 row_newbcast:14 row_mask:0xf bank_mask:0xf
	v_fmac_f32_dpp v231, v247, v123 row_newbcast:14 row_mask:0xf bank_mask:0xf
	v_fmac_f32_dpp v228, v244, v124 row_newbcast:15 row_mask:0xf bank_mask:0xf
	v_fmac_f32_dpp v229, v245, v125 row_newbcast:15 row_mask:0xf bank_mask:0xf
	v_fmac_f32_dpp v230, v246, v126 row_newbcast:15 row_mask:0xf bank_mask:0xf
	v_fmac_f32_dpp v231, v247, v127 row_newbcast:15 row_mask:0xf bank_mask:0xf
	v_add_f32_e32 v224, v224, v225
	v_add_f32_e32 v226, v226, v227
	v_sub_f32_e64 v232, -v224, v226
	v_add_f32_e32 v228, v228, v229
	v_add_f32_e32 v230, v230, v231
	v_sub_f32_e64 v233, -v228, v230
	s_waitcnt lgkmcnt(0)
	s_nop 1
	v_mfma_f32_4x4x1_16b_f32 v[0:3], v128, v232, v[0:3]
	v_mfma_f32_4x4x1_16b_f32 v[4:7], v129, v232, v[4:7]
	v_mfma_f32_4x4x1_16b_f32 v[8:11], v130, v232, v[8:11]
	v_mfma_f32_4x4x1_16b_f32 v[12:15], v131, v232, v[12:15]
	v_mfma_f32_4x4x1_16b_f32 v[16:19], v132, v232, v[16:19]
	v_mfma_f32_4x4x1_16b_f32 v[20:23], v133, v232, v[20:23]
	v_mfma_f32_4x4x1_16b_f32 v[24:27], v134, v232, v[24:27]
	v_mfma_f32_4x4x1_16b_f32 v[28:31], v135, v232, v[28:31]
	v_mfma_f32_4x4x1_16b_f32 v[32:35], v136, v232, v[32:35]
	v_mfma_f32_4x4x1_16b_f32 v[36:39], v137, v232, v[36:39]
	v_mfma_f32_4x4x1_16b_f32 v[40:43], v138, v232, v[40:43]
	v_mfma_f32_4x4x1_16b_f32 v[44:47], v139, v232, v[44:47]
	v_mfma_f32_4x4x1_16b_f32 v[48:51], v140, v232, v[48:51]
	v_mfma_f32_4x4x1_16b_f32 v[52:55], v141, v232, v[52:55]
	v_mfma_f32_4x4x1_16b_f32 v[56:59], v142, v232, v[56:59]
	v_mfma_f32_4x4x1_16b_f32 v[60:63], v143, v232, v[60:63]
	v_mfma_f32_4x4x1_16b_f32 v[0:3], v144, v234, v[0:3]
	v_mfma_f32_4x4x1_16b_f32 v[4:7], v145, v234, v[4:7]
	v_mfma_f32_4x4x1_16b_f32 v[8:11], v146, v234, v[8:11]
	v_mfma_f32_4x4x1_16b_f32 v[12:15], v147, v234, v[12:15]
	v_mfma_f32_4x4x1_16b_f32 v[16:19], v148, v234, v[16:19]
	v_mfma_f32_4x4x1_16b_f32 v[20:23], v149, v234, v[20:23]
	v_mfma_f32_4x4x1_16b_f32 v[24:27], v150, v234, v[24:27]
	v_mfma_f32_4x4x1_16b_f32 v[28:31], v151, v234, v[28:31]
	v_mfma_f32_4x4x1_16b_f32 v[32:35], v152, v234, v[32:35]
	v_mfma_f32_4x4x1_16b_f32 v[36:39], v153, v234, v[36:39]
	v_mfma_f32_4x4x1_16b_f32 v[40:43], v154, v234, v[40:43]
	v_mfma_f32_4x4x1_16b_f32 v[44:47], v155, v234, v[44:47]
	v_mfma_f32_4x4x1_16b_f32 v[48:51], v156, v234, v[48:51]
	v_mfma_f32_4x4x1_16b_f32 v[52:55], v157, v234, v[52:55]
	v_mfma_f32_4x4x1_16b_f32 v[56:59], v158, v234, v[56:59]
	v_mfma_f32_4x4x1_16b_f32 v[60:63], v159, v234, v[60:63]
	v_mfma_f32_4x4x1_16b_f32 v[64:67], v128, v233, v[64:67]
	v_mfma_f32_4x4x1_16b_f32 v[68:71], v129, v233, v[68:71]
	v_mfma_f32_4x4x1_16b_f32 v[72:75], v130, v233, v[72:75]
	v_mfma_f32_4x4x1_16b_f32 v[76:79], v131, v233, v[76:79]
	v_mfma_f32_4x4x1_16b_f32 v[80:83], v132, v233, v[80:83]
	v_mfma_f32_4x4x1_16b_f32 v[84:87], v133, v233, v[84:87]
	v_mfma_f32_4x4x1_16b_f32 v[88:91], v134, v233, v[88:91]
	v_mfma_f32_4x4x1_16b_f32 v[92:95], v135, v233, v[92:95]
	v_mfma_f32_4x4x1_16b_f32 v[96:99], v136, v233, v[96:99]
	v_mfma_f32_4x4x1_16b_f32 v[100:103], v137, v233, v[100:103]
	v_mfma_f32_4x4x1_16b_f32 v[104:107], v138, v233, v[104:107]
	v_mfma_f32_4x4x1_16b_f32 v[108:111], v139, v233, v[108:111]
	v_mfma_f32_4x4x1_16b_f32 v[112:115], v140, v233, v[112:115]
	v_mfma_f32_4x4x1_16b_f32 v[116:119], v141, v233, v[116:119]
	v_mfma_f32_4x4x1_16b_f32 v[120:123], v142, v233, v[120:123]
	v_mfma_f32_4x4x1_16b_f32 v[124:127], v143, v233, v[124:127]
	s_waitcnt vmcnt(5)
; #define SB __builtin_amdgcn_sched_barrier(0)
; #define LD1(set, s) { const int e_ = min((int)(s), LC - 1) * (int)stp; const unsigned s4_ = ob4 + (unsigned)(e_ * 4), s2_ = ob2 + (unsigned)(e_ * 2); set.w = LDX(rW, s4_); set.a = LDX(rA, s4_); set.b = LDX(rB, s4_); \
;             set.kw = __builtin_amdgcn_raw_buffer_load_b64(rK, lo8, s2_, 0); set.v = __builtin_amdgcn_raw_buffer_load_b16(rV, lo2, s2_, 0); }
; #define TOUCH1(set) asm volatile("" :: "v"(set.w), "v"(set.a), "v"(set.b), "v"(set.kw), "v"(set.v))
; #define ST1(set) { DERIVE_BK(set); float sd[4]; ScanK<0>::dot(S, set.a, sd); ScanK<0>::updS(S, set, -((sd[0] + sd[1]) + (sd[2] + sd[3])), __uint_as_float(set.v << 16)); }
; #define LD1(set, s) { const int e_ = min((int)(s), LC - 1) * (int)stp; const unsigned s4_ = ob4 + (unsigned)(e_ * 4); set.w = LDX(rW, s4_); set.a = LDX(rA, s4_); set.b = LDX(rB, s4_); }
; #define TOUCH1(set) asm volatile("" :: "v"(set.w), "v"(set.a), "v"(set.b))
; #define ST1(set) { DERIVE_B(set); float sd[4]; ScanK<0>::dot(S, set.a, sd); ScanK<0>::updP(S, set, -((sd[0] + sd[1]) + (sd[2] + sd[3]))); }
; template <bool MIX> __device__ __forceinline__ void scan_pass1(const Params& p, int d, float* ldsf) {
;     ...
;             In1 i0, i1; LD1(i0, 0);
; #pragma unroll 1
;             for (int s = 0; s < LC; s += 2) { TOUCH1(i0); SB; LD1(i1, s + 1); SB; ST1(i0); TOUCH1(i1); SB; LD1(i0, s + 2); SB; ST1(i1); }
	buffer_load_dwordx4 v[176:179], v235, s[64:67], s72 offen
	buffer_load_dwordx4 v[180:183], v250, s[64:67], s72 offen
	buffer_load_dwordx4 v[184:187], v251, s[64:67], s72 offen
	buffer_load_dwordx2 v[188:189], v252, s[64:67], s76 offen
	buffer_load_ushort v190, v253, s[64:67], s76 offen
	s_add_i32 s72, s72, 0xfffff000
	s_max_i32 s72, s72, 0
	s_add_i32 s76, s76, 0xfffff800
	s_max_i32 s76, s76, 0
	v_pk_mul_f32 v[244:245], v[196:197], v[236:237]
	v_pk_mul_f32 v[246:247], v[198:199], v[238:239]
	v_pk_mul_f32 v[236:237], v[236:237], v[192:193]
	v_pk_mul_f32 v[238:239], v[238:239], v[194:195]
	v_pk_fma_f32 v[228:229], v[200:201], v[216:217], v[220:221]
	v_pk_fma_f32 v[230:231], v[202:203], v[218:219], v[222:223]
	v_pk_mul_f32 v[208:209], v[196:197], v[200:201]
	v_pk_mul_f32 v[210:211], v[198:199], v[202:203]
	v_rcp_f32_e32 v240, v236
	v_rcp_f32_e32 v241, v237
	v_rcp_f32_e32 v242, v238
	v_rcp_f32_e32 v243, v239
	v_lshlrev_b32_e32 v212, 16, v204
	v_and_b32_e32 v213, 0xffff0000, v204
	v_lshlrev_b32_e32 v214, 16, v205
	v_and_b32_e32 v215, 0xffff0000, v205
	v_pk_mul_f32 v[212:213], v[212:213], v[228:229]
	v_pk_mul_f32 v[214:215], v[214:215], v[230:231]
	v_lshlrev_b32_e32 v234, 16, v206
	v_pk_mul_f32 v[208:209], v[208:209], v[240:241]
	v_pk_mul_f32 v[210:211], v[210:211], v[242:243]
	v_pk_mul_f32 v[212:213], v[212:213], v[240:241]
	v_pk_mul_f32 v[214:215], v[214:215], v[242:243]
	ds_write2_b32 v248, v208, v209 offset0:0 offset1:16
	ds_write2_b32 v248, v210, v211 offset0:32 offset1:48
	ds_write2_b32 v248, v212, v213 offset0:64 offset1:80
	ds_write2_b32 v248, v214, v215 offset0:96 offset1:112
	ds_read_b128 v[128:131], v249 offset:0
	ds_read_b128 v[132:135], v249 offset:16
	ds_read_b128 v[136:139], v249 offset:32
	ds_read_b128 v[140:143], v249 offset:48
	ds_read_b128 v[144:147], v249 offset:256
	ds_read_b128 v[148:151], v249 offset:272
	ds_read_b128 v[152:155], v249 offset:288
	ds_read_b128 v[156:159], v249 offset:304
	v_mul_f32_dpp v224, v244, v0 row_newbcast:0 row_mask:0xf bank_mask:0xf
	v_mul_f32_dpp v225, v245, v1 row_newbcast:0 row_mask:0xf bank_mask:0xf
	v_mul_f32_dpp v226, v246, v2 row_newbcast:0 row_mask:0xf bank_mask:0xf
	v_mul_f32_dpp v227, v247, v3 row_newbcast:0 row_mask:0xf bank_mask:0xf
	v_fmac_f32_dpp v224, v244, v4 row_newbcast:1 row_mask:0xf bank_mask:0xf
	v_fmac_f32_dpp v225, v245, v5 row_newbcast:1 row_mask:0xf bank_mask:0xf
	v_fmac_f32_dpp v226, v246, v6 row_newbcast:1 row_mask:0xf bank_mask:0xf
	v_fmac_f32_dpp v227, v247, v7 row_newbcast:1 row_mask:0xf bank_mask:0xf
	v_fmac_f32_dpp v224, v244, v8 row_newbcast:2 row_mask:0xf bank_mask:0xf
	v_fmac_f32_dpp v225, v245, v9 row_newbcast:2 row_mask:0xf bank_mask:0xf
	v_fmac_f32_dpp v226, v246, v10 row_newbcast:2 row_mask:0xf bank_mask:0xf
	v_fmac_f32_dpp v227, v247, v11 row_newbcast:2 row_mask:0xf bank_mask:0xf
	v_fmac_f32_dpp v224, v244, v12 row_newbcast:3 row_mask:0xf bank_mask:0xf
	v_fmac_f32_dpp v225, v245, v13 row_newbcast:3 row_mask:0xf bank_mask:0xf
	v_fmac_f32_dpp v226, v246, v14 row_newbcast:3 row_mask:0xf bank_mask:0xf
	v_fmac_f32_dpp v227, v247, v15 row_newbcast:3 row_mask:0xf bank_mask:0xf
	v_fmac_f32_dpp v224, v244, v16 row_newbcast:4 row_mask:0xf bank_mask:0xf
	v_fmac_f32_dpp v225, v245, v17 row_newbcast:4 row_mask:0xf bank_mask:0xf
	v_fmac_f32_dpp v226, v246, v18 row_newbcast:4 row_mask:0xf bank_mask:0xf
	v_fmac_f32_dpp v227, v247, v19 row_newbcast:4 row_mask:0xf bank_mask:0xf
	v_fmac_f32_dpp v224, v244, v20 row_newbcast:5 row_mask:0xf bank_mask:0xf
	v_fmac_f32_dpp v225, v245, v21 row_newbcast:5 row_mask:0xf bank_mask:0xf
	v_fmac_f32_dpp v226, v246, v22 row_newbcast:5 row_mask:0xf bank_mask:0xf
	v_fmac_f32_dpp v227, v247, v23 row_newbcast:5 row_mask:0xf bank_mask:0xf
	v_fmac_f32_dpp v224, v244, v24 row_newbcast:6 row_mask:0xf bank_mask:0xf
	v_fmac_f32_dpp v225, v245, v25 row_newbcast:6 row_mask:0xf bank_mask:0xf
	v_fmac_f32_dpp v226, v246, v26 row_newbcast:6 row_mask:0xf bank_mask:0xf
	v_fmac_f32_dpp v227, v247, v27 row_newbcast:6 row_mask:0xf bank_mask:0xf
	v_fmac_f32_dpp v224, v244, v28 row_newbcast:7 row_mask:0xf bank_mask:0xf
	v_fmac_f32_dpp v225, v245, v29 row_newbcast:7 row_mask:0xf bank_mask:0xf
	v_fmac_f32_dpp v226, v246, v30 row_newbcast:7 row_mask:0xf bank_mask:0xf
	v_fmac_f32_dpp v227, v247, v31 row_newbcast:7 row_mask:0xf bank_mask:0xf
	v_fmac_f32_dpp v224, v244, v32 row_newbcast:8 row_mask:0xf bank_mask:0xf
	v_fmac_f32_dpp v225, v245, v33 row_newbcast:8 row_mask:0xf bank_mask:0xf
	v_fmac_f32_dpp v226, v246, v34 row_newbcast:8 row_mask:0xf bank_mask:0xf
	v_fmac_f32_dpp v227, v247, v35 row_newbcast:8 row_mask:0xf bank_mask:0xf
	v_fmac_f32_dpp v224, v244, v36 row_newbcast:9 row_mask:0xf bank_mask:0xf
	v_fmac_f32_dpp v225, v245, v37 row_newbcast:9 row_mask:0xf bank_mask:0xf
	v_fmac_f32_dpp v226, v246, v38 row_newbcast:9 row_mask:0xf bank_mask:0xf
	v_fmac_f32_dpp v227, v247, v39 row_newbcast:9 row_mask:0xf bank_mask:0xf
	v_fmac_f32_dpp v224, v244, v40 row_newbcast:10 row_mask:0xf bank_mask:0xf
	v_fmac_f32_dpp v225, v245, v41 row_newbcast:10 row_mask:0xf bank_mask:0xf
	v_fmac_f32_dpp v226, v246, v42 row_newbcast:10 row_mask:0xf bank_mask:0xf
	v_fmac_f32_dpp v227, v247, v43 row_newbcast:10 row_mask:0xf bank_mask:0xf
	v_fmac_f32_dpp v224, v244, v44 row_newbcast:11 row_mask:0xf bank_mask:0xf
	v_fmac_f32_dpp v225, v245, v45 row_newbcast:11 row_mask:0xf bank_mask:0xf
	v_fmac_f32_dpp v226, v246, v46 row_newbcast:11 row_mask:0xf bank_mask:0xf
	v_fmac_f32_dpp v227, v247, v47 row_newbcast:11 row_mask:0xf bank_mask:0xf
	v_fmac_f32_dpp v224, v244, v48 row_newbcast:12 row_mask:0xf bank_mask:0xf
	v_fmac_f32_dpp v225, v245, v49 row_newbcast:12 row_mask:0xf bank_mask:0xf
;     static __device__ __forceinline__ void dot(const float (&S)[64], const f32x4& a, float (&s)[4]) {
;         if constexpr (K == 0) {
;             asm volatile("v_mul_f32_dpp %0, %4, %8 row_newbcast:%16" DPPM "v_mul_f32_dpp %1, %5, %9 row_newbcast:%16" DPPM "v_mul_f32_dpp %2, %6, %10 row_newbcast:%16" DPPM "v_mul_f32_dpp %3, %7, %11 row_newbcast:%16" DPPM
;                          "v_fmac_f32_dpp %0, %4, %12 row_newbcast:%17" DPPM "v_fmac_f32_dpp %1, %5, %13 row_newbcast:%17" DPPM "v_fmac_f32_dpp %2, %6, %14 row_newbcast:%17" DPPM "v_fmac_f32_dpp %3, %7, %15 row_newbcast:%17" DPPM
;                          : "=&v"(s[0]), "=&v"(s[1]), "=&v"(s[2]), "=&v"(s[3])
;                          : "v"(a[0]), "v"(a[1]), "v"(a[2]), "v"(a[3]), "v"(S[K]), "v"(S[K + 1]), "v"(S[K + 2]), "v"(S[K + 3]), "v"(S[K + 4]), "v"(S[K + 5]), "v"(S[K + 6]), "v"(S[K + 7]), "n"(N0), "n"(N1));
;         } else
;         asm volatile("v_fmac_f32_dpp %0, %4, %8 row_newbcast:%16" DPPM "v_fmac_f32_dpp %1, %5, %9 row_newbcast:%16" DPPM "v_fmac_f32_dpp %2, %6, %10 row_newbcast:%16" DPPM "v_fmac_f32_dpp %3, %7, %11 row_newbcast:%16" DPPM
;                      "v_fmac_f32_dpp %0, %4, %12 row_newbcast:%17" DPPM "v_fmac_f32_dpp %1, %5, %13 row_newbcast:%17" DPPM "v_fmac_f32_dpp %2, %6, %14 row_newbcast:%17" DPPM "v_fmac_f32_dpp %3, %7, %15 row_newbcast:%17" DPPM
;                      : "+v"(s[0]), "+v"(s[1]), "+v"(s[2]), "+v"(s[3])
;                      : "v"(a[0]), "v"(a[1]), "v"(a[2]), "v"(a[3]), "v"(S[K]), "v"(S[K + 1]), "v"(S[K + 2]), "v"(S[K + 3]), "v"(S[K + 4]), "v"(S[K + 5]), "v"(S[K + 6]), "v"(S[K + 7]), "n"(N0), "n"(N1));
;         if constexpr (K + 8 < 64) ScanK<K + 8>::dot(S, a, s);
	v_fmac_f32_dpp v226, v246, v50 row_newbcast:12 row_mask:0xf bank_mask:0xf
	v_fmac_f32_dpp v227, v247, v51 row_newbcast:12 row_mask:0xf bank_mask:0xf
	v_fmac_f32_dpp v224, v244, v52 row_newbcast:13 row_mask:0xf bank_mask:0xf
	v_fmac_f32_dpp v225, v245, v53 row_newbcast:13 row_mask:0xf bank_mask:0xf
	v_fmac_f32_dpp v226, v246, v54 row_newbcast:13 row_mask:0xf bank_mask:0xf
	v_fmac_f32_dpp v227, v247, v55 row_newbcast:13 row_mask:0xf bank_mask:0xf
	v_fmac_f32_dpp v224, v244, v56 row_newbcast:14 row_mask:0xf bank_mask:0xf
	v_fmac_f32_dpp v225, v245, v57 row_newbcast:14 row_mask:0xf bank_mask:0xf
	v_fmac_f32_dpp v226, v246, v58 row_newbcast:14 row_mask:0xf bank_mask:0xf
	v_fmac_f32_dpp v227, v247, v59 row_newbcast:14 row_mask:0xf bank_mask:0xf
	v_fmac_f32_dpp v224, v244, v60 row_newbcast:15 row_mask:0xf bank_mask:0xf
	v_fmac_f32_dpp v225, v245, v61 row_newbcast:15 row_mask:0xf bank_mask:0xf
	v_fmac_f32_dpp v226, v246, v62 row_newbcast:15 row_mask:0xf bank_mask:0xf
	v_fmac_f32_dpp v227, v247, v63 row_newbcast:15 row_mask:0xf bank_mask:0xf
	v_mul_f32_dpp v228, v244, v64 row_newbcast:0 row_mask:0xf bank_mask:0xf
	v_mul_f32_dpp v229, v245, v65 row_newbcast:0 row_mask:0xf bank_mask:0xf
	v_mul_f32_dpp v230, v246, v66 row_newbcast:0 row_mask:0xf bank_mask:0xf
	v_mul_f32_dpp v231, v247, v67 row_newbcast:0 row_mask:0xf bank_mask:0xf
	v_fmac_f32_dpp v228, v244, v68 row_newbcast:1 row_mask:0xf bank_mask:0xf
	v_fmac_f32_dpp v229, v245, v69 row_newbcast:1 row_mask:0xf bank_mask:0xf
	v_fmac_f32_dpp v230, v246, v70 row_newbcast:1 row_mask:0xf bank_mask:0xf
	v_fmac_f32_dpp v231, v247, v71 row_newbcast:1 row_mask:0xf bank_mask:0xf
	v_fmac_f32_dpp v228, v244, v72 row_newbcast:2 row_mask:0xf bank_mask:0xf
	v_fmac_f32_dpp v229, v245, v73 row_newbcast:2 row_mask:0xf bank_mask:0xf
	v_fmac_f32_dpp v230, v246, v74 row_newbcast:2 row_mask:0xf bank_mask:0xf
	v_fmac_f32_dpp v231, v247, v75 row_newbcast:2 row_mask:0xf bank_mask:0xf
	v_fmac_f32_dpp v228, v244, v76 row_newbcast:3 row_mask:0xf bank_mask:0xf
	v_fmac_f32_dpp v229, v245, v77 row_newbcast:3 row_mask:0xf bank_mask:0xf
	v_fmac_f32_dpp v230, v246, v78 row_newbcast:3 row_mask:0xf bank_mask:0xf
	v_fmac_f32_dpp v231, v247, v79 row_newbcast:3 row_mask:0xf bank_mask:0xf
	v_fmac_f32_dpp v228, v244, v80 row_newbcast:4 row_mask:0xf bank_mask:0xf
	v_fmac_f32_dpp v229, v245, v81 row_newbcast:4 row_mask:0xf bank_mask:0xf
	v_fmac_f32_dpp v230, v246, v82 row_newbcast:4 row_mask:0xf bank_mask:0xf
	v_fmac_f32_dpp v231, v247, v83 row_newbcast:4 row_mask:0xf bank_mask:0xf
	v_fmac_f32_dpp v228, v244, v84 row_newbcast:5 row_mask:0xf bank_mask:0xf
	v_fmac_f32_dpp v229, v245, v85 row_newbcast:5 row_mask:0xf bank_mask:0xf
	v_fmac_f32_dpp v230, v246, v86 row_newbcast:5 row_mask:0xf bank_mask:0xf
	v_fmac_f32_dpp v231, v247, v87 row_newbcast:5 row_mask:0xf bank_mask:0xf
	v_fmac_f32_dpp v228, v244, v88 row_newbcast:6 row_mask:0xf bank_mask:0xf
	v_fmac_f32_dpp v229, v245, v89 row_newbcast:6 row_mask:0xf bank_mask:0xf
	v_fmac_f32_dpp v230, v246, v90 row_newbcast:6 row_mask:0xf bank_mask:0xf
	v_fmac_f32_dpp v231, v247, v91 row_newbcast:6 row_mask:0xf bank_mask:0xf
	v_fmac_f32_dpp v228, v244, v92 row_newbcast:7 row_mask:0xf bank_mask:0xf
	v_fmac_f32_dpp v229, v245, v93 row_newbcast:7 row_mask:0xf bank_mask:0xf
	v_fmac_f32_dpp v230, v246, v94 row_newbcast:7 row_mask:0xf bank_mask:0xf
	v_fmac_f32_dpp v231, v247, v95 row_newbcast:7 row_mask:0xf bank_mask:0xf
	v_fmac_f32_dpp v228, v244, v96 row_newbcast:8 row_mask:0xf bank_mask:0xf
	v_fmac_f32_dpp v229, v245, v97 row_newbcast:8 row_mask:0xf bank_mask:0xf
	v_fmac_f32_dpp v230, v246, v98 row_newbcast:8 row_mask:0xf bank_mask:0xf
	v_fmac_f32_dpp v231, v247, v99 row_newbcast:8 row_mask:0xf bank_mask:0xf
	v_fmac_f32_dpp v228, v244, v100 row_newbcast:9 row_mask:0xf bank_mask:0xf
	v_fmac_f32_dpp v229, v245, v101 row_newbcast:9 row_mask:0xf bank_mask:0xf
	v_fmac_f32_dpp v230, v246, v102 row_newbcast:9 row_mask:0xf bank_mask:0xf
	v_fmac_f32_dpp v231, v247, v103 row_newbcast:9 row_mask:0xf bank_mask:0xf
	v_fmac_f32_dpp v228, v244, v104 row_newbcast:10 row_mask:0xf bank_mask:0xf
	v_fmac_f32_dpp v229, v245, v105 row_newbcast:10 row_mask:0xf bank_mask:0xf
	v_fmac_f32_dpp v230, v246, v106 row_newbcast:10 row_mask:0xf bank_mask:0xf
	v_fmac_f32_dpp v231, v247, v107 row_newbcast:10 row_mask:0xf bank_mask:0xf
	v_fmac_f32_dpp v228, v244, v108 row_newbcast:11 row_mask:0xf bank_mask:0xf
	v_fmac_f32_dpp v229, v245, v109 row_newbcast:11 row_mask:0xf bank_mask:0xf
	v_fmac_f32_dpp v230, v246, v110 row_newbcast:11 row_mask:0xf bank_mask:0xf
	v_fmac_f32_dpp v231, v247, v111 row_newbcast:11 row_mask:0xf bank_mask:0xf
	v_fmac_f32_dpp v228, v244, v112 row_newbcast:12 row_mask:0xf bank_mask:0xf
	v_fmac_f32_dpp v229, v245, v113 row_newbcast:12 row_mask:0xf bank_mask:0xf
	v_fmac_f32_dpp v230, v246, v114 row_newbcast:12 row_mask:0xf bank_mask:0xf
	v_fmac_f32_dpp v231, v247, v115 row_newbcast:12 row_mask:0xf bank_mask:0xf
	v_fmac_f32_dpp v228, v244, v116 row_newbcast:13 row_mask:0xf bank_mask:0xf
	v_fmac_f32_dpp v229, v245, v117 row_newbcast:13 row_mask:0xf bank_mask:0xf
	v_fmac_f32_dpp v230, v246, v118 row_newbcast:13 row_mask:0xf bank_mask:0xf
	v_fmac_f32_dpp v231, v247, v119 row_newbcast:13 row_mask:0xf bank_mask:0xf
	v_fmac_f32_dpp v228, v244, v120 row_newbcast:14 row_mask:0xf bank_mask:0xf
	v_fmac_f32_dpp v229, v245, v121 row_newbcast:14 row_mask:0xf bank_mask:0xf
	v_fmac_f32_dpp v230, v246, v122 row_newbcast:14 row_mask:0xf bank_mask:0xf
	v_fmac_f32_dpp v231, v247, v123 row_newbcast:14 row_mask:0xf bank_mask:0xf
	v_fmac_f32_dpp v228, v244, v124 row_newbcast:15 row_mask:0xf bank_mask:0xf
	v_fmac_f32_dpp v229, v245, v125 row_newbcast:15 row_mask:0xf bank_mask:0xf
	v_fmac_f32_dpp v230, v246, v126 row_newbcast:15 row_mask:0xf bank_mask:0xf
	v_fmac_f32_dpp v231, v247, v127 row_newbcast:15 row_mask:0xf bank_mask:0xf
	v_add_f32_e32 v224, v224, v225
	v_add_f32_e32 v226, v226, v227
	v_sub_f32_e64 v232, -v224, v226
	v_add_f32_e32 v228, v228, v229
	v_add_f32_e32 v230, v230, v231
	v_sub_f32_e64 v233, -v228, v230
	s_waitcnt lgkmcnt(0)
;     static __device__ __forceinline__ void updS(float (&S)[64], const In1& in, float sa, float vv) {
;         float t0, t1, t2, t3;
;         asm volatile("v_mul_f32_dpp %0, %8, %21 row_newbcast:%22" DPPM "v_mul_f32_dpp %1, %9, %21 row_newbcast:%22" DPPM "v_mul_f32_dpp %2, %10, %21 row_newbcast:%22" DPPM "v_mul_f32_dpp %3, %11, %21 row_newbcast:%22" DPPM
;                      "v_fmac_f32_dpp %0, %12, %4 row_newbcast:%22" DPPM "v_fmac_f32_dpp %1, %13, %5 row_newbcast:%22" DPPM "v_fmac_f32_dpp %2, %14, %6 row_newbcast:%22" DPPM "v_fmac_f32_dpp %3, %15, %7 row_newbcast:%22" DPPM
;                      "v_fmac_f32_dpp %0, %16, %20 row_newbcast:%22" DPPM "v_fmac_f32_dpp %1, %17, %20 row_newbcast:%22" DPPM "v_fmac_f32_dpp %2, %18, %20 row_newbcast:%22" DPPM "v_fmac_f32_dpp %3, %19, %20 row_newbcast:%22" DPPM
;                      : "=&v"(t0), "=&v"(t1), "=&v"(t2), "=&v"(t3)
;                      : "v"(S[K]), "v"(S[K + 1]), "v"(S[K + 2]), "v"(S[K + 3]), "v"(in.kd[0]), "v"(in.kd[1]), "v"(in.kd[2]), "v"(in.kd[3]), "v"(in.w[0]), "v"(in.w[1]), "v"(in.w[2]), "v"(in.w[3]),
;                        "v"(in.b[0]), "v"(in.b[1]), "v"(in.b[2]), "v"(in.b[3]), "v"(sa), "v"(vv), "n"(N0));
;         S[K] = t0; S[K + 1] = t1; S[K + 2] = t2; S[K + 3] = t3;
;         if constexpr (K + 4 < 64) ScanK<K + 4>::updS(S, in, sa, vv);
;     }
;     static __device__ __forceinline__ void updP(float (&P)[64], const In1& in, float sa) {
;         float u0, u1, u2, u3;
;         asm volatile("v_mul_f32_dpp %0, %8, %4 row_newbcast:%17" DPPM "v_mul_f32_dpp %1, %9, %5 row_newbcast:%17" DPPM "v_mul_f32_dpp %2, %10, %6 row_newbcast:%17" DPPM "v_mul_f32_dpp %3, %11, %7 row_newbcast:%17" DPPM
;                      "v_fmac_f32_dpp %0, %12, %16 row_newbcast:%17" DPPM "v_fmac_f32_dpp %1, %13, %16 row_newbcast:%17" DPPM "v_fmac_f32_dpp %2, %14, %16 row_newbcast:%17" DPPM "v_fmac_f32_dpp %3, %15, %16 row_newbcast:%17" DPPM
;                      : "=&v"(u0), "=&v"(u1), "=&v"(u2), "=&v"(u3)
;                      : "v"(P[K]), "v"(P[K + 1]), "v"(P[K + 2]), "v"(P[K + 3]), "v"(in.w[0]), "v"(in.w[1]), "v"(in.w[2]), "v"(in.w[3]), "v"(in.b[0]), "v"(in.b[1]), "v"(in.b[2]), "v"(in.b[3]), "v"(sa), "n"(N0));
;         P[K] = u0; P[K + 1] = u1; P[K + 2] = u2; P[K + 3] = u3;
;         if constexpr (K + 4 < 64) ScanK<K + 4>::updP(P, in, sa);
;     }
	s_nop 1
	v_mfma_f32_4x4x1_16b_f32 v[0:3], v128, v232, v[0:3]
	v_mfma_f32_4x4x1_16b_f32 v[4:7], v129, v232, v[4:7]
	v_mfma_f32_4x4x1_16b_f32 v[8:11], v130, v232, v[8:11]
	v_mfma_f32_4x4x1_16b_f32 v[12:15], v131, v232, v[12:15]
	v_mfma_f32_4x4x1_16b_f32 v[16:19], v132, v232, v[16:19]
	v_mfma_f32_4x4x1_16b_f32 v[20:23], v133, v232, v[20:23]
	v_mfma_f32_4x4x1_16b_f32 v[24:27], v134, v232, v[24:27]
	v_mfma_f32_4x4x1_16b_f32 v[28:31], v135, v232, v[28:31]
	v_mfma_f32_4x4x1_16b_f32 v[32:35], v136, v232, v[32:35]
	v_mfma_f32_4x4x1_16b_f32 v[36:39], v137, v232, v[36:39]
	v_mfma_f32_4x4x1_16b_f32 v[40:43], v138, v232, v[40:43]
	v_mfma_f32_4x4x1_16b_f32 v[44:47], v139, v232, v[44:47]
	v_mfma_f32_4x4x1_16b_f32 v[48:51], v140, v232, v[48:51]
	v_mfma_f32_4x4x1_16b_f32 v[52:55], v141, v232, v[52:55]
	v_mfma_f32_4x4x1_16b_f32 v[56:59], v142, v232, v[56:59]
	v_mfma_f32_4x4x1_16b_f32 v[60:63], v143, v232, v[60:63]
	v_mfma_f32_4x4x1_16b_f32 v[0:3], v144, v234, v[0:3]
	v_mfma_f32_4x4x1_16b_f32 v[4:7], v145, v234, v[4:7]
	v_mfma_f32_4x4x1_16b_f32 v[8:11], v146, v234, v[8:11]
	v_mfma_f32_4x4x1_16b_f32 v[12:15], v147, v234, v[12:15]
	v_mfma_f32_4x4x1_16b_f32 v[16:19], v148, v234, v[16:19]
	v_mfma_f32_4x4x1_16b_f32 v[20:23], v149, v234, v[20:23]
	v_mfma_f32_4x4x1_16b_f32 v[24:27], v150, v234, v[24:27]
	v_mfma_f32_4x4x1_16b_f32 v[28:31], v151, v234, v[28:31]
	v_mfma_f32_4x4x1_16b_f32 v[32:35], v152, v234, v[32:35]
	v_mfma_f32_4x4x1_16b_f32 v[36:39], v153, v234, v[36:39]
	v_mfma_f32_4x4x1_16b_f32 v[40:43], v154, v234, v[40:43]
	v_mfma_f32_4x4x1_16b_f32 v[44:47], v155, v234, v[44:47]
	v_mfma_f32_4x4x1_16b_f32 v[48:51], v156, v234, v[48:51]
	v_mfma_f32_4x4x1_16b_f32 v[52:55], v157, v234, v[52:55]
	v_mfma_f32_4x4x1_16b_f32 v[56:59], v158, v234, v[56:59]
	v_mfma_f32_4x4x1_16b_f32 v[60:63], v159, v234, v[60:63]
	v_mfma_f32_4x4x1_16b_f32 v[64:67], v128, v233, v[64:67]
	v_mfma_f32_4x4x1_16b_f32 v[68:71], v129, v233, v[68:71]
	v_mfma_f32_4x4x1_16b_f32 v[72:75], v130, v233, v[72:75]
	v_mfma_f32_4x4x1_16b_f32 v[76:79], v131, v233, v[76:79]
	v_mfma_f32_4x4x1_16b_f32 v[80:83], v132, v233, v[80:83]
	v_mfma_f32_4x4x1_16b_f32 v[84:87], v133, v233, v[84:87]
	v_mfma_f32_4x4x1_16b_f32 v[88:91], v134, v233, v[88:91]
	v_mfma_f32_4x4x1_16b_f32 v[92:95], v135, v233, v[92:95]
	v_mfma_f32_4x4x1_16b_f32 v[96:99], v136, v233, v[96:99]
	v_mfma_f32_4x4x1_16b_f32 v[100:103], v137, v233, v[100:103]
	v_mfma_f32_4x4x1_16b_f32 v[104:107], v138, v233, v[104:107]
	v_mfma_f32_4x4x1_16b_f32 v[108:111], v139, v233, v[108:111]
	v_mfma_f32_4x4x1_16b_f32 v[112:115], v140, v233, v[112:115]
	v_mfma_f32_4x4x1_16b_f32 v[116:119], v141, v233, v[116:119]
	v_mfma_f32_4x4x1_16b_f32 v[120:123], v142, v233, v[120:123]
	v_mfma_f32_4x4x1_16b_f32 v[124:127], v143, v233, v[124:127]
	s_sub_u32 s83, s83, 1
	s_cmp_eq_u32 s83, 0
	s_cbranch_scc1 .Lmy_p1d1_ldone
	s_sub_u32 s9, s9, 1
	s_cmp_eq_u32 s9, 0
	s_cbranch_scc1 .Lmy_p1d1_renorm
	s_branch .Lmy_p1d1_loop
.Lmy_p1d1_ldone:
	s_waitcnt vmcnt(5)
	buffer_load_dwordx4 v[192:195], v235, s[64:67], s72 offen
	buffer_load_dwordx4 v[196:199], v250, s[64:67], s72 offen
	buffer_load_dwordx4 v[200:203], v251, s[64:67], s72 offen
	buffer_load_dwordx2 v[204:205], v252, s[64:67], s76 offen
	buffer_load_ushort v206, v253, s[64:67], s76 offen
	s_add_i32 s72, s72, 0xfffff000
	s_max_i32 s72, s72, 0
	s_add_i32 s76, s76, 0xfffff800
	s_max_i32 s76, s76, 0
	v_pk_mul_f32 v[244:245], v[164:165], v[236:237]
	v_pk_mul_f32 v[246:247], v[166:167], v[238:239]
	v_pk_mul_f32 v[236:237], v[236:237], v[160:161]
	v_pk_mul_f32 v[238:239], v[238:239], v[162:163]
	v_pk_fma_f32 v[228:229], v[168:169], v[216:217], v[220:221]
	v_pk_fma_f32 v[230:231], v[170:171], v[218:219], v[222:223]
	v_pk_mul_f32 v[208:209], v[164:165], v[168:169]
	v_pk_mul_f32 v[210:211], v[166:167], v[170:171]
	v_rcp_f32_e32 v240, v236
	v_rcp_f32_e32 v241, v237
	v_rcp_f32_e32 v242, v238
	v_rcp_f32_e32 v243, v239
	v_lshlrev_b32_e32 v212, 16, v172
	v_and_b32_e32 v213, 0xffff0000, v172
	v_lshlrev_b32_e32 v214, 16, v173
	v_and_b32_e32 v215, 0xffff0000, v173
	v_pk_mul_f32 v[212:213], v[212:213], v[228:229]
	v_pk_mul_f32 v[214:215], v[214:215], v[230:231]
	v_lshlrev_b32_e32 v234, 16, v174
	v_pk_mul_f32 v[208:209], v[208:209], v[240:241]
	v_pk_mul_f32 v[210:211], v[210:211], v[242:243]
	v_pk_mul_f32 v[212:213], v[212:213], v[240:241]
	v_pk_mul_f32 v[214:215], v[214:215], v[242:243]
	ds_write2_b32 v248, v208, v209 offset0:0 offset1:16
	ds_write2_b32 v248, v210, v211 offset0:32 offset1:48
	ds_write2_b32 v248, v212, v213 offset0:64 offset1:80
	ds_write2_b32 v248, v214, v215 offset0:96 offset1:112
	ds_read_b128 v[128:131], v249 offset:0
	ds_read_b128 v[132:135], v249 offset:16
	ds_read_b128 v[136:139], v249 offset:32
	ds_read_b128 v[140:143], v249 offset:48
	ds_read_b128 v[144:147], v249 offset:256
	ds_read_b128 v[148:151], v249 offset:272
	ds_read_b128 v[152:155], v249 offset:288
	ds_read_b128 v[156:159], v249 offset:304
	v_mul_f32_dpp v224, v244, v0 row_newbcast:0 row_mask:0xf bank_mask:0xf
	v_mul_f32_dpp v225, v245, v1 row_newbcast:0 row_mask:0xf bank_mask:0xf
	v_mul_f32_dpp v226, v246, v2 row_newbcast:0 row_mask:0xf bank_mask:0xf
	v_mul_f32_dpp v227, v247, v3 row_newbcast:0 row_mask:0xf bank_mask:0xf
	v_fmac_f32_dpp v224, v244, v4 row_newbcast:1 row_mask:0xf bank_mask:0xf
	v_fmac_f32_dpp v225, v245, v5 row_newbcast:1 row_mask:0xf bank_mask:0xf
	v_fmac_f32_dpp v226, v246, v6 row_newbcast:1 row_mask:0xf bank_mask:0xf
	v_fmac_f32_dpp v227, v247, v7 row_newbcast:1 row_mask:0xf bank_mask:0xf
	v_fmac_f32_dpp v224, v244, v8 row_newbcast:2 row_mask:0xf bank_mask:0xf
	v_fmac_f32_dpp v225, v245, v9 row_newbcast:2 row_mask:0xf bank_mask:0xf
;     static __device__ __forceinline__ void dot(const float (&S)[64], const f32x4& a, float (&s)[4]) {
;         if constexpr (K == 0) {
;             asm volatile("v_mul_f32_dpp %0, %4, %8 row_newbcast:%16" DPPM "v_mul_f32_dpp %1, %5, %9 row_newbcast:%16" DPPM "v_mul_f32_dpp %2, %6, %10 row_newbcast:%16" DPPM "v_mul_f32_dpp %3, %7, %11 row_newbcast:%16" DPPM
;                          "v_fmac_f32_dpp %0, %4, %12 row_newbcast:%17" DPPM "v_fmac_f32_dpp %1, %5, %13 row_newbcast:%17" DPPM "v_fmac_f32_dpp %2, %6, %14 row_newbcast:%17" DPPM "v_fmac_f32_dpp %3, %7, %15 row_newbcast:%17" DPPM
;                          : "=&v"(s[0]), "=&v"(s[1]), "=&v"(s[2]), "=&v"(s[3])
;                          : "v"(a[0]), "v"(a[1]), "v"(a[2]), "v"(a[3]), "v"(S[K]), "v"(S[K + 1]), "v"(S[K + 2]), "v"(S[K + 3]), "v"(S[K + 4]), "v"(S[K + 5]), "v"(S[K + 6]), "v"(S[K + 7]), "n"(N0), "n"(N1));
;         } else
;         asm volatile("v_fmac_f32_dpp %0, %4, %8 row_newbcast:%16" DPPM "v_fmac_f32_dpp %1, %5, %9 row_newbcast:%16" DPPM "v_fmac_f32_dpp %2, %6, %10 row_newbcast:%16" DPPM "v_fmac_f32_dpp %3, %7, %11 row_newbcast:%16" DPPM
;                      "v_fmac_f32_dpp %0, %4, %12 row_newbcast:%17" DPPM "v_fmac_f32_dpp %1, %5, %13 row_newbcast:%17" DPPM "v_fmac_f32_dpp %2, %6, %14 row_newbcast:%17" DPPM "v_fmac_f32_dpp %3, %7, %15 row_newbcast:%17" DPPM
;                      : "+v"(s[0]), "+v"(s[1]), "+v"(s[2]), "+v"(s[3])
;                      : "v"(a[0]), "v"(a[1]), "v"(a[2]), "v"(a[3]), "v"(S[K]), "v"(S[K + 1]), "v"(S[K + 2]), "v"(S[K + 3]), "v"(S[K + 4]), "v"(S[K + 5]), "v"(S[K + 6]), "v"(S[K + 7]), "n"(N0), "n"(N1));
;         if constexpr (K + 8 < 64) ScanK<K + 8>::dot(S, a, s);
	v_fmac_f32_dpp v226, v246, v10 row_newbcast:2 row_mask:0xf bank_mask:0xf
	v_fmac_f32_dpp v227, v247, v11 row_newbcast:2 row_mask:0xf bank_mask:0xf
	v_fmac_f32_dpp v224, v244, v12 row_newbcast:3 row_mask:0xf bank_mask:0xf
	v_fmac_f32_dpp v225, v245, v13 row_newbcast:3 row_mask:0xf bank_mask:0xf
	v_fmac_f32_dpp v226, v246, v14 row_newbcast:3 row_mask:0xf bank_mask:0xf
	v_fmac_f32_dpp v227, v247, v15 row_newbcast:3 row_mask:0xf bank_mask:0xf
	v_fmac_f32_dpp v224, v244, v16 row_newbcast:4 row_mask:0xf bank_mask:0xf
	v_fmac_f32_dpp v225, v245, v17 row_newbcast:4 row_mask:0xf bank_mask:0xf
	v_fmac_f32_dpp v226, v246, v18 row_newbcast:4 row_mask:0xf bank_mask:0xf
	v_fmac_f32_dpp v227, v247, v19 row_newbcast:4 row_mask:0xf bank_mask:0xf
	v_fmac_f32_dpp v224, v244, v20 row_newbcast:5 row_mask:0xf bank_mask:0xf
	v_fmac_f32_dpp v225, v245, v21 row_newbcast:5 row_mask:0xf bank_mask:0xf
	v_fmac_f32_dpp v226, v246, v22 row_newbcast:5 row_mask:0xf bank_mask:0xf
	v_fmac_f32_dpp v227, v247, v23 row_newbcast:5 row_mask:0xf bank_mask:0xf
	v_fmac_f32_dpp v224, v244, v24 row_newbcast:6 row_mask:0xf bank_mask:0xf
	v_fmac_f32_dpp v225, v245, v25 row_newbcast:6 row_mask:0xf bank_mask:0xf
	v_fmac_f32_dpp v226, v246, v26 row_newbcast:6 row_mask:0xf bank_mask:0xf
	v_fmac_f32_dpp v227, v247, v27 row_newbcast:6 row_mask:0xf bank_mask:0xf
	v_fmac_f32_dpp v224, v244, v28 row_newbcast:7 row_mask:0xf bank_mask:0xf
	v_fmac_f32_dpp v225, v245, v29 row_newbcast:7 row_mask:0xf bank_mask:0xf
	v_fmac_f32_dpp v226, v246, v30 row_newbcast:7 row_mask:0xf bank_mask:0xf
	v_fmac_f32_dpp v227, v247, v31 row_newbcast:7 row_mask:0xf bank_mask:0xf
	v_fmac_f32_dpp v224, v244, v32 row_newbcast:8 row_mask:0xf bank_mask:0xf
	v_fmac_f32_dpp v225, v245, v33 row_newbcast:8 row_mask:0xf bank_mask:0xf
	v_fmac_f32_dpp v226, v246, v34 row_newbcast:8 row_mask:0xf bank_mask:0xf
	v_fmac_f32_dpp v227, v247, v35 row_newbcast:8 row_mask:0xf bank_mask:0xf
	v_fmac_f32_dpp v224, v244, v36 row_newbcast:9 row_mask:0xf bank_mask:0xf
	v_fmac_f32_dpp v225, v245, v37 row_newbcast:9 row_mask:0xf bank_mask:0xf
	v_fmac_f32_dpp v226, v246, v38 row_newbcast:9 row_mask:0xf bank_mask:0xf
	v_fmac_f32_dpp v227, v247, v39 row_newbcast:9 row_mask:0xf bank_mask:0xf
	v_fmac_f32_dpp v224, v244, v40 row_newbcast:10 row_mask:0xf bank_mask:0xf
	v_fmac_f32_dpp v225, v245, v41 row_newbcast:10 row_mask:0xf bank_mask:0xf
	v_fmac_f32_dpp v226, v246, v42 row_newbcast:10 row_mask:0xf bank_mask:0xf
	v_fmac_f32_dpp v227, v247, v43 row_newbcast:10 row_mask:0xf bank_mask:0xf
	v_fmac_f32_dpp v224, v244, v44 row_newbcast:11 row_mask:0xf bank_mask:0xf
	v_fmac_f32_dpp v225, v245, v45 row_newbcast:11 row_mask:0xf bank_mask:0xf
	v_fmac_f32_dpp v226, v246, v46 row_newbcast:11 row_mask:0xf bank_mask:0xf
	v_fmac_f32_dpp v227, v247, v47 row_newbcast:11 row_mask:0xf bank_mask:0xf
	v_fmac_f32_dpp v224, v244, v48 row_newbcast:12 row_mask:0xf bank_mask:0xf
	v_fmac_f32_dpp v225, v245, v49 row_newbcast:12 row_mask:0xf bank_mask:0xf
	v_fmac_f32_dpp v226, v246, v50 row_newbcast:12 row_mask:0xf bank_mask:0xf
	v_fmac_f32_dpp v227, v247, v51 row_newbcast:12 row_mask:0xf bank_mask:0xf
	v_fmac_f32_dpp v224, v244, v52 row_newbcast:13 row_mask:0xf bank_mask:0xf
	v_fmac_f32_dpp v225, v245, v53 row_newbcast:13 row_mask:0xf bank_mask:0xf
	v_fmac_f32_dpp v226, v246, v54 row_newbcast:13 row_mask:0xf bank_mask:0xf
	v_fmac_f32_dpp v227, v247, v55 row_newbcast:13 row_mask:0xf bank_mask:0xf
	v_fmac_f32_dpp v224, v244, v56 row_newbcast:14 row_mask:0xf bank_mask:0xf
	v_fmac_f32_dpp v225, v245, v57 row_newbcast:14 row_mask:0xf bank_mask:0xf
	v_fmac_f32_dpp v226, v246, v58 row_newbcast:14 row_mask:0xf bank_mask:0xf
	v_fmac_f32_dpp v227, v247, v59 row_newbcast:14 row_mask:0xf bank_mask:0xf
	v_fmac_f32_dpp v224, v244, v60 row_newbcast:15 row_mask:0xf bank_mask:0xf
	v_fmac_f32_dpp v225, v245, v61 row_newbcast:15 row_mask:0xf bank_mask:0xf
	v_fmac_f32_dpp v226, v246, v62 row_newbcast:15 row_mask:0xf bank_mask:0xf
	v_fmac_f32_dpp v227, v247, v63 row_newbcast:15 row_mask:0xf bank_mask:0xf
	v_mul_f32_dpp v228, v244, v64 row_newbcast:0 row_mask:0xf bank_mask:0xf
	v_mul_f32_dpp v229, v245, v65 row_newbcast:0 row_mask:0xf bank_mask:0xf
	v_mul_f32_dpp v230, v246, v66 row_newbcast:0 row_mask:0xf bank_mask:0xf
	v_mul_f32_dpp v231, v247, v67 row_newbcast:0 row_mask:0xf bank_mask:0xf
	v_fmac_f32_dpp v228, v244, v68 row_newbcast:1 row_mask:0xf bank_mask:0xf
	v_fmac_f32_dpp v229, v245, v69 row_newbcast:1 row_mask:0xf bank_mask:0xf
	v_fmac_f32_dpp v230, v246, v70 row_newbcast:1 row_mask:0xf bank_mask:0xf
	v_fmac_f32_dpp v231, v247, v71 row_newbcast:1 row_mask:0xf bank_mask:0xf
	v_fmac_f32_dpp v228, v244, v72 row_newbcast:2 row_mask:0xf bank_mask:0xf
	v_fmac_f32_dpp v229, v245, v73 row_newbcast:2 row_mask:0xf bank_mask:0xf
	v_fmac_f32_dpp v230, v246, v74 row_newbcast:2 row_mask:0xf bank_mask:0xf
	v_fmac_f32_dpp v231, v247, v75 row_newbcast:2 row_mask:0xf bank_mask:0xf
	v_fmac_f32_dpp v228, v244, v76 row_newbcast:3 row_mask:0xf bank_mask:0xf
	v_fmac_f32_dpp v229, v245, v77 row_newbcast:3 row_mask:0xf bank_mask:0xf
	v_fmac_f32_dpp v230, v246, v78 row_newbcast:3 row_mask:0xf bank_mask:0xf
	v_fmac_f32_dpp v231, v247, v79 row_newbcast:3 row_mask:0xf bank_mask:0xf
	v_fmac_f32_dpp v228, v244, v80 row_newbcast:4 row_mask:0xf bank_mask:0xf
	v_fmac_f32_dpp v229, v245, v81 row_newbcast:4 row_mask:0xf bank_mask:0xf
	v_fmac_f32_dpp v230, v246, v82 row_newbcast:4 row_mask:0xf bank_mask:0xf
	v_fmac_f32_dpp v231, v247, v83 row_newbcast:4 row_mask:0xf bank_mask:0xf
	v_fmac_f32_dpp v228, v244, v84 row_newbcast:5 row_mask:0xf bank_mask:0xf
	v_fmac_f32_dpp v229, v245, v85 row_newbcast:5 row_mask:0xf bank_mask:0xf
;     static __device__ __forceinline__ void dot(const float (&S)[64], const f32x4& a, float (&s)[4]) {
;         if constexpr (K == 0) {
;             asm volatile("v_mul_f32_dpp %0, %4, %8 row_newbcast:%16" DPPM "v_mul_f32_dpp %1, %5, %9 row_newbcast:%16" DPPM "v_mul_f32_dpp %2, %6, %10 row_newbcast:%16" DPPM "v_mul_f32_dpp %3, %7, %11 row_newbcast:%16" DPPM
;                          "v_fmac_f32_dpp %0, %4, %12 row_newbcast:%17" DPPM "v_fmac_f32_dpp %1, %5, %13 row_newbcast:%17" DPPM "v_fmac_f32_dpp %2, %6, %14 row_newbcast:%17" DPPM "v_fmac_f32_dpp %3, %7, %15 row_newbcast:%17" DPPM
;                          : "=&v"(s[0]), "=&v"(s[1]), "=&v"(s[2]), "=&v"(s[3])
;                          : "v"(a[0]), "v"(a[1]), "v"(a[2]), "v"(a[3]), "v"(S[K]), "v"(S[K + 1]), "v"(S[K + 2]), "v"(S[K + 3]), "v"(S[K + 4]), "v"(S[K + 5]), "v"(S[K + 6]), "v"(S[K + 7]), "n"(N0), "n"(N1));
;         } else
;         asm volatile("v_fmac_f32_dpp %0, %4, %8 row_newbcast:%16" DPPM "v_fmac_f32_dpp %1, %5, %9 row_newbcast:%16" DPPM "v_fmac_f32_dpp %2, %6, %10 row_newbcast:%16" DPPM "v_fmac_f32_dpp %3, %7, %11 row_newbcast:%16" DPPM
;                      "v_fmac_f32_dpp %0, %4, %12 row_newbcast:%17" DPPM "v_fmac_f32_dpp %1, %5, %13 row_newbcast:%17" DPPM "v_fmac_f32_dpp %2, %6, %14 row_newbcast:%17" DPPM "v_fmac_f32_dpp %3, %7, %15 row_newbcast:%17" DPPM
;                      : "+v"(s[0]), "+v"(s[1]), "+v"(s[2]), "+v"(s[3])
;                      : "v"(a[0]), "v"(a[1]), "v"(a[2]), "v"(a[3]), "v"(S[K]), "v"(S[K + 1]), "v"(S[K + 2]), "v"(S[K + 3]), "v"(S[K + 4]), "v"(S[K + 5]), "v"(S[K + 6]), "v"(S[K + 7]), "n"(N0), "n"(N1));
;         if constexpr (K + 8 < 64) ScanK<K + 8>::dot(S, a, s);
;     }
;     static __device__ __forceinline__ void upd(float (&S)[64], const In2& in, float sa, float vv, float& y0, float& y1) {
;         float t0, t1, t2, t3;
;         asm volatile("v_mul_f32_dpp %0, %10, %27 row_newbcast:%28" DPPM "v_mul_f32_dpp %1, %11, %27 row_newbcast:%28" DPPM "v_mul_f32_dpp %2, %12, %27 row_newbcast:%28" DPPM "v_mul_f32_dpp %3, %13, %27 row_newbcast:%28" DPPM
;                      "v_fmac_f32_dpp %0, %14, %6 row_newbcast:%28" DPPM "v_fmac_f32_dpp %1, %15, %7 row_newbcast:%28" DPPM "v_fmac_f32_dpp %2, %16, %8 row_newbcast:%28" DPPM "v_fmac_f32_dpp %3, %17, %9 row_newbcast:%28" DPPM
	v_fmac_f32_dpp v230, v246, v86 row_newbcast:5 row_mask:0xf bank_mask:0xf
	v_fmac_f32_dpp v231, v247, v87 row_newbcast:5 row_mask:0xf bank_mask:0xf
	v_fmac_f32_dpp v228, v244, v88 row_newbcast:6 row_mask:0xf bank_mask:0xf
	v_fmac_f32_dpp v229, v245, v89 row_newbcast:6 row_mask:0xf bank_mask:0xf
	v_fmac_f32_dpp v230, v246, v90 row_newbcast:6 row_mask:0xf bank_mask:0xf
	v_fmac_f32_dpp v231, v247, v91 row_newbcast:6 row_mask:0xf bank_mask:0xf
	v_fmac_f32_dpp v228, v244, v92 row_newbcast:7 row_mask:0xf bank_mask:0xf
	v_fmac_f32_dpp v229, v245, v93 row_newbcast:7 row_mask:0xf bank_mask:0xf
	v_fmac_f32_dpp v230, v246, v94 row_newbcast:7 row_mask:0xf bank_mask:0xf
	v_fmac_f32_dpp v231, v247, v95 row_newbcast:7 row_mask:0xf bank_mask:0xf
	v_fmac_f32_dpp v228, v244, v96 row_newbcast:8 row_mask:0xf bank_mask:0xf
	v_fmac_f32_dpp v229, v245, v97 row_newbcast:8 row_mask:0xf bank_mask:0xf
	v_fmac_f32_dpp v230, v246, v98 row_newbcast:8 row_mask:0xf bank_mask:0xf
	v_fmac_f32_dpp v231, v247, v99 row_newbcast:8 row_mask:0xf bank_mask:0xf
	v_fmac_f32_dpp v228, v244, v100 row_newbcast:9 row_mask:0xf bank_mask:0xf
	v_fmac_f32_dpp v229, v245, v101 row_newbcast:9 row_mask:0xf bank_mask:0xf
	v_fmac_f32_dpp v230, v246, v102 row_newbcast:9 row_mask:0xf bank_mask:0xf
	v_fmac_f32_dpp v231, v247, v103 row_newbcast:9 row_mask:0xf bank_mask:0xf
	v_fmac_f32_dpp v228, v244, v104 row_newbcast:10 row_mask:0xf bank_mask:0xf
	v_fmac_f32_dpp v229, v245, v105 row_newbcast:10 row_mask:0xf bank_mask:0xf
	v_fmac_f32_dpp v230, v246, v106 row_newbcast:10 row_mask:0xf bank_mask:0xf
	v_fmac_f32_dpp v231, v247, v107 row_newbcast:10 row_mask:0xf bank_mask:0xf
	v_fmac_f32_dpp v228, v244, v108 row_newbcast:11 row_mask:0xf bank_mask:0xf
	v_fmac_f32_dpp v229, v245, v109 row_newbcast:11 row_mask:0xf bank_mask:0xf
	v_fmac_f32_dpp v230, v246, v110 row_newbcast:11 row_mask:0xf bank_mask:0xf
	v_fmac_f32_dpp v231, v247, v111 row_newbcast:11 row_mask:0xf bank_mask:0xf
	v_fmac_f32_dpp v228, v244, v112 row_newbcast:12 row_mask:0xf bank_mask:0xf
	v_fmac_f32_dpp v229, v245, v113 row_newbcast:12 row_mask:0xf bank_mask:0xf
	v_fmac_f32_dpp v230, v246, v114 row_newbcast:12 row_mask:0xf bank_mask:0xf
	v_fmac_f32_dpp v231, v247, v115 row_newbcast:12 row_mask:0xf bank_mask:0xf
	v_fmac_f32_dpp v228, v244, v116 row_newbcast:13 row_mask:0xf bank_mask:0xf
	v_fmac_f32_dpp v229, v245, v117 row_newbcast:13 row_mask:0xf bank_mask:0xf
	v_fmac_f32_dpp v230, v246, v118 row_newbcast:13 row_mask:0xf bank_mask:0xf
	v_fmac_f32_dpp v231, v247, v119 row_newbcast:13 row_mask:0xf bank_mask:0xf
	v_fmac_f32_dpp v228, v244, v120 row_newbcast:14 row_mask:0xf bank_mask:0xf
	v_fmac_f32_dpp v229, v245, v121 row_newbcast:14 row_mask:0xf bank_mask:0xf
	v_fmac_f32_dpp v230, v246, v122 row_newbcast:14 row_mask:0xf bank_mask:0xf
	v_fmac_f32_dpp v231, v247, v123 row_newbcast:14 row_mask:0xf bank_mask:0xf
	v_fmac_f32_dpp v228, v244, v124 row_newbcast:15 row_mask:0xf bank_mask:0xf
	v_fmac_f32_dpp v229, v245, v125 row_newbcast:15 row_mask:0xf bank_mask:0xf
	v_fmac_f32_dpp v230, v246, v126 row_newbcast:15 row_mask:0xf bank_mask:0xf
	v_fmac_f32_dpp v231, v247, v127 row_newbcast:15 row_mask:0xf bank_mask:0xf
	v_add_f32_e32 v224, v224, v225
	v_add_f32_e32 v226, v226, v227
	v_sub_f32_e64 v232, -v224, v226
	v_add_f32_e32 v228, v228, v229
	v_add_f32_e32 v230, v230, v231
	v_sub_f32_e64 v233, -v228, v230
	s_waitcnt lgkmcnt(0)
	s_nop 1
	v_mfma_f32_4x4x1_16b_f32 v[0:3], v128, v232, v[0:3]
	v_mfma_f32_4x4x1_16b_f32 v[4:7], v129, v232, v[4:7]
	v_mfma_f32_4x4x1_16b_f32 v[8:11], v130, v232, v[8:11]
	v_mfma_f32_4x4x1_16b_f32 v[12:15], v131, v232, v[12:15]
	v_mfma_f32_4x4x1_16b_f32 v[16:19], v132, v232, v[16:19]
	v_mfma_f32_4x4x1_16b_f32 v[20:23], v133, v232, v[20:23]
	v_mfma_f32_4x4x1_16b_f32 v[24:27], v134, v232, v[24:27]
	v_mfma_f32_4x4x1_16b_f32 v[28:31], v135, v232, v[28:31]
	v_mfma_f32_4x4x1_16b_f32 v[32:35], v136, v232, v[32:35]
	v_mfma_f32_4x4x1_16b_f32 v[36:39], v137, v232, v[36:39]
	v_mfma_f32_4x4x1_16b_f32 v[40:43], v138, v232, v[40:43]
	v_mfma_f32_4x4x1_16b_f32 v[44:47], v139, v232, v[44:47]
	v_mfma_f32_4x4x1_16b_f32 v[48:51], v140, v232, v[48:51]
	v_mfma_f32_4x4x1_16b_f32 v[52:55], v141, v232, v[52:55]
	v_mfma_f32_4x4x1_16b_f32 v[56:59], v142, v232, v[56:59]
	v_mfma_f32_4x4x1_16b_f32 v[60:63], v143, v232, v[60:63]
	v_mfma_f32_4x4x1_16b_f32 v[0:3], v144, v234, v[0:3]
	v_mfma_f32_4x4x1_16b_f32 v[4:7], v145, v234, v[4:7]
	v_mfma_f32_4x4x1_16b_f32 v[8:11], v146, v234, v[8:11]
	v_mfma_f32_4x4x1_16b_f32 v[12:15], v147, v234, v[12:15]
	v_mfma_f32_4x4x1_16b_f32 v[16:19], v148, v234, v[16:19]
	v_mfma_f32_4x4x1_16b_f32 v[20:23], v149, v234, v[20:23]
	v_mfma_f32_4x4x1_16b_f32 v[24:27], v150, v234, v[24:27]
	v_mfma_f32_4x4x1_16b_f32 v[28:31], v151, v234, v[28:31]
	v_mfma_f32_4x4x1_16b_f32 v[32:35], v152, v234, v[32:35]
	v_mfma_f32_4x4x1_16b_f32 v[36:39], v153, v234, v[36:39]
	v_mfma_f32_4x4x1_16b_f32 v[40:43], v154, v234, v[40:43]
	v_mfma_f32_4x4x1_16b_f32 v[44:47], v155, v234, v[44:47]
	v_mfma_f32_4x4x1_16b_f32 v[48:51], v156, v234, v[48:51]
	v_mfma_f32_4x4x1_16b_f32 v[52:55], v157, v234, v[52:55]
	v_mfma_f32_4x4x1_16b_f32 v[56:59], v158, v234, v[56:59]
	v_mfma_f32_4x4x1_16b_f32 v[60:63], v159, v234, v[60:63]
	v_mfma_f32_4x4x1_16b_f32 v[64:67], v128, v233, v[64:67]
	v_mfma_f32_4x4x1_16b_f32 v[68:71], v129, v233, v[68:71]
	v_mfma_f32_4x4x1_16b_f32 v[72:75], v130, v233, v[72:75]
	v_mfma_f32_4x4x1_16b_f32 v[76:79], v131, v233, v[76:79]
	v_mfma_f32_4x4x1_16b_f32 v[80:83], v132, v233, v[80:83]
	v_mfma_f32_4x4x1_16b_f32 v[84:87], v133, v233, v[84:87]
	v_mfma_f32_4x4x1_16b_f32 v[88:91], v134, v233, v[88:91]
	v_mfma_f32_4x4x1_16b_f32 v[92:95], v135, v233, v[92:95]
;     static __device__ __forceinline__ void updS(float (&S)[64], const In1& in, float sa, float vv) {
;         float t0, t1, t2, t3;
;         asm volatile("v_mul_f32_dpp %0, %8, %21 row_newbcast:%22" DPPM "v_mul_f32_dpp %1, %9, %21 row_newbcast:%22" DPPM "v_mul_f32_dpp %2, %10, %21 row_newbcast:%22" DPPM "v_mul_f32_dpp %3, %11, %21 row_newbcast:%22" DPPM
;                      "v_fmac_f32_dpp %0, %12, %4 row_newbcast:%22" DPPM "v_fmac_f32_dpp %1, %13, %5 row_newbcast:%22" DPPM "v_fmac_f32_dpp %2, %14, %6 row_newbcast:%22" DPPM "v_fmac_f32_dpp %3, %15, %7 row_newbcast:%22" DPPM
;                      "v_fmac_f32_dpp %0, %16, %20 row_newbcast:%22" DPPM "v_fmac_f32_dpp %1, %17, %20 row_newbcast:%22" DPPM "v_fmac_f32_dpp %2, %18, %20 row_newbcast:%22" DPPM "v_fmac_f32_dpp %3, %19, %20 row_newbcast:%22" DPPM
;                      : "=&v"(t0), "=&v"(t1), "=&v"(t2), "=&v"(t3)
;                      : "v"(S[K]), "v"(S[K + 1]), "v"(S[K + 2]), "v"(S[K + 3]), "v"(in.kd[0]), "v"(in.kd[1]), "v"(in.kd[2]), "v"(in.kd[3]), "v"(in.w[0]), "v"(in.w[1]), "v"(in.w[2]), "v"(in.w[3]),
;                        "v"(in.b[0]), "v"(in.b[1]), "v"(in.b[2]), "v"(in.b[3]), "v"(sa), "v"(vv), "n"(N0));
;         S[K] = t0; S[K + 1] = t1; S[K + 2] = t2; S[K + 3] = t3;
;         if constexpr (K + 4 < 64) ScanK<K + 4>::updS(S, in, sa, vv);
;     }
;     static __device__ __forceinline__ void updP(float (&P)[64], const In1& in, float sa) {
;         float u0, u1, u2, u3;
;         asm volatile("v_mul_f32_dpp %0, %8, %4 row_newbcast:%17" DPPM "v_mul_f32_dpp %1, %9, %5 row_newbcast:%17" DPPM "v_mul_f32_dpp %2, %10, %6 row_newbcast:%17" DPPM "v_mul_f32_dpp %3, %11, %7 row_newbcast:%17" DPPM
;                      "v_fmac_f32_dpp %0, %12, %16 row_newbcast:%17" DPPM "v_fmac_f32_dpp %1, %13, %16 row_newbcast:%17" DPPM "v_fmac_f32_dpp %2, %14, %16 row_newbcast:%17" DPPM "v_fmac_f32_dpp %3, %15, %16 row_newbcast:%17" DPPM
;                      : "=&v"(u0), "=&v"(u1), "=&v"(u2), "=&v"(u3)
;                      : "v"(P[K]), "v"(P[K + 1]), "v"(P[K + 2]), "v"(P[K + 3]), "v"(in.w[0]), "v"(in.w[1]), "v"(in.w[2]), "v"(in.w[3]), "v"(in.b[0]), "v"(in.b[1]), "v"(in.b[2]), "v"(in.b[3]), "v"(sa), "n"(N0));
;         P[K] = u0; P[K + 1] = u1; P[K + 2] = u2; P[K + 3] = u3;
;         if constexpr (K + 4 < 64) ScanK<K + 4>::updP(P, in, sa);
;     }
	v_mfma_f32_4x4x1_16b_f32 v[96:99], v136, v233, v[96:99]
	v_mfma_f32_4x4x1_16b_f32 v[100:103], v137, v233, v[100:103]
	v_mfma_f32_4x4x1_16b_f32 v[104:107], v138, v233, v[104:107]
	v_mfma_f32_4x4x1_16b_f32 v[108:111], v139, v233, v[108:111]
	v_mfma_f32_4x4x1_16b_f32 v[112:115], v140, v233, v[112:115]
	v_mfma_f32_4x4x1_16b_f32 v[116:119], v141, v233, v[116:119]
	v_mfma_f32_4x4x1_16b_f32 v[120:123], v142, v233, v[120:123]
	v_mfma_f32_4x4x1_16b_f32 v[124:127], v143, v233, v[124:127]
	v_mul_f32_dpp v0, v236, v0 row_newbcast:0 row_mask:0xf bank_mask:0xf
	v_mul_f32_dpp v1, v237, v1 row_newbcast:0 row_mask:0xf bank_mask:0xf
	v_mul_f32_dpp v2, v238, v2 row_newbcast:0 row_mask:0xf bank_mask:0xf
	v_mul_f32_dpp v3, v239, v3 row_newbcast:0 row_mask:0xf bank_mask:0xf
	v_mul_f32_dpp v4, v236, v4 row_newbcast:1 row_mask:0xf bank_mask:0xf
	v_mul_f32_dpp v5, v237, v5 row_newbcast:1 row_mask:0xf bank_mask:0xf
	v_mul_f32_dpp v6, v238, v6 row_newbcast:1 row_mask:0xf bank_mask:0xf
	v_mul_f32_dpp v7, v239, v7 row_newbcast:1 row_mask:0xf bank_mask:0xf
	v_mul_f32_dpp v8, v236, v8 row_newbcast:2 row_mask:0xf bank_mask:0xf
	v_mul_f32_dpp v9, v237, v9 row_newbcast:2 row_mask:0xf bank_mask:0xf
	v_mul_f32_dpp v10, v238, v10 row_newbcast:2 row_mask:0xf bank_mask:0xf
	v_mul_f32_dpp v11, v239, v11 row_newbcast:2 row_mask:0xf bank_mask:0xf
	v_mul_f32_dpp v12, v236, v12 row_newbcast:3 row_mask:0xf bank_mask:0xf
	v_mul_f32_dpp v13, v237, v13 row_newbcast:3 row_mask:0xf bank_mask:0xf
	v_mul_f32_dpp v14, v238, v14 row_newbcast:3 row_mask:0xf bank_mask:0xf
	v_mul_f32_dpp v15, v239, v15 row_newbcast:3 row_mask:0xf bank_mask:0xf
	v_mul_f32_dpp v16, v236, v16 row_newbcast:4 row_mask:0xf bank_mask:0xf
	v_mul_f32_dpp v17, v237, v17 row_newbcast:4 row_mask:0xf bank_mask:0xf
	v_mul_f32_dpp v18, v238, v18 row_newbcast:4 row_mask:0xf bank_mask:0xf
	v_mul_f32_dpp v19, v239, v19 row_newbcast:4 row_mask:0xf bank_mask:0xf
	v_mul_f32_dpp v20, v236, v20 row_newbcast:5 row_mask:0xf bank_mask:0xf
	v_mul_f32_dpp v21, v237, v21 row_newbcast:5 row_mask:0xf bank_mask:0xf
	v_mul_f32_dpp v22, v238, v22 row_newbcast:5 row_mask:0xf bank_mask:0xf
	v_mul_f32_dpp v23, v239, v23 row_newbcast:5 row_mask:0xf bank_mask:0xf
	v_mul_f32_dpp v24, v236, v24 row_newbcast:6 row_mask:0xf bank_mask:0xf
	v_mul_f32_dpp v25, v237, v25 row_newbcast:6 row_mask:0xf bank_mask:0xf
	v_mul_f32_dpp v26, v238, v26 row_newbcast:6 row_mask:0xf bank_mask:0xf
	v_mul_f32_dpp v27, v239, v27 row_newbcast:6 row_mask:0xf bank_mask:0xf
	v_mul_f32_dpp v28, v236, v28 row_newbcast:7 row_mask:0xf bank_mask:0xf
	v_mul_f32_dpp v29, v237, v29 row_newbcast:7 row_mask:0xf bank_mask:0xf
	v_mul_f32_dpp v30, v238, v30 row_newbcast:7 row_mask:0xf bank_mask:0xf
	v_mul_f32_dpp v31, v239, v31 row_newbcast:7 row_mask:0xf bank_mask:0xf
	v_mul_f32_dpp v32, v236, v32 row_newbcast:8 row_mask:0xf bank_mask:0xf
	v_mul_f32_dpp v33, v237, v33 row_newbcast:8 row_mask:0xf bank_mask:0xf
	v_mul_f32_dpp v34, v238, v34 row_newbcast:8 row_mask:0xf bank_mask:0xf
	v_mul_f32_dpp v35, v239, v35 row_newbcast:8 row_mask:0xf bank_mask:0xf
	v_mul_f32_dpp v36, v236, v36 row_newbcast:9 row_mask:0xf bank_mask:0xf
	v_mul_f32_dpp v37, v237, v37 row_newbcast:9 row_mask:0xf bank_mask:0xf
	v_mul_f32_dpp v38, v238, v38 row_newbcast:9 row_mask:0xf bank_mask:0xf
	v_mul_f32_dpp v39, v239, v39 row_newbcast:9 row_mask:0xf bank_mask:0xf
	v_mul_f32_dpp v40, v236, v40 row_newbcast:10 row_mask:0xf bank_mask:0xf
	v_mul_f32_dpp v41, v237, v41 row_newbcast:10 row_mask:0xf bank_mask:0xf
	v_mul_f32_dpp v42, v238, v42 row_newbcast:10 row_mask:0xf bank_mask:0xf
	v_mul_f32_dpp v43, v239, v43 row_newbcast:10 row_mask:0xf bank_mask:0xf
	v_mul_f32_dpp v44, v236, v44 row_newbcast:11 row_mask:0xf bank_mask:0xf
	v_mul_f32_dpp v45, v237, v45 row_newbcast:11 row_mask:0xf bank_mask:0xf
	v_mul_f32_dpp v46, v238, v46 row_newbcast:11 row_mask:0xf bank_mask:0xf
	v_mul_f32_dpp v47, v239, v47 row_newbcast:11 row_mask:0xf bank_mask:0xf
	v_mul_f32_dpp v48, v236, v48 row_newbcast:12 row_mask:0xf bank_mask:0xf
	v_mul_f32_dpp v49, v237, v49 row_newbcast:12 row_mask:0xf bank_mask:0xf
	v_mul_f32_dpp v50, v238, v50 row_newbcast:12 row_mask:0xf bank_mask:0xf
	v_mul_f32_dpp v51, v239, v51 row_newbcast:12 row_mask:0xf bank_mask:0xf
	v_mul_f32_dpp v52, v236, v52 row_newbcast:13 row_mask:0xf bank_mask:0xf
	v_mul_f32_dpp v53, v237, v53 row_newbcast:13 row_mask:0xf bank_mask:0xf
	v_mul_f32_dpp v54, v238, v54 row_newbcast:13 row_mask:0xf bank_mask:0xf
	v_mul_f32_dpp v55, v239, v55 row_newbcast:13 row_mask:0xf bank_mask:0xf
	v_mul_f32_dpp v56, v236, v56 row_newbcast:14 row_mask:0xf bank_mask:0xf
	v_mul_f32_dpp v57, v237, v57 row_newbcast:14 row_mask:0xf bank_mask:0xf
	v_mul_f32_dpp v58, v238, v58 row_newbcast:14 row_mask:0xf bank_mask:0xf
	v_mul_f32_dpp v59, v239, v59 row_newbcast:14 row_mask:0xf bank_mask:0xf
	v_mul_f32_dpp v60, v236, v60 row_newbcast:15 row_mask:0xf bank_mask:0xf
	v_mul_f32_dpp v61, v237, v61 row_newbcast:15 row_mask:0xf bank_mask:0xf
	v_mul_f32_dpp v62, v238, v62 row_newbcast:15 row_mask:0xf bank_mask:0xf
	v_mul_f32_dpp v63, v239, v63 row_newbcast:15 row_mask:0xf bank_mask:0xf
	v_mul_f32_dpp v64, v236, v64 row_newbcast:0 row_mask:0xf bank_mask:0xf
	v_mul_f32_dpp v65, v237, v65 row_newbcast:0 row_mask:0xf bank_mask:0xf
	v_mul_f32_dpp v66, v238, v66 row_newbcast:0 row_mask:0xf bank_mask:0xf
	v_mul_f32_dpp v67, v239, v67 row_newbcast:0 row_mask:0xf bank_mask:0xf
	v_mul_f32_dpp v68, v236, v68 row_newbcast:1 row_mask:0xf bank_mask:0xf
	v_mul_f32_dpp v69, v237, v69 row_newbcast:1 row_mask:0xf bank_mask:0xf
	v_mul_f32_dpp v70, v238, v70 row_newbcast:1 row_mask:0xf bank_mask:0xf
	v_mul_f32_dpp v71, v239, v71 row_newbcast:1 row_mask:0xf bank_mask:0xf
;     static __device__ __forceinline__ void updS(float (&S)[64], const In1& in, float sa, float vv) {
;         float t0, t1, t2, t3;
;         asm volatile("v_mul_f32_dpp %0, %8, %21 row_newbcast:%22" DPPM "v_mul_f32_dpp %1, %9, %21 row_newbcast:%22" DPPM "v_mul_f32_dpp %2, %10, %21 row_newbcast:%22" DPPM "v_mul_f32_dpp %3, %11, %21 row_newbcast:%22" DPPM
;                      "v_fmac_f32_dpp %0, %12, %4 row_newbcast:%22" DPPM "v_fmac_f32_dpp %1, %13, %5 row_newbcast:%22" DPPM "v_fmac_f32_dpp %2, %14, %6 row_newbcast:%22" DPPM "v_fmac_f32_dpp %3, %15, %7 row_newbcast:%22" DPPM
;                      "v_fmac_f32_dpp %0, %16, %20 row_newbcast:%22" DPPM "v_fmac_f32_dpp %1, %17, %20 row_newbcast:%22" DPPM "v_fmac_f32_dpp %2, %18, %20 row_newbcast:%22" DPPM "v_fmac_f32_dpp %3, %19, %20 row_newbcast:%22" DPPM
;                      : "=&v"(t0), "=&v"(t1), "=&v"(t2), "=&v"(t3)
;                      : "v"(S[K]), "v"(S[K + 1]), "v"(S[K + 2]), "v"(S[K + 3]), "v"(in.kd[0]), "v"(in.kd[1]), "v"(in.kd[2]), "v"(in.kd[3]), "v"(in.w[0]), "v"(in.w[1]), "v"(in.w[2]), "v"(in.w[3]),
;                        "v"(in.b[0]), "v"(in.b[1]), "v"(in.b[2]), "v"(in.b[3]), "v"(sa), "v"(vv), "n"(N0));
;         S[K] = t0; S[K + 1] = t1; S[K + 2] = t2; S[K + 3] = t3;
;         if constexpr (K + 4 < 64) ScanK<K + 4>::updS(S, in, sa, vv);
;     }
;     static __device__ __forceinline__ void updP(float (&P)[64], const In1& in, float sa) {
;         float u0, u1, u2, u3;
;         asm volatile("v_mul_f32_dpp %0, %8, %4 row_newbcast:%17" DPPM "v_mul_f32_dpp %1, %9, %5 row_newbcast:%17" DPPM "v_mul_f32_dpp %2, %10, %6 row_newbcast:%17" DPPM "v_mul_f32_dpp %3, %11, %7 row_newbcast:%17" DPPM
;                      "v_fmac_f32_dpp %0, %12, %16 row_newbcast:%17" DPPM "v_fmac_f32_dpp %1, %13, %16 row_newbcast:%17" DPPM "v_fmac_f32_dpp %2, %14, %16 row_newbcast:%17" DPPM "v_fmac_f32_dpp %3, %15, %16 row_newbcast:%17" DPPM
;                      : "=&v"(u0), "=&v"(u1), "=&v"(u2), "=&v"(u3)
;                      : "v"(P[K]), "v"(P[K + 1]), "v"(P[K + 2]), "v"(P[K + 3]), "v"(in.w[0]), "v"(in.w[1]), "v"(in.w[2]), "v"(in.w[3]), "v"(in.b[0]), "v"(in.b[1]), "v"(in.b[2]), "v"(in.b[3]), "v"(sa), "n"(N0));
;         P[K] = u0; P[K + 1] = u1; P[K + 2] = u2; P[K + 3] = u3;
;         if constexpr (K + 4 < 64) ScanK<K + 4>::updP(P, in, sa);
;     }
	v_mul_f32_dpp v72, v236, v72 row_newbcast:2 row_mask:0xf bank_mask:0xf
	v_mul_f32_dpp v73, v237, v73 row_newbcast:2 row_mask:0xf bank_mask:0xf
	v_mul_f32_dpp v74, v238, v74 row_newbcast:2 row_mask:0xf bank_mask:0xf
	v_mul_f32_dpp v75, v239, v75 row_newbcast:2 row_mask:0xf bank_mask:0xf
	v_mul_f32_dpp v76, v236, v76 row_newbcast:3 row_mask:0xf bank_mask:0xf
	v_mul_f32_dpp v77, v237, v77 row_newbcast:3 row_mask:0xf bank_mask:0xf
	v_mul_f32_dpp v78, v238, v78 row_newbcast:3 row_mask:0xf bank_mask:0xf
	v_mul_f32_dpp v79, v239, v79 row_newbcast:3 row_mask:0xf bank_mask:0xf
	v_mul_f32_dpp v80, v236, v80 row_newbcast:4 row_mask:0xf bank_mask:0xf
	v_mul_f32_dpp v81, v237, v81 row_newbcast:4 row_mask:0xf bank_mask:0xf
	v_mul_f32_dpp v82, v238, v82 row_newbcast:4 row_mask:0xf bank_mask:0xf
	v_mul_f32_dpp v83, v239, v83 row_newbcast:4 row_mask:0xf bank_mask:0xf
	v_mul_f32_dpp v84, v236, v84 row_newbcast:5 row_mask:0xf bank_mask:0xf
	v_mul_f32_dpp v85, v237, v85 row_newbcast:5 row_mask:0xf bank_mask:0xf
	v_mul_f32_dpp v86, v238, v86 row_newbcast:5 row_mask:0xf bank_mask:0xf
	v_mul_f32_dpp v87, v239, v87 row_newbcast:5 row_mask:0xf bank_mask:0xf
	v_mul_f32_dpp v88, v236, v88 row_newbcast:6 row_mask:0xf bank_mask:0xf
	v_mul_f32_dpp v89, v237, v89 row_newbcast:6 row_mask:0xf bank_mask:0xf
	v_mul_f32_dpp v90, v238, v90 row_newbcast:6 row_mask:0xf bank_mask:0xf
	v_mul_f32_dpp v91, v239, v91 row_newbcast:6 row_mask:0xf bank_mask:0xf
	v_mul_f32_dpp v92, v236, v92 row_newbcast:7 row_mask:0xf bank_mask:0xf
	v_mul_f32_dpp v93, v237, v93 row_newbcast:7 row_mask:0xf bank_mask:0xf
	v_mul_f32_dpp v94, v238, v94 row_newbcast:7 row_mask:0xf bank_mask:0xf
	v_mul_f32_dpp v95, v239, v95 row_newbcast:7 row_mask:0xf bank_mask:0xf
	v_mul_f32_dpp v96, v236, v96 row_newbcast:8 row_mask:0xf bank_mask:0xf
	v_mul_f32_dpp v97, v237, v97 row_newbcast:8 row_mask:0xf bank_mask:0xf
	v_mul_f32_dpp v98, v238, v98 row_newbcast:8 row_mask:0xf bank_mask:0xf
	v_mul_f32_dpp v99, v239, v99 row_newbcast:8 row_mask:0xf bank_mask:0xf
	v_mul_f32_dpp v100, v236, v100 row_newbcast:9 row_mask:0xf bank_mask:0xf
	v_mul_f32_dpp v101, v237, v101 row_newbcast:9 row_mask:0xf bank_mask:0xf
	v_mul_f32_dpp v102, v238, v102 row_newbcast:9 row_mask:0xf bank_mask:0xf
	v_mul_f32_dpp v103, v239, v103 row_newbcast:9 row_mask:0xf bank_mask:0xf
	v_mul_f32_dpp v104, v236, v104 row_newbcast:10 row_mask:0xf bank_mask:0xf
	v_mul_f32_dpp v105, v237, v105 row_newbcast:10 row_mask:0xf bank_mask:0xf
	v_mul_f32_dpp v106, v238, v106 row_newbcast:10 row_mask:0xf bank_mask:0xf
	v_mul_f32_dpp v107, v239, v107 row_newbcast:10 row_mask:0xf bank_mask:0xf
	v_mul_f32_dpp v108, v236, v108 row_newbcast:11 row_mask:0xf bank_mask:0xf
	v_mul_f32_dpp v109, v237, v109 row_newbcast:11 row_mask:0xf bank_mask:0xf
	v_mul_f32_dpp v110, v238, v110 row_newbcast:11 row_mask:0xf bank_mask:0xf
	v_mul_f32_dpp v111, v239, v111 row_newbcast:11 row_mask:0xf bank_mask:0xf
	v_mul_f32_dpp v112, v236, v112 row_newbcast:12 row_mask:0xf bank_mask:0xf
	v_mul_f32_dpp v113, v237, v113 row_newbcast:12 row_mask:0xf bank_mask:0xf
	v_mul_f32_dpp v114, v238, v114 row_newbcast:12 row_mask:0xf bank_mask:0xf
	v_mul_f32_dpp v115, v239, v115 row_newbcast:12 row_mask:0xf bank_mask:0xf
	v_mul_f32_dpp v116, v236, v116 row_newbcast:13 row_mask:0xf bank_mask:0xf
	v_mul_f32_dpp v117, v237, v117 row_newbcast:13 row_mask:0xf bank_mask:0xf
	v_mul_f32_dpp v118, v238, v118 row_newbcast:13 row_mask:0xf bank_mask:0xf
	v_mul_f32_dpp v119, v239, v119 row_newbcast:13 row_mask:0xf bank_mask:0xf
	v_mul_f32_dpp v120, v236, v120 row_newbcast:14 row_mask:0xf bank_mask:0xf
	v_mul_f32_dpp v121, v237, v121 row_newbcast:14 row_mask:0xf bank_mask:0xf
	v_mul_f32_dpp v122, v238, v122 row_newbcast:14 row_mask:0xf bank_mask:0xf
	v_mul_f32_dpp v123, v239, v123 row_newbcast:14 row_mask:0xf bank_mask:0xf
	v_mul_f32_dpp v124, v236, v124 row_newbcast:15 row_mask:0xf bank_mask:0xf
	v_mul_f32_dpp v125, v237, v125 row_newbcast:15 row_mask:0xf bank_mask:0xf
	v_mul_f32_dpp v126, v238, v126 row_newbcast:15 row_mask:0xf bank_mask:0xf
	v_mul_f32_dpp v127, v239, v127 row_newbcast:15 row_mask:0xf bank_mask:0xf
	v_mov_b32_e32 v236, 1.0
	v_mov_b32_e32 v237, 1.0
	v_mov_b32_e32 v238, 1.0
	v_mov_b32_e32 v239, 1.0
	s_waitcnt vmcnt(0)
; #define NEXT_ITEM() (MIX ? (int)__builtin_amdgcn_readfirstlane(lane == 0 ? __hip_atomic_fetch_add(qctr, 1u, __ATOMIC_RELAXED, __HIP_MEMORY_SCOPE_AGENT) : 0u) : item + (int)gridDim.x * 8)
; template <bool MIX> __device__ __forceinline__ void scan_pass1(const Params& p, int d, float* ldsf) {
;     ...
;     for (int item = MIX ? NEXT_ITEM() : (int)(blockIdx.x * 8 + wid); item < 2 * NS; item = NEXT_ITEM()) {
;     ...
;         float* po = (isP ? PT : SLT) + ((size_t)(bh * NC + c)) * 4096 + lane * 64;
; #pragma unroll
;         for (int i = 0; i < 16; ++i) *(f32x4*)(po + 4 * i) = (f32x4){S[4 * i], S[4 * i + 1], S[4 * i + 2], S[4 * i + 3]};
;     }
	s_nop 1
	v_and_b32_e32 v128, 63, v254
	v_lshlrev_b32_e32 v129, 8, v128
	v_lshlrev_b32_e32 v130, 2, v128
	global_store_dwordx4 v129, v[0:3], s[90:91] offset:0
	global_store_dwordx4 v129, v[4:7], s[90:91] offset:16
	global_store_dwordx4 v129, v[8:11], s[90:91] offset:32
	global_store_dwordx4 v129, v[12:15], s[90:91] offset:48
	global_store_dwordx4 v129, v[16:19], s[90:91] offset:64
	global_store_dwordx4 v129, v[20:23], s[90:91] offset:80
	global_store_dwordx4 v129, v[24:27], s[90:91] offset:96
	global_store_dwordx4 v129, v[28:31], s[90:91] offset:112
	global_store_dwordx4 v129, v[32:35], s[90:91] offset:128
	global_store_dwordx4 v129, v[36:39], s[90:91] offset:144
	global_store_dwordx4 v129, v[40:43], s[90:91] offset:160
	global_store_dwordx4 v129, v[44:47], s[90:91] offset:176
	global_store_dwordx4 v129, v[48:51], s[90:91] offset:192
	global_store_dwordx4 v129, v[52:55], s[90:91] offset:208
	global_store_dwordx4 v129, v[56:59], s[90:91] offset:224
	global_store_dwordx4 v129, v[60:63], s[90:91] offset:240
	global_store_dword v130, v64, s[92:93] offset:0
	global_store_dword v130, v65, s[92:93] offset:256
	global_store_dword v130, v66, s[92:93] offset:512
	global_store_dword v130, v67, s[92:93] offset:768
	global_store_dword v130, v68, s[92:93] offset:1024
	global_store_dword v130, v69, s[92:93] offset:1280
	global_store_dword v130, v70, s[92:93] offset:1536
	global_store_dword v130, v71, s[92:93] offset:1792
	global_store_dword v130, v72, s[92:93] offset:2048
	global_store_dword v130, v73, s[92:93] offset:2304
	global_store_dword v130, v74, s[92:93] offset:2560
	global_store_dword v130, v75, s[92:93] offset:2816
	global_store_dword v130, v76, s[92:93] offset:3072
	global_store_dword v130, v77, s[92:93] offset:3328
	global_store_dword v130, v78, s[92:93] offset:3584
	global_store_dword v130, v79, s[92:93] offset:3840
	s_add_u32 s92, s92, 0x1000
	s_addc_u32 s93, s93, 0
	global_store_dword v130, v80, s[92:93] offset:0
	global_store_dword v130, v81, s[92:93] offset:256
	global_store_dword v130, v82, s[92:93] offset:512
	global_store_dword v130, v83, s[92:93] offset:768
	global_store_dword v130, v84, s[92:93] offset:1024
	global_store_dword v130, v85, s[92:93] offset:1280
	global_store_dword v130, v86, s[92:93] offset:1536
	global_store_dword v130, v87, s[92:93] offset:1792
	global_store_dword v130, v88, s[92:93] offset:2048
	global_store_dword v130, v89, s[92:93] offset:2304
	global_store_dword v130, v90, s[92:93] offset:2560
	global_store_dword v130, v91, s[92:93] offset:2816
	global_store_dword v130, v92, s[92:93] offset:3072
	global_store_dword v130, v93, s[92:93] offset:3328
	global_store_dword v130, v94, s[92:93] offset:3584
	global_store_dword v130, v95, s[92:93] offset:3840
	s_add_u32 s92, s92, 0x1000
	s_addc_u32 s93, s93, 0
	global_store_dword v130, v96, s[92:93] offset:0
	global_store_dword v130, v97, s[92:93] offset:256
	global_store_dword v130, v98, s[92:93] offset:512
	global_store_dword v130, v99, s[92:93] offset:768
	global_store_dword v130, v100, s[92:93] offset:1024
	global_store_dword v130, v101, s[92:93] offset:1280
	global_store_dword v130, v102, s[92:93] offset:1536
	global_store_dword v130, v103, s[92:93] offset:1792
	global_store_dword v130, v104, s[92:93] offset:2048
	global_store_dword v130, v105, s[92:93] offset:2304
	global_store_dword v130, v106, s[92:93] offset:2560
	global_store_dword v130, v107, s[92:93] offset:2816
	global_store_dword v130, v108, s[92:93] offset:3072
	global_store_dword v130, v109, s[92:93] offset:3328
	global_store_dword v130, v110, s[92:93] offset:3584
	global_store_dword v130, v111, s[92:93] offset:3840
	s_add_u32 s92, s92, 0x1000
	s_addc_u32 s93, s93, 0
	global_store_dword v130, v112, s[92:93] offset:0
	global_store_dword v130, v113, s[92:93] offset:256
	global_store_dword v130, v114, s[92:93] offset:512
	global_store_dword v130, v115, s[92:93] offset:768
	global_store_dword v130, v116, s[92:93] offset:1024
	global_store_dword v130, v117, s[92:93] offset:1280
	global_store_dword v130, v118, s[92:93] offset:1536
	global_store_dword v130, v119, s[92:93] offset:1792
	global_store_dword v130, v120, s[92:93] offset:2048
	global_store_dword v130, v121, s[92:93] offset:2304
	global_store_dword v130, v122, s[92:93] offset:2560
	global_store_dword v130, v123, s[92:93] offset:2816
	global_store_dword v130, v124, s[92:93] offset:3072
	global_store_dword v130, v125, s[92:93] offset:3328
	global_store_dword v130, v126, s[92:93] offset:3584
	global_store_dword v130, v127, s[92:93] offset:3840
	s_nop 1
	s_lshl_b32 s6, s96, 3
	s_add_i32 s0, s0, s6
	s_branch .Lmy_p1d1_item
